# v17 + epilogues wait vmcnt(0) before their first store; the first two counted waits of each unit's first K iteration run only in the first unit of a phase
# speedup vs baseline: 1.0017x; 1.0017x over previous
; template <class Epi, class Sched, bool ALIGN_EPI = false, bool SP2 = false>
; __device__ __forceinline__ void gemm_phase(PG8_LAS unsigned char* lds, const Gemm g, const Sched& S, const Epi& E) {
;     ...
;     const char* cA = (const char*)g.A + (size_t)cur.pm * tA + (size_t)cur.pn * pnA; const char* cB = (const char*)g.Bt + (size_t)cur.pn * tB;
;     S.a_ready(cur);
;     if constexpr (SP2) {
;         PG8_STAGE(PG8_SB(0, 0), cB, voffB); PG8_STAGE(PG8_SB(0, 1), cB + hB, voffB); PG8_STAGE(PG8_SA(0, 0), cA, voffA); PG8_STAGE(PG8_SA(0, 1), cA + hA, voffA);
;         if (wr == 1) PG8_BAR;
;         PG8_WAIT_V(2); PG8_BAR;
;         PG8_STAGE(PG8_SB(1, 0), cB + kstep, voffB); PG8_STAGE(PG8_SA(1, 0), cA + kstep, voffA); PG8_STAGE(PG8_SB(1, 1), cB + hB + kstep, voffB);
;         PG8_WAIT_V(6); PG8_BAR;
;     __device__ __forceinline__ void operator()(AccRef acc, const pg8::Unit& u, int wr, int wc, int fr, int fq) const {
;         const int pn = u.pn, row0 = u.pm * 256 + wr * 64 + fr, cl = wc * 32 + 8 * fq;
;         if (pn < 16) {
;             const bool isk = pn >= 8; const int h = pn & 7; bf16* dst = isk ? k : q;
;             const float lg2 = head_lg2(h);
; #pragma unroll
;             for (int ai = 0; ai < 2; ++ai) {
;                 f32x4 tcv[4][2], tsv[4][2];
; #pragma unroll
;                 for (int m = 0; m < 4; ++m) { const int pos_ = (row0 + ai * 128 + m * 16) & 4095; const float* tc = tcos + pos_ * 128 + cl; const float* ts = tsin + pos_ * 128 + cl;
;                     tcv[m][0] = *(const f32x4*)tc; tcv[m][1] = *(const f32x4*)(tc + 4); tsv[m][0] = *(const f32x4*)ts; tsv[m][1] = *(const f32x4*)(ts + 4); }
; #pragma unroll
;                 for (int m = 0; m < 4; ++m) {
;                     int r = row0 + ai * 128 + m * 16; asm volatile("" : "+v"(r)); const int pos = r & 4095;
;                     const f32x4 c0 = tcv[m][0], c1 = tcv[m][1], s0 = tsv[m][0], s1 = tsv[m][1];
;                     const f32x4 a0 = acc[ai][0][m][0], a1 = acc[ai][0][m][1], b0 = acc[ai][1][m][0], b1 = acc[ai][1][m][1];
;                     const f32x4 o10 = (a0 * c0 - b0 * s0) * 0.0625f, o11 = (a1 * c1 - b1 * s1) * 0.0625f;
;                     const f32x4 o20 = (a0 * s0 + b0 * c0) * 0.0625f, o21 = (a1 * s1 + b1 * c1) * 0.0625f;
;                     const size_t blk = ((size_t)(((r >> 12) * 8 + h) * 64 + (pos >> 6))) * 16384;
;                     const int nn = r & 63;
.LBB0_184:
	s_add_u32 s14, s0, 0x15800000
	s_waitcnt vmcnt(0)
	v_bfe_u32 v19, v10, 4, 2
	s_addc_u32 s15, s1, 0
	v_and_b32_e32 v18, 15, v10
	v_lshlrev_b32_e32 v20, 3, v19
	v_lshlrev_b32_e32 v19, 4, v19
	s_add_u32 s16, s0, 0x1d800000
	v_lshl_or_b32 v1, s5, 6, v18
	v_lshl_or_b32 v19, v18, 6, v19
	v_lshlrev_b32_e32 v18, 2, v18
	s_mov_b64 s[38:39], 0x80
	s_addc_u32 s17, s1, 0
	s_and_b32 s8, s4, 3
	s_lshl_b32 s4, s5, 13
	v_and_b32_e32 v21, 32, v18
	s_add_i32 m0, s74, 0x18000
	v_lshl_add_u64 v[8:9], v[8:9], 0, s[38:39]
	v_bitop3_b32 v22, v19, s4, v21 bitop3:0xde
	s_lshl_b32 s4, s8, 12
	s_waitcnt vmcnt(2)
	s_barrier
	global_load_lds_dwordx4 v[8:9], off
	v_lshl_add_u64 v[6:7], v[6:7], 0, s[38:39]
	s_add_i32 m0, s74, 0x1a000
	s_add_i32 s81, s74, 0x8000
	s_add_i32 s82, s74, 0xa000
	v_bitop3_b32 v223, v19, s4, v21 bitop3:0xde
	global_load_lds_dwordx4 v[6:7], off
	v_lshl_add_u64 v[4:5], v[4:5], 0, s[38:39]
	s_mov_b32 m0, s81
	s_add_u32 s4, s64, 0x80080
	global_load_lds_dwordx4 v[4:5], off
	v_lshl_add_u64 v[2:3], v[2:3], 0, s[38:39]
	s_mov_b32 m0, s82
	s_addc_u32 s5, s65, 0
	global_load_lds_dwordx4 v[2:3], off
	s_add_i32 m0, s74, 0x1c000
	v_lshl_add_u64 v[2:3], s[4:5], 0, v[196:197]
	global_load_lds_dwordx4 v[2:3], off
	v_lshl_add_u64 v[2:3], s[4:5], 0, v[200:201]
	s_add_i32 m0, s74, 0x1e000
	v_lshrrev_b32_e32 v17, 4, v10
	global_load_lds_dwordx4 v[2:3], off
	v_and_b32_e32 v2, 3, v10
	s_cmpk_lt_u32 s6, 0x100
	v_lshlrev_b32_e32 v3, 1, v2
	v_cmp_gt_u32_e64 s[6:7], 2, v2
	v_bfe_u32 v2, v17, 1, 1
	v_lshl_or_b32 v227, s8, 2, v2
	v_lshlrev_b32_e32 v2, 1, v10
	v_or_b32_e32 v5, v20, v3
	v_and_b32_e32 v228, 32, v2
	v_bitop3_b32 v2, v20, 18, v3 bitop3:0xc8
	v_lshrrev_b32_e32 v3, 2, v10
	s_cselect_b64 s[40:41], -1, 0
	s_lshl_b32 s9, s8, 8
	v_and_b32_e32 v6, 4, v10
	v_and_b32_e32 v3, 4, v3
	v_or3_b32 v5, v21, s9, v5
	v_and_b32_e32 v7, 1, v10
	v_and_or_b32 v3, v18, 40, v3
	v_lshlrev_b32_e32 v6, 1, v6
	v_cmp_eq_u32_e64 s[4:5], 0, v7
	v_or3_b32 v7, v3, v2, s9
	v_lshl_or_b32 v202, v5, 4, v6
	v_lshl_or_b32 v4, s8, 5, v20
	v_lshl_add_u64 v[2:3], s[0:1], 0, v[202:203]
	s_mov_b64 s[8:9], 0xd800000
	v_lshl_or_b32 v202, v7, 4, v6
	v_lshl_add_u64 v[204:205], v[2:3], 0, s[8:9]
	v_lshl_add_u64 v[2:3], s[0:1], 0, v[202:203]
	s_mov_b64 s[8:9], 0x11800000
	v_lshlrev_b32_e32 v202, 2, v4
	v_lshl_add_u64 v[206:207], v[2:3], 0, s[8:9]
	v_lshl_add_u64 v[2:3], s[0:1], 0, v[202:203]
	s_mov_b64 s[42:43], 0x100000
	s_mov_b64 s[8:9], 0x300000
	v_lshl_add_u64 v[208:209], v[2:3], 0, s[42:43]
	v_lshl_add_u64 v[210:211], v[2:3], 0, s[8:9]
	v_lshlrev_b32_e32 v2, 15, v11
	v_and_b32_e32 v2, 0xffff0000, v2
	v_lshl_add_u32 v2, v12, 12, v2
	v_and_b32_e32 v3, 1, v11
	v_lshl_or_b32 v2, v3, 6, v2
	v_lshl_add_u32 v212, v13, 1, v2
	v_lshlrev_b32_e32 v2, 15, v14
	v_and_b32_e32 v2, 0xffff0000, v2
	s_waitcnt vmcnt(6)
	v_lshl_add_u32 v2, v15, 12, v2
	v_and_b32_e32 v3, 1, v14
	v_lshl_or_b32 v2, v3, 6, v2
	s_add_i32 s84, 0, 0x10000
	s_add_i32 s85, 0, 0x14000
	v_or_b32_e32 v224, 0xffffdc00, v4
	v_or_b32_e32 v225, 0xffffe000, v4
	v_or_b32_e32 v226, 0xffffe800, v4
	s_waitcnt lgkmcnt(0)
	s_ashr_i32 s83, s78, 31
	v_mov_b32_e32 v213, v203
	v_lshl_add_u32 v214, v16, 1, v2
	v_mov_b32_e32 v215, v203
	v_mov_b64_e32 v[216:217], 0xd00
	v_mov_b64_e32 v[218:219], 0xcff
	v_add_u32_e32 v229, s84, v223
	v_add_u32_e32 v230, s85, v223
	v_add_u32_e32 v231, 0, v22
	s_mov_b32 s18, 0x58000
	s_mov_b32 s87, 0x80000
	s_mov_b64 s[44:45], 0x90000
	s_mov_b32 s88, 0x90000
	s_mov_b64 s[46:47], 0xa0000
	s_mov_b32 s89, 0xa0000
	s_mov_b64 s[48:49], 0xb0000
	s_mov_b32 s90, 0xb0000
	s_mov_b32 s91, 0x5040100
	s_mov_b32 s92, 0x7060302
	s_mov_b32 s93, 0x9800000
	s_mov_b32 s94, 0xc2fc0000
	s_mov_b32 s95, 0x800000
	s_mov_b32 s50, 0x3d800000
	v_mov_b32_e32 v232, 0x42800000
	v_mov_b32_e32 v233, 0x42000000
	v_not_b32_e32 v234, 63
	s_barrier
	s_mov_b32 s101, 1
	s_branch .LBB0_187

; #define PG8_STAGE(bufoff, gbase, voff) do { _Pragma("unroll") for (int _i = 0; _i < 2; ++_i) \
;         __builtin_amdgcn_global_load_lds((const unsigned*)((const char*)(gbase) + (voff)[_i]), (PG8_LAS unsigned*)(lds + (bufoff) + ldsw + _i * 8192), 16, 0, 0); } while (0)
; #define PG8_LDA(dst, b, h) do { _Pragma("unroll") for (int m = 0; m < 4; ++m) _Pragma("unroll") for (int k = 0; k < 2; ++k) dst[m][k] = *(const PG8_LAS bf16x8*)(lds + PG8_SA(b, h) + aoff + m * 2048 + k * 1024); } while (0)
; #define PG8_LDB(dst, b, h) do { _Pragma("unroll") for (int n = 0; n < 2; ++n) _Pragma("unroll") for (int k = 0; k < 2; ++k) dst[n][k] = *(const PG8_LAS bf16x8*)(lds + PG8_SB(b, h) + boff + n * 2048 + k * 1024); } while (0)
; #define PG8_WAIT_V(n) asm volatile("s_waitcnt vmcnt(" #n ")" ::: "memory")
; #define PG8_WAIT_L(n) asm volatile("s_waitcnt lgkmcnt(" #n ")" ::: "memory")
; #define PG8_BAR __builtin_amdgcn_s_barrier()
; #define PG8_SCHED __builtin_amdgcn_sched_barrier(0)
; template <class Epi, class Sched, bool ALIGN_EPI = false, bool SP2 = false>
; __device__ __forceinline__ void gemm_phase(PG8_LAS unsigned char* lds, const Gemm g, const Sched& S, const Epi& E) {
;     ...
;         const bool has_next = S.next(ui + 1, nxt);
;         const char* nA = has_next ? (const char*)g.A + (size_t)nxt.pm * tA + (size_t)nxt.pn * pnA : cA; const char* nB = has_next ? (const char*)g.Bt + (size_t)nxt.pn * tB : cB;
; #pragma nounroll
;         for (int t = 0; t < nt; t += 2) {
;             const bool last = (t == nt - 2);
;             const char* a1 = cA + (size_t)(t + 1) * kstep;
;             const char* a2 = last ? nA : cA + (size_t)(t + 2) * kstep; const char* b2 = last ? nB : cB + (size_t)(t + 2) * kstep;
;             const char* a3 = a2 + kstep; const char* b3 = b2 + kstep;
;             if (last && has_next) S.a_ready(nxt);
;             if constexpr (SP2) {
;             PG8_LDB(B0, 0, 0); PG8_LDB(B1, 0, 1); PG8_SCHED; PG8_LDA(At, 0, 0); PG8_STAGE(PG8_SA(1, 1), a1 + hA, voffA);
;             PG8_WAIT_V(8); PG8_WAIT_L(0); PG8_BAR; PG8_MMA(0, 0, At, B0); PG8_MMA(0, 1, At, B1); PG8_BAR; PG8_SCHED;
;             PG8_LDA(At, 0, 1); PG8_STAGE(PG8_SB(0, 0), b2, voffB); PG8_STAGE(PG8_SB(0, 1), b2 + hB, voffB); PG8_STAGE(PG8_SA(0, 0), a2, voffA);
;             PG8_WAIT_V(8); PG8_WAIT_L(0); PG8_BAR; PG8_MMA(1, 0, At, B0); PG8_MMA(1, 1, At, B1); PG8_BAR; PG8_SCHED;
.LBB0_189:
	s_ashr_i32 s55, s54, 31
	s_lshl_b64 s[56:57], s[54:55], 20
	s_add_u32 s56, s69, s56
	s_addc_u32 s57, s70, s57
	s_and_b64 s[58:59], s[8:9], exec
	s_cselect_b32 s11, s57, s63
	s_cselect_b32 s33, s56, s62
	s_ashr_i32 s53, s52, 31
	s_lshl_b64 s[58:59], s[52:53], 20
	s_add_u32 s58, s71, s58
	s_addc_u32 s59, s72, s59
	s_and_b64 s[66:67], s[8:9], exec
	s_cselect_b32 s53, s59, s65
	s_cselect_b32 s55, s58, s64
	s_add_u32 s62, s62, 0x80080
	s_addc_u32 s63, s63, 0
	s_add_u32 s61, s64, 0x100
	v_mov_b32_e32 v2, 0
	s_addc_u32 s96, s65, 0
	s_mov_b32 s97, -2
	v_mov_b32_e32 v3, v2
	ds_read_b128 v[130:133], v229
	ds_read_b128 v[134:137], v229 offset:1024
	ds_read_b128 v[138:141], v229 offset:2048
	ds_read_b128 v[142:145], v229 offset:3072
	ds_read_b128 v[146:149], v230
	ds_read_b128 v[150:153], v230 offset:1024
	ds_read_b128 v[154:157], v230 offset:2048
	ds_read_b128 v[158:161], v230 offset:3072
	s_add_u32 s64, s62, 0xfff80080
	s_addc_u32 s65, s63, -1
	s_cmp_eq_u32 s97, 28
	s_cselect_b32 s67, s11, s65
	s_cselect_b32 s66, s33, s64
	s_cselect_b32 s65, s53, s96
	s_cselect_b32 s64, s55, s61
	s_add_i32 m0, s74, 0xc000
	ds_read_b128 v[162:165], v231
	ds_read_b128 v[166:169], v231 offset:1024
	ds_read_b128 v[170:173], v231 offset:2048
	ds_read_b128 v[174:177], v231 offset:3072
	ds_read_b128 v[178:181], v231 offset:4096
	ds_read_b128 v[182:185], v231 offset:5120
	ds_read_b128 v[186:189], v231 offset:6144
	ds_read_b128 v[190:193], v231 offset:7168
	global_load_lds_dwordx4 v212, s[62:63]
	s_add_i32 m0, s74, 0xe000
	s_nop 0
	global_load_lds_dwordx4 v214, s[62:63]
	s_cmp_eq_u32 s101, 0
	s_cbranch_scc1 .Lfw_0_0
	s_waitcnt vmcnt(8)
.Lfw_0_0:
	s_waitcnt lgkmcnt(0)
	s_barrier
	s_waitcnt lgkmcnt(0)
	v_mfma_f32_16x16x32_bf16 v[126:129], v[130:133], v[162:165], 0
	v_mfma_f32_16x16x32_bf16 v[122:125], v[138:141], v[162:165], 0
	v_mfma_f32_16x16x32_bf16 v[110:113], v[130:133], v[170:173], 0
	v_mfma_f32_16x16x32_bf16 v[106:109], v[138:141], v[170:173], 0
	v_mfma_f32_16x16x32_bf16 v[94:97], v[130:133], v[178:181], 0
	v_mfma_f32_16x16x32_bf16 v[90:93], v[138:141], v[178:181], 0
	v_mfma_f32_16x16x32_bf16 v[78:81], v[130:133], v[186:189], 0
	v_mfma_f32_16x16x32_bf16 v[74:77], v[138:141], v[186:189], 0
	v_mfma_f32_16x16x32_bf16 v[126:129], v[134:137], v[166:169], v[126:129]
	v_mfma_f32_16x16x32_bf16 v[122:125], v[142:145], v[166:169], v[122:125]
	v_mfma_f32_16x16x32_bf16 v[110:113], v[134:137], v[174:177], v[110:113]
	v_mfma_f32_16x16x32_bf16 v[106:109], v[142:145], v[174:177], v[106:109]
	v_mfma_f32_16x16x32_bf16 v[94:97], v[134:137], v[182:185], v[94:97]
	v_mfma_f32_16x16x32_bf16 v[90:93], v[142:145], v[182:185], v[90:93]
	v_mfma_f32_16x16x32_bf16 v[78:81], v[134:137], v[190:193], v[78:81]
	v_mfma_f32_16x16x32_bf16 v[74:77], v[142:145], v[190:193], v[74:77]
	v_mfma_f32_16x16x32_bf16 v[118:121], v[146:149], v[162:165], 0
	v_mfma_f32_16x16x32_bf16 v[114:117], v[154:157], v[162:165], 0
	v_mfma_f32_16x16x32_bf16 v[102:105], v[146:149], v[170:173], 0
	v_mfma_f32_16x16x32_bf16 v[98:101], v[154:157], v[170:173], 0
	v_mfma_f32_16x16x32_bf16 v[86:89], v[146:149], v[178:181], 0
	v_mfma_f32_16x16x32_bf16 v[82:85], v[154:157], v[178:181], 0
	v_mfma_f32_16x16x32_bf16 v[70:73], v[146:149], v[186:189], 0
	v_mfma_f32_16x16x32_bf16 v[66:69], v[154:157], v[186:189], 0
	v_mfma_f32_16x16x32_bf16 v[118:121], v[150:153], v[166:169], v[118:121]
	v_mfma_f32_16x16x32_bf16 v[114:117], v[158:161], v[166:169], v[114:117]
	v_mfma_f32_16x16x32_bf16 v[102:105], v[150:153], v[174:177], v[102:105]
	v_mfma_f32_16x16x32_bf16 v[98:101], v[158:161], v[174:177], v[98:101]
	v_mfma_f32_16x16x32_bf16 v[86:89], v[150:153], v[182:185], v[86:89]
	v_mfma_f32_16x16x32_bf16 v[82:85], v[158:161], v[182:185], v[82:85]
	v_mfma_f32_16x16x32_bf16 v[70:73], v[150:153], v[190:193], v[70:73]
	v_mfma_f32_16x16x32_bf16 v[66:69], v[158:161], v[190:193], v[66:69]
	s_barrier
	s_add_i32 vcc_lo, s84, s73
	s_add_u32 s34, s64, s38
	s_addc_u32 s35, s65, s39
	s_mov_b32 m0, vcc_lo
	ds_read_b128 v[162:165], v231 offset:16384
	ds_read_b128 v[166:169], v231 offset:17408
	ds_read_b128 v[170:173], v231 offset:18432
	ds_read_b128 v[174:177], v231 offset:19456
	ds_read_b128 v[178:181], v231 offset:20480
	ds_read_b128 v[182:185], v231 offset:21504
	ds_read_b128 v[186:189], v231 offset:22528
	ds_read_b128 v[190:193], v231 offset:23552
	global_load_lds_dwordx4 v196, s[64:65]
	s_add_i32 m0, vcc_lo, 0x2000
	s_add_u32 vcc_lo, s64, 0x80000
	s_addc_u32 vcc_hi, s65, 0
	s_add_i32 s86, s85, s73
	global_load_lds_dwordx4 v200, s[64:65]
	s_mov_b32 m0, s86
	s_nop 0
	global_load_lds_dwordx4 v196, vcc
	s_add_i32 m0, s86, 0x2000
	s_nop 0
	global_load_lds_dwordx4 v200, vcc
	s_add_u32 s98, s66, s38
	s_addc_u32 s99, s67, s39
	s_mov_b32 m0, s74
	s_nop 0
	global_load_lds_dwordx4 v194, s[66:67]
	s_mov_b32 m0, s75
	s_nop 0
	global_load_lds_dwordx4 v198, s[66:67]
	s_cmp_eq_u32 s101, 0
	s_cbranch_scc1 .Lfw_0_1
	s_waitcnt vmcnt(8)
; #define PG8_STAGE(bufoff, gbase, voff) do { _Pragma("unroll") for (int _i = 0; _i < 2; ++_i) \
;         __builtin_amdgcn_global_load_lds((const unsigned*)((const char*)(gbase) + (voff)[_i]), (PG8_LAS unsigned*)(lds + (bufoff) + ldsw + _i * 8192), 16, 0, 0); } while (0)
; #define PG8_LDA(dst, b, h) do { _Pragma("unroll") for (int m = 0; m < 4; ++m) _Pragma("unroll") for (int k = 0; k < 2; ++k) dst[m][k] = *(const PG8_LAS bf16x8*)(lds + PG8_SA(b, h) + aoff + m * 2048 + k * 1024); } while (0)
; #define PG8_LDB(dst, b, h) do { _Pragma("unroll") for (int n = 0; n < 2; ++n) _Pragma("unroll") for (int k = 0; k < 2; ++k) dst[n][k] = *(const PG8_LAS bf16x8*)(lds + PG8_SB(b, h) + boff + n * 2048 + k * 1024); } while (0)
; #define PG8_MMA(ai, bj, At, Bt) do { __builtin_amdgcn_s_setprio(1); _Pragma("unroll") for (int m = 0; m < 4; ++m) _Pragma("unroll") for (int n = 0; n < 2; ++n) _Pragma("unroll") for (int k = 0; k < 2; ++k) \
;         acc[ai][bj][m][n] = __builtin_amdgcn_mfma_f32_16x16x32_bf16(Bt[n][k], At[m][k], acc[ai][bj][m][n], 0, 0, 0); __builtin_amdgcn_s_setprio(0); } while (0)
; #define PG8_WAIT_V(n) asm volatile("s_waitcnt vmcnt(" #n ")" ::: "memory")
; #define PG8_WAIT_L(n) asm volatile("s_waitcnt lgkmcnt(" #n ")" ::: "memory")
; #define PG8_BAR __builtin_amdgcn_s_barrier()
; #define PG8_SCHED __builtin_amdgcn_sched_barrier(0)
; template <class Epi, class Sched, bool ALIGN_EPI = false, bool SP2 = false>
; __device__ __forceinline__ void gemm_phase(PG8_LAS unsigned char* lds, const Gemm g, const Sched& S, const Epi& E) {
;     ...
;             PG8_WAIT_V(8); PG8_WAIT_L(0); PG8_BAR; PG8_MMA(1, 0, At, B0); PG8_MMA(1, 1, At, B1); PG8_BAR; PG8_SCHED;
;             PG8_LDB(B0, 1, 0); PG8_LDB(B1, 1, 1); PG8_SCHED; PG8_LDA(At, 1, 0); PG8_STAGE(PG8_SA(0, 1), a2 + hA, voffA);
;             PG8_WAIT_V(8); PG8_WAIT_L(0); PG8_BAR; PG8_MMA(0, 0, At, B0); PG8_MMA(0, 1, At, B1); PG8_BAR; PG8_SCHED;
.Lfw_0_1:
	s_waitcnt lgkmcnt(0)
	s_barrier
	s_waitcnt lgkmcnt(0)
	v_mfma_f32_16x16x32_bf16 v[62:65], v[130:133], v[162:165], 0
	v_mfma_f32_16x16x32_bf16 v[58:61], v[138:141], v[162:165], 0
	v_mfma_f32_16x16x32_bf16 v[46:49], v[130:133], v[170:173], 0
	v_mfma_f32_16x16x32_bf16 v[42:45], v[138:141], v[170:173], 0
	v_mfma_f32_16x16x32_bf16 v[30:33], v[130:133], v[178:181], 0
	v_mfma_f32_16x16x32_bf16 v[26:29], v[138:141], v[178:181], 0
	v_mfma_f32_16x16x32_bf16 v[14:17], v[130:133], v[186:189], 0
	v_mfma_f32_16x16x32_bf16 v[10:13], v[138:141], v[186:189], 0
	v_mfma_f32_16x16x32_bf16 v[62:65], v[134:137], v[166:169], v[62:65]
	v_mfma_f32_16x16x32_bf16 v[58:61], v[142:145], v[166:169], v[58:61]
	v_mfma_f32_16x16x32_bf16 v[46:49], v[134:137], v[174:177], v[46:49]
	v_mfma_f32_16x16x32_bf16 v[42:45], v[142:145], v[174:177], v[42:45]
	v_mfma_f32_16x16x32_bf16 v[30:33], v[134:137], v[182:185], v[30:33]
	v_mfma_f32_16x16x32_bf16 v[26:29], v[142:145], v[182:185], v[26:29]
	v_mfma_f32_16x16x32_bf16 v[14:17], v[134:137], v[190:193], v[14:17]
	v_mfma_f32_16x16x32_bf16 v[10:13], v[142:145], v[190:193], v[10:13]
	v_mfma_f32_16x16x32_bf16 v[54:57], v[146:149], v[162:165], 0
	v_mfma_f32_16x16x32_bf16 v[50:53], v[154:157], v[162:165], 0
	v_mfma_f32_16x16x32_bf16 v[38:41], v[146:149], v[170:173], 0
	v_mfma_f32_16x16x32_bf16 v[34:37], v[154:157], v[170:173], 0
	v_mfma_f32_16x16x32_bf16 v[22:25], v[146:149], v[178:181], 0
	v_mfma_f32_16x16x32_bf16 v[18:21], v[154:157], v[178:181], 0
	v_mfma_f32_16x16x32_bf16 v[6:9], v[146:149], v[186:189], 0
	v_mfma_f32_16x16x32_bf16 v[2:5], v[154:157], v[186:189], 0
	v_mfma_f32_16x16x32_bf16 v[54:57], v[150:153], v[166:169], v[54:57]
	v_mfma_f32_16x16x32_bf16 v[50:53], v[158:161], v[166:169], v[50:53]
	v_mfma_f32_16x16x32_bf16 v[38:41], v[150:153], v[174:177], v[38:41]
	v_mfma_f32_16x16x32_bf16 v[34:37], v[158:161], v[174:177], v[34:37]
	v_mfma_f32_16x16x32_bf16 v[22:25], v[150:153], v[182:185], v[22:25]
	v_mfma_f32_16x16x32_bf16 v[18:21], v[158:161], v[182:185], v[18:21]
	v_mfma_f32_16x16x32_bf16 v[6:9], v[150:153], v[190:193], v[6:9]
	v_mfma_f32_16x16x32_bf16 v[2:5], v[158:161], v[190:193], v[2:5]
	s_barrier
	s_add_i32 s86, 0, 0x18000
	s_add_i32 vcc_lo, 0, 0x1c000
	v_add_u32_e32 v142, s86, v223
	v_add_u32_e32 v158, vcc_lo, v223
	ds_read_b128 v[130:133], v142
	ds_read_b128 v[134:137], v142 offset:1024
	ds_read_b128 v[138:141], v142 offset:2048
	ds_read_b128 v[142:145], v142 offset:3072
	ds_read_b128 v[146:149], v158
	ds_read_b128 v[150:153], v158 offset:1024
	ds_read_b128 v[154:157], v158 offset:2048
	ds_read_b128 v[158:161], v158 offset:3072
	s_add_u32 s66, s66, 0x80000
	s_addc_u32 s67, s67, 0
	s_mov_b32 m0, s76
	ds_read_b128 v[162:165], v231 offset:32768
	ds_read_b128 v[166:169], v231 offset:33792
	ds_read_b128 v[170:173], v231 offset:34816
	ds_read_b128 v[174:177], v231 offset:35840
	ds_read_b128 v[178:181], v231 offset:36864
	ds_read_b128 v[182:185], v231 offset:37888
	ds_read_b128 v[186:189], v231 offset:38912
	ds_read_b128 v[190:193], v231 offset:39936
	global_load_lds_dwordx4 v194, s[66:67]
	s_mov_b32 m0, s77
	s_nop 0
	global_load_lds_dwordx4 v198, s[66:67]
	s_waitcnt vmcnt(8)
	s_waitcnt lgkmcnt(0)
	s_barrier
	s_waitcnt lgkmcnt(0)
	v_mfma_f32_16x16x32_bf16 v[126:129], v[130:133], v[162:165], v[126:129]
	v_mfma_f32_16x16x32_bf16 v[122:125], v[138:141], v[162:165], v[122:125]
	v_mfma_f32_16x16x32_bf16 v[110:113], v[130:133], v[170:173], v[110:113]
	v_mfma_f32_16x16x32_bf16 v[106:109], v[138:141], v[170:173], v[106:109]
	v_mfma_f32_16x16x32_bf16 v[94:97], v[130:133], v[178:181], v[94:97]
	v_mfma_f32_16x16x32_bf16 v[90:93], v[138:141], v[178:181], v[90:93]
	v_mfma_f32_16x16x32_bf16 v[78:81], v[130:133], v[186:189], v[78:81]
	v_mfma_f32_16x16x32_bf16 v[74:77], v[138:141], v[186:189], v[74:77]
	v_mfma_f32_16x16x32_bf16 v[126:129], v[134:137], v[166:169], v[126:129]
	v_mfma_f32_16x16x32_bf16 v[122:125], v[142:145], v[166:169], v[122:125]
	v_mfma_f32_16x16x32_bf16 v[110:113], v[134:137], v[174:177], v[110:113]
	v_mfma_f32_16x16x32_bf16 v[106:109], v[142:145], v[174:177], v[106:109]
	v_mfma_f32_16x16x32_bf16 v[94:97], v[134:137], v[182:185], v[94:97]
	v_mfma_f32_16x16x32_bf16 v[90:93], v[142:145], v[182:185], v[90:93]
	v_mfma_f32_16x16x32_bf16 v[78:81], v[134:137], v[190:193], v[78:81]
	v_mfma_f32_16x16x32_bf16 v[74:77], v[142:145], v[190:193], v[74:77]
	v_mfma_f32_16x16x32_bf16 v[118:121], v[146:149], v[162:165], v[118:121]
	v_mfma_f32_16x16x32_bf16 v[114:117], v[154:157], v[162:165], v[114:117]
	v_mfma_f32_16x16x32_bf16 v[102:105], v[146:149], v[170:173], v[102:105]
	v_mfma_f32_16x16x32_bf16 v[98:101], v[154:157], v[170:173], v[98:101]
	v_mfma_f32_16x16x32_bf16 v[86:89], v[146:149], v[178:181], v[86:89]
	v_mfma_f32_16x16x32_bf16 v[82:85], v[154:157], v[178:181], v[82:85]
	v_mfma_f32_16x16x32_bf16 v[70:73], v[146:149], v[186:189], v[70:73]
	v_mfma_f32_16x16x32_bf16 v[66:69], v[154:157], v[186:189], v[66:69]
	v_mfma_f32_16x16x32_bf16 v[118:121], v[150:153], v[166:169], v[118:121]
	v_mfma_f32_16x16x32_bf16 v[114:117], v[158:161], v[166:169], v[114:117]
	v_mfma_f32_16x16x32_bf16 v[102:105], v[150:153], v[174:177], v[102:105]
	v_mfma_f32_16x16x32_bf16 v[98:101], v[158:161], v[174:177], v[98:101]
	v_mfma_f32_16x16x32_bf16 v[86:89], v[150:153], v[182:185], v[86:89]
	v_mfma_f32_16x16x32_bf16 v[82:85], v[158:161], v[182:185], v[82:85]
	v_mfma_f32_16x16x32_bf16 v[70:73], v[150:153], v[190:193], v[70:73]
	v_mfma_f32_16x16x32_bf16 v[66:69], v[158:161], v[190:193], v[66:69]
	s_barrier
; #define PG8_STAGE(bufoff, gbase, voff) do { _Pragma("unroll") for (int _i = 0; _i < 2; ++_i) \
;         __builtin_amdgcn_global_load_lds((const unsigned*)((const char*)(gbase) + (voff)[_i]), (PG8_LAS unsigned*)(lds + (bufoff) + ldsw + _i * 8192), 16, 0, 0); } while (0)
; #define PG8_LDA(dst, b, h) do { _Pragma("unroll") for (int m = 0; m < 4; ++m) _Pragma("unroll") for (int k = 0; k < 2; ++k) dst[m][k] = *(const PG8_LAS bf16x8*)(lds + PG8_SA(b, h) + aoff + m * 2048 + k * 1024); } while (0)
; #define PG8_MMA(ai, bj, At, Bt) do { __builtin_amdgcn_s_setprio(1); _Pragma("unroll") for (int m = 0; m < 4; ++m) _Pragma("unroll") for (int n = 0; n < 2; ++n) _Pragma("unroll") for (int k = 0; k < 2; ++k) \
;         acc[ai][bj][m][n] = __builtin_amdgcn_mfma_f32_16x16x32_bf16(Bt[n][k], At[m][k], acc[ai][bj][m][n], 0, 0, 0); __builtin_amdgcn_s_setprio(0); } while (0)
; #define PG8_WAIT_V(n) asm volatile("s_waitcnt vmcnt(" #n ")" ::: "memory")
; #define PG8_WAIT_L(n) asm volatile("s_waitcnt lgkmcnt(" #n ")" ::: "memory")
; #define PG8_BAR __builtin_amdgcn_s_barrier()
; #define PG8_SCHED __builtin_amdgcn_sched_barrier(0)
; template <class Epi, class Sched, bool ALIGN_EPI = false, bool SP2 = false>
; __device__ __forceinline__ void gemm_phase(PG8_LAS unsigned char* lds, const Gemm g, const Sched& S, const Epi& E) {
;     ...
;             PG8_LDA(At, 1, 1); PG8_STAGE(PG8_SB(1, 0), b3, voffB); PG8_STAGE(PG8_SB(1, 1), b3 + hB, voffB); PG8_STAGE(PG8_SA(1, 0), a3, voffA);
;             PG8_WAIT_V(8); PG8_WAIT_L(0); PG8_BAR; PG8_MMA(1, 0, At, B0); PG8_MMA(1, 1, At, B1); PG8_BAR; PG8_SCHED;
	s_add_i32 s66, s86, s73
	s_mov_b32 m0, s66
	ds_read_b128 v[162:165], v231 offset:49152
	ds_read_b128 v[166:169], v231 offset:50176
	ds_read_b128 v[170:173], v231 offset:51200
	ds_read_b128 v[174:177], v231 offset:52224
	ds_read_b128 v[178:181], v231 offset:53248
	ds_read_b128 v[182:185], v231 offset:54272
	ds_read_b128 v[186:189], v231 offset:55296
	ds_read_b128 v[190:193], v231 offset:56320
	global_load_lds_dwordx4 v196, s[34:35]
	s_add_i32 m0, s66, 0x2000
	s_add_u32 s64, s64, 0x80080
	s_addc_u32 s65, s65, 0
	s_add_i32 s66, vcc_lo, s73
	global_load_lds_dwordx4 v200, s[34:35]
	s_mov_b32 m0, s66
	s_nop 0
	global_load_lds_dwordx4 v196, s[64:65]
	s_add_i32 m0, s66, 0x2000
	s_nop 0
	global_load_lds_dwordx4 v200, s[64:65]
	s_mov_b32 m0, s81
	s_nop 0
	global_load_lds_dwordx4 v194, s[98:99]
	s_mov_b32 m0, s82
	s_nop 0
	global_load_lds_dwordx4 v198, s[98:99]
	s_waitcnt vmcnt(8)
	s_waitcnt lgkmcnt(0)
	s_barrier
	s_waitcnt lgkmcnt(0)
	v_mfma_f32_16x16x32_bf16 v[62:65], v[130:133], v[162:165], v[62:65]
	v_mfma_f32_16x16x32_bf16 v[58:61], v[138:141], v[162:165], v[58:61]
	v_mfma_f32_16x16x32_bf16 v[46:49], v[130:133], v[170:173], v[46:49]
	v_mfma_f32_16x16x32_bf16 v[42:45], v[138:141], v[170:173], v[42:45]
	v_mfma_f32_16x16x32_bf16 v[30:33], v[130:133], v[178:181], v[30:33]
	v_mfma_f32_16x16x32_bf16 v[26:29], v[138:141], v[178:181], v[26:29]
	v_mfma_f32_16x16x32_bf16 v[14:17], v[130:133], v[186:189], v[14:17]
	v_mfma_f32_16x16x32_bf16 v[10:13], v[138:141], v[186:189], v[10:13]
	v_mfma_f32_16x16x32_bf16 v[62:65], v[134:137], v[166:169], v[62:65]
	v_mfma_f32_16x16x32_bf16 v[58:61], v[142:145], v[166:169], v[58:61]
	v_mfma_f32_16x16x32_bf16 v[46:49], v[134:137], v[174:177], v[46:49]
	v_mfma_f32_16x16x32_bf16 v[42:45], v[142:145], v[174:177], v[42:45]
	v_mfma_f32_16x16x32_bf16 v[30:33], v[134:137], v[182:185], v[30:33]
	v_mfma_f32_16x16x32_bf16 v[26:29], v[142:145], v[182:185], v[26:29]
	v_mfma_f32_16x16x32_bf16 v[14:17], v[134:137], v[190:193], v[14:17]
	v_mfma_f32_16x16x32_bf16 v[10:13], v[142:145], v[190:193], v[10:13]
	v_mfma_f32_16x16x32_bf16 v[54:57], v[146:149], v[162:165], v[54:57]
	v_mfma_f32_16x16x32_bf16 v[50:53], v[154:157], v[162:165], v[50:53]
	v_mfma_f32_16x16x32_bf16 v[38:41], v[146:149], v[170:173], v[38:41]
	v_mfma_f32_16x16x32_bf16 v[34:37], v[154:157], v[170:173], v[34:37]
	v_mfma_f32_16x16x32_bf16 v[22:25], v[146:149], v[178:181], v[22:25]
	v_mfma_f32_16x16x32_bf16 v[18:21], v[154:157], v[178:181], v[18:21]
	v_mfma_f32_16x16x32_bf16 v[6:9], v[146:149], v[186:189], v[6:9]
	v_mfma_f32_16x16x32_bf16 v[2:5], v[154:157], v[186:189], v[2:5]
	v_mfma_f32_16x16x32_bf16 v[54:57], v[150:153], v[166:169], v[54:57]
	v_mfma_f32_16x16x32_bf16 v[50:53], v[158:161], v[166:169], v[50:53]
	v_mfma_f32_16x16x32_bf16 v[38:41], v[150:153], v[174:177], v[38:41]
	v_mfma_f32_16x16x32_bf16 v[34:37], v[158:161], v[174:177], v[34:37]
	v_mfma_f32_16x16x32_bf16 v[22:25], v[150:153], v[182:185], v[22:25]
	v_mfma_f32_16x16x32_bf16 v[18:21], v[158:161], v[182:185], v[18:21]
	v_mfma_f32_16x16x32_bf16 v[6:9], v[150:153], v[190:193], v[6:9]
	v_mfma_f32_16x16x32_bf16 v[2:5], v[158:161], v[190:193], v[2:5]
	s_barrier
	s_add_i32 s97, s97, 2
	s_add_u32 s62, s62, 0x100
	s_addc_u32 s63, s63, 0
	s_add_u32 s61, s61, 0x100
	s_addc_u32 s96, s96, 0
	s_cmp_gt_u32 s97, 29
	s_mov_b32 s101, 0

; __device__ __forceinline__ u32x4 pack8(f32x4 a, f32x4 b) { u32x4 w; w.x = cvt_pk_bf16(a[0], a[1]); w.y = cvt_pk_bf16(a[2], a[3]); w.z = cvt_pk_bf16(b[0], b[1]); w.w = cvt_pk_bf16(b[2], b[3]); return w; }
;     __device__ __forceinline__ void operator()(AccRef acc, const pg8::Unit& u, int wr, int wc, int fr, int fq) const {
;     ...
; #pragma unroll
;             for (int ai = 0; ai < 2; ++ai) {
;                 f32x4 tcv[4][2], tsv[4][2];
; #pragma unroll
;                 for (int m = 0; m < 4; ++m) { const int pos_ = (row0 + ai * 128 + m * 16) & 4095; const float* tc = tcos + pos_ * 128 + cl; const float* ts = tsin + pos_ * 128 + cl;
;                     tcv[m][0] = *(const f32x4*)tc; tcv[m][1] = *(const f32x4*)(tc + 4); tsv[m][0] = *(const f32x4*)ts; tsv[m][1] = *(const f32x4*)(ts + 4); }
; #pragma unroll
;                 for (int m = 0; m < 4; ++m) {
;                     int r = row0 + ai * 128 + m * 16; asm volatile("" : "+v"(r)); const int pos = r & 4095;
;                     const f32x4 c0 = tcv[m][0], c1 = tcv[m][1], s0 = tsv[m][0], s1 = tsv[m][1];
;                     const f32x4 a0 = acc[ai][0][m][0], a1 = acc[ai][0][m][1], b0 = acc[ai][1][m][0], b1 = acc[ai][1][m][1];
;                     const f32x4 o10 = (a0 * c0 - b0 * s0) * 0.0625f, o11 = (a1 * c1 - b1 * s1) * 0.0625f;
;                     const f32x4 o20 = (a0 * s0 + b0 * c0) * 0.0625f, o21 = (a1 * s1 + b1 * c1) * 0.0625f;
;                     const size_t blk = ((size_t)(((r >> 12) * 8 + h) * 64 + (pos >> 6))) * 16384;
;                     const int nn = r & 63;
;                     bf16* rp = dst + blk + (size_t)(((((cl >> 5) * 2 + (nn >> 5)) * 2 + ((cl >> 4) & 1)) * 64 + ((cl >> 3) & 1) * 32 + (nn & 31)) * 8);
;                     *(u32x4*)rp = pack8(o10, o11); *(u32x4*)(rp + 4 * 2048) = pack8(o20, o21);
.LBB0_194:
	v_lshlrev_b32_e32 v130, 9, v220
	v_and_b32_e32 v202, 0x1f9e00, v130
	v_lshl_add_u64 v[130:131], v[210:211], 0, v[202:203]
	global_load_dwordx4 v[190:193], v[130:131], off
	global_load_dwordx4 v[186:189], v[130:131], off offset:16
	v_lshl_add_u64 v[130:131], v[208:209], 0, v[202:203]
	global_load_dwordx4 v[182:185], v[130:131], off
	global_load_dwordx4 v[178:181], v[130:131], off offset:16
	v_mov_b32_e32 v131, v203
	v_mov_b32_e32 v133, v203
	v_or_b32_e32 v130, 0x2000, v202
	v_or_b32_e32 v132, 0x4000, v202
	v_or_b32_e32 v202, 0x6000, v202
	v_lshl_add_u64 v[134:135], v[208:209], 0, v[130:131]
	v_lshl_add_u64 v[130:131], v[210:211], 0, v[130:131]
	v_lshl_add_u64 v[136:137], v[208:209], 0, v[132:133]
	v_lshl_add_u64 v[132:133], v[210:211], 0, v[132:133]
	v_lshl_add_u64 v[138:139], v[208:209], 0, v[202:203]
	v_lshl_add_u64 v[142:143], v[210:211], 0, v[202:203]
	global_load_dwordx4 v[162:165], v[134:135], off offset:16
	global_load_dwordx4 v[170:173], v[134:135], off
	global_load_dwordx4 v[166:169], v[130:131], off offset:16
	global_load_dwordx4 v[174:177], v[130:131], off
	global_load_dwordx4 v[146:149], v[136:137], off offset:16
	global_load_dwordx4 v[154:157], v[136:137], off
	global_load_dwordx4 v[150:153], v[132:133], off offset:16
	global_load_dwordx4 v[158:161], v[132:133], off
	s_nop 0
	global_load_dwordx4 v[130:133], v[138:139], off offset:16
	s_nop 0
	global_load_dwordx4 v[138:141], v[138:139], off
	s_nop 0
	global_load_dwordx4 v[134:137], v[142:143], off offset:16
	s_nop 0
	global_load_dwordx4 v[142:145], v[142:143], off
	s_and_b32 s33, s10, 7
	v_cvt_f32_ubyte0_e32 v202, s33
	s_cmp_gt_i32 s10, 7
	v_sub_f32_e32 v202, 0xc0a00000, v202
	s_cselect_b64 s[62:63], -1, 0
	v_cmp_gt_f32_e32 vcc, s94, v202
	s_and_b64 s[60:61], s[62:63], exec
	s_cselect_b32 s11, s93, 0x5800000
	v_cndmask_b32_e32 v221, 0, v232, vcc
	v_add_f32_e32 v202, v202, v221
	s_add_u32 s60, s0, s11
	v_exp_f32_e32 v202, v202
	s_addc_u32 s61, s1, 0
	s_and_b64 s[64:65], vcc, exec
	s_cselect_b32 s11, 0xffffffc0, 0
	v_ldexp_f32 v202, v202, s11
	v_sub_f32_e32 v202, 1.0, v202
	v_cmp_gt_f32_e32 vcc, s95, v202
	s_and_b64 s[64:65], vcc, exec
	s_cselect_b32 s11, 32, 0
	v_ldexp_f32 v202, v202, s11
	v_log_f32_e32 v202, v202
	v_mov_b32_e32 v235, v220
	v_cndmask_b32_e32 v236, 0, v233, vcc
	v_ashrrev_i32_e32 v221, 9, v235
	v_and_b32_e32 v221, 0x3fffff8, v221
	v_or_b32_e32 v245, s33, v221
	v_sub_f32_e32 v221, v202, v236
	v_bfe_u32 v244, v235, 6, 6
	s_cmp_lt_i32 s10, 8
	s_waitcnt vmcnt(0)
	v_pk_mul_f32 v[236:237], v[120:121], v[192:193]
	v_pk_mul_f32 v[238:239], v[118:119], v[190:191]
	v_pk_mul_f32 v[192:193], v[128:129], v[192:193]
	v_pk_mul_f32 v[190:191], v[126:127], v[190:191]
	v_pk_mul_f32 v[240:241], v[116:117], v[188:189]
	v_pk_mul_f32 v[242:243], v[114:115], v[186:187]
	v_pk_mul_f32 v[188:189], v[124:125], v[188:189]
	v_pk_mul_f32 v[186:187], v[122:123], v[186:187]
	v_pk_fma_f32 v[128:129], v[128:129], v[184:185], v[236:237] neg_lo:[0,0,1] neg_hi:[0,0,1]
	v_pk_fma_f32 v[236:237], v[126:127], v[182:183], v[238:239] neg_lo:[0,0,1] neg_hi:[0,0,1]
	v_pk_fma_f32 v[120:121], v[120:121], v[184:185], v[192:193]
	v_pk_fma_f32 v[182:183], v[118:119], v[182:183], v[190:191]
	v_pk_fma_f32 v[238:239], v[122:123], v[178:179], v[242:243] neg_lo:[0,0,1] neg_hi:[0,0,1]
	v_pk_fma_f32 v[116:117], v[116:117], v[180:181], v[188:189]
	v_pk_fma_f32 v[178:179], v[114:115], v[178:179], v[186:187]
	v_pk_mul_f32 v[118:119], v[120:121], s[50:51] op_sel_hi:[1,0]
	v_pk_mul_f32 v[120:121], v[182:183], s[50:51] op_sel_hi:[1,0]
	v_lshrrev_b32_e32 v182, 4, v235
	v_pk_mul_f32 v[114:115], v[116:117], s[50:51] op_sel_hi:[1,0]
	v_pk_mul_f32 v[116:117], v[178:179], s[50:51] op_sel_hi:[1,0]
	v_lshl_or_b32 v178, v245, 6, v244
	v_and_or_b32 v182, v182, 2, v227
	v_ashrrev_i32_e32 v179, 31, v178
	v_lshlrev_b32_e32 v182, 6, v182
	v_and_b32_e32 v183, 31, v235
	v_pk_fma_f32 v[124:125], v[124:125], v[180:181], v[240:241] neg_lo:[0,0,1] neg_hi:[0,0,1]
	v_lshlrev_b64 v[180:181], 15, v[178:179]
	v_or3_b32 v182, v182, v183, v228
	v_pk_mul_f32 v[126:127], v[128:129], s[50:51] op_sel_hi:[1,0]
	v_pk_mul_f32 v[128:129], v[236:237], s[50:51] op_sel_hi:[1,0]
	v_pk_mul_f32 v[122:123], v[124:125], s[50:51] op_sel_hi:[1,0]
	v_pk_mul_f32 v[124:125], v[238:239], s[50:51] op_sel_hi:[1,0]
	v_lshl_add_u64 v[180:181], s[60:61], 0, v[180:181]
	v_lshlrev_b32_e32 v202, 4, v182
	v_lshl_add_u64 v[184:185], v[180:181], 0, v[202:203]
	v_cvt_pk_bf16_f32 v180, v128, v129
	v_cvt_pk_bf16_f32 v181, v126, v127
	v_cvt_pk_bf16_f32 v182, v124, v125
	v_cvt_pk_bf16_f32 v183, v122, v123
	s_waitcnt vmcnt(0)
	global_store_dwordx4 v[184:185], v[180:183], off
	v_add_co_u32_e32 v184, vcc, 0x4000, v184
	s_nop 0
	v_cvt_pk_bf16_f32 v180, v120, v121
	v_cvt_pk_bf16_f32 v181, v118, v119
	v_cvt_pk_bf16_f32 v182, v116, v117
	v_cvt_pk_bf16_f32 v183, v114, v115
	v_addc_co_u32_e32 v185, vcc, 0, v185, vcc
	global_store_dwordx4 v[184:185], v[180:183], off
	s_cbranch_scc1 .LBB0_196
; __device__ __forceinline__ unsigned cvt_pk_bf16(float lo, float hi) { const f32x2_cv v = {lo, hi}; const bf16x2_cv b = __builtin_convertvector(v, bf16x2_cv); return __builtin_bit_cast(unsigned, b); }
; __device__ __forceinline__ unsigned dpp_xor1(unsigned v) { return (unsigned)__builtin_amdgcn_update_dpp(0, (int)v, 0xB1, 0xF, 0xF, true); }
; __device__ __forceinline__ unsigned dpp_xor2(unsigned v) { return (unsigned)__builtin_amdgcn_update_dpp(0, (int)v, 0x4E, 0xF, 0xF, true); }
; __device__ __forceinline__ void quad_transpose(unsigned& x0, unsigned& x1, unsigned& x2, unsigned& x3, int b) {
;     const bool o1 = (b & 1) != 0, o2 = (b & 2) != 0;
;     const unsigned r01 = dpp_xor1(o1 ? x0 : x1), r23 = dpp_xor1(o1 ? x2 : x3);
;     if (o1) { x0 = r01; x2 = r23; } else { x1 = r01; x3 = r23; }
;     const unsigned r02 = dpp_xor2(o2 ? x0 : x2), r13 = dpp_xor2(o2 ? x1 : x3);
;     if (o2) { x0 = r02; x1 = r13; } else { x2 = r02; x3 = r13; }
; }
; __device__ __forceinline__ void tr_store(bf16* p, int second, f32x4 v0, f32x4 v1, int b) {
;     unsigned x0 = cvt_pk_bf16(v0[0], v0[1]), x1 = cvt_pk_bf16(v0[2], v0[3]), x2 = cvt_pk_bf16(v1[0], v1[1]), x3 = cvt_pk_bf16(v1[2], v1[3]);
;     quad_transpose(x0, x1, x2, x3, b);
;     u32x2 lo, hi; lo.x = __builtin_amdgcn_perm(x1, x0, 0x05040100u); lo.y = __builtin_amdgcn_perm(x3, x2, 0x05040100u);
;     hi.x = __builtin_amdgcn_perm(x1, x0, 0x07060302u); hi.y = __builtin_amdgcn_perm(x3, x2, 0x07060302u);
;     *(u32x2*)p = lo; *(u32x2*)(p + second) = hi;
; }
;     __device__ __forceinline__ void operator()(AccRef acc, const pg8::Unit& u, int wr, int wc, int fr, int fq) const {
;     ...
;                         const float kd = exp2f((float)(63 - (r & 63)) * lg2);
;                         const int dq = cl + 2 * (fr & 3), dl = dq & 31, sg2 = (dl & 0x13) | ((dl & 4) << 1) | ((dl & 8) >> 1);
;                         bf16* tb = kdT + blk + (size_t)((((dq >> 5) * 4 + m) * 64 + ((fr >> 3) & 1) * 32 + sg2) * 8 + (fr & 4));
;                         tr_store(tb, 8, o10 * kd, o11 * kd, fr & 3); tr_store(tb + 4 * 4 * 64 * 8, 8, o20 * kd, o21 * kd, fr & 3);
	s_nop 0
	v_bitop3_b32 v180, v235, 63, v235 bitop3:0xc
	v_cvt_f32_ubyte0_e32 v180, v180
	v_mul_f32_e32 v181, v221, v180
	v_cmp_gt_f32_e32 vcc, s94, v181
	v_lshlrev_b64 v[178:179], 14, v[178:179]
	v_lshl_add_u64 v[178:179], v[178:179], 1, v[206:207]
	v_cndmask_b32_e32 v181, 0, v232, vcc
	v_fmac_f32_e32 v181, v221, v180
	v_exp_f32_e32 v180, v181
	v_cndmask_b32_e32 v181, 0, v234, vcc
	v_ldexp_f32 v180, v180, v181
	v_pk_mul_f32 v[118:119], v[118:119], v[180:181] op_sel_hi:[1,0]
	v_pk_mul_f32 v[120:121], v[120:121], v[180:181] op_sel_hi:[1,0]
	v_pk_mul_f32 v[114:115], v[114:115], v[180:181] op_sel_hi:[1,0]
	v_pk_mul_f32 v[116:117], v[116:117], v[180:181] op_sel_hi:[1,0]
	v_pk_mul_f32 v[126:127], v[126:127], v[180:181] op_sel_hi:[1,0]
	v_pk_mul_f32 v[128:129], v[128:129], v[180:181] op_sel_hi:[1,0]
	v_pk_mul_f32 v[122:123], v[122:123], v[180:181] op_sel_hi:[1,0]
	v_pk_mul_f32 v[124:125], v[124:125], v[180:181] op_sel_hi:[1,0]
	v_cvt_pk_bf16_f32 v120, v120, v121
	v_cvt_pk_bf16_f32 v118, v118, v119
	v_cvt_pk_bf16_f32 v116, v116, v117
	v_cvt_pk_bf16_f32 v114, v114, v115
	v_cvt_pk_bf16_f32 v128, v128, v129
	v_cvt_pk_bf16_f32 v126, v126, v127
	v_cvt_pk_bf16_f32 v124, v124, v125
	v_cvt_pk_bf16_f32 v122, v122, v123
	v_cndmask_b32_e64 v115, v120, v118, s[4:5]
	v_cndmask_b32_e64 v117, v116, v114, s[4:5]
	v_cndmask_b32_e64 v123, v128, v126, s[4:5]
	v_cndmask_b32_e64 v125, v124, v122, s[4:5]
	v_mov_b32_dpp v115, v115 quad_perm:[1,0,3,2] row_mask:0xf bank_mask:0xf bound_ctrl:1
	v_mov_b32_dpp v117, v117 quad_perm:[1,0,3,2] row_mask:0xf bank_mask:0xf bound_ctrl:1
	v_mov_b32_dpp v123, v123 quad_perm:[1,0,3,2] row_mask:0xf bank_mask:0xf bound_ctrl:1
	v_mov_b32_dpp v125, v125 quad_perm:[1,0,3,2] row_mask:0xf bank_mask:0xf bound_ctrl:1
	v_cndmask_b32_e64 v119, v115, v120, s[4:5]
	v_cndmask_b32_e64 v115, v118, v115, s[4:5]
	v_cndmask_b32_e64 v116, v117, v116, s[4:5]
	v_cndmask_b32_e64 v114, v114, v117, s[4:5]
	v_cndmask_b32_e64 v127, v123, v128, s[4:5]
	v_cndmask_b32_e64 v123, v126, v123, s[4:5]
	v_cndmask_b32_e64 v124, v125, v124, s[4:5]
	v_cndmask_b32_e64 v122, v122, v125, s[4:5]
	v_cndmask_b32_e64 v117, v119, v116, s[6:7]
	v_cndmask_b32_e64 v118, v115, v114, s[6:7]
	v_cndmask_b32_e64 v125, v127, v124, s[6:7]
	v_cndmask_b32_e64 v126, v123, v122, s[6:7]
	v_mov_b32_dpp v117, v117 quad_perm:[2,3,0,1] row_mask:0xf bank_mask:0xf bound_ctrl:1
	v_mov_b32_dpp v118, v118 quad_perm:[2,3,0,1] row_mask:0xf bank_mask:0xf bound_ctrl:1
	v_mov_b32_dpp v125, v125 quad_perm:[2,3,0,1] row_mask:0xf bank_mask:0xf bound_ctrl:1
	v_mov_b32_dpp v126, v126 quad_perm:[2,3,0,1] row_mask:0xf bank_mask:0xf bound_ctrl:1
	v_cndmask_b32_e64 v119, v117, v119, s[6:7]
	v_cndmask_b32_e64 v117, v116, v117, s[6:7]
	v_cndmask_b32_e64 v116, v118, v115, s[6:7]
	v_cndmask_b32_e64 v118, v114, v118, s[6:7]
	v_cndmask_b32_e64 v127, v125, v127, s[6:7]
	v_cndmask_b32_e64 v125, v124, v125, s[6:7]
	v_cndmask_b32_e64 v124, v126, v123, s[6:7]
	v_cndmask_b32_e64 v126, v122, v126, s[6:7]
	v_perm_b32 v115, v118, v117, s91
	v_perm_b32 v117, v118, v117, s92
	v_add_co_u32_e32 v118, vcc, 0x4000, v178
	v_perm_b32 v122, v124, v127, s91
	v_perm_b32 v123, v126, v125, s91
	v_perm_b32 v114, v116, v119, s91
	v_perm_b32 v116, v116, v119, s92
	v_addc_co_u32_e32 v119, vcc, 0, v179, vcc
	v_perm_b32 v124, v124, v127, s92
	v_perm_b32 v125, v126, v125, s92
	global_store_dwordx2 v[178:179], v[122:123], off
	global_store_dwordx2 v[178:179], v[124:125], off offset:16
	global_store_dwordx2 v[118:119], v[114:115], off
	global_store_dwordx2 v[118:119], v[116:117], off offset:16

; __device__ __forceinline__ u32x4 pack8(f32x4 a, f32x4 b) { u32x4 w; w.x = cvt_pk_bf16(a[0], a[1]); w.y = cvt_pk_bf16(a[2], a[3]); w.z = cvt_pk_bf16(b[0], b[1]); w.w = cvt_pk_bf16(b[2], b[3]); return w; }
; __device__ __forceinline__ float sigmoidf_(float x) { return __builtin_amdgcn_rcpf(1.0f + __expf(-x)); }
; __device__ __forceinline__ f32x4 sig4(f32x4 v) { f32x4 r; r[0] = sigmoidf_(v[0]); r[1] = sigmoidf_(v[1]); r[2] = sigmoidf_(v[2]); r[3] = sigmoidf_(v[3]); return r; }
;     __device__ __forceinline__ void operator()(AccRef acc, const pg8::Unit& u, int wr, int wc, int fr, int fq) const {
;     ...
;         } else {
;             const int c0 = (pn - 36) * 256 + cl;
; #pragma unroll
;             for (int ai = 0; ai < 2; ++ai)
; #pragma unroll
;                 for (int m = 0; m < 4; ++m) { const int r = row0 + ai * 128 + m * 16;
; #pragma unroll
;                     for (int bj = 0; bj < 2; ++bj) *(u32x4*)(sg + (size_t)r * 4096 + c0 + bj * 128) = pack8(sig4(acc[ai][bj][m][0]), sig4(acc[ai][bj][m][1])); }
;         }
.LBB0_212:
	s_cmp_gt_u32 s10, 23
	s_cbranch_scc0 .LBB0_222
	s_cmp_gt_u32 s10, 31
	v_ashrrev_i32_e32 v221, 31, v220
	s_cbranch_scc0 .LBB0_219
	s_lshl_b32 s11, s10, 8
	s_cmp_gt_u32 s10, 35
	s_cbranch_scc0 .LBB0_216
	v_mul_f32_e32 v134, 0xbfb8aa3b, v128
	v_exp_f32_e32 v134, v134
	v_mul_f32_e32 v135, 0xbfb8aa3b, v129
	v_exp_f32_e32 v135, v135
	v_mul_f32_e32 v137, 0xbfb8aa3b, v123
	v_add_f32_e32 v134, 1.0, v134
	v_rcp_f32_e32 v136, v134
	v_add_f32_e32 v134, 1.0, v135
	v_mul_f32_e32 v135, 0xbfb8aa3b, v122
	v_exp_f32_e32 v135, v135
	v_exp_f32_e32 v137, v137
	v_mul_f32_e32 v130, 0xbfb8aa3b, v126
	v_exp_f32_e32 v132, v130
	v_mul_f32_e32 v130, 0xbfb8aa3b, v127
	v_rcp_f32_e32 v138, v134
	v_add_f32_e32 v134, 1.0, v135
	v_mul_f32_e32 v135, 0xbfb8aa3b, v124
	v_exp_f32_e32 v133, v130
	v_rcp_f32_e32 v139, v134
	v_add_f32_e32 v134, 1.0, v137
	v_exp_f32_e32 v135, v135
	v_mul_f32_e32 v137, 0xbfb8aa3b, v125
	v_exp_f32_e32 v137, v137
	v_rcp_f32_e32 v140, v134
	v_add_f32_e32 v132, 1.0, v132
	v_add_f32_e32 v133, 1.0, v133
	v_add_f32_e32 v134, 1.0, v135
	v_rcp_f32_e32 v132, v132
	v_rcp_f32_e32 v133, v133
	v_rcp_f32_e32 v141, v134
	v_add_f32_e32 v134, 1.0, v137
	v_rcp_f32_e32 v137, v134
	v_cvt_pk_bf16_f32 v135, v136, v138
	v_cvt_pk_bf16_f32 v136, v139, v140
	v_mul_f32_e32 v138, 0xbfb8aa3b, v118
	v_mul_f32_e32 v139, 0xbfb8aa3b, v119
	v_exp_f32_e32 v138, v138
	v_exp_f32_e32 v139, v139
	v_add_u32_e32 v202, s11, v224
	v_lshlrev_b64 v[130:131], 13, v[220:221]
	v_cvt_pk_bf16_f32 v134, v132, v133
	v_lshl_add_u64 v[130:131], s[28:29], 0, v[130:131]
	v_lshlrev_b64 v[132:133], 1, v[202:203]
	v_cvt_pk_bf16_f32 v137, v141, v137
	v_lshl_add_u64 v[130:131], v[130:131], 0, v[132:133]
	s_waitcnt vmcnt(0)
	global_store_dwordx4 v[130:131], v[134:137], off
	v_mul_f32_e32 v140, 0xbfb8aa3b, v116
	v_mul_f32_e32 v141, 0xbfb8aa3b, v117
	v_add_f32_e32 v134, 1.0, v138
	v_add_f32_e32 v135, 1.0, v139
	v_mul_f32_e32 v136, 0xbfb8aa3b, v120
	v_mul_f32_e32 v137, 0xbfb8aa3b, v121
	v_mul_f32_e32 v138, 0xbfb8aa3b, v114
	v_mul_f32_e32 v139, 0xbfb8aa3b, v115
	v_exp_f32_e32 v136, v136
	v_exp_f32_e32 v137, v137
	v_exp_f32_e32 v138, v138
	v_exp_f32_e32 v139, v139
	v_exp_f32_e32 v140, v140
	v_exp_f32_e32 v141, v141
	v_add_f32_e32 v136, 1.0, v136
	v_add_f32_e32 v137, 1.0, v137
	v_add_f32_e32 v138, 1.0, v138
	v_add_f32_e32 v139, 1.0, v139
	v_add_f32_e32 v140, 1.0, v140
	v_add_f32_e32 v141, 1.0, v141
	v_rcp_f32_e32 v134, v134
	v_rcp_f32_e32 v135, v135
	v_rcp_f32_e32 v136, v136
	v_rcp_f32_e32 v137, v137
	v_rcp_f32_e32 v138, v138
	v_rcp_f32_e32 v139, v139
	v_rcp_f32_e32 v140, v140
	v_rcp_f32_e32 v141, v141
	v_cvt_pk_bf16_f32 v134, v134, v135
	v_cvt_pk_bf16_f32 v135, v136, v137
	v_cvt_pk_bf16_f32 v136, v138, v139
	v_cvt_pk_bf16_f32 v137, v140, v141
	global_store_dwordx4 v[130:131], v[134:137], off offset:256
	v_mul_f32_e32 v140, 0xbfb8aa3b, v106
	v_mul_f32_e32 v141, 0xbfb8aa3b, v107
	v_mul_f32_e32 v136, 0xbfb8aa3b, v110
	v_mul_f32_e32 v137, 0xbfb8aa3b, v111
	v_exp_f32_e32 v136, v136
	v_exp_f32_e32 v137, v137
	v_or_b32_e32 v134, 16, v220
	v_ashrrev_i32_e32 v135, 31, v134
	v_lshlrev_b64 v[138:139], 13, v[134:135]
	v_add_f32_e32 v134, 1.0, v136
	v_add_f32_e32 v135, 1.0, v137
	v_mul_f32_e32 v136, 0xbfb8aa3b, v112
	v_mul_f32_e32 v137, 0xbfb8aa3b, v113
	v_exp_f32_e32 v136, v136
	v_exp_f32_e32 v137, v137
	v_exp_f32_e32 v140, v140
	v_exp_f32_e32 v141, v141
	v_mul_f32_e32 v142, 0xbfb8aa3b, v108
	v_mul_f32_e32 v143, 0xbfb8aa3b, v109
	v_add_f32_e32 v136, 1.0, v136
	v_add_f32_e32 v137, 1.0, v137
	v_add_f32_e32 v140, 1.0, v140
	v_add_f32_e32 v141, 1.0, v141
	v_exp_f32_e32 v142, v142
	v_exp_f32_e32 v143, v143
	v_rcp_f32_e32 v134, v134
	v_rcp_f32_e32 v135, v135
	v_rcp_f32_e32 v136, v136
	v_rcp_f32_e32 v137, v137
	v_rcp_f32_e32 v140, v140
	v_rcp_f32_e32 v141, v141
	v_add_f32_e32 v142, 1.0, v142
	v_add_f32_e32 v143, 1.0, v143
	v_rcp_f32_e32 v142, v142
	v_rcp_f32_e32 v143, v143
	v_cvt_pk_bf16_f32 v134, v134, v135
	v_cvt_pk_bf16_f32 v135, v136, v137
	v_cvt_pk_bf16_f32 v136, v140, v141
	v_mul_f32_e32 v140, 0xbfb8aa3b, v102
	v_mul_f32_e32 v141, 0xbfb8aa3b, v103
	v_exp_f32_e32 v140, v140
	v_exp_f32_e32 v141, v141
	v_lshl_add_u64 v[138:139], s[28:29], 0, v[138:139]
	v_cvt_pk_bf16_f32 v137, v142, v143
	v_lshl_add_u64 v[138:139], v[138:139], 0, v[132:133]
	global_store_dwordx4 v[138:139], v[134:137], off
	v_mul_f32_e32 v142, 0xbfb8aa3b, v100
	v_mul_f32_e32 v143, 0xbfb8aa3b, v101
	v_add_f32_e32 v134, 1.0, v140
	v_add_f32_e32 v135, 1.0, v141
	v_mul_f32_e32 v136, 0xbfb8aa3b, v104
	v_mul_f32_e32 v137, 0xbfb8aa3b, v105
	v_mul_f32_e32 v140, 0xbfb8aa3b, v98
	v_mul_f32_e32 v141, 0xbfb8aa3b, v99
	v_exp_f32_e32 v136, v136
	v_exp_f32_e32 v137, v137
	v_exp_f32_e32 v140, v140
	v_exp_f32_e32 v141, v141
	v_exp_f32_e32 v142, v142
	v_exp_f32_e32 v143, v143
	v_add_f32_e32 v136, 1.0, v136
	v_add_f32_e32 v137, 1.0, v137
	v_add_f32_e32 v140, 1.0, v140
	v_add_f32_e32 v141, 1.0, v141
	v_add_f32_e32 v142, 1.0, v142
	v_add_f32_e32 v143, 1.0, v143
	v_rcp_f32_e32 v134, v134
	v_rcp_f32_e32 v135, v135
	v_rcp_f32_e32 v136, v136
	v_rcp_f32_e32 v137, v137
	v_rcp_f32_e32 v140, v140
	v_rcp_f32_e32 v141, v141
	v_rcp_f32_e32 v142, v142
	v_rcp_f32_e32 v143, v143
	v_cvt_pk_bf16_f32 v134, v134, v135
	v_cvt_pk_bf16_f32 v135, v136, v137
	v_cvt_pk_bf16_f32 v136, v140, v141
	v_cvt_pk_bf16_f32 v137, v142, v143
	global_store_dwordx4 v[138:139], v[134:137], off offset:256
	v_mul_f32_e32 v140, 0xbfb8aa3b, v90
	v_mul_f32_e32 v141, 0xbfb8aa3b, v91
	v_mul_f32_e32 v136, 0xbfb8aa3b, v94
	v_mul_f32_e32 v137, 0xbfb8aa3b, v95
	v_exp_f32_e32 v136, v136
	v_exp_f32_e32 v137, v137
	v_or_b32_e32 v134, 32, v220
	v_ashrrev_i32_e32 v135, 31, v134
	v_lshlrev_b64 v[138:139], 13, v[134:135]
; __device__ __forceinline__ u32x4 pack8(f32x4 a, f32x4 b) { u32x4 w; w.x = cvt_pk_bf16(a[0], a[1]); w.y = cvt_pk_bf16(a[2], a[3]); w.z = cvt_pk_bf16(b[0], b[1]); w.w = cvt_pk_bf16(b[2], b[3]); return w; }
; __device__ __forceinline__ f32x4 sig4(f32x4 v) { f32x4 r; r[0] = sigmoidf_(v[0]); r[1] = sigmoidf_(v[1]); r[2] = sigmoidf_(v[2]); r[3] = sigmoidf_(v[3]); return r; }
;     __device__ __forceinline__ void operator()(AccRef acc, const pg8::Unit& u, int wr, int wc, int fr, int fq) const {
;     ...
;                 for (int m = 0; m < 4; ++m) { const int r = row0 + ai * 128 + m * 16;
; #pragma unroll
;                     for (int bj = 0; bj < 2; ++bj) *(u32x4*)(sg + (size_t)r * 4096 + c0 + bj * 128) = pack8(sig4(acc[ai][bj][m][0]), sig4(acc[ai][bj][m][1])); }
	v_add_f32_e32 v134, 1.0, v136
	v_add_f32_e32 v135, 1.0, v137
	v_mul_f32_e32 v136, 0xbfb8aa3b, v96
	v_mul_f32_e32 v137, 0xbfb8aa3b, v97
	v_exp_f32_e32 v136, v136
	v_exp_f32_e32 v137, v137
	v_exp_f32_e32 v140, v140
	v_exp_f32_e32 v141, v141
	v_mul_f32_e32 v142, 0xbfb8aa3b, v92
	v_mul_f32_e32 v143, 0xbfb8aa3b, v93
	v_add_f32_e32 v136, 1.0, v136
	v_add_f32_e32 v137, 1.0, v137
	v_add_f32_e32 v140, 1.0, v140
	v_add_f32_e32 v141, 1.0, v141
	v_exp_f32_e32 v142, v142
	v_exp_f32_e32 v143, v143
	v_rcp_f32_e32 v134, v134
	v_rcp_f32_e32 v135, v135
	v_rcp_f32_e32 v136, v136
	v_rcp_f32_e32 v137, v137
	v_rcp_f32_e32 v140, v140
	v_rcp_f32_e32 v141, v141
	v_add_f32_e32 v142, 1.0, v142
	v_add_f32_e32 v143, 1.0, v143
	v_rcp_f32_e32 v142, v142
	v_rcp_f32_e32 v143, v143
	v_cvt_pk_bf16_f32 v134, v134, v135
	v_cvt_pk_bf16_f32 v135, v136, v137
	v_cvt_pk_bf16_f32 v136, v140, v141
	v_mul_f32_e32 v140, 0xbfb8aa3b, v86
	v_mul_f32_e32 v141, 0xbfb8aa3b, v87
	v_exp_f32_e32 v140, v140
	v_exp_f32_e32 v141, v141
	v_lshl_add_u64 v[138:139], s[28:29], 0, v[138:139]
	v_cvt_pk_bf16_f32 v137, v142, v143
	v_lshl_add_u64 v[138:139], v[138:139], 0, v[132:133]
	global_store_dwordx4 v[138:139], v[134:137], off
	v_mul_f32_e32 v142, 0xbfb8aa3b, v84
	v_mul_f32_e32 v143, 0xbfb8aa3b, v85
	v_add_f32_e32 v134, 1.0, v140
	v_add_f32_e32 v135, 1.0, v141
	v_mul_f32_e32 v136, 0xbfb8aa3b, v88
	v_mul_f32_e32 v137, 0xbfb8aa3b, v89
	v_mul_f32_e32 v140, 0xbfb8aa3b, v82
	v_mul_f32_e32 v141, 0xbfb8aa3b, v83
	v_exp_f32_e32 v136, v136
	v_exp_f32_e32 v137, v137
	v_exp_f32_e32 v140, v140
	v_exp_f32_e32 v141, v141
	v_exp_f32_e32 v142, v142
	v_exp_f32_e32 v143, v143
	v_add_f32_e32 v136, 1.0, v136
	v_add_f32_e32 v137, 1.0, v137
	v_add_f32_e32 v140, 1.0, v140
	v_add_f32_e32 v141, 1.0, v141
	v_add_f32_e32 v142, 1.0, v142
	v_add_f32_e32 v143, 1.0, v143
	v_rcp_f32_e32 v134, v134
	v_rcp_f32_e32 v135, v135
	v_rcp_f32_e32 v136, v136
	v_rcp_f32_e32 v137, v137
	v_rcp_f32_e32 v140, v140
	v_rcp_f32_e32 v141, v141
	v_rcp_f32_e32 v142, v142
	v_rcp_f32_e32 v143, v143
	v_cvt_pk_bf16_f32 v134, v134, v135
	v_cvt_pk_bf16_f32 v135, v136, v137
	v_cvt_pk_bf16_f32 v136, v140, v141
	v_cvt_pk_bf16_f32 v137, v142, v143
	global_store_dwordx4 v[138:139], v[134:137], off offset:256
	v_mul_f32_e32 v140, 0xbfb8aa3b, v74
	v_mul_f32_e32 v141, 0xbfb8aa3b, v75
	v_mul_f32_e32 v136, 0xbfb8aa3b, v78
	v_mul_f32_e32 v137, 0xbfb8aa3b, v79
	v_exp_f32_e32 v136, v136
	v_exp_f32_e32 v137, v137
	v_or_b32_e32 v134, 48, v220
	v_ashrrev_i32_e32 v135, 31, v134
	v_lshlrev_b64 v[138:139], 13, v[134:135]
	v_add_f32_e32 v134, 1.0, v136
	v_add_f32_e32 v135, 1.0, v137
	v_mul_f32_e32 v136, 0xbfb8aa3b, v80
	v_mul_f32_e32 v137, 0xbfb8aa3b, v81
	v_mul_f32_e32 v142, 0xbfb8aa3b, v76
	v_mul_f32_e32 v143, 0xbfb8aa3b, v77
	v_exp_f32_e32 v136, v136
	v_exp_f32_e32 v137, v137
	v_exp_f32_e32 v140, v140
	v_exp_f32_e32 v141, v141
	v_exp_f32_e32 v142, v142
	v_exp_f32_e32 v143, v143
	v_add_f32_e32 v136, 1.0, v136
	v_add_f32_e32 v137, 1.0, v137
	v_add_f32_e32 v140, 1.0, v140
	v_add_f32_e32 v141, 1.0, v141
	v_add_f32_e32 v142, 1.0, v142
	v_add_f32_e32 v143, 1.0, v143
	v_rcp_f32_e32 v134, v134
	v_rcp_f32_e32 v135, v135
	v_rcp_f32_e32 v136, v136
	v_rcp_f32_e32 v137, v137
	v_rcp_f32_e32 v140, v140
	v_rcp_f32_e32 v141, v141
	v_rcp_f32_e32 v142, v142
	v_rcp_f32_e32 v143, v143
	v_lshl_add_u64 v[138:139], s[28:29], 0, v[138:139]
	v_cvt_pk_bf16_f32 v134, v134, v135
	v_cvt_pk_bf16_f32 v135, v136, v137
	v_cvt_pk_bf16_f32 v136, v140, v141
	v_cvt_pk_bf16_f32 v137, v142, v143
	v_lshl_add_u64 v[138:139], v[138:139], 0, v[132:133]
	v_mul_f32_e32 v132, 0xbfb8aa3b, v70
	v_mul_f32_e32 v133, 0xbfb8aa3b, v71
	global_store_dwordx4 v[138:139], v[134:137], off
	v_exp_f32_e32 v132, v132
	v_exp_f32_e32 v133, v133
	v_mul_f32_e32 v134, 0xbfb8aa3b, v72
	v_mul_f32_e32 v135, 0xbfb8aa3b, v73
	v_mul_f32_e32 v136, 0xbfb8aa3b, v66
	v_mul_f32_e32 v137, 0xbfb8aa3b, v67
	v_exp_f32_e32 v134, v134
	v_exp_f32_e32 v135, v135
	v_exp_f32_e32 v136, v136
	v_exp_f32_e32 v137, v137
	v_mul_f32_e32 v140, 0xbfb8aa3b, v68
	v_mul_f32_e32 v141, 0xbfb8aa3b, v69
	v_exp_f32_e32 v140, v140
	v_exp_f32_e32 v141, v141
	v_add_f32_e32 v132, 1.0, v132
	v_add_f32_e32 v133, 1.0, v133
	v_add_f32_e32 v134, 1.0, v134
	v_add_f32_e32 v135, 1.0, v135
	v_add_f32_e32 v136, 1.0, v136
	v_add_f32_e32 v137, 1.0, v137
	v_rcp_f32_e32 v132, v132
	v_rcp_f32_e32 v133, v133
	v_rcp_f32_e32 v134, v134
	v_rcp_f32_e32 v135, v135
	v_rcp_f32_e32 v136, v136
	v_rcp_f32_e32 v137, v137
	v_add_f32_e32 v140, 1.0, v140
	v_add_f32_e32 v141, 1.0, v141
	v_rcp_f32_e32 v140, v140
	v_rcp_f32_e32 v141, v141
	v_cvt_pk_bf16_f32 v132, v132, v133
	v_cvt_pk_bf16_f32 v133, v134, v135
	v_cvt_pk_bf16_f32 v134, v136, v137
	v_mul_f32_e32 v136, 0xbfb8aa3b, v62
	v_mul_f32_e32 v137, 0xbfb8aa3b, v63
	v_exp_f32_e32 v136, v136
	v_exp_f32_e32 v137, v137
	v_cvt_pk_bf16_f32 v135, v140, v141
	global_store_dwordx4 v[138:139], v[132:135], off offset:256
	v_mul_f32_e32 v138, 0xbfb8aa3b, v60
	v_mul_f32_e32 v139, 0xbfb8aa3b, v61
	v_mul_f32_e32 v134, 0xbfb8aa3b, v64
	v_mul_f32_e32 v135, 0xbfb8aa3b, v65
	v_add_f32_e32 v132, 1.0, v136
	v_add_f32_e32 v133, 1.0, v137
	v_exp_f32_e32 v134, v134
	v_exp_f32_e32 v135, v135
	v_mul_f32_e32 v136, 0xbfb8aa3b, v58
	v_mul_f32_e32 v137, 0xbfb8aa3b, v59
	v_exp_f32_e32 v138, v138
	v_exp_f32_e32 v139, v139
	v_exp_f32_e32 v136, v136
	v_exp_f32_e32 v137, v137
	v_add_f32_e32 v134, 1.0, v134
	v_add_f32_e32 v135, 1.0, v135
	v_add_f32_e32 v138, 1.0, v138
	v_add_f32_e32 v139, 1.0, v139
	v_rcp_f32_e32 v132, v132
	v_rcp_f32_e32 v133, v133
	v_rcp_f32_e32 v134, v134
	v_rcp_f32_e32 v135, v135
	v_add_f32_e32 v136, 1.0, v136
	v_add_f32_e32 v137, 1.0, v137
	v_rcp_f32_e32 v138, v138
; __device__ __forceinline__ u32x4 pack8(f32x4 a, f32x4 b) { u32x4 w; w.x = cvt_pk_bf16(a[0], a[1]); w.y = cvt_pk_bf16(a[2], a[3]); w.z = cvt_pk_bf16(b[0], b[1]); w.w = cvt_pk_bf16(b[2], b[3]); return w; }
; __device__ __forceinline__ f32x4 sig4(f32x4 v) { f32x4 r; r[0] = sigmoidf_(v[0]); r[1] = sigmoidf_(v[1]); r[2] = sigmoidf_(v[2]); r[3] = sigmoidf_(v[3]); return r; }
;     __device__ __forceinline__ void operator()(AccRef acc, const pg8::Unit& u, int wr, int wc, int fr, int fq) const {
;     ...
;                 for (int m = 0; m < 4; ++m) { const int r = row0 + ai * 128 + m * 16;
; #pragma unroll
;                     for (int bj = 0; bj < 2; ++bj) *(u32x4*)(sg + (size_t)r * 4096 + c0 + bj * 128) = pack8(sig4(acc[ai][bj][m][0]), sig4(acc[ai][bj][m][1])); }
	v_rcp_f32_e32 v139, v139
	v_rcp_f32_e32 v136, v136
	v_rcp_f32_e32 v137, v137
	s_mov_b32 s33, 0x100000
	v_cvt_pk_bf16_f32 v132, v132, v133
	v_cvt_pk_bf16_f32 v133, v134, v135
	v_cvt_pk_bf16_f32 v135, v138, v139
	v_add_co_u32_e32 v138, vcc, s33, v130
	v_cvt_pk_bf16_f32 v134, v136, v137
	s_nop 0
	v_addc_co_u32_e32 v139, vcc, 0, v131, vcc
	v_mul_f32_e32 v140, 0xbfb8aa3b, v54
	v_mul_f32_e32 v141, 0xbfb8aa3b, v55
	v_exp_f32_e32 v140, v140
	v_exp_f32_e32 v141, v141
	global_store_dwordx4 v[138:139], v[132:135], off
	v_mul_f32_e32 v138, 0xbfb8aa3b, v50
	v_mul_f32_e32 v139, 0xbfb8aa3b, v51
	v_mul_f32_e32 v134, 0xbfb8aa3b, v56
	v_mul_f32_e32 v135, 0xbfb8aa3b, v57
	v_exp_f32_e32 v134, v134
	v_exp_f32_e32 v135, v135
	v_exp_f32_e32 v138, v138
	v_exp_f32_e32 v139, v139
	v_add_f32_e32 v132, 1.0, v140
	v_add_f32_e32 v133, 1.0, v141
	v_mul_f32_e32 v140, 0xbfb8aa3b, v52
	v_mul_f32_e32 v141, 0xbfb8aa3b, v53
	v_add_f32_e32 v134, 1.0, v134
	v_add_f32_e32 v135, 1.0, v135
	v_add_f32_e32 v138, 1.0, v138
	v_add_f32_e32 v139, 1.0, v139
	v_exp_f32_e32 v140, v140
	v_exp_f32_e32 v141, v141
	v_rcp_f32_e32 v132, v132
	v_rcp_f32_e32 v133, v133
	v_rcp_f32_e32 v134, v134
	v_rcp_f32_e32 v135, v135
	v_rcp_f32_e32 v138, v138
	v_rcp_f32_e32 v139, v139
	v_add_f32_e32 v140, 1.0, v140
	v_add_f32_e32 v141, 1.0, v141
	v_rcp_f32_e32 v140, v140
	v_rcp_f32_e32 v141, v141
	v_cvt_pk_bf16_f32 v132, v132, v133
	v_cvt_pk_bf16_f32 v133, v134, v135
	v_cvt_pk_bf16_f32 v134, v138, v139
	v_mul_f32_e32 v138, 0xbfb8aa3b, v46
	v_mul_f32_e32 v139, 0xbfb8aa3b, v47
	v_exp_f32_e32 v138, v138
	v_exp_f32_e32 v139, v139
	v_lshl_add_u64 v[136:137], v[130:131], 0, s[42:43]
	v_cvt_pk_bf16_f32 v135, v140, v141
	global_store_dwordx4 v[136:137], v[132:135], off offset:256
	v_mul_f32_e32 v136, 0xbfb8aa3b, v42
	v_mul_f32_e32 v137, 0xbfb8aa3b, v43
	v_add_f32_e32 v132, 1.0, v138
	v_add_f32_e32 v133, 1.0, v139
	v_mul_f32_e32 v134, 0xbfb8aa3b, v48
	v_mul_f32_e32 v135, 0xbfb8aa3b, v49
	v_mul_f32_e32 v138, 0xbfb8aa3b, v44
	v_mul_f32_e32 v139, 0xbfb8aa3b, v45
	v_exp_f32_e32 v134, v134
	v_exp_f32_e32 v135, v135
	v_exp_f32_e32 v138, v138
	v_exp_f32_e32 v139, v139
	v_exp_f32_e32 v136, v136
	v_exp_f32_e32 v137, v137
	v_add_f32_e32 v134, 1.0, v134
	v_add_f32_e32 v135, 1.0, v135
	v_add_f32_e32 v138, 1.0, v138
	v_add_f32_e32 v139, 1.0, v139
	v_rcp_f32_e32 v132, v132
	v_rcp_f32_e32 v133, v133
	v_rcp_f32_e32 v134, v134
	v_rcp_f32_e32 v135, v135
	v_add_f32_e32 v136, 1.0, v136
	v_add_f32_e32 v137, 1.0, v137
	v_rcp_f32_e32 v138, v138
	v_rcp_f32_e32 v139, v139
	v_rcp_f32_e32 v136, v136
	v_rcp_f32_e32 v137, v137
	s_mov_b32 s33, 0x120000
	v_cvt_pk_bf16_f32 v132, v132, v133
	v_cvt_pk_bf16_f32 v133, v134, v135
	v_cvt_pk_bf16_f32 v135, v138, v139
	v_add_co_u32_e32 v138, vcc, s33, v130
	v_cvt_pk_bf16_f32 v134, v136, v137
	s_nop 0
	v_addc_co_u32_e32 v139, vcc, 0, v131, vcc
	v_mul_f32_e32 v140, 0xbfb8aa3b, v38
	v_mul_f32_e32 v141, 0xbfb8aa3b, v39
	v_exp_f32_e32 v140, v140
	v_exp_f32_e32 v141, v141
	global_store_dwordx4 v[138:139], v[132:135], off
	v_mul_f32_e32 v138, 0xbfb8aa3b, v34
	v_mul_f32_e32 v139, 0xbfb8aa3b, v35
	v_mul_f32_e32 v134, 0xbfb8aa3b, v40
	v_mul_f32_e32 v135, 0xbfb8aa3b, v41
	v_exp_f32_e32 v134, v134
	v_exp_f32_e32 v135, v135
	v_exp_f32_e32 v138, v138
	v_exp_f32_e32 v139, v139
	v_add_f32_e32 v132, 1.0, v140
	v_add_f32_e32 v133, 1.0, v141
	v_mul_f32_e32 v140, 0xbfb8aa3b, v36
	v_mul_f32_e32 v141, 0xbfb8aa3b, v37
	v_add_f32_e32 v134, 1.0, v134
	v_add_f32_e32 v135, 1.0, v135
	v_add_f32_e32 v138, 1.0, v138
	v_add_f32_e32 v139, 1.0, v139
	v_exp_f32_e32 v140, v140
	v_exp_f32_e32 v141, v141
	v_rcp_f32_e32 v132, v132
	v_rcp_f32_e32 v133, v133
	v_rcp_f32_e32 v134, v134
	v_rcp_f32_e32 v135, v135
	v_rcp_f32_e32 v138, v138
	v_rcp_f32_e32 v139, v139
	v_add_f32_e32 v140, 1.0, v140
	v_add_f32_e32 v141, 1.0, v141
	v_rcp_f32_e32 v140, v140
	v_rcp_f32_e32 v141, v141
	v_cvt_pk_bf16_f32 v132, v132, v133
	v_cvt_pk_bf16_f32 v133, v134, v135
	v_cvt_pk_bf16_f32 v134, v138, v139
	v_mul_f32_e32 v138, 0xbfb8aa3b, v30
	v_mul_f32_e32 v139, 0xbfb8aa3b, v31
	v_exp_f32_e32 v138, v138
	v_exp_f32_e32 v139, v139
	s_mov_b64 s[60:61], 0x120000
	v_lshl_add_u64 v[136:137], v[130:131], 0, s[60:61]
	v_cvt_pk_bf16_f32 v135, v140, v141
	global_store_dwordx4 v[136:137], v[132:135], off offset:256
	v_mul_f32_e32 v136, 0xbfb8aa3b, v26
	v_mul_f32_e32 v137, 0xbfb8aa3b, v27
	v_add_f32_e32 v132, 1.0, v138
	v_add_f32_e32 v133, 1.0, v139
	v_mul_f32_e32 v134, 0xbfb8aa3b, v32
	v_mul_f32_e32 v135, 0xbfb8aa3b, v33
	v_mul_f32_e32 v138, 0xbfb8aa3b, v28
	v_mul_f32_e32 v139, 0xbfb8aa3b, v29
	v_exp_f32_e32 v134, v134
	v_exp_f32_e32 v135, v135
	v_exp_f32_e32 v138, v138
	v_exp_f32_e32 v139, v139
	v_exp_f32_e32 v136, v136
	v_exp_f32_e32 v137, v137
	v_add_f32_e32 v134, 1.0, v134
	v_add_f32_e32 v135, 1.0, v135
	v_add_f32_e32 v138, 1.0, v138
	v_add_f32_e32 v139, 1.0, v139
	v_rcp_f32_e32 v132, v132
	v_rcp_f32_e32 v133, v133
	v_rcp_f32_e32 v134, v134
	v_rcp_f32_e32 v135, v135
	v_add_f32_e32 v136, 1.0, v136
	v_add_f32_e32 v137, 1.0, v137
	v_rcp_f32_e32 v138, v138
	v_rcp_f32_e32 v139, v139
	v_rcp_f32_e32 v136, v136
	v_rcp_f32_e32 v137, v137
	s_mov_b32 s33, 0x140000
	v_cvt_pk_bf16_f32 v132, v132, v133
	v_cvt_pk_bf16_f32 v133, v134, v135
	v_cvt_pk_bf16_f32 v135, v138, v139
	v_add_co_u32_e32 v138, vcc, s33, v130
	v_cvt_pk_bf16_f32 v134, v136, v137
	s_nop 0
	v_addc_co_u32_e32 v139, vcc, 0, v131, vcc
	v_mul_f32_e32 v140, 0xbfb8aa3b, v22
	v_mul_f32_e32 v141, 0xbfb8aa3b, v23
	v_exp_f32_e32 v140, v140
	v_exp_f32_e32 v141, v141
	global_store_dwordx4 v[138:139], v[132:135], off
	v_mul_f32_e32 v138, 0xbfb8aa3b, v18
	v_mul_f32_e32 v139, 0xbfb8aa3b, v19
	v_mul_f32_e32 v134, 0xbfb8aa3b, v24
; __device__ __forceinline__ u32x4 pack8(f32x4 a, f32x4 b) { u32x4 w; w.x = cvt_pk_bf16(a[0], a[1]); w.y = cvt_pk_bf16(a[2], a[3]); w.z = cvt_pk_bf16(b[0], b[1]); w.w = cvt_pk_bf16(b[2], b[3]); return w; }
; __device__ __forceinline__ f32x4 sig4(f32x4 v) { f32x4 r; r[0] = sigmoidf_(v[0]); r[1] = sigmoidf_(v[1]); r[2] = sigmoidf_(v[2]); r[3] = sigmoidf_(v[3]); return r; }
;     __device__ __forceinline__ void operator()(AccRef acc, const pg8::Unit& u, int wr, int wc, int fr, int fq) const {
;     ...
;                 for (int m = 0; m < 4; ++m) { const int r = row0 + ai * 128 + m * 16;
; #pragma unroll
;                     for (int bj = 0; bj < 2; ++bj) *(u32x4*)(sg + (size_t)r * 4096 + c0 + bj * 128) = pack8(sig4(acc[ai][bj][m][0]), sig4(acc[ai][bj][m][1])); }
	v_mul_f32_e32 v135, 0xbfb8aa3b, v25
	v_exp_f32_e32 v134, v134
	v_exp_f32_e32 v135, v135
	v_exp_f32_e32 v138, v138
	v_exp_f32_e32 v139, v139
	v_add_f32_e32 v132, 1.0, v140
	v_add_f32_e32 v133, 1.0, v141
	v_mul_f32_e32 v140, 0xbfb8aa3b, v20
	v_mul_f32_e32 v141, 0xbfb8aa3b, v21
	v_add_f32_e32 v134, 1.0, v134
	v_add_f32_e32 v135, 1.0, v135
	v_add_f32_e32 v138, 1.0, v138
	v_add_f32_e32 v139, 1.0, v139
	v_exp_f32_e32 v140, v140
	v_exp_f32_e32 v141, v141
	v_rcp_f32_e32 v132, v132
	v_rcp_f32_e32 v133, v133
	v_rcp_f32_e32 v134, v134
	v_rcp_f32_e32 v135, v135
	v_rcp_f32_e32 v138, v138
	v_rcp_f32_e32 v139, v139
	v_add_f32_e32 v140, 1.0, v140
	v_add_f32_e32 v141, 1.0, v141
	v_rcp_f32_e32 v140, v140
	v_rcp_f32_e32 v141, v141
	v_cvt_pk_bf16_f32 v132, v132, v133
	v_cvt_pk_bf16_f32 v133, v134, v135
	v_cvt_pk_bf16_f32 v134, v138, v139
	v_mul_f32_e32 v138, 0xbfb8aa3b, v14
	v_mul_f32_e32 v139, 0xbfb8aa3b, v15
	v_exp_f32_e32 v138, v138
	v_exp_f32_e32 v139, v139
	s_mov_b64 s[60:61], 0x140000
	v_lshl_add_u64 v[136:137], v[130:131], 0, s[60:61]
	v_cvt_pk_bf16_f32 v135, v140, v141
	global_store_dwordx4 v[136:137], v[132:135], off offset:256
	v_mul_f32_e32 v136, 0xbfb8aa3b, v10
	v_mul_f32_e32 v137, 0xbfb8aa3b, v11
	v_add_f32_e32 v132, 1.0, v138
	v_add_f32_e32 v133, 1.0, v139
	v_mul_f32_e32 v134, 0xbfb8aa3b, v16
	v_mul_f32_e32 v135, 0xbfb8aa3b, v17
	v_mul_f32_e32 v138, 0xbfb8aa3b, v12
	v_mul_f32_e32 v139, 0xbfb8aa3b, v13
	v_exp_f32_e32 v134, v134
	v_exp_f32_e32 v135, v135
	v_exp_f32_e32 v138, v138
	v_exp_f32_e32 v139, v139
	v_exp_f32_e32 v136, v136
	v_exp_f32_e32 v137, v137
	v_add_f32_e32 v134, 1.0, v134
	v_add_f32_e32 v135, 1.0, v135
	v_add_f32_e32 v138, 1.0, v138
	v_add_f32_e32 v139, 1.0, v139
	v_rcp_f32_e32 v132, v132
	v_rcp_f32_e32 v133, v133
	v_rcp_f32_e32 v134, v134
	v_rcp_f32_e32 v135, v135
	v_rcp_f32_e32 v138, v138
	v_rcp_f32_e32 v139, v139
	v_add_f32_e32 v136, 1.0, v136
	v_add_f32_e32 v137, 1.0, v137
	v_rcp_f32_e32 v136, v136
	v_rcp_f32_e32 v137, v137
	v_cvt_pk_bf16_f32 v132, v132, v133
	v_cvt_pk_bf16_f32 v133, v134, v135
	v_cvt_pk_bf16_f32 v135, v138, v139
	v_mul_f32_e32 v138, 0xbfb8aa3b, v6
	v_mul_f32_e32 v139, 0xbfb8aa3b, v7
	v_exp_f32_e32 v138, v138
	v_exp_f32_e32 v139, v139
	s_mov_b64 s[60:61], 0x160000
	s_mov_b32 s33, 0x160000
	v_cvt_pk_bf16_f32 v134, v136, v137
	v_lshl_add_u64 v[136:137], v[130:131], 0, s[60:61]
	v_add_co_u32_e32 v130, vcc, s33, v130
	s_mov_b64 s[60:61], 0
	s_nop 0
	v_addc_co_u32_e32 v131, vcc, 0, v131, vcc
	global_store_dwordx4 v[130:131], v[132:135], off
	v_add_f32_e32 v130, 1.0, v138
	v_add_f32_e32 v131, 1.0, v139
	v_mul_f32_e32 v132, 0xbfb8aa3b, v8
	v_mul_f32_e32 v133, 0xbfb8aa3b, v9
	v_mul_f32_e32 v134, 0xbfb8aa3b, v2
	v_mul_f32_e32 v135, 0xbfb8aa3b, v3
	v_mul_f32_e32 v138, 0xbfb8aa3b, v4
	v_mul_f32_e32 v139, 0xbfb8aa3b, v5
	v_exp_f32_e32 v132, v132
	v_exp_f32_e32 v133, v133
	v_exp_f32_e32 v134, v134
	v_exp_f32_e32 v135, v135
	v_exp_f32_e32 v138, v138
	v_exp_f32_e32 v139, v139
	v_add_f32_e32 v132, 1.0, v132
	v_add_f32_e32 v133, 1.0, v133
	v_add_f32_e32 v134, 1.0, v134
	v_add_f32_e32 v135, 1.0, v135
	v_add_f32_e32 v138, 1.0, v138
	v_add_f32_e32 v139, 1.0, v139
	v_rcp_f32_e32 v130, v130
	v_rcp_f32_e32 v131, v131
	v_rcp_f32_e32 v132, v132
	v_rcp_f32_e32 v133, v133
	v_rcp_f32_e32 v134, v134
	v_rcp_f32_e32 v135, v135
	v_rcp_f32_e32 v138, v138
	v_rcp_f32_e32 v139, v139
	v_cvt_pk_bf16_f32 v130, v130, v131
	v_cvt_pk_bf16_f32 v131, v132, v133
	v_cvt_pk_bf16_f32 v132, v134, v135
	v_cvt_pk_bf16_f32 v133, v138, v139
	global_store_dwordx4 v[136:137], v[130:133], off offset:256
; __device__ __forceinline__ u32x4 pack8(f32x4 a, f32x4 b) { u32x4 w; w.x = cvt_pk_bf16(a[0], a[1]); w.y = cvt_pk_bf16(a[2], a[3]); w.z = cvt_pk_bf16(b[0], b[1]); w.w = cvt_pk_bf16(b[2], b[3]); return w; }
;     __device__ __forceinline__ void operator()(AccRef acc, const pg8::Unit& u, int wr, int wc, int fr, int fq) const {
;     ...
;         } else if (pn < 36) {
;             const int c0 = (pn - 32) * 256 + cl;
; #pragma unroll
;             for (int ai = 0; ai < 2; ++ai)
; #pragma unroll
;                 for (int m = 0; m < 4; ++m) { const int r = row0 + ai * 128 + m * 16;
; #pragma unroll
;                     for (int bj = 0; bj < 2; ++bj) *(u32x4*)(pz + (size_t)r * 1024 + c0 + bj * 128) = pack8(acc[ai][bj][m][0], acc[ai][bj][m][1]); }
.LBB0_216:
	s_andn2_b64 vcc, exec, s[60:61]
	s_cbranch_vccnz .LBB0_218
	v_add_u32_e32 v202, s11, v225
	v_lshlrev_b64 v[134:135], 11, v[220:221]
	v_lshl_add_u64 v[134:135], s[16:17], 0, v[134:135]
	v_lshlrev_b64 v[136:137], 1, v[202:203]
	v_cvt_pk_bf16_f32 v130, v126, v127
	v_cvt_pk_bf16_f32 v131, v128, v129
	v_cvt_pk_bf16_f32 v132, v122, v123
	v_cvt_pk_bf16_f32 v133, v124, v125
	v_lshl_add_u64 v[134:135], v[134:135], 0, v[136:137]
	s_waitcnt vmcnt(0)
	global_store_dwordx4 v[134:135], v[130:133], off
	s_mov_b32 s11, 0x40000
	s_mov_b64 s[60:61], 0x40000
	v_cvt_pk_bf16_f32 v130, v118, v119
	v_cvt_pk_bf16_f32 v131, v120, v121
	v_cvt_pk_bf16_f32 v132, v114, v115
	v_cvt_pk_bf16_f32 v133, v116, v117
	global_store_dwordx4 v[134:135], v[130:133], off offset:256
	s_nop 1
	v_or_b32_e32 v130, 16, v220
	v_ashrrev_i32_e32 v131, 31, v130
	v_lshlrev_b64 v[134:135], 11, v[130:131]
	v_lshl_add_u64 v[134:135], s[16:17], 0, v[134:135]
	v_cvt_pk_bf16_f32 v130, v110, v111
	v_cvt_pk_bf16_f32 v131, v112, v113
	v_cvt_pk_bf16_f32 v132, v106, v107
	v_cvt_pk_bf16_f32 v133, v108, v109
	v_lshl_add_u64 v[134:135], v[134:135], 0, v[136:137]
	global_store_dwordx4 v[134:135], v[130:133], off
	s_nop 1
	v_cvt_pk_bf16_f32 v130, v102, v103
	v_cvt_pk_bf16_f32 v131, v104, v105
	v_cvt_pk_bf16_f32 v132, v98, v99
	v_cvt_pk_bf16_f32 v133, v100, v101
	global_store_dwordx4 v[134:135], v[130:133], off offset:256
	s_nop 1
	v_or_b32_e32 v130, 32, v220
	v_ashrrev_i32_e32 v131, 31, v130
	v_lshlrev_b64 v[134:135], 11, v[130:131]
	v_lshl_add_u64 v[134:135], s[16:17], 0, v[134:135]
	v_cvt_pk_bf16_f32 v130, v94, v95
	v_cvt_pk_bf16_f32 v131, v96, v97
	v_cvt_pk_bf16_f32 v132, v90, v91
	v_cvt_pk_bf16_f32 v133, v92, v93
	v_lshl_add_u64 v[134:135], v[134:135], 0, v[136:137]
	global_store_dwordx4 v[134:135], v[130:133], off
	s_nop 1
	v_cvt_pk_bf16_f32 v130, v86, v87
	v_cvt_pk_bf16_f32 v131, v88, v89
	v_cvt_pk_bf16_f32 v132, v82, v83
	v_cvt_pk_bf16_f32 v133, v84, v85
	global_store_dwordx4 v[134:135], v[130:133], off offset:256
	s_nop 1
	v_or_b32_e32 v130, 48, v220
	v_ashrrev_i32_e32 v131, 31, v130
	v_lshlrev_b64 v[134:135], 11, v[130:131]
	v_lshl_add_u64 v[134:135], s[16:17], 0, v[134:135]
	v_cvt_pk_bf16_f32 v130, v78, v79
	v_cvt_pk_bf16_f32 v131, v80, v81
	v_cvt_pk_bf16_f32 v132, v74, v75
	v_cvt_pk_bf16_f32 v133, v76, v77
	v_lshl_add_u64 v[134:135], v[134:135], 0, v[136:137]
	global_store_dwordx4 v[134:135], v[130:133], off
	s_nop 1
	v_cvt_pk_bf16_f32 v130, v70, v71
	v_cvt_pk_bf16_f32 v131, v72, v73
	v_cvt_pk_bf16_f32 v132, v66, v67
	v_cvt_pk_bf16_f32 v133, v68, v69
	global_store_dwordx4 v[134:135], v[130:133], off offset:256
	v_lshlrev_b64 v[134:135], 11, v[220:221]
	v_lshl_add_u64 v[134:135], s[16:17], 0, v[134:135]
	v_lshl_add_u64 v[134:135], v[134:135], 0, v[136:137]
	v_add_co_u32_e32 v138, vcc, s11, v134
	v_cvt_pk_bf16_f32 v130, v62, v63
	v_cvt_pk_bf16_f32 v131, v64, v65
	v_cvt_pk_bf16_f32 v132, v58, v59
	v_cvt_pk_bf16_f32 v133, v60, v61
	v_addc_co_u32_e32 v139, vcc, 0, v135, vcc
	s_mov_b32 s11, 0x48000
	v_lshl_add_u64 v[136:137], v[134:135], 0, s[60:61]
	global_store_dwordx4 v[138:139], v[130:133], off
	v_add_co_u32_e32 v138, vcc, s11, v134
	s_nop 0
	v_cvt_pk_bf16_f32 v130, v54, v55
	v_cvt_pk_bf16_f32 v131, v56, v57
	v_cvt_pk_bf16_f32 v132, v50, v51
	v_cvt_pk_bf16_f32 v133, v52, v53
	global_store_dwordx4 v[136:137], v[130:133], off offset:256
	s_mov_b64 s[60:61], 0x48000
	v_addc_co_u32_e32 v139, vcc, 0, v135, vcc
	v_cvt_pk_bf16_f32 v130, v46, v47
	v_cvt_pk_bf16_f32 v131, v48, v49
	v_cvt_pk_bf16_f32 v132, v42, v43
	v_cvt_pk_bf16_f32 v133, v44, v45
	s_mov_b32 s11, 0x50000
	v_lshl_add_u64 v[136:137], v[134:135], 0, s[60:61]
	global_store_dwordx4 v[138:139], v[130:133], off
	v_add_co_u32_e32 v138, vcc, s11, v134
	s_nop 0
	v_cvt_pk_bf16_f32 v130, v38, v39
	v_cvt_pk_bf16_f32 v131, v40, v41
	v_cvt_pk_bf16_f32 v132, v34, v35
	v_cvt_pk_bf16_f32 v133, v36, v37
	global_store_dwordx4 v[136:137], v[130:133], off offset:256
	s_mov_b64 s[60:61], 0x50000
	v_addc_co_u32_e32 v139, vcc, 0, v135, vcc
	v_cvt_pk_bf16_f32 v130, v30, v31
	v_cvt_pk_bf16_f32 v131, v32, v33
	v_cvt_pk_bf16_f32 v132, v26, v27
	v_cvt_pk_bf16_f32 v133, v28, v29
	v_lshl_add_u64 v[136:137], v[134:135], 0, s[60:61]
	global_store_dwordx4 v[138:139], v[130:133], off
	s_mov_b64 s[60:61], 0x58000
	s_nop 0
	v_cvt_pk_bf16_f32 v130, v22, v23
	v_cvt_pk_bf16_f32 v131, v24, v25
	v_cvt_pk_bf16_f32 v132, v18, v19
	v_cvt_pk_bf16_f32 v133, v20, v21
	global_store_dwordx4 v[136:137], v[130:133], off offset:256
	v_lshl_add_u64 v[136:137], v[134:135], 0, s[60:61]
	v_add_co_u32_e32 v134, vcc, s18, v134
	v_cvt_pk_bf16_f32 v130, v14, v15
	v_cvt_pk_bf16_f32 v131, v16, v17
	v_cvt_pk_bf16_f32 v132, v10, v11
	v_cvt_pk_bf16_f32 v133, v12, v13
	v_addc_co_u32_e32 v135, vcc, 0, v135, vcc
	global_store_dwordx4 v[134:135], v[130:133], off
	s_nop 1
	v_cvt_pk_bf16_f32 v130, v6, v7
	v_cvt_pk_bf16_f32 v131, v8, v9
	v_cvt_pk_bf16_f32 v132, v2, v3
	v_cvt_pk_bf16_f32 v133, v4, v5
	global_store_dwordx4 v[136:137], v[130:133], off offset:256

; __device__ __forceinline__ u32x4 pack8(f32x4 a, f32x4 b) { u32x4 w; w.x = cvt_pk_bf16(a[0], a[1]); w.y = cvt_pk_bf16(a[2], a[3]); w.z = cvt_pk_bf16(b[0], b[1]); w.w = cvt_pk_bf16(b[2], b[3]); return w; }
; __device__ __forceinline__ f32x4 sig4(f32x4 v) { f32x4 r; r[0] = sigmoidf_(v[0]); r[1] = sigmoidf_(v[1]); r[2] = sigmoidf_(v[2]); r[3] = sigmoidf_(v[3]); return r; }
;     __device__ __forceinline__ void operator()(AccRef acc, const pg8::Unit& u, int wr, int wc, int fr, int fq) const {
;     ...
;         } else if (pn < 32) {
;             const int c0 = (pn - 24) * 256 + cl;
; #pragma unroll
;             for (int ai = 0; ai < 2; ++ai)
; #pragma unroll
;                 for (int m = 0; m < 4; ++m) { const int r = row0 + ai * 128 + m * 16;
; #pragma unroll
;                     for (int bj = 0; bj < 2; ++bj) { const f32x4 v0 = acc[ai][bj][m][0], v1 = acc[ai][bj][m][1];
;                         *(u32x4*)(srg + (size_t)r * 2048 + c0 + bj * 128) = pack8(v0 * sig4(v0), v1 * sig4(v1)); } }
.LBB0_219:
	s_andn2_b64 vcc, exec, s[60:61]
	s_cbranch_vccnz .LBB0_221
	v_mul_f32_e32 v130, 0xbfb8aa3b, v126
	v_mul_f32_e32 v133, 0xbfb8aa3b, v127
	v_exp_f32_e32 v132, v130
	v_exp_f32_e32 v133, v133
	v_mul_f32_e32 v134, 0xbfb8aa3b, v128
	v_mul_f32_e32 v135, 0xbfb8aa3b, v129
	v_mul_f32_e32 v136, 0xbfb8aa3b, v122
	v_mul_f32_e32 v137, 0xbfb8aa3b, v123
	v_mul_f32_e32 v138, 0xbfb8aa3b, v124
	v_mul_f32_e32 v139, 0xbfb8aa3b, v125
	v_exp_f32_e32 v134, v134
	v_exp_f32_e32 v135, v135
	v_exp_f32_e32 v136, v136
	v_exp_f32_e32 v137, v137
	v_exp_f32_e32 v138, v138
	v_exp_f32_e32 v139, v139
	v_add_f32_e32 v132, 1.0, v132
	v_add_f32_e32 v133, 1.0, v133
	v_rcp_f32_e32 v132, v132
	v_rcp_f32_e32 v133, v133
	v_add_f32_e32 v134, 1.0, v134
	v_add_f32_e32 v135, 1.0, v135
	v_add_f32_e32 v136, 1.0, v136
	v_add_f32_e32 v137, 1.0, v137
	v_add_f32_e32 v138, 1.0, v138
	v_add_f32_e32 v139, 1.0, v139
	v_rcp_f32_e32 v134, v134
	v_rcp_f32_e32 v135, v135
	v_rcp_f32_e32 v136, v136
	v_rcp_f32_e32 v138, v138
	v_rcp_f32_e32 v139, v139
	v_rcp_f32_e32 v137, v137
	v_pk_mul_f32 v[132:133], v[126:127], v[132:133]
	v_pk_mul_f32 v[140:141], v[128:129], v[134:135]
	v_pk_mul_f32 v[138:139], v[124:125], v[138:139]
	v_pk_mul_f32 v[136:137], v[122:123], v[136:137]
	v_cvt_pk_bf16_f32 v134, v132, v133
	v_mul_f32_e32 v132, 0xbfb8aa3b, v118
	v_cvt_pk_bf16_f32 v136, v136, v137
	v_cvt_pk_bf16_f32 v137, v138, v139
	v_exp_f32_e32 v138, v132
	v_lshl_add_u32 v202, s10, 8, v226
	v_lshlrev_b64 v[130:131], 12, v[220:221]
	v_lshl_add_u64 v[130:131], s[14:15], 0, v[130:131]
	v_lshlrev_b64 v[132:133], 1, v[202:203]
	v_cvt_pk_bf16_f32 v135, v140, v141
	v_lshl_add_u64 v[130:131], v[130:131], 0, v[132:133]
	s_waitcnt vmcnt(0)
	global_store_dwordx4 v[130:131], v[134:137], off
	v_mul_f32_e32 v139, 0xbfb8aa3b, v115
	v_mul_f32_e32 v140, 0xbfb8aa3b, v116
	v_add_f32_e32 v134, 1.0, v138
	v_mul_f32_e32 v135, 0xbfb8aa3b, v119
	v_mul_f32_e32 v136, 0xbfb8aa3b, v120
	v_mul_f32_e32 v137, 0xbfb8aa3b, v121
	v_mul_f32_e32 v138, 0xbfb8aa3b, v114
	v_mul_f32_e32 v141, 0xbfb8aa3b, v117
	v_exp_f32_e32 v135, v135
	v_exp_f32_e32 v136, v136
	v_exp_f32_e32 v137, v137
	v_exp_f32_e32 v138, v138
	v_exp_f32_e32 v139, v139
	v_exp_f32_e32 v140, v140
	v_exp_f32_e32 v141, v141
	v_add_f32_e32 v135, 1.0, v135
	v_add_f32_e32 v136, 1.0, v136
	v_add_f32_e32 v137, 1.0, v137
	v_add_f32_e32 v138, 1.0, v138
	v_add_f32_e32 v139, 1.0, v139
	v_add_f32_e32 v140, 1.0, v140
	v_add_f32_e32 v141, 1.0, v141
	v_rcp_f32_e32 v134, v134
	v_rcp_f32_e32 v135, v135
	v_rcp_f32_e32 v136, v136
	v_rcp_f32_e32 v137, v137
	v_rcp_f32_e32 v138, v138
	v_rcp_f32_e32 v140, v140
	v_rcp_f32_e32 v141, v141
	v_rcp_f32_e32 v139, v139
	v_pk_mul_f32 v[136:137], v[120:121], v[136:137]
	v_pk_mul_f32 v[134:135], v[118:119], v[134:135]
	v_pk_mul_f32 v[140:141], v[116:117], v[140:141]
	v_pk_mul_f32 v[138:139], v[114:115], v[138:139]
	v_cvt_pk_bf16_f32 v134, v134, v135
	v_cvt_pk_bf16_f32 v135, v136, v137
	v_cvt_pk_bf16_f32 v136, v138, v139
	v_cvt_pk_bf16_f32 v137, v140, v141
	global_store_dwordx4 v[130:131], v[134:137], off offset:256
	v_mul_f32_e32 v140, 0xbfb8aa3b, v106
	v_mul_f32_e32 v141, 0xbfb8aa3b, v107
	v_mul_f32_e32 v134, 0xbfb8aa3b, v110
	v_exp_f32_e32 v136, v134
	v_or_b32_e32 v134, 16, v220
	v_ashrrev_i32_e32 v135, 31, v134
	v_lshlrev_b64 v[138:139], 12, v[134:135]
	v_add_f32_e32 v134, 1.0, v136
	v_mul_f32_e32 v135, 0xbfb8aa3b, v111
	v_mul_f32_e32 v136, 0xbfb8aa3b, v112
	v_mul_f32_e32 v137, 0xbfb8aa3b, v113
	v_exp_f32_e32 v135, v135
	v_exp_f32_e32 v136, v136
	v_exp_f32_e32 v137, v137
	v_exp_f32_e32 v140, v140
	v_exp_f32_e32 v141, v141
	v_mul_f32_e32 v142, 0xbfb8aa3b, v108
	v_mul_f32_e32 v143, 0xbfb8aa3b, v109
	v_add_f32_e32 v135, 1.0, v135
	v_add_f32_e32 v136, 1.0, v136
	v_add_f32_e32 v137, 1.0, v137
	v_add_f32_e32 v140, 1.0, v140
	v_exp_f32_e32 v142, v142
	v_exp_f32_e32 v143, v143
	v_add_f32_e32 v141, 1.0, v141
	v_rcp_f32_e32 v134, v134
	v_rcp_f32_e32 v135, v135
	v_rcp_f32_e32 v136, v136
	v_rcp_f32_e32 v137, v137
	v_rcp_f32_e32 v140, v140
	v_rcp_f32_e32 v141, v141
	v_add_f32_e32 v142, 1.0, v142
	v_add_f32_e32 v143, 1.0, v143
	v_rcp_f32_e32 v142, v142
	v_rcp_f32_e32 v143, v143
	v_pk_mul_f32 v[136:137], v[112:113], v[136:137]
	v_pk_mul_f32 v[134:135], v[110:111], v[134:135]
	v_pk_mul_f32 v[140:141], v[106:107], v[140:141]
	v_cvt_pk_bf16_f32 v134, v134, v135
	v_cvt_pk_bf16_f32 v135, v136, v137
	v_cvt_pk_bf16_f32 v136, v140, v141
	v_mul_f32_e32 v140, 0xbfb8aa3b, v102
	v_exp_f32_e32 v140, v140
	v_pk_mul_f32 v[142:143], v[108:109], v[142:143]
	v_lshl_add_u64 v[138:139], s[14:15], 0, v[138:139]
	v_cvt_pk_bf16_f32 v137, v142, v143
	v_lshl_add_u64 v[138:139], v[138:139], 0, v[132:133]
	global_store_dwordx4 v[138:139], v[134:137], off
	v_mul_f32_e32 v141, 0xbfb8aa3b, v99
	v_mul_f32_e32 v142, 0xbfb8aa3b, v100
	v_add_f32_e32 v134, 1.0, v140
	v_mul_f32_e32 v135, 0xbfb8aa3b, v103
	v_mul_f32_e32 v136, 0xbfb8aa3b, v104
	v_mul_f32_e32 v137, 0xbfb8aa3b, v105
	v_mul_f32_e32 v140, 0xbfb8aa3b, v98
	v_mul_f32_e32 v143, 0xbfb8aa3b, v101
	v_exp_f32_e32 v135, v135
	v_exp_f32_e32 v136, v136
	v_exp_f32_e32 v137, v137
	v_exp_f32_e32 v140, v140
	v_exp_f32_e32 v141, v141
	v_exp_f32_e32 v142, v142
	v_exp_f32_e32 v143, v143
	v_add_f32_e32 v135, 1.0, v135
	v_add_f32_e32 v136, 1.0, v136
	v_add_f32_e32 v137, 1.0, v137
	v_add_f32_e32 v140, 1.0, v140
	v_add_f32_e32 v141, 1.0, v141
	v_add_f32_e32 v142, 1.0, v142
	v_add_f32_e32 v143, 1.0, v143
	v_rcp_f32_e32 v134, v134
	v_rcp_f32_e32 v135, v135
	v_rcp_f32_e32 v136, v136
	v_rcp_f32_e32 v137, v137
	v_rcp_f32_e32 v140, v140
	v_rcp_f32_e32 v142, v142
	v_rcp_f32_e32 v143, v143
	v_rcp_f32_e32 v141, v141
	v_pk_mul_f32 v[136:137], v[104:105], v[136:137]
; __device__ __forceinline__ u32x4 pack8(f32x4 a, f32x4 b) { u32x4 w; w.x = cvt_pk_bf16(a[0], a[1]); w.y = cvt_pk_bf16(a[2], a[3]); w.z = cvt_pk_bf16(b[0], b[1]); w.w = cvt_pk_bf16(b[2], b[3]); return w; }
; __device__ __forceinline__ f32x4 sig4(f32x4 v) { f32x4 r; r[0] = sigmoidf_(v[0]); r[1] = sigmoidf_(v[1]); r[2] = sigmoidf_(v[2]); r[3] = sigmoidf_(v[3]); return r; }
;     __device__ __forceinline__ void operator()(AccRef acc, const pg8::Unit& u, int wr, int wc, int fr, int fq) const {
;     ...
;                 for (int m = 0; m < 4; ++m) { const int r = row0 + ai * 128 + m * 16;
; #pragma unroll
;                     for (int bj = 0; bj < 2; ++bj) { const f32x4 v0 = acc[ai][bj][m][0], v1 = acc[ai][bj][m][1];
;                         *(u32x4*)(srg + (size_t)r * 2048 + c0 + bj * 128) = pack8(v0 * sig4(v0), v1 * sig4(v1)); } }
	v_pk_mul_f32 v[134:135], v[102:103], v[134:135]
	v_pk_mul_f32 v[142:143], v[100:101], v[142:143]
	v_pk_mul_f32 v[140:141], v[98:99], v[140:141]
	v_cvt_pk_bf16_f32 v134, v134, v135
	v_cvt_pk_bf16_f32 v135, v136, v137
	v_cvt_pk_bf16_f32 v136, v140, v141
	v_cvt_pk_bf16_f32 v137, v142, v143
	global_store_dwordx4 v[138:139], v[134:137], off offset:256
	v_mul_f32_e32 v140, 0xbfb8aa3b, v90
	v_mul_f32_e32 v141, 0xbfb8aa3b, v91
	v_mul_f32_e32 v134, 0xbfb8aa3b, v94
	v_exp_f32_e32 v136, v134
	v_or_b32_e32 v134, 32, v220
	v_ashrrev_i32_e32 v135, 31, v134
	v_lshlrev_b64 v[138:139], 12, v[134:135]
	v_add_f32_e32 v134, 1.0, v136
	v_mul_f32_e32 v135, 0xbfb8aa3b, v95
	v_mul_f32_e32 v136, 0xbfb8aa3b, v96
	v_mul_f32_e32 v137, 0xbfb8aa3b, v97
	v_exp_f32_e32 v135, v135
	v_exp_f32_e32 v136, v136
	v_exp_f32_e32 v137, v137
	v_exp_f32_e32 v140, v140
	v_exp_f32_e32 v141, v141
	v_mul_f32_e32 v142, 0xbfb8aa3b, v92
	v_mul_f32_e32 v143, 0xbfb8aa3b, v93
	v_add_f32_e32 v135, 1.0, v135
	v_add_f32_e32 v136, 1.0, v136
	v_add_f32_e32 v137, 1.0, v137
	v_add_f32_e32 v140, 1.0, v140
	v_exp_f32_e32 v142, v142
	v_exp_f32_e32 v143, v143
	v_add_f32_e32 v141, 1.0, v141
	v_rcp_f32_e32 v134, v134
	v_rcp_f32_e32 v135, v135
	v_rcp_f32_e32 v136, v136
	v_rcp_f32_e32 v137, v137
	v_rcp_f32_e32 v140, v140
	v_rcp_f32_e32 v141, v141
	v_add_f32_e32 v142, 1.0, v142
	v_add_f32_e32 v143, 1.0, v143
	v_rcp_f32_e32 v142, v142
	v_rcp_f32_e32 v143, v143
	v_pk_mul_f32 v[136:137], v[96:97], v[136:137]
	v_pk_mul_f32 v[134:135], v[94:95], v[134:135]
	v_pk_mul_f32 v[140:141], v[90:91], v[140:141]
	v_cvt_pk_bf16_f32 v134, v134, v135
	v_cvt_pk_bf16_f32 v135, v136, v137
	v_cvt_pk_bf16_f32 v136, v140, v141
	v_mul_f32_e32 v140, 0xbfb8aa3b, v86
	v_exp_f32_e32 v140, v140
	v_pk_mul_f32 v[142:143], v[92:93], v[142:143]
	v_lshl_add_u64 v[138:139], s[14:15], 0, v[138:139]
	v_cvt_pk_bf16_f32 v137, v142, v143
	v_lshl_add_u64 v[138:139], v[138:139], 0, v[132:133]
	global_store_dwordx4 v[138:139], v[134:137], off
	v_mul_f32_e32 v141, 0xbfb8aa3b, v83
	v_mul_f32_e32 v142, 0xbfb8aa3b, v84
	v_add_f32_e32 v134, 1.0, v140
	v_mul_f32_e32 v135, 0xbfb8aa3b, v87
	v_mul_f32_e32 v136, 0xbfb8aa3b, v88
	v_mul_f32_e32 v137, 0xbfb8aa3b, v89
	v_mul_f32_e32 v140, 0xbfb8aa3b, v82
	v_mul_f32_e32 v143, 0xbfb8aa3b, v85
	v_exp_f32_e32 v135, v135
	v_exp_f32_e32 v136, v136
	v_exp_f32_e32 v137, v137
	v_exp_f32_e32 v140, v140
	v_exp_f32_e32 v141, v141
	v_exp_f32_e32 v142, v142
	v_exp_f32_e32 v143, v143
	v_add_f32_e32 v135, 1.0, v135
	v_add_f32_e32 v136, 1.0, v136
	v_add_f32_e32 v137, 1.0, v137
	v_add_f32_e32 v140, 1.0, v140
	v_add_f32_e32 v141, 1.0, v141
	v_add_f32_e32 v142, 1.0, v142
	v_add_f32_e32 v143, 1.0, v143
	v_rcp_f32_e32 v134, v134
	v_rcp_f32_e32 v135, v135
	v_rcp_f32_e32 v136, v136
	v_rcp_f32_e32 v137, v137
	v_rcp_f32_e32 v140, v140
	v_rcp_f32_e32 v142, v142
	v_rcp_f32_e32 v143, v143
	v_rcp_f32_e32 v141, v141
	v_pk_mul_f32 v[136:137], v[88:89], v[136:137]
	v_pk_mul_f32 v[134:135], v[86:87], v[134:135]
	v_pk_mul_f32 v[142:143], v[84:85], v[142:143]
	v_pk_mul_f32 v[140:141], v[82:83], v[140:141]
	v_cvt_pk_bf16_f32 v134, v134, v135
	v_cvt_pk_bf16_f32 v135, v136, v137
	v_cvt_pk_bf16_f32 v136, v140, v141
	v_cvt_pk_bf16_f32 v137, v142, v143
	global_store_dwordx4 v[138:139], v[134:137], off offset:256
	v_mul_f32_e32 v140, 0xbfb8aa3b, v74
	v_mul_f32_e32 v141, 0xbfb8aa3b, v75
	v_mul_f32_e32 v134, 0xbfb8aa3b, v78
	v_exp_f32_e32 v136, v134
	v_or_b32_e32 v134, 48, v220
	v_ashrrev_i32_e32 v135, 31, v134
	v_lshlrev_b64 v[138:139], 12, v[134:135]
	v_add_f32_e32 v134, 1.0, v136
	v_mul_f32_e32 v135, 0xbfb8aa3b, v79
	v_mul_f32_e32 v136, 0xbfb8aa3b, v80
	v_mul_f32_e32 v137, 0xbfb8aa3b, v81
	v_exp_f32_e32 v135, v135
	v_exp_f32_e32 v136, v136
	v_exp_f32_e32 v137, v137
	v_exp_f32_e32 v140, v140
	v_exp_f32_e32 v141, v141
	v_mul_f32_e32 v142, 0xbfb8aa3b, v76
	v_mul_f32_e32 v143, 0xbfb8aa3b, v77
	v_exp_f32_e32 v142, v142
	v_exp_f32_e32 v143, v143
	v_add_f32_e32 v135, 1.0, v135
	v_add_f32_e32 v136, 1.0, v136
	v_add_f32_e32 v137, 1.0, v137
	v_add_f32_e32 v140, 1.0, v140
	v_add_f32_e32 v141, 1.0, v141
	v_rcp_f32_e32 v134, v134
	v_rcp_f32_e32 v135, v135
	v_rcp_f32_e32 v136, v136
	v_rcp_f32_e32 v137, v137
	v_rcp_f32_e32 v140, v140
	v_rcp_f32_e32 v141, v141
	v_add_f32_e32 v142, 1.0, v142
	v_add_f32_e32 v143, 1.0, v143
	v_rcp_f32_e32 v142, v142
	v_rcp_f32_e32 v143, v143
	v_pk_mul_f32 v[136:137], v[80:81], v[136:137]
	v_pk_mul_f32 v[134:135], v[78:79], v[134:135]
	v_pk_mul_f32 v[140:141], v[74:75], v[140:141]
	v_cvt_pk_bf16_f32 v134, v134, v135
	v_cvt_pk_bf16_f32 v135, v136, v137
	v_cvt_pk_bf16_f32 v136, v140, v141
	v_mul_f32_e32 v140, 0xbfb8aa3b, v70
	v_exp_f32_e32 v140, v140
	v_pk_mul_f32 v[142:143], v[76:77], v[142:143]
	v_lshl_add_u64 v[138:139], s[14:15], 0, v[138:139]
	v_cvt_pk_bf16_f32 v137, v142, v143
	v_lshl_add_u64 v[138:139], v[138:139], 0, v[132:133]
	global_store_dwordx4 v[138:139], v[134:137], off
	v_mul_f32_e32 v133, 0xbfb8aa3b, v71
	v_add_f32_e32 v132, 1.0, v140
	v_mul_f32_e32 v134, 0xbfb8aa3b, v72
	v_mul_f32_e32 v135, 0xbfb8aa3b, v73
	v_exp_f32_e32 v133, v133
	v_exp_f32_e32 v134, v134
	v_exp_f32_e32 v135, v135
	v_mul_f32_e32 v136, 0xbfb8aa3b, v66
	v_mul_f32_e32 v137, 0xbfb8aa3b, v67
	v_mul_f32_e32 v140, 0xbfb8aa3b, v68
	v_mul_f32_e32 v141, 0xbfb8aa3b, v69
	v_exp_f32_e32 v136, v136
	v_exp_f32_e32 v137, v137
	v_exp_f32_e32 v140, v140
	v_exp_f32_e32 v141, v141
	v_add_f32_e32 v133, 1.0, v133
	v_add_f32_e32 v134, 1.0, v134
	v_add_f32_e32 v135, 1.0, v135
	v_rcp_f32_e32 v132, v132
	v_rcp_f32_e32 v133, v133
	v_rcp_f32_e32 v134, v134
	v_rcp_f32_e32 v135, v135
	v_add_f32_e32 v136, 1.0, v136
	v_add_f32_e32 v137, 1.0, v137
	v_add_f32_e32 v140, 1.0, v140
; __device__ __forceinline__ u32x4 pack8(f32x4 a, f32x4 b) { u32x4 w; w.x = cvt_pk_bf16(a[0], a[1]); w.y = cvt_pk_bf16(a[2], a[3]); w.z = cvt_pk_bf16(b[0], b[1]); w.w = cvt_pk_bf16(b[2], b[3]); return w; }
; __device__ __forceinline__ f32x4 sig4(f32x4 v) { f32x4 r; r[0] = sigmoidf_(v[0]); r[1] = sigmoidf_(v[1]); r[2] = sigmoidf_(v[2]); r[3] = sigmoidf_(v[3]); return r; }
;     __device__ __forceinline__ void operator()(AccRef acc, const pg8::Unit& u, int wr, int wc, int fr, int fq) const {
;     ...
;                 for (int m = 0; m < 4; ++m) { const int r = row0 + ai * 128 + m * 16;
; #pragma unroll
;                     for (int bj = 0; bj < 2; ++bj) { const f32x4 v0 = acc[ai][bj][m][0], v1 = acc[ai][bj][m][1];
;                         *(u32x4*)(srg + (size_t)r * 2048 + c0 + bj * 128) = pack8(v0 * sig4(v0), v1 * sig4(v1)); } }
	v_add_f32_e32 v141, 1.0, v141
	v_rcp_f32_e32 v136, v136
	v_rcp_f32_e32 v140, v140
	v_rcp_f32_e32 v141, v141
	v_rcp_f32_e32 v137, v137
	v_pk_mul_f32 v[134:135], v[72:73], v[134:135]
	v_pk_mul_f32 v[132:133], v[70:71], v[132:133]
	v_pk_mul_f32 v[140:141], v[68:69], v[140:141]
	v_pk_mul_f32 v[136:137], v[66:67], v[136:137]
	v_cvt_pk_bf16_f32 v132, v132, v133
	v_cvt_pk_bf16_f32 v133, v134, v135
	v_mul_f32_e32 v134, 0xbfb8aa3b, v62
	v_exp_f32_e32 v142, v134
	v_cvt_pk_bf16_f32 v134, v136, v137
	v_cvt_pk_bf16_f32 v135, v140, v141
	global_store_dwordx4 v[138:139], v[132:135], off offset:256
	v_mul_f32_e32 v138, 0xbfb8aa3b, v60
	v_mul_f32_e32 v139, 0xbfb8aa3b, v61
	v_mul_f32_e32 v133, 0xbfb8aa3b, v63
	v_mul_f32_e32 v134, 0xbfb8aa3b, v64
	v_mul_f32_e32 v135, 0xbfb8aa3b, v65
	v_exp_f32_e32 v133, v133
	v_exp_f32_e32 v134, v134
	v_exp_f32_e32 v135, v135
	v_exp_f32_e32 v138, v138
	v_exp_f32_e32 v139, v139
	v_mul_f32_e32 v136, 0xbfb8aa3b, v58
	v_mul_f32_e32 v137, 0xbfb8aa3b, v59
	v_exp_f32_e32 v136, v136
	v_exp_f32_e32 v137, v137
	v_add_f32_e32 v132, 1.0, v142
	v_add_f32_e32 v133, 1.0, v133
	v_add_f32_e32 v134, 1.0, v134
	v_add_f32_e32 v135, 1.0, v135
	v_add_f32_e32 v138, 1.0, v138
	v_add_f32_e32 v139, 1.0, v139
	v_rcp_f32_e32 v132, v132
	v_rcp_f32_e32 v133, v133
	v_rcp_f32_e32 v134, v134
	v_rcp_f32_e32 v135, v135
	v_rcp_f32_e32 v138, v138
	v_rcp_f32_e32 v139, v139
	v_add_f32_e32 v136, 1.0, v136
	v_add_f32_e32 v137, 1.0, v137
	v_rcp_f32_e32 v136, v136
	v_rcp_f32_e32 v137, v137
	v_pk_mul_f32 v[134:135], v[64:65], v[134:135]
	v_pk_mul_f32 v[132:133], v[62:63], v[132:133]
	v_pk_mul_f32 v[138:139], v[60:61], v[138:139]
	v_cvt_pk_bf16_f32 v132, v132, v133
	v_cvt_pk_bf16_f32 v133, v134, v135
	v_cvt_pk_bf16_f32 v135, v138, v139
	v_mul_f32_e32 v138, 0xbfb8aa3b, v54
	v_exp_f32_e32 v140, v138
	v_pk_mul_f32 v[136:137], v[58:59], v[136:137]
	v_add_co_u32_e32 v138, vcc, s87, v130
	v_cvt_pk_bf16_f32 v134, v136, v137
	s_nop 0
	v_addc_co_u32_e32 v139, vcc, 0, v131, vcc
	global_store_dwordx4 v[138:139], v[132:135], off
	v_mul_f32_e32 v138, 0xbfb8aa3b, v50
	v_mul_f32_e32 v139, 0xbfb8aa3b, v51
	v_mul_f32_e32 v133, 0xbfb8aa3b, v55
	v_mul_f32_e32 v134, 0xbfb8aa3b, v56
	v_mul_f32_e32 v135, 0xbfb8aa3b, v57
	v_add_f32_e32 v132, 1.0, v140
	v_exp_f32_e32 v133, v133
	v_exp_f32_e32 v134, v134
	v_exp_f32_e32 v135, v135
	v_mul_f32_e32 v140, 0xbfb8aa3b, v52
	v_mul_f32_e32 v141, 0xbfb8aa3b, v53
	v_exp_f32_e32 v138, v138
	v_exp_f32_e32 v139, v139
	v_exp_f32_e32 v140, v140
	v_exp_f32_e32 v141, v141
	v_add_f32_e32 v133, 1.0, v133
	v_add_f32_e32 v134, 1.0, v134
	v_add_f32_e32 v135, 1.0, v135
	v_rcp_f32_e32 v132, v132
	v_rcp_f32_e32 v133, v133
	v_rcp_f32_e32 v134, v134
	v_rcp_f32_e32 v135, v135
	v_add_f32_e32 v138, 1.0, v138
	v_add_f32_e32 v139, 1.0, v139
	v_add_f32_e32 v140, 1.0, v140
	v_add_f32_e32 v141, 1.0, v141
	v_rcp_f32_e32 v138, v138
	v_rcp_f32_e32 v140, v140
	v_rcp_f32_e32 v141, v141
	v_rcp_f32_e32 v139, v139
	v_pk_mul_f32 v[134:135], v[56:57], v[134:135]
	v_pk_mul_f32 v[132:133], v[54:55], v[132:133]
	s_mov_b64 s[60:61], 0x80000
	v_pk_mul_f32 v[140:141], v[52:53], v[140:141]
	v_pk_mul_f32 v[138:139], v[50:51], v[138:139]
	v_cvt_pk_bf16_f32 v132, v132, v133
	v_cvt_pk_bf16_f32 v133, v134, v135
	v_mul_f32_e32 v134, 0xbfb8aa3b, v46
	v_lshl_add_u64 v[136:137], v[130:131], 0, s[60:61]
	v_exp_f32_e32 v142, v134
	v_cvt_pk_bf16_f32 v134, v138, v139
	v_cvt_pk_bf16_f32 v135, v140, v141
	global_store_dwordx4 v[136:137], v[132:135], off offset:256
	v_mul_f32_e32 v138, 0xbfb8aa3b, v44
	v_mul_f32_e32 v139, 0xbfb8aa3b, v45
	v_mul_f32_e32 v133, 0xbfb8aa3b, v47
	v_mul_f32_e32 v134, 0xbfb8aa3b, v48
	v_mul_f32_e32 v135, 0xbfb8aa3b, v49
	v_exp_f32_e32 v133, v133
	v_exp_f32_e32 v134, v134
	v_exp_f32_e32 v135, v135
	v_exp_f32_e32 v138, v138
	v_exp_f32_e32 v139, v139
	v_mul_f32_e32 v136, 0xbfb8aa3b, v42
	v_mul_f32_e32 v137, 0xbfb8aa3b, v43
	v_exp_f32_e32 v136, v136
	v_exp_f32_e32 v137, v137
	v_add_f32_e32 v132, 1.0, v142
	v_add_f32_e32 v133, 1.0, v133
	v_add_f32_e32 v134, 1.0, v134
	v_add_f32_e32 v135, 1.0, v135
	v_add_f32_e32 v138, 1.0, v138
	v_add_f32_e32 v139, 1.0, v139
	v_rcp_f32_e32 v132, v132
	v_rcp_f32_e32 v133, v133
	v_rcp_f32_e32 v134, v134
	v_rcp_f32_e32 v135, v135
	v_rcp_f32_e32 v138, v138
	v_rcp_f32_e32 v139, v139
	v_add_f32_e32 v136, 1.0, v136
	v_add_f32_e32 v137, 1.0, v137
	v_rcp_f32_e32 v136, v136
	v_rcp_f32_e32 v137, v137
	v_pk_mul_f32 v[134:135], v[48:49], v[134:135]
	v_pk_mul_f32 v[132:133], v[46:47], v[132:133]
	v_pk_mul_f32 v[138:139], v[44:45], v[138:139]
	v_cvt_pk_bf16_f32 v132, v132, v133
	v_cvt_pk_bf16_f32 v133, v134, v135
	v_cvt_pk_bf16_f32 v135, v138, v139
	v_mul_f32_e32 v138, 0xbfb8aa3b, v38
	v_exp_f32_e32 v140, v138
	v_pk_mul_f32 v[136:137], v[42:43], v[136:137]
	v_add_co_u32_e32 v138, vcc, s88, v130
	v_cvt_pk_bf16_f32 v134, v136, v137
	s_nop 0
	v_addc_co_u32_e32 v139, vcc, 0, v131, vcc
	global_store_dwordx4 v[138:139], v[132:135], off
	v_mul_f32_e32 v138, 0xbfb8aa3b, v34
	v_mul_f32_e32 v139, 0xbfb8aa3b, v35
	v_mul_f32_e32 v133, 0xbfb8aa3b, v39
	v_mul_f32_e32 v134, 0xbfb8aa3b, v40
	v_mul_f32_e32 v135, 0xbfb8aa3b, v41
	v_add_f32_e32 v132, 1.0, v140
	v_exp_f32_e32 v133, v133
	v_exp_f32_e32 v134, v134
	v_exp_f32_e32 v135, v135
	v_mul_f32_e32 v140, 0xbfb8aa3b, v36
	v_mul_f32_e32 v141, 0xbfb8aa3b, v37
	v_exp_f32_e32 v138, v138
	v_exp_f32_e32 v139, v139
	v_exp_f32_e32 v140, v140
	v_exp_f32_e32 v141, v141
	v_add_f32_e32 v133, 1.0, v133
	v_add_f32_e32 v134, 1.0, v134
	v_add_f32_e32 v135, 1.0, v135
	v_rcp_f32_e32 v132, v132
	v_rcp_f32_e32 v133, v133
	v_rcp_f32_e32 v134, v134
	v_rcp_f32_e32 v135, v135
	v_add_f32_e32 v138, 1.0, v138
	v_add_f32_e32 v139, 1.0, v139
	v_add_f32_e32 v140, 1.0, v140
; __device__ __forceinline__ u32x4 pack8(f32x4 a, f32x4 b) { u32x4 w; w.x = cvt_pk_bf16(a[0], a[1]); w.y = cvt_pk_bf16(a[2], a[3]); w.z = cvt_pk_bf16(b[0], b[1]); w.w = cvt_pk_bf16(b[2], b[3]); return w; }
; __device__ __forceinline__ f32x4 sig4(f32x4 v) { f32x4 r; r[0] = sigmoidf_(v[0]); r[1] = sigmoidf_(v[1]); r[2] = sigmoidf_(v[2]); r[3] = sigmoidf_(v[3]); return r; }
;     __device__ __forceinline__ void operator()(AccRef acc, const pg8::Unit& u, int wr, int wc, int fr, int fq) const {
;     ...
;                 for (int m = 0; m < 4; ++m) { const int r = row0 + ai * 128 + m * 16;
; #pragma unroll
;                     for (int bj = 0; bj < 2; ++bj) { const f32x4 v0 = acc[ai][bj][m][0], v1 = acc[ai][bj][m][1];
;                         *(u32x4*)(srg + (size_t)r * 2048 + c0 + bj * 128) = pack8(v0 * sig4(v0), v1 * sig4(v1)); } }
	v_add_f32_e32 v141, 1.0, v141
	v_rcp_f32_e32 v138, v138
	v_rcp_f32_e32 v140, v140
	v_rcp_f32_e32 v141, v141
	v_rcp_f32_e32 v139, v139
	v_pk_mul_f32 v[134:135], v[40:41], v[134:135]
	v_pk_mul_f32 v[132:133], v[38:39], v[132:133]
	v_pk_mul_f32 v[140:141], v[36:37], v[140:141]
	v_pk_mul_f32 v[138:139], v[34:35], v[138:139]
	v_cvt_pk_bf16_f32 v132, v132, v133
	v_cvt_pk_bf16_f32 v133, v134, v135
	v_mul_f32_e32 v134, 0xbfb8aa3b, v30
	v_lshl_add_u64 v[136:137], v[130:131], 0, s[44:45]
	v_exp_f32_e32 v142, v134
	v_cvt_pk_bf16_f32 v134, v138, v139
	v_cvt_pk_bf16_f32 v135, v140, v141
	global_store_dwordx4 v[136:137], v[132:135], off offset:256
	v_mul_f32_e32 v138, 0xbfb8aa3b, v28
	v_mul_f32_e32 v139, 0xbfb8aa3b, v29
	v_mul_f32_e32 v133, 0xbfb8aa3b, v31
	v_mul_f32_e32 v134, 0xbfb8aa3b, v32
	v_mul_f32_e32 v135, 0xbfb8aa3b, v33
	v_exp_f32_e32 v133, v133
	v_exp_f32_e32 v134, v134
	v_exp_f32_e32 v135, v135
	v_exp_f32_e32 v138, v138
	v_exp_f32_e32 v139, v139
	v_mul_f32_e32 v136, 0xbfb8aa3b, v26
	v_mul_f32_e32 v137, 0xbfb8aa3b, v27
	v_exp_f32_e32 v136, v136
	v_exp_f32_e32 v137, v137
	v_add_f32_e32 v132, 1.0, v142
	v_add_f32_e32 v133, 1.0, v133
	v_add_f32_e32 v134, 1.0, v134
	v_add_f32_e32 v135, 1.0, v135
	v_add_f32_e32 v138, 1.0, v138
	v_add_f32_e32 v139, 1.0, v139
	v_rcp_f32_e32 v132, v132
	v_rcp_f32_e32 v133, v133
	v_rcp_f32_e32 v134, v134
	v_rcp_f32_e32 v135, v135
	v_rcp_f32_e32 v138, v138
	v_rcp_f32_e32 v139, v139
	v_add_f32_e32 v136, 1.0, v136
	v_add_f32_e32 v137, 1.0, v137
	v_rcp_f32_e32 v136, v136
	v_rcp_f32_e32 v137, v137
	v_pk_mul_f32 v[134:135], v[32:33], v[134:135]
	v_pk_mul_f32 v[132:133], v[30:31], v[132:133]
	v_pk_mul_f32 v[138:139], v[28:29], v[138:139]
	v_cvt_pk_bf16_f32 v132, v132, v133
	v_cvt_pk_bf16_f32 v133, v134, v135
	v_cvt_pk_bf16_f32 v135, v138, v139
	v_mul_f32_e32 v138, 0xbfb8aa3b, v22
	v_exp_f32_e32 v140, v138
	v_pk_mul_f32 v[136:137], v[26:27], v[136:137]
	v_add_co_u32_e32 v138, vcc, s89, v130
	v_cvt_pk_bf16_f32 v134, v136, v137
	s_nop 0
	v_addc_co_u32_e32 v139, vcc, 0, v131, vcc
	global_store_dwordx4 v[138:139], v[132:135], off
	v_mul_f32_e32 v138, 0xbfb8aa3b, v18
	v_mul_f32_e32 v139, 0xbfb8aa3b, v19
	v_mul_f32_e32 v133, 0xbfb8aa3b, v23
	v_mul_f32_e32 v134, 0xbfb8aa3b, v24
	v_mul_f32_e32 v135, 0xbfb8aa3b, v25
	v_add_f32_e32 v132, 1.0, v140
	v_exp_f32_e32 v133, v133
	v_exp_f32_e32 v134, v134
	v_exp_f32_e32 v135, v135
	v_mul_f32_e32 v140, 0xbfb8aa3b, v20
	v_mul_f32_e32 v141, 0xbfb8aa3b, v21
	v_exp_f32_e32 v138, v138
	v_exp_f32_e32 v139, v139
	v_exp_f32_e32 v140, v140
	v_exp_f32_e32 v141, v141
	v_add_f32_e32 v133, 1.0, v133
	v_add_f32_e32 v134, 1.0, v134
	v_add_f32_e32 v135, 1.0, v135
	v_rcp_f32_e32 v132, v132
	v_rcp_f32_e32 v133, v133
	v_rcp_f32_e32 v134, v134
	v_rcp_f32_e32 v135, v135
	v_add_f32_e32 v138, 1.0, v138
	v_add_f32_e32 v139, 1.0, v139
	v_add_f32_e32 v140, 1.0, v140
	v_add_f32_e32 v141, 1.0, v141
	v_rcp_f32_e32 v138, v138
	v_rcp_f32_e32 v140, v140
	v_rcp_f32_e32 v141, v141
	v_rcp_f32_e32 v139, v139
	v_pk_mul_f32 v[134:135], v[24:25], v[134:135]
	v_pk_mul_f32 v[132:133], v[22:23], v[132:133]
	v_pk_mul_f32 v[140:141], v[20:21], v[140:141]
	v_pk_mul_f32 v[138:139], v[18:19], v[138:139]
	v_cvt_pk_bf16_f32 v132, v132, v133
	v_cvt_pk_bf16_f32 v133, v134, v135
	v_mul_f32_e32 v134, 0xbfb8aa3b, v14
	v_lshl_add_u64 v[136:137], v[130:131], 0, s[46:47]
	v_exp_f32_e32 v142, v134
	v_cvt_pk_bf16_f32 v134, v138, v139
	v_cvt_pk_bf16_f32 v135, v140, v141
	global_store_dwordx4 v[136:137], v[132:135], off offset:256
	v_mul_f32_e32 v138, 0xbfb8aa3b, v12
	v_mul_f32_e32 v139, 0xbfb8aa3b, v13
	v_mul_f32_e32 v133, 0xbfb8aa3b, v15
	v_mul_f32_e32 v134, 0xbfb8aa3b, v16
	v_mul_f32_e32 v135, 0xbfb8aa3b, v17
	v_exp_f32_e32 v133, v133
	v_exp_f32_e32 v134, v134
	v_exp_f32_e32 v135, v135
	v_exp_f32_e32 v138, v138
	v_exp_f32_e32 v139, v139
	v_mul_f32_e32 v136, 0xbfb8aa3b, v10
	v_mul_f32_e32 v137, 0xbfb8aa3b, v11
	v_exp_f32_e32 v136, v136
	v_exp_f32_e32 v137, v137
	v_add_f32_e32 v132, 1.0, v142
	v_add_f32_e32 v133, 1.0, v133
	v_add_f32_e32 v134, 1.0, v134
	v_add_f32_e32 v135, 1.0, v135
	v_add_f32_e32 v138, 1.0, v138
	v_add_f32_e32 v139, 1.0, v139
	v_rcp_f32_e32 v132, v132
	v_rcp_f32_e32 v133, v133
	v_rcp_f32_e32 v134, v134
	v_rcp_f32_e32 v135, v135
	v_rcp_f32_e32 v138, v138
	v_rcp_f32_e32 v139, v139
	v_add_f32_e32 v136, 1.0, v136
	v_add_f32_e32 v137, 1.0, v137
	v_rcp_f32_e32 v136, v136
	v_rcp_f32_e32 v137, v137
	v_pk_mul_f32 v[134:135], v[16:17], v[134:135]
	v_pk_mul_f32 v[132:133], v[14:15], v[132:133]
	v_pk_mul_f32 v[138:139], v[12:13], v[138:139]
	v_cvt_pk_bf16_f32 v132, v132, v133
	v_cvt_pk_bf16_f32 v133, v134, v135
	v_cvt_pk_bf16_f32 v135, v138, v139
	v_mul_f32_e32 v138, 0xbfb8aa3b, v6
	v_exp_f32_e32 v138, v138
	v_pk_mul_f32 v[136:137], v[10:11], v[136:137]
	v_mul_f32_e32 v139, 0xbfb8aa3b, v5
	v_cvt_pk_bf16_f32 v134, v136, v137
	v_lshl_add_u64 v[136:137], v[130:131], 0, s[48:49]
	v_add_co_u32_e32 v130, vcc, s90, v130
	v_exp_f32_e32 v139, v139
	s_nop 0
	v_addc_co_u32_e32 v131, vcc, 0, v131, vcc
	global_store_dwordx4 v[130:131], v[132:135], off
	v_add_f32_e32 v130, 1.0, v138
	v_mul_f32_e32 v131, 0xbfb8aa3b, v7
	v_mul_f32_e32 v132, 0xbfb8aa3b, v8
	v_mul_f32_e32 v133, 0xbfb8aa3b, v9
	v_mul_f32_e32 v134, 0xbfb8aa3b, v2
	v_mul_f32_e32 v135, 0xbfb8aa3b, v3
	v_mul_f32_e32 v138, 0xbfb8aa3b, v4
	v_exp_f32_e32 v131, v131
	v_exp_f32_e32 v132, v132
	v_exp_f32_e32 v133, v133
	v_exp_f32_e32 v134, v134
	v_exp_f32_e32 v135, v135
	v_exp_f32_e32 v138, v138
	v_add_f32_e32 v131, 1.0, v131
	v_add_f32_e32 v132, 1.0, v132
	v_add_f32_e32 v133, 1.0, v133
	v_add_f32_e32 v134, 1.0, v134
	v_add_f32_e32 v135, 1.0, v135
	v_add_f32_e32 v138, 1.0, v138
	v_add_f32_e32 v139, 1.0, v139
	v_rcp_f32_e32 v130, v130
	v_rcp_f32_e32 v131, v131
	v_rcp_f32_e32 v132, v132
	v_rcp_f32_e32 v133, v133
	v_rcp_f32_e32 v134, v134
	v_rcp_f32_e32 v138, v138
	v_rcp_f32_e32 v139, v139
	v_rcp_f32_e32 v135, v135
	v_pk_mul_f32 v[132:133], v[8:9], v[132:133]
	v_pk_mul_f32 v[130:131], v[6:7], v[130:131]
	v_pk_mul_f32 v[138:139], v[4:5], v[138:139]
	v_pk_mul_f32 v[134:135], v[2:3], v[134:135]
	v_cvt_pk_bf16_f32 v130, v130, v131
	v_cvt_pk_bf16_f32 v131, v132, v133
	v_cvt_pk_bf16_f32 v132, v134, v135
	v_cvt_pk_bf16_f32 v133, v138, v139
	global_store_dwordx4 v[136:137], v[130:133], off offset:256

; __device__ __forceinline__ unsigned cvt_pk_bf16(float lo, float hi) { const f32x2_cv v = {lo, hi}; const bf16x2_cv b = __builtin_convertvector(v, bf16x2_cv); return __builtin_bit_cast(unsigned, b); }
; __device__ __forceinline__ unsigned dpp_xor1(unsigned v) { return (unsigned)__builtin_amdgcn_update_dpp(0, (int)v, 0xB1, 0xF, 0xF, true); }
; __device__ __forceinline__ unsigned dpp_xor2(unsigned v) { return (unsigned)__builtin_amdgcn_update_dpp(0, (int)v, 0x4E, 0xF, 0xF, true); }
; __device__ __forceinline__ void quad_transpose(unsigned& x0, unsigned& x1, unsigned& x2, unsigned& x3, int b) {
;     const bool o1 = (b & 1) != 0, o2 = (b & 2) != 0;
;     const unsigned r01 = dpp_xor1(o1 ? x0 : x1), r23 = dpp_xor1(o1 ? x2 : x3);
;     if (o1) { x0 = r01; x2 = r23; } else { x1 = r01; x3 = r23; }
;     const unsigned r02 = dpp_xor2(o2 ? x0 : x2), r13 = dpp_xor2(o2 ? x1 : x3);
;     if (o2) { x0 = r02; x1 = r13; } else { x2 = r02; x3 = r13; }
; }
; __device__ __forceinline__ void tr_store(bf16* p, int second, f32x4 v0, f32x4 v1, int b) {
;     unsigned x0 = cvt_pk_bf16(v0[0], v0[1]), x1 = cvt_pk_bf16(v0[2], v0[3]), x2 = cvt_pk_bf16(v1[0], v1[1]), x3 = cvt_pk_bf16(v1[2], v1[3]);
;     quad_transpose(x0, x1, x2, x3, b);
;     u32x2 lo, hi; lo.x = __builtin_amdgcn_perm(x1, x0, 0x05040100u); lo.y = __builtin_amdgcn_perm(x3, x2, 0x05040100u);
;     hi.x = __builtin_amdgcn_perm(x1, x0, 0x07060302u); hi.y = __builtin_amdgcn_perm(x3, x2, 0x07060302u);
;     *(u32x2*)p = lo; *(u32x2*)(p + second) = hi;
; }
;     __device__ __forceinline__ void operator()(AccRef acc, const pg8::Unit& u, int wr, int wc, int fr, int fq) const {
;     ...
;         } else if (pn < 24) {
;             const int h = pn - 16;
; #pragma unroll
;             for (int ai = 0; ai < 2; ++ai)
; #pragma unroll
;                 for (int m = 0; m < 4; ++m) {
;                     int r = row0 + ai * 128 + m * 16; asm volatile("" : "+v"(r)); const int pos = r & 4095;
;                     const int vq = cl + 2 * (fr & 3);
;                     bf16* tb = vT + ((size_t)(((r >> 12) * 8 + h) * 64 + (pos >> 6))) * 16384 + (size_t)((((vq >> 5) * 4 + m) * 64 + ((fr >> 3) & 1) * 32 + (vq & 31)) * 8 + (fr & 4));
;                     tr_store(tb, 8, acc[ai][0][m][0], acc[ai][0][m][1], fr & 3); tr_store(tb + 4 * 4 * 64 * 8, 8, acc[ai][1][m][0], acc[ai][1][m][1], fr & 3);
;                 }
.LBB0_222:
	s_andn2_b64 vcc, exec, s[60:61]
	s_cbranch_vccnz .LBB0_224
	v_mov_b32_e32 v130, v220
	v_cvt_pk_bf16_f32 v132, v126, v127
	v_cvt_pk_bf16_f32 v133, v128, v129
	v_cvt_pk_bf16_f32 v134, v122, v123
	v_cvt_pk_bf16_f32 v135, v124, v125
	v_cndmask_b32_e64 v136, v132, v133, s[4:5]
	v_ashrrev_i32_e32 v131, 9, v130
	v_cndmask_b32_e64 v137, v134, v135, s[4:5]
	s_add_i32 s11, s10, -16
	v_and_b32_e32 v131, 0x3fffff8, v131
	v_mov_b32_dpp v136, v136 quad_perm:[1,0,3,2] row_mask:0xf bank_mask:0xf bound_ctrl:1
	v_mov_b32_dpp v137, v137 quad_perm:[1,0,3,2] row_mask:0xf bank_mask:0xf bound_ctrl:1
	v_add_u32_e32 v131, s11, v131
	v_bfe_u32 v130, v130, 6, 6
	v_cndmask_b32_e64 v132, v136, v132, s[4:5]
	v_cndmask_b32_e64 v133, v133, v136, s[4:5]
	v_cndmask_b32_e64 v134, v137, v134, s[4:5]
	v_cndmask_b32_e64 v135, v135, v137, s[4:5]
	v_lshl_or_b32 v130, v131, 6, v130
	v_cndmask_b32_e64 v136, v132, v134, s[6:7]
	v_cndmask_b32_e64 v137, v133, v135, s[6:7]
	v_ashrrev_i32_e32 v131, 31, v130
	v_mov_b32_dpp v136, v136 quad_perm:[2,3,0,1] row_mask:0xf bank_mask:0xf bound_ctrl:1
	v_mov_b32_dpp v137, v137 quad_perm:[2,3,0,1] row_mask:0xf bank_mask:0xf bound_ctrl:1
	v_lshlrev_b64 v[130:131], 15, v[130:131]
	v_cndmask_b32_e64 v138, v136, v132, s[6:7]
	v_cndmask_b32_e64 v136, v134, v136, s[6:7]
	v_cndmask_b32_e64 v134, v137, v133, s[6:7]
	v_cndmask_b32_e64 v135, v135, v137, s[6:7]
	v_lshl_add_u64 v[130:131], v[204:205], 0, v[130:131]
	v_perm_b32 v132, v134, v138, s91
	v_perm_b32 v133, v135, v136, s91
	v_perm_b32 v134, v134, v138, s92
	v_perm_b32 v135, v135, v136, s92
	s_waitcnt vmcnt(0)
	global_store_dwordx2 v[130:131], v[132:133], off
	global_store_dwordx2 v[130:131], v[134:135], off offset:16
	v_cvt_pk_bf16_f32 v132, v118, v119
	v_cvt_pk_bf16_f32 v133, v120, v121
	v_cvt_pk_bf16_f32 v134, v114, v115
	v_cvt_pk_bf16_f32 v135, v116, v117
	v_cndmask_b32_e64 v136, v132, v133, s[4:5]
	v_cndmask_b32_e64 v137, v134, v135, s[4:5]
	v_add_co_u32_e32 v130, vcc, s80, v130
	v_mov_b32_dpp v136, v136 quad_perm:[1,0,3,2] row_mask:0xf bank_mask:0xf bound_ctrl:1
	v_mov_b32_dpp v137, v137 quad_perm:[1,0,3,2] row_mask:0xf bank_mask:0xf bound_ctrl:1
	v_cndmask_b32_e64 v132, v136, v132, s[4:5]
	v_cndmask_b32_e64 v133, v133, v136, s[4:5]
	v_cndmask_b32_e64 v134, v137, v134, s[4:5]
	v_cndmask_b32_e64 v135, v135, v137, s[4:5]
	v_cndmask_b32_e64 v136, v132, v134, s[6:7]
	v_cndmask_b32_e64 v137, v133, v135, s[6:7]
	v_addc_co_u32_e32 v131, vcc, 0, v131, vcc
	v_mov_b32_dpp v136, v136 quad_perm:[2,3,0,1] row_mask:0xf bank_mask:0xf bound_ctrl:1
	v_mov_b32_dpp v137, v137 quad_perm:[2,3,0,1] row_mask:0xf bank_mask:0xf bound_ctrl:1
	v_cndmask_b32_e64 v138, v136, v132, s[6:7]
	v_cndmask_b32_e64 v136, v134, v136, s[6:7]
	v_cndmask_b32_e64 v134, v137, v133, s[6:7]
	v_cndmask_b32_e64 v135, v135, v137, s[6:7]
	v_perm_b32 v132, v134, v138, s91
	v_perm_b32 v133, v135, v136, s91
	v_perm_b32 v134, v134, v138, s92
	v_perm_b32 v135, v135, v136, s92
	global_store_dwordx2 v[130:131], v[132:133], off
	global_store_dwordx2 v[130:131], v[134:135], off offset:16
	v_or_b32_e32 v130, 16, v220
	v_cvt_pk_bf16_f32 v132, v110, v111
	v_cvt_pk_bf16_f32 v133, v112, v113
	v_cvt_pk_bf16_f32 v134, v106, v107
	v_cvt_pk_bf16_f32 v135, v108, v109
	v_cndmask_b32_e64 v136, v132, v133, s[4:5]
	v_ashrrev_i32_e32 v131, 9, v130
	v_cndmask_b32_e64 v137, v134, v135, s[4:5]
	v_and_b32_e32 v131, 0x3fffff8, v131
	v_mov_b32_dpp v136, v136 quad_perm:[1,0,3,2] row_mask:0xf bank_mask:0xf bound_ctrl:1
	v_mov_b32_dpp v137, v137 quad_perm:[1,0,3,2] row_mask:0xf bank_mask:0xf bound_ctrl:1
	v_add_u32_e32 v131, s11, v131
	v_bfe_u32 v130, v130, 6, 6
	v_cndmask_b32_e64 v132, v136, v132, s[4:5]
	v_cndmask_b32_e64 v133, v133, v136, s[4:5]
	v_cndmask_b32_e64 v134, v137, v134, s[4:5]
	v_cndmask_b32_e64 v135, v135, v137, s[4:5]
	v_lshl_or_b32 v130, v131, 6, v130
	v_cndmask_b32_e64 v136, v132, v134, s[6:7]
	v_cndmask_b32_e64 v137, v133, v135, s[6:7]
	v_ashrrev_i32_e32 v131, 31, v130
	v_mov_b32_dpp v136, v136 quad_perm:[2,3,0,1] row_mask:0xf bank_mask:0xf bound_ctrl:1
	v_mov_b32_dpp v137, v137 quad_perm:[2,3,0,1] row_mask:0xf bank_mask:0xf bound_ctrl:1
	v_lshlrev_b64 v[130:131], 15, v[130:131]
	v_cndmask_b32_e64 v138, v136, v132, s[6:7]
	v_cndmask_b32_e64 v136, v134, v136, s[6:7]
	v_cndmask_b32_e64 v134, v137, v133, s[6:7]
	v_cndmask_b32_e64 v135, v135, v137, s[6:7]
	v_lshl_add_u64 v[130:131], v[204:205], 0, v[130:131]
	v_perm_b32 v132, v134, v138, s91
	v_perm_b32 v133, v135, v136, s91
	v_perm_b32 v134, v134, v138, s92
	v_perm_b32 v135, v135, v136, s92
	global_store_dwordx2 v[130:131], v[132:133], off offset:1024
	global_store_dwordx2 v[130:131], v[134:135], off offset:1040
	v_cvt_pk_bf16_f32 v132, v102, v103
	v_cvt_pk_bf16_f32 v133, v104, v105
	v_cvt_pk_bf16_f32 v134, v98, v99
	v_cvt_pk_bf16_f32 v135, v100, v101
	v_cndmask_b32_e64 v136, v132, v133, s[4:5]
	v_cndmask_b32_e64 v137, v134, v135, s[4:5]
	v_add_co_u32_e32 v130, vcc, s80, v130
	v_mov_b32_dpp v136, v136 quad_perm:[1,0,3,2] row_mask:0xf bank_mask:0xf bound_ctrl:1
	v_mov_b32_dpp v137, v137 quad_perm:[1,0,3,2] row_mask:0xf bank_mask:0xf bound_ctrl:1
	v_cndmask_b32_e64 v132, v136, v132, s[4:5]
	v_cndmask_b32_e64 v133, v133, v136, s[4:5]
	v_cndmask_b32_e64 v134, v137, v134, s[4:5]
	v_cndmask_b32_e64 v135, v135, v137, s[4:5]
	v_cndmask_b32_e64 v136, v132, v134, s[6:7]
	v_cndmask_b32_e64 v137, v133, v135, s[6:7]
	v_addc_co_u32_e32 v131, vcc, 0, v131, vcc
	v_mov_b32_dpp v136, v136 quad_perm:[2,3,0,1] row_mask:0xf bank_mask:0xf bound_ctrl:1
	v_mov_b32_dpp v137, v137 quad_perm:[2,3,0,1] row_mask:0xf bank_mask:0xf bound_ctrl:1
	v_cndmask_b32_e64 v138, v136, v132, s[6:7]
	v_cndmask_b32_e64 v136, v134, v136, s[6:7]
;     __device__ __forceinline__ void operator()(AccRef acc, const pg8::Unit& u, int wr, int wc, int fr, int fq) const {
;     ...
;                 for (int m = 0; m < 4; ++m) {
;                     int r = row0 + ai * 128 + m * 16; asm volatile("" : "+v"(r)); const int pos = r & 4095;
;                     const int vq = cl + 2 * (fr & 3);
;                     bf16* tb = vT + ((size_t)(((r >> 12) * 8 + h) * 64 + (pos >> 6))) * 16384 + (size_t)((((vq >> 5) * 4 + m) * 64 + ((fr >> 3) & 1) * 32 + (vq & 31)) * 8 + (fr & 4));
;                     tr_store(tb, 8, acc[ai][0][m][0], acc[ai][0][m][1], fr & 3); tr_store(tb + 4 * 4 * 64 * 8, 8, acc[ai][1][m][0], acc[ai][1][m][1], fr & 3);
	v_cndmask_b32_e64 v134, v137, v133, s[6:7]
	v_cndmask_b32_e64 v135, v135, v137, s[6:7]
	v_perm_b32 v132, v134, v138, s91
	v_perm_b32 v133, v135, v136, s91
	v_perm_b32 v134, v134, v138, s92
	v_perm_b32 v135, v135, v136, s92
	global_store_dwordx2 v[130:131], v[132:133], off offset:1024
	global_store_dwordx2 v[130:131], v[134:135], off offset:1040
	v_or_b32_e32 v130, 32, v220
	v_cvt_pk_bf16_f32 v132, v94, v95
	v_cvt_pk_bf16_f32 v133, v96, v97
	v_cvt_pk_bf16_f32 v134, v90, v91
	v_cvt_pk_bf16_f32 v135, v92, v93
	v_cndmask_b32_e64 v136, v132, v133, s[4:5]
	v_ashrrev_i32_e32 v131, 9, v130
	v_cndmask_b32_e64 v137, v134, v135, s[4:5]
	v_and_b32_e32 v131, 0x3fffff8, v131
	v_mov_b32_dpp v136, v136 quad_perm:[1,0,3,2] row_mask:0xf bank_mask:0xf bound_ctrl:1
	v_mov_b32_dpp v137, v137 quad_perm:[1,0,3,2] row_mask:0xf bank_mask:0xf bound_ctrl:1
	v_add_u32_e32 v131, s11, v131
	v_bfe_u32 v130, v130, 6, 6
	v_cndmask_b32_e64 v132, v136, v132, s[4:5]
	v_cndmask_b32_e64 v133, v133, v136, s[4:5]
	v_cndmask_b32_e64 v134, v137, v134, s[4:5]
	v_cndmask_b32_e64 v135, v135, v137, s[4:5]
	v_lshl_or_b32 v130, v131, 6, v130
	v_cndmask_b32_e64 v136, v132, v134, s[6:7]
	v_cndmask_b32_e64 v137, v133, v135, s[6:7]
	v_ashrrev_i32_e32 v131, 31, v130
	v_mov_b32_dpp v136, v136 quad_perm:[2,3,0,1] row_mask:0xf bank_mask:0xf bound_ctrl:1
	v_mov_b32_dpp v137, v137 quad_perm:[2,3,0,1] row_mask:0xf bank_mask:0xf bound_ctrl:1
	v_lshlrev_b64 v[130:131], 15, v[130:131]
	v_cndmask_b32_e64 v138, v136, v132, s[6:7]
	v_cndmask_b32_e64 v136, v134, v136, s[6:7]
	v_cndmask_b32_e64 v134, v137, v133, s[6:7]
	v_cndmask_b32_e64 v135, v135, v137, s[6:7]
	v_lshl_add_u64 v[130:131], v[204:205], 0, v[130:131]
	v_perm_b32 v132, v134, v138, s91
	v_perm_b32 v133, v135, v136, s91
	v_perm_b32 v134, v134, v138, s92
	v_perm_b32 v135, v135, v136, s92
	global_store_dwordx2 v[130:131], v[132:133], off offset:2048
	global_store_dwordx2 v[130:131], v[134:135], off offset:2064
	v_cvt_pk_bf16_f32 v132, v86, v87
	v_cvt_pk_bf16_f32 v133, v88, v89
	v_cvt_pk_bf16_f32 v134, v82, v83
	v_cvt_pk_bf16_f32 v135, v84, v85
	v_cndmask_b32_e64 v136, v132, v133, s[4:5]
	v_cndmask_b32_e64 v137, v134, v135, s[4:5]
	v_add_co_u32_e32 v130, vcc, s80, v130
	v_mov_b32_dpp v136, v136 quad_perm:[1,0,3,2] row_mask:0xf bank_mask:0xf bound_ctrl:1
	v_mov_b32_dpp v137, v137 quad_perm:[1,0,3,2] row_mask:0xf bank_mask:0xf bound_ctrl:1
	v_cndmask_b32_e64 v132, v136, v132, s[4:5]
	v_cndmask_b32_e64 v133, v133, v136, s[4:5]
	v_cndmask_b32_e64 v134, v137, v134, s[4:5]
	v_cndmask_b32_e64 v135, v135, v137, s[4:5]
	v_cndmask_b32_e64 v136, v132, v134, s[6:7]
	v_cndmask_b32_e64 v137, v133, v135, s[6:7]
	v_addc_co_u32_e32 v131, vcc, 0, v131, vcc
	v_mov_b32_dpp v136, v136 quad_perm:[2,3,0,1] row_mask:0xf bank_mask:0xf bound_ctrl:1
	v_mov_b32_dpp v137, v137 quad_perm:[2,3,0,1] row_mask:0xf bank_mask:0xf bound_ctrl:1
	v_cndmask_b32_e64 v138, v136, v132, s[6:7]
	v_cndmask_b32_e64 v136, v134, v136, s[6:7]
	v_cndmask_b32_e64 v134, v137, v133, s[6:7]
	v_cndmask_b32_e64 v135, v135, v137, s[6:7]
	v_perm_b32 v132, v134, v138, s91
	v_perm_b32 v133, v135, v136, s91
	v_perm_b32 v134, v134, v138, s92
	v_perm_b32 v135, v135, v136, s92
	global_store_dwordx2 v[130:131], v[132:133], off offset:2048
	global_store_dwordx2 v[130:131], v[134:135], off offset:2064
	v_or_b32_e32 v130, 48, v220
	v_cvt_pk_bf16_f32 v132, v78, v79
	v_cvt_pk_bf16_f32 v133, v80, v81
	v_cvt_pk_bf16_f32 v134, v74, v75
	v_cvt_pk_bf16_f32 v135, v76, v77
	v_cndmask_b32_e64 v136, v132, v133, s[4:5]
	v_ashrrev_i32_e32 v131, 9, v130
	v_cndmask_b32_e64 v137, v134, v135, s[4:5]
	v_and_b32_e32 v131, 0x3fffff8, v131
	v_mov_b32_dpp v136, v136 quad_perm:[1,0,3,2] row_mask:0xf bank_mask:0xf bound_ctrl:1
	v_mov_b32_dpp v137, v137 quad_perm:[1,0,3,2] row_mask:0xf bank_mask:0xf bound_ctrl:1
	v_add_u32_e32 v131, s11, v131
	v_bfe_u32 v130, v130, 6, 6
	v_cndmask_b32_e64 v132, v136, v132, s[4:5]
	v_cndmask_b32_e64 v133, v133, v136, s[4:5]
	v_cndmask_b32_e64 v134, v137, v134, s[4:5]
	v_cndmask_b32_e64 v135, v135, v137, s[4:5]
	v_lshl_or_b32 v130, v131, 6, v130
	v_cndmask_b32_e64 v136, v132, v134, s[6:7]
	v_cndmask_b32_e64 v137, v133, v135, s[6:7]
	v_ashrrev_i32_e32 v131, 31, v130
	v_mov_b32_dpp v136, v136 quad_perm:[2,3,0,1] row_mask:0xf bank_mask:0xf bound_ctrl:1
	v_mov_b32_dpp v137, v137 quad_perm:[2,3,0,1] row_mask:0xf bank_mask:0xf bound_ctrl:1
	v_lshlrev_b64 v[130:131], 15, v[130:131]
	v_cndmask_b32_e64 v138, v136, v132, s[6:7]
	v_cndmask_b32_e64 v136, v134, v136, s[6:7]
	v_cndmask_b32_e64 v134, v137, v133, s[6:7]
	v_cndmask_b32_e64 v135, v135, v137, s[6:7]
	v_lshl_add_u64 v[130:131], v[204:205], 0, v[130:131]
	v_perm_b32 v132, v134, v138, s91
	v_perm_b32 v133, v135, v136, s91
	v_perm_b32 v134, v134, v138, s92
	v_perm_b32 v135, v135, v136, s92
	global_store_dwordx2 v[130:131], v[132:133], off offset:3072
	global_store_dwordx2 v[130:131], v[134:135], off offset:3088
	v_cvt_pk_bf16_f32 v132, v70, v71
	v_cvt_pk_bf16_f32 v133, v72, v73
	v_cvt_pk_bf16_f32 v134, v66, v67
	v_cvt_pk_bf16_f32 v135, v68, v69
	v_cndmask_b32_e64 v136, v132, v133, s[4:5]
	v_cndmask_b32_e64 v137, v134, v135, s[4:5]
	v_add_co_u32_e32 v130, vcc, s80, v130
	v_mov_b32_dpp v136, v136 quad_perm:[1,0,3,2] row_mask:0xf bank_mask:0xf bound_ctrl:1
	v_mov_b32_dpp v137, v137 quad_perm:[1,0,3,2] row_mask:0xf bank_mask:0xf bound_ctrl:1
	v_cndmask_b32_e64 v132, v136, v132, s[4:5]
	v_cndmask_b32_e64 v133, v133, v136, s[4:5]
	v_cndmask_b32_e64 v134, v137, v134, s[4:5]
	v_cndmask_b32_e64 v135, v135, v137, s[4:5]
	v_cndmask_b32_e64 v136, v132, v134, s[6:7]
	v_cndmask_b32_e64 v137, v133, v135, s[6:7]
	v_addc_co_u32_e32 v131, vcc, 0, v131, vcc
;     __device__ __forceinline__ void operator()(AccRef acc, const pg8::Unit& u, int wr, int wc, int fr, int fq) const {
;     ...
;                 for (int m = 0; m < 4; ++m) {
;                     int r = row0 + ai * 128 + m * 16; asm volatile("" : "+v"(r)); const int pos = r & 4095;
;                     const int vq = cl + 2 * (fr & 3);
;                     bf16* tb = vT + ((size_t)(((r >> 12) * 8 + h) * 64 + (pos >> 6))) * 16384 + (size_t)((((vq >> 5) * 4 + m) * 64 + ((fr >> 3) & 1) * 32 + (vq & 31)) * 8 + (fr & 4));
;                     tr_store(tb, 8, acc[ai][0][m][0], acc[ai][0][m][1], fr & 3); tr_store(tb + 4 * 4 * 64 * 8, 8, acc[ai][1][m][0], acc[ai][1][m][1], fr & 3);
	v_mov_b32_dpp v136, v136 quad_perm:[2,3,0,1] row_mask:0xf bank_mask:0xf bound_ctrl:1
	v_mov_b32_dpp v137, v137 quad_perm:[2,3,0,1] row_mask:0xf bank_mask:0xf bound_ctrl:1
	v_cndmask_b32_e64 v138, v136, v132, s[6:7]
	v_cndmask_b32_e64 v136, v134, v136, s[6:7]
	v_cndmask_b32_e64 v134, v137, v133, s[6:7]
	v_cndmask_b32_e64 v135, v135, v137, s[6:7]
	v_perm_b32 v132, v134, v138, s91
	v_perm_b32 v133, v135, v136, s91
	v_perm_b32 v134, v134, v138, s92
	v_perm_b32 v135, v135, v136, s92
	global_store_dwordx2 v[130:131], v[132:133], off offset:3072
	global_store_dwordx2 v[130:131], v[134:135], off offset:3088
	v_add_u32_e32 v130, 0x80, v220
	v_cvt_pk_bf16_f32 v132, v62, v63
	v_cvt_pk_bf16_f32 v133, v64, v65
	v_cvt_pk_bf16_f32 v134, v58, v59
	v_cvt_pk_bf16_f32 v135, v60, v61
	v_cndmask_b32_e64 v136, v132, v133, s[4:5]
	v_ashrrev_i32_e32 v131, 9, v130
	v_cndmask_b32_e64 v137, v134, v135, s[4:5]
	v_and_b32_e32 v131, 0x3fffff8, v131
	v_mov_b32_dpp v136, v136 quad_perm:[1,0,3,2] row_mask:0xf bank_mask:0xf bound_ctrl:1
	v_mov_b32_dpp v137, v137 quad_perm:[1,0,3,2] row_mask:0xf bank_mask:0xf bound_ctrl:1
	v_add_u32_e32 v131, s11, v131
	v_bfe_u32 v130, v130, 6, 6
	v_cndmask_b32_e64 v132, v136, v132, s[4:5]
	v_cndmask_b32_e64 v133, v133, v136, s[4:5]
	v_cndmask_b32_e64 v134, v137, v134, s[4:5]
	v_cndmask_b32_e64 v135, v135, v137, s[4:5]
	v_lshl_or_b32 v130, v131, 6, v130
	v_cndmask_b32_e64 v136, v132, v134, s[6:7]
	v_cndmask_b32_e64 v137, v133, v135, s[6:7]
	v_ashrrev_i32_e32 v131, 31, v130
	v_mov_b32_dpp v136, v136 quad_perm:[2,3,0,1] row_mask:0xf bank_mask:0xf bound_ctrl:1
	v_mov_b32_dpp v137, v137 quad_perm:[2,3,0,1] row_mask:0xf bank_mask:0xf bound_ctrl:1
	v_lshlrev_b64 v[130:131], 15, v[130:131]
	v_cndmask_b32_e64 v138, v136, v132, s[6:7]
	v_cndmask_b32_e64 v136, v134, v136, s[6:7]
	v_cndmask_b32_e64 v134, v137, v133, s[6:7]
	v_cndmask_b32_e64 v135, v135, v137, s[6:7]
	v_lshl_add_u64 v[130:131], v[204:205], 0, v[130:131]
	v_perm_b32 v132, v134, v138, s91
	v_perm_b32 v133, v135, v136, s91
	v_perm_b32 v134, v134, v138, s92
	v_perm_b32 v135, v135, v136, s92
	global_store_dwordx2 v[130:131], v[132:133], off
	global_store_dwordx2 v[130:131], v[134:135], off offset:16
	v_cvt_pk_bf16_f32 v132, v54, v55
	v_cvt_pk_bf16_f32 v133, v56, v57
	v_cvt_pk_bf16_f32 v134, v50, v51
	v_cvt_pk_bf16_f32 v135, v52, v53
	v_cndmask_b32_e64 v136, v132, v133, s[4:5]
	v_cndmask_b32_e64 v137, v134, v135, s[4:5]
	v_add_co_u32_e32 v130, vcc, s80, v130
	v_mov_b32_dpp v136, v136 quad_perm:[1,0,3,2] row_mask:0xf bank_mask:0xf bound_ctrl:1
	v_mov_b32_dpp v137, v137 quad_perm:[1,0,3,2] row_mask:0xf bank_mask:0xf bound_ctrl:1
	v_cndmask_b32_e64 v132, v136, v132, s[4:5]
	v_cndmask_b32_e64 v133, v133, v136, s[4:5]
	v_cndmask_b32_e64 v134, v137, v134, s[4:5]
	v_cndmask_b32_e64 v135, v135, v137, s[4:5]
	v_cndmask_b32_e64 v136, v132, v134, s[6:7]
	v_cndmask_b32_e64 v137, v133, v135, s[6:7]
	v_addc_co_u32_e32 v131, vcc, 0, v131, vcc
	v_mov_b32_dpp v136, v136 quad_perm:[2,3,0,1] row_mask:0xf bank_mask:0xf bound_ctrl:1
	v_mov_b32_dpp v137, v137 quad_perm:[2,3,0,1] row_mask:0xf bank_mask:0xf bound_ctrl:1
	v_cndmask_b32_e64 v138, v136, v132, s[6:7]
	v_cndmask_b32_e64 v136, v134, v136, s[6:7]
	v_cndmask_b32_e64 v134, v137, v133, s[6:7]
	v_cndmask_b32_e64 v135, v135, v137, s[6:7]
	v_perm_b32 v132, v134, v138, s91
	v_perm_b32 v133, v135, v136, s91
	v_perm_b32 v134, v134, v138, s92
	v_perm_b32 v135, v135, v136, s92
	global_store_dwordx2 v[130:131], v[132:133], off
	global_store_dwordx2 v[130:131], v[134:135], off offset:16
	v_add_u32_e32 v130, 0x90, v220
	v_cvt_pk_bf16_f32 v132, v46, v47
	v_cvt_pk_bf16_f32 v133, v48, v49
	v_cvt_pk_bf16_f32 v134, v42, v43
	v_cvt_pk_bf16_f32 v135, v44, v45
	v_cndmask_b32_e64 v136, v132, v133, s[4:5]
	v_ashrrev_i32_e32 v131, 9, v130
	v_cndmask_b32_e64 v137, v134, v135, s[4:5]
	v_and_b32_e32 v131, 0x3fffff8, v131
	v_mov_b32_dpp v136, v136 quad_perm:[1,0,3,2] row_mask:0xf bank_mask:0xf bound_ctrl:1
	v_mov_b32_dpp v137, v137 quad_perm:[1,0,3,2] row_mask:0xf bank_mask:0xf bound_ctrl:1
	v_add_u32_e32 v131, s11, v131
	v_bfe_u32 v130, v130, 6, 6
	v_cndmask_b32_e64 v132, v136, v132, s[4:5]
	v_cndmask_b32_e64 v133, v133, v136, s[4:5]
	v_cndmask_b32_e64 v134, v137, v134, s[4:5]
	v_cndmask_b32_e64 v135, v135, v137, s[4:5]
	v_lshl_or_b32 v130, v131, 6, v130
	v_cndmask_b32_e64 v136, v132, v134, s[6:7]
	v_cndmask_b32_e64 v137, v133, v135, s[6:7]
	v_ashrrev_i32_e32 v131, 31, v130
	v_mov_b32_dpp v136, v136 quad_perm:[2,3,0,1] row_mask:0xf bank_mask:0xf bound_ctrl:1
	v_mov_b32_dpp v137, v137 quad_perm:[2,3,0,1] row_mask:0xf bank_mask:0xf bound_ctrl:1
	v_lshlrev_b64 v[130:131], 15, v[130:131]
	v_cndmask_b32_e64 v138, v136, v132, s[6:7]
	v_cndmask_b32_e64 v136, v134, v136, s[6:7]
	v_cndmask_b32_e64 v134, v137, v133, s[6:7]
	v_cndmask_b32_e64 v135, v135, v137, s[6:7]
	v_lshl_add_u64 v[130:131], v[204:205], 0, v[130:131]
	v_perm_b32 v132, v134, v138, s91
	v_perm_b32 v133, v135, v136, s91
	v_perm_b32 v134, v134, v138, s92
	v_perm_b32 v135, v135, v136, s92
	global_store_dwordx2 v[130:131], v[132:133], off offset:1024
	global_store_dwordx2 v[130:131], v[134:135], off offset:1040
	v_cvt_pk_bf16_f32 v132, v38, v39
	v_cvt_pk_bf16_f32 v133, v40, v41
	v_cvt_pk_bf16_f32 v134, v34, v35
	v_cvt_pk_bf16_f32 v135, v36, v37
	v_cndmask_b32_e64 v136, v132, v133, s[4:5]
	v_cndmask_b32_e64 v137, v134, v135, s[4:5]
	v_add_co_u32_e32 v130, vcc, s80, v130
	v_mov_b32_dpp v136, v136 quad_perm:[1,0,3,2] row_mask:0xf bank_mask:0xf bound_ctrl:1
	v_mov_b32_dpp v137, v137 quad_perm:[1,0,3,2] row_mask:0xf bank_mask:0xf bound_ctrl:1
	v_cndmask_b32_e64 v132, v136, v132, s[4:5]
	v_cndmask_b32_e64 v133, v133, v136, s[4:5]
;     __device__ __forceinline__ void operator()(AccRef acc, const pg8::Unit& u, int wr, int wc, int fr, int fq) const {
;     ...
;                 for (int m = 0; m < 4; ++m) {
;                     int r = row0 + ai * 128 + m * 16; asm volatile("" : "+v"(r)); const int pos = r & 4095;
;                     const int vq = cl + 2 * (fr & 3);
;                     bf16* tb = vT + ((size_t)(((r >> 12) * 8 + h) * 64 + (pos >> 6))) * 16384 + (size_t)((((vq >> 5) * 4 + m) * 64 + ((fr >> 3) & 1) * 32 + (vq & 31)) * 8 + (fr & 4));
;                     tr_store(tb, 8, acc[ai][0][m][0], acc[ai][0][m][1], fr & 3); tr_store(tb + 4 * 4 * 64 * 8, 8, acc[ai][1][m][0], acc[ai][1][m][1], fr & 3);
	v_cndmask_b32_e64 v134, v137, v134, s[4:5]
	v_cndmask_b32_e64 v135, v135, v137, s[4:5]
	v_cndmask_b32_e64 v136, v132, v134, s[6:7]
	v_cndmask_b32_e64 v137, v133, v135, s[6:7]
	v_addc_co_u32_e32 v131, vcc, 0, v131, vcc
	v_mov_b32_dpp v136, v136 quad_perm:[2,3,0,1] row_mask:0xf bank_mask:0xf bound_ctrl:1
	v_mov_b32_dpp v137, v137 quad_perm:[2,3,0,1] row_mask:0xf bank_mask:0xf bound_ctrl:1
	v_cndmask_b32_e64 v138, v136, v132, s[6:7]
	v_cndmask_b32_e64 v136, v134, v136, s[6:7]
	v_cndmask_b32_e64 v134, v137, v133, s[6:7]
	v_cndmask_b32_e64 v135, v135, v137, s[6:7]
	v_perm_b32 v132, v134, v138, s91
	v_perm_b32 v133, v135, v136, s91
	v_perm_b32 v134, v134, v138, s92
	v_perm_b32 v135, v135, v136, s92
	global_store_dwordx2 v[130:131], v[132:133], off offset:1024
	global_store_dwordx2 v[130:131], v[134:135], off offset:1040
	v_add_u32_e32 v130, 0xa0, v220
	v_cvt_pk_bf16_f32 v132, v30, v31
	v_cvt_pk_bf16_f32 v133, v32, v33
	v_cvt_pk_bf16_f32 v134, v26, v27
	v_cvt_pk_bf16_f32 v135, v28, v29
	v_cndmask_b32_e64 v136, v132, v133, s[4:5]
	v_ashrrev_i32_e32 v131, 9, v130
	v_cndmask_b32_e64 v137, v134, v135, s[4:5]
	v_and_b32_e32 v131, 0x3fffff8, v131
	v_mov_b32_dpp v136, v136 quad_perm:[1,0,3,2] row_mask:0xf bank_mask:0xf bound_ctrl:1
	v_mov_b32_dpp v137, v137 quad_perm:[1,0,3,2] row_mask:0xf bank_mask:0xf bound_ctrl:1
	v_add_u32_e32 v131, s11, v131
	v_bfe_u32 v130, v130, 6, 6
	v_cndmask_b32_e64 v132, v136, v132, s[4:5]
	v_cndmask_b32_e64 v133, v133, v136, s[4:5]
	v_cndmask_b32_e64 v134, v137, v134, s[4:5]
	v_cndmask_b32_e64 v135, v135, v137, s[4:5]
	v_lshl_or_b32 v130, v131, 6, v130
	v_cndmask_b32_e64 v136, v132, v134, s[6:7]
	v_cndmask_b32_e64 v137, v133, v135, s[6:7]
	v_ashrrev_i32_e32 v131, 31, v130
	v_mov_b32_dpp v136, v136 quad_perm:[2,3,0,1] row_mask:0xf bank_mask:0xf bound_ctrl:1
	v_mov_b32_dpp v137, v137 quad_perm:[2,3,0,1] row_mask:0xf bank_mask:0xf bound_ctrl:1
	v_lshlrev_b64 v[130:131], 15, v[130:131]
	v_cndmask_b32_e64 v138, v136, v132, s[6:7]
	v_cndmask_b32_e64 v136, v134, v136, s[6:7]
	v_cndmask_b32_e64 v134, v137, v133, s[6:7]
	v_cndmask_b32_e64 v135, v135, v137, s[6:7]
	v_lshl_add_u64 v[130:131], v[204:205], 0, v[130:131]
	v_perm_b32 v132, v134, v138, s91
	v_perm_b32 v133, v135, v136, s91
	v_perm_b32 v134, v134, v138, s92
	v_perm_b32 v135, v135, v136, s92
	global_store_dwordx2 v[130:131], v[132:133], off offset:2048
	global_store_dwordx2 v[130:131], v[134:135], off offset:2064
	v_cvt_pk_bf16_f32 v132, v22, v23
	v_cvt_pk_bf16_f32 v133, v24, v25
	v_cvt_pk_bf16_f32 v134, v18, v19
	v_cvt_pk_bf16_f32 v135, v20, v21
	v_cndmask_b32_e64 v136, v132, v133, s[4:5]
	v_cndmask_b32_e64 v137, v134, v135, s[4:5]
	v_add_co_u32_e32 v130, vcc, s80, v130
	v_mov_b32_dpp v136, v136 quad_perm:[1,0,3,2] row_mask:0xf bank_mask:0xf bound_ctrl:1
	v_mov_b32_dpp v137, v137 quad_perm:[1,0,3,2] row_mask:0xf bank_mask:0xf bound_ctrl:1
	v_cndmask_b32_e64 v132, v136, v132, s[4:5]
	v_cndmask_b32_e64 v133, v133, v136, s[4:5]
	v_cndmask_b32_e64 v134, v137, v134, s[4:5]
	v_cndmask_b32_e64 v135, v135, v137, s[4:5]
	v_cndmask_b32_e64 v136, v132, v134, s[6:7]
	v_cndmask_b32_e64 v137, v133, v135, s[6:7]
	v_addc_co_u32_e32 v131, vcc, 0, v131, vcc
	v_mov_b32_dpp v136, v136 quad_perm:[2,3,0,1] row_mask:0xf bank_mask:0xf bound_ctrl:1
	v_mov_b32_dpp v137, v137 quad_perm:[2,3,0,1] row_mask:0xf bank_mask:0xf bound_ctrl:1
	v_cndmask_b32_e64 v138, v136, v132, s[6:7]
	v_cndmask_b32_e64 v136, v134, v136, s[6:7]
	v_cndmask_b32_e64 v134, v137, v133, s[6:7]
	v_cndmask_b32_e64 v135, v135, v137, s[6:7]
	v_perm_b32 v132, v134, v138, s91
	v_perm_b32 v133, v135, v136, s91
	v_perm_b32 v134, v134, v138, s92
	v_perm_b32 v135, v135, v136, s92
	global_store_dwordx2 v[130:131], v[132:133], off offset:2048
	global_store_dwordx2 v[130:131], v[134:135], off offset:2064
	v_add_u32_e32 v130, 0xb0, v220
	v_cvt_pk_bf16_f32 v132, v14, v15
	v_cvt_pk_bf16_f32 v133, v16, v17
	v_cvt_pk_bf16_f32 v134, v10, v11
	v_cvt_pk_bf16_f32 v135, v12, v13
	v_cndmask_b32_e64 v136, v132, v133, s[4:5]
	v_ashrrev_i32_e32 v131, 9, v130
	v_cndmask_b32_e64 v137, v134, v135, s[4:5]
	v_and_b32_e32 v131, 0x3fffff8, v131
	v_mov_b32_dpp v136, v136 quad_perm:[1,0,3,2] row_mask:0xf bank_mask:0xf bound_ctrl:1
	v_mov_b32_dpp v137, v137 quad_perm:[1,0,3,2] row_mask:0xf bank_mask:0xf bound_ctrl:1
	v_add_u32_e32 v131, s11, v131
	v_bfe_u32 v130, v130, 6, 6
	v_cndmask_b32_e64 v132, v136, v132, s[4:5]
	v_cndmask_b32_e64 v133, v133, v136, s[4:5]
	v_cndmask_b32_e64 v134, v137, v134, s[4:5]
	v_cndmask_b32_e64 v135, v135, v137, s[4:5]
	v_lshl_or_b32 v130, v131, 6, v130
	v_cndmask_b32_e64 v136, v132, v134, s[6:7]
	v_cndmask_b32_e64 v137, v133, v135, s[6:7]
	v_ashrrev_i32_e32 v131, 31, v130
	v_mov_b32_dpp v136, v136 quad_perm:[2,3,0,1] row_mask:0xf bank_mask:0xf bound_ctrl:1
	v_mov_b32_dpp v137, v137 quad_perm:[2,3,0,1] row_mask:0xf bank_mask:0xf bound_ctrl:1
	v_lshlrev_b64 v[130:131], 15, v[130:131]
	v_cndmask_b32_e64 v138, v136, v132, s[6:7]
	v_cndmask_b32_e64 v136, v134, v136, s[6:7]
	v_cndmask_b32_e64 v134, v137, v133, s[6:7]
	v_cndmask_b32_e64 v135, v135, v137, s[6:7]
	v_lshl_add_u64 v[130:131], v[204:205], 0, v[130:131]
	v_perm_b32 v132, v134, v138, s91
	v_perm_b32 v133, v135, v136, s91
	v_perm_b32 v134, v134, v138, s92
	v_perm_b32 v135, v135, v136, s92
	global_store_dwordx2 v[130:131], v[132:133], off offset:3072
	global_store_dwordx2 v[130:131], v[134:135], off offset:3088
	v_cvt_pk_bf16_f32 v132, v6, v7
	v_cvt_pk_bf16_f32 v133, v8, v9
	v_cvt_pk_bf16_f32 v134, v2, v3
	v_cvt_pk_bf16_f32 v135, v4, v5
	v_cndmask_b32_e64 v136, v132, v133, s[4:5]
	v_cndmask_b32_e64 v137, v134, v135, s[4:5]
	v_add_co_u32_e32 v130, vcc, 0x4000, v130
	v_mov_b32_dpp v136, v136 quad_perm:[1,0,3,2] row_mask:0xf bank_mask:0xf bound_ctrl:1
	v_mov_b32_dpp v137, v137 quad_perm:[1,0,3,2] row_mask:0xf bank_mask:0xf bound_ctrl:1
	v_cndmask_b32_e64 v132, v136, v132, s[4:5]
	v_cndmask_b32_e64 v133, v133, v136, s[4:5]
	v_cndmask_b32_e64 v134, v137, v134, s[4:5]
	v_cndmask_b32_e64 v135, v135, v137, s[4:5]
	v_cndmask_b32_e64 v136, v132, v134, s[6:7]
	v_cndmask_b32_e64 v137, v133, v135, s[6:7]
	v_addc_co_u32_e32 v131, vcc, 0, v131, vcc
	v_mov_b32_dpp v136, v136 quad_perm:[2,3,0,1] row_mask:0xf bank_mask:0xf bound_ctrl:1
	v_mov_b32_dpp v137, v137 quad_perm:[2,3,0,1] row_mask:0xf bank_mask:0xf bound_ctrl:1
	v_cndmask_b32_e64 v138, v136, v132, s[6:7]
	v_cndmask_b32_e64 v136, v134, v136, s[6:7]
	v_cndmask_b32_e64 v134, v137, v133, s[6:7]
	v_cndmask_b32_e64 v135, v135, v137, s[6:7]
	v_perm_b32 v132, v134, v138, s91
	v_perm_b32 v133, v135, v136, s91
	v_perm_b32 v134, v134, v138, s92
	v_perm_b32 v135, v135, v136, s92
	global_store_dwordx2 v[130:131], v[132:133], off offset:3072
	global_store_dwordx2 v[130:131], v[134:135], off offset:3088

; #define PG8_STAGE(bufoff, gbase, voff) do { _Pragma("unroll") for (int _i = 0; _i < 2; ++_i) \
;         __builtin_amdgcn_global_load_lds((const unsigned*)((const char*)(gbase) + (voff)[_i]), (PG8_LAS unsigned*)(lds + (bufoff) + ldsw + _i * 8192), 16, 0, 0); } while (0)
; #define PG8_WAIT_V(n) asm volatile("s_waitcnt vmcnt(" #n ")" ::: "memory")
; #define PG8_BAR __builtin_amdgcn_s_barrier()
; template <class Epi, class Sched, bool ALIGN_EPI = false, bool SP2 = false>
; __device__ __forceinline__ void gemm_phase(PG8_LAS unsigned char* lds, const Gemm g, const Sched& S, const Epi& E) {
;     ...
;     const char* cA = (const char*)g.A + (size_t)cur.pm * tA + (size_t)cur.pn * pnA; const char* cB = (const char*)g.Bt + (size_t)cur.pn * tB;
;     S.a_ready(cur);
;     if constexpr (SP2) {
;         PG8_STAGE(PG8_SB(0, 0), cB, voffB); PG8_STAGE(PG8_SB(0, 1), cB + hB, voffB); PG8_STAGE(PG8_SA(0, 0), cA, voffA); PG8_STAGE(PG8_SA(0, 1), cA + hA, voffA);
;         if (wr == 1) PG8_BAR;
;         PG8_WAIT_V(2); PG8_BAR;
;         PG8_STAGE(PG8_SB(1, 0), cB + kstep, voffB); PG8_STAGE(PG8_SA(1, 0), cA + kstep, voffA); PG8_STAGE(PG8_SB(1, 1), cB + hB + kstep, voffB);
;         PG8_WAIT_V(6); PG8_BAR;
; __global__ void __launch_bounds__(512, 2) fwd_megakernel(Args a) {
;     ...
;           pg8::Gemm g{(const bf16*)(ws + WS_P2), (const bf16*)(ws + WS_WPB), DPOOL, DPOOL, DPOOL, 0}; pg8::StaticOrder S; S.init(M, D, G, bid);
;           EpiGate<false> E{(const bf16*)a.out, (bf16*)(ws + WS_TMP), (bf16*)(ws + WS_MERGED)};
;           pg8::gemm_phase<EpiGate<false>, pg8::StaticOrder, true, true>(lds, g, S, E); }
.LBB0_858:
	s_add_u32 s6, s4, 0xd800000
	s_addc_u32 s7, s5, 0
	s_lshl_b32 s4, s8, 5
	s_mov_b64 s[8:9], 0x80
	s_and_b32 s18, s4, 0x60
	s_add_i32 m0, s41, 0x18000
	v_lshl_add_u64 v[8:9], v[8:9], 0, s[8:9]
	s_lshl_b32 s17, s16, 13
	s_lshl_b32 s19, s18, 7
	s_waitcnt vmcnt(2)
	s_barrier
	global_load_lds_dwordx4 v[8:9], off
	v_lshl_add_u64 v[6:7], v[6:7], 0, s[8:9]
	s_add_i32 m0, s41, 0x1a000
	s_add_i32 s60, s41, 0x8000
	s_add_i32 s61, s41, 0xa000
	global_load_lds_dwordx4 v[6:7], off
	v_lshl_add_u64 v[2:3], v[2:3], 0, s[8:9]
	s_mov_b32 m0, s60
	s_add_u32 s4, s44, 0x40080
	global_load_lds_dwordx4 v[2:3], off
	v_lshl_add_u64 v[2:3], v[4:5], 0, s[8:9]
	s_mov_b32 m0, s61
	s_addc_u32 s5, s45, 0
	global_load_lds_dwordx4 v[2:3], off
	s_add_i32 m0, s41, 0x1c000
	v_lshl_add_u64 v[2:3], s[4:5], 0, v[134:135]
	global_load_lds_dwordx4 v[2:3], off
	v_lshl_add_u64 v[2:3], s[4:5], 0, v[130:131]
	s_add_i32 m0, s41, 0x1e000
	s_cmpk_lt_u32 s15, 0x100
	global_load_lds_dwordx4 v[2:3], off
	v_lshrrev_b32_e32 v3, 1, v11
	v_and_b32_e32 v3, 24, v3
	v_and_b32_e32 v2, 15, v11
	v_lshlrev_b32_e32 v4, 1, v3
	v_lshl_or_b32 v1, s16, 6, v2
	v_lshl_or_b32 v2, v2, 6, v4
	v_lshlrev_b32_e32 v4, 2, v11
	v_and_b32_e32 v4, 32, v4
	v_bitop3_b32 v5, v2, s17, v4 bitop3:0xde
	v_bitop3_b32 v154, v2, s19, v4 bitop3:0xde
	v_lshlrev_b32_e32 v2, 14, v15
	v_and_b32_e32 v2, 0xffff8000, v2
	v_or_b32_e32 v155, s18, v3
	v_lshl_add_u32 v2, v14, 11, v2
	v_and_b32_e32 v3, 1, v15
	v_lshl_or_b32 v2, v3, 6, v2
	v_lshl_add_u32 v138, v16, 1, v2
	v_lshlrev_b32_e32 v2, 14, v10
	v_and_b32_e32 v2, 0xffff8000, v2
	s_waitcnt vmcnt(6)
	v_lshl_add_u32 v2, v12, 11, v2
	v_and_b32_e32 v3, 1, v10
	s_sext_i32_i8 s66, s14
	s_cselect_b64 s[14:15], -1, 0
	v_lshl_or_b32 v2, v3, 6, v2
	s_add_i32 s64, 0, 0x10000
	s_add_i32 s65, 0, 0x14000
	s_mov_b32 s62, 0
	s_waitcnt lgkmcnt(0)
	s_ashr_i32 s63, s50, 31
	v_mov_b32_e32 v139, v135
	v_lshl_add_u32 v140, v13, 1, v2
	v_mov_b32_e32 v141, v135
	v_mov_b64_e32 v[142:143], 0x200
	v_mov_b64_e32 v[144:145], 0x1ff
	v_add_u32_e32 v156, s64, v154
	v_add_u32_e32 v157, s65, v154
	v_add_u32_e32 v158, 0, v5
	s_mov_b64 s[16:17], 0x1000
	s_barrier
	s_mov_b32 s101, 1
	s_branch .LBB0_861

; #define PG8_STAGE(bufoff, gbase, voff) do { _Pragma("unroll") for (int _i = 0; _i < 2; ++_i) \
;         __builtin_amdgcn_global_load_lds((const unsigned*)((const char*)(gbase) + (voff)[_i]), (PG8_LAS unsigned*)(lds + (bufoff) + ldsw + _i * 8192), 16, 0, 0); } while (0)
; #define PG8_LDA(dst, b, h) do { _Pragma("unroll") for (int m = 0; m < 4; ++m) _Pragma("unroll") for (int k = 0; k < 2; ++k) dst[m][k] = *(const PG8_LAS bf16x8*)(lds + PG8_SA(b, h) + aoff + m * 2048 + k * 1024); } while (0)
; #define PG8_LDB(dst, b, h) do { _Pragma("unroll") for (int n = 0; n < 2; ++n) _Pragma("unroll") for (int k = 0; k < 2; ++k) dst[n][k] = *(const PG8_LAS bf16x8*)(lds + PG8_SB(b, h) + boff + n * 2048 + k * 1024); } while (0)
; #define PG8_MMA(ai, bj, At, Bt) do { __builtin_amdgcn_s_setprio(1); _Pragma("unroll") for (int m = 0; m < 4; ++m) _Pragma("unroll") for (int n = 0; n < 2; ++n) _Pragma("unroll") for (int k = 0; k < 2; ++k) \
;         acc[ai][bj][m][n] = __builtin_amdgcn_mfma_f32_16x16x32_bf16(Bt[n][k], At[m][k], acc[ai][bj][m][n], 0, 0, 0); __builtin_amdgcn_s_setprio(0); } while (0)
; template <class Epi, class Sched, bool ALIGN_EPI = false, bool SP2 = false>
; __device__ __forceinline__ void gemm_phase(PG8_LAS unsigned char* lds, const Gemm g, const Sched& S, const Epi& E) {
;     ...
;     for (;;) {
;         const bool has_next = S.next(ui + 1, nxt);
;         const char* nA = has_next ? (const char*)g.A + (size_t)nxt.pm * tA + (size_t)nxt.pn * pnA : cA; const char* nB = has_next ? (const char*)g.Bt + (size_t)nxt.pn * tB : cB;
; #pragma nounroll
;         for (int t = 0; t < nt; t += 2) {
;             const bool last = (t == nt - 2);
;             const char* a1 = cA + (size_t)(t + 1) * kstep;
;             const char* a2 = last ? nA : cA + (size_t)(t + 2) * kstep; const char* b2 = last ? nB : cB + (size_t)(t + 2) * kstep;
;             const char* a3 = a2 + kstep; const char* b3 = b2 + kstep;
;             if (last && has_next) S.a_ready(nxt);
;             if constexpr (SP2) {
;             PG8_LDB(B0, 0, 0); PG8_LDB(B1, 0, 1); PG8_SCHED; PG8_LDA(At, 0, 0); PG8_STAGE(PG8_SA(1, 1), a1 + hA, voffA);
;             PG8_WAIT_V(8); PG8_WAIT_L(0); PG8_BAR; PG8_MMA(0, 0, At, B0); PG8_MMA(0, 1, At, B1); PG8_BAR; PG8_SCHED;
;             PG8_LDA(At, 0, 1); PG8_STAGE(PG8_SB(0, 0), b2, voffB); PG8_STAGE(PG8_SB(0, 1), b2 + hB, voffB); PG8_STAGE(PG8_SA(0, 0), a2, voffA);
.LBB0_867:
	s_ashr_i32 s23, s22, 31
	s_lshl_b64 s[24:25], s[22:23], 19
	s_add_u32 s24, s33, s24
	s_addc_u32 s25, s48, s25
	s_and_b64 s[38:39], s[4:5], exec
	s_cselect_b32 s23, s25, s43
	s_cselect_b32 s67, s24, s42
	s_ashr_i32 s21, s20, 31
	s_lshl_b64 s[38:39], s[20:21], 19
	s_add_u32 s38, s49, s38
	s_addc_u32 s39, s51, s39
	s_and_b64 s[46:47], s[4:5], exec
	s_cselect_b32 s21, s39, s45
	s_cselect_b32 s69, s38, s44
	s_add_u32 s42, s42, 0x40080
	s_addc_u32 s43, s43, 0
	s_add_u32 s70, s44, 0x100
	v_mov_b32_e32 v2, 0
	s_addc_u32 s71, s45, 0
	s_mov_b32 s72, -2
	v_mov_b32_e32 v3, v2
	ds_read_b128 v[146:149], v156
	ds_read_b128 v[150:153], v156 offset:1024
	ds_read_b128 v[160:163], v156 offset:2048
	ds_read_b128 v[164:167], v156 offset:3072
	ds_read_b128 v[168:171], v157
	ds_read_b128 v[172:175], v157 offset:1024
	ds_read_b128 v[176:179], v157 offset:2048
	ds_read_b128 v[180:183], v157 offset:3072
	s_add_u32 s18, s42, 0xfffc0080
	s_addc_u32 s19, s43, -1
	s_cmp_eq_u32 s72, 12
	s_cselect_b32 s47, s23, s19
	s_cselect_b32 s46, s67, s18
	s_cselect_b32 s45, s21, s71
	s_cselect_b32 s44, s69, s70
	s_add_i32 m0, s41, 0xc000
	ds_read_b128 v[184:187], v158
	ds_read_b128 v[188:191], v158 offset:1024
	ds_read_b128 v[192:195], v158 offset:2048
	ds_read_b128 v[196:199], v158 offset:3072
	ds_read_b128 v[200:203], v158 offset:4096
	ds_read_b128 v[204:207], v158 offset:5120
	ds_read_b128 v[208:211], v158 offset:6144
	ds_read_b128 v[212:215], v158 offset:7168
	global_load_lds_dwordx4 v138, s[42:43]
	s_add_i32 m0, s41, 0xe000
	s_nop 0
	global_load_lds_dwordx4 v140, s[42:43]
	s_cmp_eq_u32 s101, 0
	s_cbranch_scc1 .Lfw_1_0
	s_waitcnt vmcnt(8)
.Lfw_1_0:
	s_waitcnt lgkmcnt(0)
	s_barrier
	s_waitcnt lgkmcnt(0)
	v_mfma_f32_16x16x32_bf16 v[126:129], v[146:149], v[184:187], 0
	v_mfma_f32_16x16x32_bf16 v[122:125], v[160:163], v[184:187], 0
	v_mfma_f32_16x16x32_bf16 v[114:117], v[146:149], v[192:195], 0
	v_mfma_f32_16x16x32_bf16 v[106:109], v[160:163], v[192:195], 0
	v_mfma_f32_16x16x32_bf16 v[98:101], v[146:149], v[200:203], 0
	v_mfma_f32_16x16x32_bf16 v[90:93], v[160:163], v[200:203], 0
	v_mfma_f32_16x16x32_bf16 v[82:85], v[146:149], v[208:211], 0
	v_mfma_f32_16x16x32_bf16 v[74:77], v[160:163], v[208:211], 0
	v_mfma_f32_16x16x32_bf16 v[126:129], v[150:153], v[188:191], v[126:129]
	v_mfma_f32_16x16x32_bf16 v[122:125], v[164:167], v[188:191], v[122:125]
	v_mfma_f32_16x16x32_bf16 v[114:117], v[150:153], v[196:199], v[114:117]
	v_mfma_f32_16x16x32_bf16 v[106:109], v[164:167], v[196:199], v[106:109]
	v_mfma_f32_16x16x32_bf16 v[98:101], v[150:153], v[204:207], v[98:101]
	v_mfma_f32_16x16x32_bf16 v[90:93], v[164:167], v[204:207], v[90:93]
	v_mfma_f32_16x16x32_bf16 v[82:85], v[150:153], v[212:215], v[82:85]
	v_mfma_f32_16x16x32_bf16 v[74:77], v[164:167], v[212:215], v[74:77]
	v_mfma_f32_16x16x32_bf16 v[118:121], v[168:171], v[184:187], 0
	v_mfma_f32_16x16x32_bf16 v[110:113], v[176:179], v[184:187], 0
	v_mfma_f32_16x16x32_bf16 v[102:105], v[168:171], v[192:195], 0
	v_mfma_f32_16x16x32_bf16 v[94:97], v[176:179], v[192:195], 0
	v_mfma_f32_16x16x32_bf16 v[86:89], v[168:171], v[200:203], 0
	v_mfma_f32_16x16x32_bf16 v[78:81], v[176:179], v[200:203], 0
	v_mfma_f32_16x16x32_bf16 v[70:73], v[168:171], v[208:211], 0
	v_mfma_f32_16x16x32_bf16 v[66:69], v[176:179], v[208:211], 0
	v_mfma_f32_16x16x32_bf16 v[118:121], v[172:175], v[188:191], v[118:121]
	v_mfma_f32_16x16x32_bf16 v[110:113], v[180:183], v[188:191], v[110:113]
	v_mfma_f32_16x16x32_bf16 v[102:105], v[172:175], v[196:199], v[102:105]
	v_mfma_f32_16x16x32_bf16 v[94:97], v[180:183], v[196:199], v[94:97]
	v_mfma_f32_16x16x32_bf16 v[86:89], v[172:175], v[204:207], v[86:89]
	v_mfma_f32_16x16x32_bf16 v[78:81], v[180:183], v[204:207], v[78:81]
	v_mfma_f32_16x16x32_bf16 v[70:73], v[172:175], v[212:215], v[70:73]
	v_mfma_f32_16x16x32_bf16 v[66:69], v[180:183], v[212:215], v[66:69]
	s_barrier
	s_add_i32 s18, s64, s52
	s_add_u32 s78, s44, s8
	s_addc_u32 s79, s45, s9
	s_mov_b32 m0, s18
	ds_read_b128 v[184:187], v158 offset:16384
	ds_read_b128 v[188:191], v158 offset:17408
	ds_read_b128 v[192:195], v158 offset:18432
	ds_read_b128 v[196:199], v158 offset:19456
	ds_read_b128 v[200:203], v158 offset:20480
	ds_read_b128 v[204:207], v158 offset:21504
	ds_read_b128 v[208:211], v158 offset:22528
	ds_read_b128 v[212:215], v158 offset:23552
	global_load_lds_dwordx4 v134, s[44:45]
	s_add_i32 m0, s18, 0x2000
	s_add_u32 s74, s44, 0x40000
	s_addc_u32 s75, s45, 0
	s_add_i32 s18, s65, s52
	global_load_lds_dwordx4 v130, s[44:45]
	s_mov_b32 m0, s18
	s_nop 0
	global_load_lds_dwordx4 v134, s[74:75]
	s_add_i32 m0, s18, 0x2000
	s_nop 0
	global_load_lds_dwordx4 v130, s[74:75]
	s_add_u32 s80, s46, s8
	s_addc_u32 s81, s47, s9
	s_mov_b32 m0, s41
	s_nop 0
	global_load_lds_dwordx4 v136, s[46:47]
	s_mov_b32 m0, s53
	s_nop 0
	global_load_lds_dwordx4 v132, s[46:47]
	s_cmp_eq_u32 s101, 0
	s_cbranch_scc1 .Lfw_1_1
	s_waitcnt vmcnt(8)
; #define PG8_STAGE(bufoff, gbase, voff) do { _Pragma("unroll") for (int _i = 0; _i < 2; ++_i) \
;         __builtin_amdgcn_global_load_lds((const unsigned*)((const char*)(gbase) + (voff)[_i]), (PG8_LAS unsigned*)(lds + (bufoff) + ldsw + _i * 8192), 16, 0, 0); } while (0)
; #define PG8_LDA(dst, b, h) do { _Pragma("unroll") for (int m = 0; m < 4; ++m) _Pragma("unroll") for (int k = 0; k < 2; ++k) dst[m][k] = *(const PG8_LAS bf16x8*)(lds + PG8_SA(b, h) + aoff + m * 2048 + k * 1024); } while (0)
; #define PG8_LDB(dst, b, h) do { _Pragma("unroll") for (int n = 0; n < 2; ++n) _Pragma("unroll") for (int k = 0; k < 2; ++k) dst[n][k] = *(const PG8_LAS bf16x8*)(lds + PG8_SB(b, h) + boff + n * 2048 + k * 1024); } while (0)
; #define PG8_MMA(ai, bj, At, Bt) do { __builtin_amdgcn_s_setprio(1); _Pragma("unroll") for (int m = 0; m < 4; ++m) _Pragma("unroll") for (int n = 0; n < 2; ++n) _Pragma("unroll") for (int k = 0; k < 2; ++k) \
;         acc[ai][bj][m][n] = __builtin_amdgcn_mfma_f32_16x16x32_bf16(Bt[n][k], At[m][k], acc[ai][bj][m][n], 0, 0, 0); __builtin_amdgcn_s_setprio(0); } while (0)
; #define PG8_WAIT_V(n) asm volatile("s_waitcnt vmcnt(" #n ")" ::: "memory")
; #define PG8_WAIT_L(n) asm volatile("s_waitcnt lgkmcnt(" #n ")" ::: "memory")
; #define PG8_BAR __builtin_amdgcn_s_barrier()
; #define PG8_SCHED __builtin_amdgcn_sched_barrier(0)
; template <class Epi, class Sched, bool ALIGN_EPI = false, bool SP2 = false>
; __device__ __forceinline__ void gemm_phase(PG8_LAS unsigned char* lds, const Gemm g, const Sched& S, const Epi& E) {
;     ...
;             PG8_WAIT_V(8); PG8_WAIT_L(0); PG8_BAR; PG8_MMA(1, 0, At, B0); PG8_MMA(1, 1, At, B1); PG8_BAR; PG8_SCHED;
;             PG8_LDB(B0, 1, 0); PG8_LDB(B1, 1, 1); PG8_SCHED; PG8_LDA(At, 1, 0); PG8_STAGE(PG8_SA(0, 1), a2 + hA, voffA);
;             PG8_WAIT_V(8); PG8_WAIT_L(0); PG8_BAR; PG8_MMA(0, 0, At, B0); PG8_MMA(0, 1, At, B1); PG8_BAR; PG8_SCHED;
.Lfw_1_1:
	s_waitcnt lgkmcnt(0)
	s_barrier
	s_waitcnt lgkmcnt(0)
	v_mfma_f32_16x16x32_bf16 v[62:65], v[146:149], v[184:187], 0
	v_mfma_f32_16x16x32_bf16 v[58:61], v[160:163], v[184:187], 0
	v_mfma_f32_16x16x32_bf16 v[50:53], v[146:149], v[192:195], 0
	v_mfma_f32_16x16x32_bf16 v[42:45], v[160:163], v[192:195], 0
	v_mfma_f32_16x16x32_bf16 v[34:37], v[146:149], v[200:203], 0
	v_mfma_f32_16x16x32_bf16 v[26:29], v[160:163], v[200:203], 0
	v_mfma_f32_16x16x32_bf16 v[18:21], v[146:149], v[208:211], 0
	v_mfma_f32_16x16x32_bf16 v[10:13], v[160:163], v[208:211], 0
	v_mfma_f32_16x16x32_bf16 v[62:65], v[150:153], v[188:191], v[62:65]
	v_mfma_f32_16x16x32_bf16 v[58:61], v[164:167], v[188:191], v[58:61]
	v_mfma_f32_16x16x32_bf16 v[50:53], v[150:153], v[196:199], v[50:53]
	v_mfma_f32_16x16x32_bf16 v[42:45], v[164:167], v[196:199], v[42:45]
	v_mfma_f32_16x16x32_bf16 v[34:37], v[150:153], v[204:207], v[34:37]
	v_mfma_f32_16x16x32_bf16 v[26:29], v[164:167], v[204:207], v[26:29]
	v_mfma_f32_16x16x32_bf16 v[18:21], v[150:153], v[212:215], v[18:21]
	v_mfma_f32_16x16x32_bf16 v[10:13], v[164:167], v[212:215], v[10:13]
	v_mfma_f32_16x16x32_bf16 v[54:57], v[168:171], v[184:187], 0
	v_mfma_f32_16x16x32_bf16 v[46:49], v[176:179], v[184:187], 0
	v_mfma_f32_16x16x32_bf16 v[38:41], v[168:171], v[192:195], 0
	v_mfma_f32_16x16x32_bf16 v[30:33], v[176:179], v[192:195], 0
	v_mfma_f32_16x16x32_bf16 v[22:25], v[168:171], v[200:203], 0
	v_mfma_f32_16x16x32_bf16 v[14:17], v[176:179], v[200:203], 0
	v_mfma_f32_16x16x32_bf16 v[6:9], v[168:171], v[208:211], 0
	v_mfma_f32_16x16x32_bf16 v[2:5], v[176:179], v[208:211], 0
	v_mfma_f32_16x16x32_bf16 v[54:57], v[172:175], v[188:191], v[54:57]
	v_mfma_f32_16x16x32_bf16 v[46:49], v[180:183], v[188:191], v[46:49]
	v_mfma_f32_16x16x32_bf16 v[38:41], v[172:175], v[196:199], v[38:41]
	v_mfma_f32_16x16x32_bf16 v[30:33], v[180:183], v[196:199], v[30:33]
	v_mfma_f32_16x16x32_bf16 v[22:25], v[172:175], v[204:207], v[22:25]
	v_mfma_f32_16x16x32_bf16 v[14:17], v[180:183], v[204:207], v[14:17]
	v_mfma_f32_16x16x32_bf16 v[6:9], v[172:175], v[212:215], v[6:9]
	v_mfma_f32_16x16x32_bf16 v[2:5], v[180:183], v[212:215], v[2:5]
	s_barrier
	s_add_i32 s18, 0, 0x18000
	v_add_u32_e32 v159, s18, v154
	s_add_i32 s19, 0, 0x1c000
	ds_read_b128 v[146:149], v159
	ds_read_b128 v[150:153], v159 offset:1024
	ds_read_b128 v[160:163], v159 offset:2048
	ds_read_b128 v[164:167], v159 offset:3072
	v_add_u32_e32 v159, s19, v154
	ds_read_b128 v[168:171], v159
	ds_read_b128 v[172:175], v159 offset:1024
	ds_read_b128 v[176:179], v159 offset:2048
	ds_read_b128 v[180:183], v159 offset:3072
	s_add_u32 s46, s46, 0x40000
	s_addc_u32 s47, s47, 0
	s_mov_b32 m0, s58
	ds_read_b128 v[184:187], v158 offset:32768
	ds_read_b128 v[188:191], v158 offset:33792
	ds_read_b128 v[192:195], v158 offset:34816
	ds_read_b128 v[196:199], v158 offset:35840
	ds_read_b128 v[200:203], v158 offset:36864
	ds_read_b128 v[204:207], v158 offset:37888
	ds_read_b128 v[208:211], v158 offset:38912
	ds_read_b128 v[212:215], v158 offset:39936
	global_load_lds_dwordx4 v136, s[46:47]
	s_mov_b32 m0, s59
	s_nop 0
	global_load_lds_dwordx4 v132, s[46:47]
	s_waitcnt vmcnt(8)
	s_waitcnt lgkmcnt(0)
	s_barrier
	s_waitcnt lgkmcnt(0)
	v_mfma_f32_16x16x32_bf16 v[126:129], v[146:149], v[184:187], v[126:129]
	v_mfma_f32_16x16x32_bf16 v[122:125], v[160:163], v[184:187], v[122:125]
	v_mfma_f32_16x16x32_bf16 v[114:117], v[146:149], v[192:195], v[114:117]
	v_mfma_f32_16x16x32_bf16 v[106:109], v[160:163], v[192:195], v[106:109]
	v_mfma_f32_16x16x32_bf16 v[98:101], v[146:149], v[200:203], v[98:101]
	v_mfma_f32_16x16x32_bf16 v[90:93], v[160:163], v[200:203], v[90:93]
	v_mfma_f32_16x16x32_bf16 v[82:85], v[146:149], v[208:211], v[82:85]
	v_mfma_f32_16x16x32_bf16 v[74:77], v[160:163], v[208:211], v[74:77]
	v_mfma_f32_16x16x32_bf16 v[126:129], v[150:153], v[188:191], v[126:129]
	v_mfma_f32_16x16x32_bf16 v[122:125], v[164:167], v[188:191], v[122:125]
	v_mfma_f32_16x16x32_bf16 v[114:117], v[150:153], v[196:199], v[114:117]
	v_mfma_f32_16x16x32_bf16 v[106:109], v[164:167], v[196:199], v[106:109]
	v_mfma_f32_16x16x32_bf16 v[98:101], v[150:153], v[204:207], v[98:101]
	v_mfma_f32_16x16x32_bf16 v[90:93], v[164:167], v[204:207], v[90:93]
	v_mfma_f32_16x16x32_bf16 v[82:85], v[150:153], v[212:215], v[82:85]
	v_mfma_f32_16x16x32_bf16 v[74:77], v[164:167], v[212:215], v[74:77]
	v_mfma_f32_16x16x32_bf16 v[118:121], v[168:171], v[184:187], v[118:121]
	v_mfma_f32_16x16x32_bf16 v[110:113], v[176:179], v[184:187], v[110:113]
	v_mfma_f32_16x16x32_bf16 v[102:105], v[168:171], v[192:195], v[102:105]
	v_mfma_f32_16x16x32_bf16 v[94:97], v[176:179], v[192:195], v[94:97]
	v_mfma_f32_16x16x32_bf16 v[86:89], v[168:171], v[200:203], v[86:89]
	v_mfma_f32_16x16x32_bf16 v[78:81], v[176:179], v[200:203], v[78:81]
	v_mfma_f32_16x16x32_bf16 v[70:73], v[168:171], v[208:211], v[70:73]
	v_mfma_f32_16x16x32_bf16 v[66:69], v[176:179], v[208:211], v[66:69]
	v_mfma_f32_16x16x32_bf16 v[118:121], v[172:175], v[188:191], v[118:121]
	v_mfma_f32_16x16x32_bf16 v[110:113], v[180:183], v[188:191], v[110:113]
	v_mfma_f32_16x16x32_bf16 v[102:105], v[172:175], v[196:199], v[102:105]
	v_mfma_f32_16x16x32_bf16 v[94:97], v[180:183], v[196:199], v[94:97]
	v_mfma_f32_16x16x32_bf16 v[86:89], v[172:175], v[204:207], v[86:89]
	v_mfma_f32_16x16x32_bf16 v[78:81], v[180:183], v[204:207], v[78:81]
	v_mfma_f32_16x16x32_bf16 v[70:73], v[172:175], v[212:215], v[70:73]
	v_mfma_f32_16x16x32_bf16 v[66:69], v[180:183], v[212:215], v[66:69]
	s_barrier
; #define PG8_STAGE(bufoff, gbase, voff) do { _Pragma("unroll") for (int _i = 0; _i < 2; ++_i) \
;         __builtin_amdgcn_global_load_lds((const unsigned*)((const char*)(gbase) + (voff)[_i]), (PG8_LAS unsigned*)(lds + (bufoff) + ldsw + _i * 8192), 16, 0, 0); } while (0)
; #define PG8_LDA(dst, b, h) do { _Pragma("unroll") for (int m = 0; m < 4; ++m) _Pragma("unroll") for (int k = 0; k < 2; ++k) dst[m][k] = *(const PG8_LAS bf16x8*)(lds + PG8_SA(b, h) + aoff + m * 2048 + k * 1024); } while (0)
; #define PG8_MMA(ai, bj, At, Bt) do { __builtin_amdgcn_s_setprio(1); _Pragma("unroll") for (int m = 0; m < 4; ++m) _Pragma("unroll") for (int n = 0; n < 2; ++n) _Pragma("unroll") for (int k = 0; k < 2; ++k) \
;         acc[ai][bj][m][n] = __builtin_amdgcn_mfma_f32_16x16x32_bf16(Bt[n][k], At[m][k], acc[ai][bj][m][n], 0, 0, 0); __builtin_amdgcn_s_setprio(0); } while (0)
; #define PG8_WAIT_V(n) asm volatile("s_waitcnt vmcnt(" #n ")" ::: "memory")
; #define PG8_WAIT_L(n) asm volatile("s_waitcnt lgkmcnt(" #n ")" ::: "memory")
; #define PG8_BAR __builtin_amdgcn_s_barrier()
; #define PG8_SCHED __builtin_amdgcn_sched_barrier(0)
; template <class Epi, class Sched, bool ALIGN_EPI = false, bool SP2 = false>
; __device__ __forceinline__ void gemm_phase(PG8_LAS unsigned char* lds, const Gemm g, const Sched& S, const Epi& E) {
;     ...
;         for (int t = 0; t < nt; t += 2) {
;             const bool last = (t == nt - 2);
;             const char* a1 = cA + (size_t)(t + 1) * kstep;
;             const char* a2 = last ? nA : cA + (size_t)(t + 2) * kstep; const char* b2 = last ? nB : cB + (size_t)(t + 2) * kstep;
;     ...
;             PG8_LDA(At, 1, 1); PG8_STAGE(PG8_SB(1, 0), b3, voffB); PG8_STAGE(PG8_SB(1, 1), b3 + hB, voffB); PG8_STAGE(PG8_SA(1, 0), a3, voffA);
;             PG8_WAIT_V(8); PG8_WAIT_L(0); PG8_BAR; PG8_MMA(1, 0, At, B0); PG8_MMA(1, 1, At, B1); PG8_BAR; PG8_SCHED;
	s_add_i32 s18, s18, s52
	s_mov_b32 m0, s18
	ds_read_b128 v[184:187], v158 offset:49152
	ds_read_b128 v[188:191], v158 offset:50176
	ds_read_b128 v[192:195], v158 offset:51200
	ds_read_b128 v[196:199], v158 offset:52224
	ds_read_b128 v[200:203], v158 offset:53248
	ds_read_b128 v[204:207], v158 offset:54272
	ds_read_b128 v[208:211], v158 offset:55296
	ds_read_b128 v[212:215], v158 offset:56320
	global_load_lds_dwordx4 v134, s[78:79]
	s_add_i32 m0, s18, 0x2000
	s_add_u32 s44, s44, 0x40080
	s_addc_u32 s45, s45, 0
	s_add_i32 s18, s19, s52
	global_load_lds_dwordx4 v130, s[78:79]
	s_mov_b32 m0, s18
	s_nop 0
	global_load_lds_dwordx4 v134, s[44:45]
	s_add_i32 m0, s18, 0x2000
	s_nop 0
	global_load_lds_dwordx4 v130, s[44:45]
	s_mov_b32 m0, s60
	s_nop 0
	global_load_lds_dwordx4 v136, s[80:81]
	s_mov_b32 m0, s61
	s_nop 0
	global_load_lds_dwordx4 v132, s[80:81]
	s_waitcnt vmcnt(8)
	s_waitcnt lgkmcnt(0)
	s_barrier
	s_waitcnt lgkmcnt(0)
	v_mfma_f32_16x16x32_bf16 v[62:65], v[146:149], v[184:187], v[62:65]
	v_mfma_f32_16x16x32_bf16 v[58:61], v[160:163], v[184:187], v[58:61]
	v_mfma_f32_16x16x32_bf16 v[50:53], v[146:149], v[192:195], v[50:53]
	v_mfma_f32_16x16x32_bf16 v[42:45], v[160:163], v[192:195], v[42:45]
	v_mfma_f32_16x16x32_bf16 v[34:37], v[146:149], v[200:203], v[34:37]
	v_mfma_f32_16x16x32_bf16 v[26:29], v[160:163], v[200:203], v[26:29]
	v_mfma_f32_16x16x32_bf16 v[18:21], v[146:149], v[208:211], v[18:21]
	v_mfma_f32_16x16x32_bf16 v[10:13], v[160:163], v[208:211], v[10:13]
	v_mfma_f32_16x16x32_bf16 v[62:65], v[150:153], v[188:191], v[62:65]
	v_mfma_f32_16x16x32_bf16 v[58:61], v[164:167], v[188:191], v[58:61]
	v_mfma_f32_16x16x32_bf16 v[50:53], v[150:153], v[196:199], v[50:53]
	v_mfma_f32_16x16x32_bf16 v[42:45], v[164:167], v[196:199], v[42:45]
	v_mfma_f32_16x16x32_bf16 v[34:37], v[150:153], v[204:207], v[34:37]
	v_mfma_f32_16x16x32_bf16 v[26:29], v[164:167], v[204:207], v[26:29]
	v_mfma_f32_16x16x32_bf16 v[18:21], v[150:153], v[212:215], v[18:21]
	v_mfma_f32_16x16x32_bf16 v[10:13], v[164:167], v[212:215], v[10:13]
	v_mfma_f32_16x16x32_bf16 v[54:57], v[168:171], v[184:187], v[54:57]
	v_mfma_f32_16x16x32_bf16 v[46:49], v[176:179], v[184:187], v[46:49]
	v_mfma_f32_16x16x32_bf16 v[38:41], v[168:171], v[192:195], v[38:41]
	v_mfma_f32_16x16x32_bf16 v[30:33], v[176:179], v[192:195], v[30:33]
	v_mfma_f32_16x16x32_bf16 v[22:25], v[168:171], v[200:203], v[22:25]
	v_mfma_f32_16x16x32_bf16 v[14:17], v[176:179], v[200:203], v[14:17]
	v_mfma_f32_16x16x32_bf16 v[6:9], v[168:171], v[208:211], v[6:9]
	v_mfma_f32_16x16x32_bf16 v[2:5], v[176:179], v[208:211], v[2:5]
	v_mfma_f32_16x16x32_bf16 v[54:57], v[172:175], v[188:191], v[54:57]
	v_mfma_f32_16x16x32_bf16 v[46:49], v[180:183], v[188:191], v[46:49]
	v_mfma_f32_16x16x32_bf16 v[38:41], v[172:175], v[196:199], v[38:41]
	v_mfma_f32_16x16x32_bf16 v[30:33], v[180:183], v[196:199], v[30:33]
	v_mfma_f32_16x16x32_bf16 v[22:25], v[172:175], v[204:207], v[22:25]
	v_mfma_f32_16x16x32_bf16 v[14:17], v[180:183], v[204:207], v[14:17]
	v_mfma_f32_16x16x32_bf16 v[6:9], v[172:175], v[212:215], v[6:9]
	v_mfma_f32_16x16x32_bf16 v[2:5], v[180:183], v[212:215], v[2:5]
	s_barrier
	s_add_i32 s72, s72, 2
	s_add_u32 s42, s42, 0x100
	s_addc_u32 s43, s43, 0
	s_add_u32 s70, s70, 0x100
	s_addc_u32 s71, s71, 0
	s_cmp_gt_u32 s72, 13
	s_mov_b32 s101, 0

; #define PG8_STAGE(bufoff, gbase, voff) do { _Pragma("unroll") for (int _i = 0; _i < 2; ++_i) \
;         __builtin_amdgcn_global_load_lds((const unsigned*)((const char*)(gbase) + (voff)[_i]), (PG8_LAS unsigned*)(lds + (bufoff) + ldsw + _i * 8192), 16, 0, 0); } while (0)
; #define PG8_WAIT_V(n) asm volatile("s_waitcnt vmcnt(" #n ")" ::: "memory")
; #define PG8_BAR __builtin_amdgcn_s_barrier()
; template <class Epi, class Sched, bool ALIGN_EPI = false, bool SP2 = false>
; __device__ __forceinline__ void gemm_phase(PG8_LAS unsigned char* lds, const Gemm g, const Sched& S, const Epi& E) {
;     ...
;     const char* cA = (const char*)g.A + (size_t)cur.pm * tA + (size_t)cur.pn * pnA; const char* cB = (const char*)g.Bt + (size_t)cur.pn * tB;
;     S.a_ready(cur);
;     if constexpr (SP2) {
;         PG8_STAGE(PG8_SB(0, 0), cB, voffB); PG8_STAGE(PG8_SB(0, 1), cB + hB, voffB); PG8_STAGE(PG8_SA(0, 0), cA, voffA); PG8_STAGE(PG8_SA(0, 1), cA + hA, voffA);
;         if (wr == 1) PG8_BAR;
;         PG8_WAIT_V(2); PG8_BAR;
;         PG8_STAGE(PG8_SB(1, 0), cB + kstep, voffB); PG8_STAGE(PG8_SA(1, 0), cA + kstep, voffA); PG8_STAGE(PG8_SB(1, 1), cB + hB + kstep, voffB);
;         PG8_WAIT_V(6); PG8_BAR;
.LBB0_878:
	s_add_u32 s8, s6, 0xd800000
	s_addc_u32 s9, s7, 0
	s_add_u32 s14, s6, 0x9800000
	s_addc_u32 s15, s7, 0
	s_lshl_b32 s6, s16, 5
	s_mov_b64 s[16:17], 0x80
	s_and_b32 s19, s6, 0x60
	s_add_i32 m0, s43, 0x18000
	v_lshl_add_u64 v[8:9], v[8:9], 0, s[16:17]
	s_lshl_b32 s18, s22, 13
	s_lshl_b32 s23, s19, 7
	s_waitcnt vmcnt(2)
	s_barrier
	global_load_lds_dwordx4 v[8:9], off
	v_lshl_add_u64 v[6:7], v[6:7], 0, s[16:17]
	s_add_i32 m0, s43, 0x1a000
	s_add_i32 s63, s43, 0x8000
	s_add_i32 s64, s43, 0xa000
	global_load_lds_dwordx4 v[6:7], off
	v_lshl_add_u64 v[2:3], v[2:3], 0, s[16:17]
	s_mov_b32 m0, s63
	s_add_u32 s6, s46, 0x80080
	global_load_lds_dwordx4 v[2:3], off
	v_lshl_add_u64 v[2:3], v[4:5], 0, s[16:17]
	s_mov_b32 m0, s64
	s_addc_u32 s7, s47, 0
	global_load_lds_dwordx4 v[2:3], off
	s_add_i32 m0, s43, 0x1c000
	v_lshl_add_u64 v[2:3], s[6:7], 0, v[150:151]
	global_load_lds_dwordx4 v[2:3], off
	v_lshl_add_u64 v[2:3], s[6:7], 0, v[146:147]
	s_add_i32 m0, s43, 0x1e000
	s_cmpk_lt_u32 s21, 0x100
	global_load_lds_dwordx4 v[2:3], off
	v_lshrrev_b32_e32 v3, 1, v11
	v_and_b32_e32 v3, 24, v3
	v_and_b32_e32 v2, 15, v11
	v_lshlrev_b32_e32 v4, 1, v3
	v_lshl_or_b32 v1, s22, 6, v2
	v_lshl_or_b32 v2, v2, 6, v4
	v_lshlrev_b32_e32 v4, 2, v11
	v_and_b32_e32 v4, 32, v4
	v_bitop3_b32 v5, v2, s18, v4 bitop3:0xde
	v_bitop3_b32 v170, v2, s23, v4 bitop3:0xde
	v_lshlrev_b32_e32 v2, 15, v15
	v_and_b32_e32 v2, 0xffff0000, v2
	v_or_b32_e32 v171, s19, v3
	v_lshl_add_u32 v2, v14, 12, v2
	v_and_b32_e32 v3, 1, v15
	v_lshl_or_b32 v2, v3, 6, v2
	v_lshl_add_u32 v154, v16, 1, v2
	v_lshlrev_b32_e32 v2, 15, v10
	v_and_b32_e32 v2, 0xffff0000, v2
	s_waitcnt vmcnt(6)
	v_lshl_add_u32 v2, v12, 12, v2
	v_and_b32_e32 v3, 1, v10
	s_sext_i32_i8 s69, s20
	s_cselect_b64 s[20:21], -1, 0
	v_lshl_or_b32 v2, v3, 6, v2
	s_add_i32 s66, 0, 0x10000
	s_add_i32 s67, 0, 0x14000
	s_waitcnt lgkmcnt(0)
	s_ashr_i32 s65, s50, 31
	v_mov_b32_e32 v155, v151
	v_lshl_add_u32 v156, v13, 1, v2
	v_mov_b32_e32 v157, v151
	v_mov_b64_e32 v[158:159], 0x200
	v_mov_b64_e32 v[160:161], 0x1ff
	v_add_u32_e32 v172, s66, v170
	v_add_u32_e32 v173, s67, v170
	v_add_u32_e32 v174, 0, v5
	s_barrier
	s_mov_b32 s101, 1
	s_branch .LBB0_881

; #define PG8_STAGE(bufoff, gbase, voff) do { _Pragma("unroll") for (int _i = 0; _i < 2; ++_i) \
;         __builtin_amdgcn_global_load_lds((const unsigned*)((const char*)(gbase) + (voff)[_i]), (PG8_LAS unsigned*)(lds + (bufoff) + ldsw + _i * 8192), 16, 0, 0); } while (0)
; #define PG8_LDA(dst, b, h) do { _Pragma("unroll") for (int m = 0; m < 4; ++m) _Pragma("unroll") for (int k = 0; k < 2; ++k) dst[m][k] = *(const PG8_LAS bf16x8*)(lds + PG8_SA(b, h) + aoff + m * 2048 + k * 1024); } while (0)
; #define PG8_LDB(dst, b, h) do { _Pragma("unroll") for (int n = 0; n < 2; ++n) _Pragma("unroll") for (int k = 0; k < 2; ++k) dst[n][k] = *(const PG8_LAS bf16x8*)(lds + PG8_SB(b, h) + boff + n * 2048 + k * 1024); } while (0)
; #define PG8_MMA(ai, bj, At, Bt) do { __builtin_amdgcn_s_setprio(1); _Pragma("unroll") for (int m = 0; m < 4; ++m) _Pragma("unroll") for (int n = 0; n < 2; ++n) _Pragma("unroll") for (int k = 0; k < 2; ++k) \
;         acc[ai][bj][m][n] = __builtin_amdgcn_mfma_f32_16x16x32_bf16(Bt[n][k], At[m][k], acc[ai][bj][m][n], 0, 0, 0); __builtin_amdgcn_s_setprio(0); } while (0)
; template <class Epi, class Sched, bool ALIGN_EPI = false, bool SP2 = false>
; __device__ __forceinline__ void gemm_phase(PG8_LAS unsigned char* lds, const Gemm g, const Sched& S, const Epi& E) {
;     ...
;     for (;;) {
;         const bool has_next = S.next(ui + 1, nxt);
;         const char* nA = has_next ? (const char*)g.A + (size_t)nxt.pm * tA + (size_t)nxt.pn * pnA : cA; const char* nB = has_next ? (const char*)g.Bt + (size_t)nxt.pn * tB : cB;
; #pragma nounroll
;         for (int t = 0; t < nt; t += 2) {
;             const bool last = (t == nt - 2);
;             const char* a1 = cA + (size_t)(t + 1) * kstep;
;             const char* a2 = last ? nA : cA + (size_t)(t + 2) * kstep; const char* b2 = last ? nB : cB + (size_t)(t + 2) * kstep;
;             const char* a3 = a2 + kstep; const char* b3 = b2 + kstep;
;             if (last && has_next) S.a_ready(nxt);
;             if constexpr (SP2) {
;             PG8_LDB(B0, 0, 0); PG8_LDB(B1, 0, 1); PG8_SCHED; PG8_LDA(At, 0, 0); PG8_STAGE(PG8_SA(1, 1), a1 + hA, voffA);
;             PG8_WAIT_V(8); PG8_WAIT_L(0); PG8_BAR; PG8_MMA(0, 0, At, B0); PG8_MMA(0, 1, At, B1); PG8_BAR; PG8_SCHED;
;             PG8_LDA(At, 0, 1); PG8_STAGE(PG8_SB(0, 0), b2, voffB); PG8_STAGE(PG8_SB(0, 1), b2 + hB, voffB); PG8_STAGE(PG8_SA(0, 0), a2, voffA);
.LBB0_887:
	s_ashr_i32 s25, s24, 31
	s_lshl_b64 s[38:39], s[24:25], 20
	s_add_u32 s38, s33, s38
	s_addc_u32 s39, s51, s39
	s_and_b64 s[40:41], s[6:7], exec
	s_cselect_b32 s25, s39, s45
	s_cselect_b32 s70, s38, s44
	s_ashr_i32 s23, s22, 31
	s_lshl_b64 s[40:41], s[22:23], 20
	s_add_u32 s40, s52, s40
	s_addc_u32 s41, s53, s41
	s_and_b64 s[48:49], s[6:7], exec
	s_cselect_b32 s23, s41, s47
	s_cselect_b32 s71, s40, s46
	s_add_u32 s44, s44, 0x80080
	s_addc_u32 s45, s45, 0
	s_add_u32 s72, s46, 0x100
	v_mov_b32_e32 v2, 0
	s_addc_u32 s73, s47, 0
	s_mov_b32 s74, -2
	v_mov_b32_e32 v3, v2
	ds_read_b128 v[130:133], v172
	ds_read_b128 v[134:137], v172 offset:1024
	ds_read_b128 v[138:141], v172 offset:2048
	ds_read_b128 v[142:145], v172 offset:3072
	ds_read_b128 v[162:165], v173
	ds_read_b128 v[166:169], v173 offset:1024
	ds_read_b128 v[176:179], v173 offset:2048
	ds_read_b128 v[180:183], v173 offset:3072
	s_add_u32 s18, s44, 0xfff80080
	s_addc_u32 s19, s45, -1
	s_cmp_eq_u32 s74, 28
	s_cselect_b32 s49, s25, s19
	s_cselect_b32 s48, s70, s18
	s_cselect_b32 s47, s23, s73
	s_cselect_b32 s46, s71, s72
	s_add_i32 m0, s43, 0xc000
	ds_read_b128 v[184:187], v174
	ds_read_b128 v[188:191], v174 offset:1024
	ds_read_b128 v[192:195], v174 offset:2048
	ds_read_b128 v[196:199], v174 offset:3072
	ds_read_b128 v[200:203], v174 offset:4096
	ds_read_b128 v[204:207], v174 offset:5120
	ds_read_b128 v[208:211], v174 offset:6144
	ds_read_b128 v[212:215], v174 offset:7168
	global_load_lds_dwordx4 v154, s[44:45]
	s_add_i32 m0, s43, 0xe000
	s_nop 0
	global_load_lds_dwordx4 v156, s[44:45]
	s_cmp_eq_u32 s101, 0
	s_cbranch_scc1 .Lfw_2_0
	s_waitcnt vmcnt(8)
.Lfw_2_0:
	s_waitcnt lgkmcnt(0)
	s_barrier
	s_waitcnt lgkmcnt(0)
	v_mfma_f32_16x16x32_bf16 v[126:129], v[130:133], v[184:187], 0
	v_mfma_f32_16x16x32_bf16 v[122:125], v[138:141], v[184:187], 0
	v_mfma_f32_16x16x32_bf16 v[110:113], v[130:133], v[192:195], 0
	v_mfma_f32_16x16x32_bf16 v[106:109], v[138:141], v[192:195], 0
	v_mfma_f32_16x16x32_bf16 v[94:97], v[130:133], v[200:203], 0
	v_mfma_f32_16x16x32_bf16 v[90:93], v[138:141], v[200:203], 0
	v_mfma_f32_16x16x32_bf16 v[78:81], v[130:133], v[208:211], 0
	v_mfma_f32_16x16x32_bf16 v[74:77], v[138:141], v[208:211], 0
	v_mfma_f32_16x16x32_bf16 v[126:129], v[134:137], v[188:191], v[126:129]
	v_mfma_f32_16x16x32_bf16 v[122:125], v[142:145], v[188:191], v[122:125]
	v_mfma_f32_16x16x32_bf16 v[110:113], v[134:137], v[196:199], v[110:113]
	v_mfma_f32_16x16x32_bf16 v[106:109], v[142:145], v[196:199], v[106:109]
	v_mfma_f32_16x16x32_bf16 v[94:97], v[134:137], v[204:207], v[94:97]
	v_mfma_f32_16x16x32_bf16 v[90:93], v[142:145], v[204:207], v[90:93]
	v_mfma_f32_16x16x32_bf16 v[78:81], v[134:137], v[212:215], v[78:81]
	v_mfma_f32_16x16x32_bf16 v[74:77], v[142:145], v[212:215], v[74:77]
	v_mfma_f32_16x16x32_bf16 v[118:121], v[162:165], v[184:187], 0
	v_mfma_f32_16x16x32_bf16 v[114:117], v[176:179], v[184:187], 0
	v_mfma_f32_16x16x32_bf16 v[102:105], v[162:165], v[192:195], 0
	v_mfma_f32_16x16x32_bf16 v[98:101], v[176:179], v[192:195], 0
	v_mfma_f32_16x16x32_bf16 v[86:89], v[162:165], v[200:203], 0
	v_mfma_f32_16x16x32_bf16 v[82:85], v[176:179], v[200:203], 0
	v_mfma_f32_16x16x32_bf16 v[70:73], v[162:165], v[208:211], 0
	v_mfma_f32_16x16x32_bf16 v[66:69], v[176:179], v[208:211], 0
	v_mfma_f32_16x16x32_bf16 v[118:121], v[166:169], v[188:191], v[118:121]
	v_mfma_f32_16x16x32_bf16 v[114:117], v[180:183], v[188:191], v[114:117]
	v_mfma_f32_16x16x32_bf16 v[102:105], v[166:169], v[196:199], v[102:105]
	v_mfma_f32_16x16x32_bf16 v[98:101], v[180:183], v[196:199], v[98:101]
	v_mfma_f32_16x16x32_bf16 v[86:89], v[166:169], v[204:207], v[86:89]
	v_mfma_f32_16x16x32_bf16 v[82:85], v[180:183], v[204:207], v[82:85]
	v_mfma_f32_16x16x32_bf16 v[70:73], v[166:169], v[212:215], v[70:73]
	v_mfma_f32_16x16x32_bf16 v[66:69], v[180:183], v[212:215], v[66:69]
	s_barrier
	s_add_i32 s18, s66, s58
	s_add_u32 s78, s46, s16
	s_addc_u32 s79, s47, s17
	s_mov_b32 m0, s18
	ds_read_b128 v[184:187], v174 offset:16384
	ds_read_b128 v[188:191], v174 offset:17408
	ds_read_b128 v[192:195], v174 offset:18432
	ds_read_b128 v[196:199], v174 offset:19456
	ds_read_b128 v[200:203], v174 offset:20480
	ds_read_b128 v[204:207], v174 offset:21504
	ds_read_b128 v[208:211], v174 offset:22528
	ds_read_b128 v[212:215], v174 offset:23552
	global_load_lds_dwordx4 v150, s[46:47]
	s_add_i32 m0, s18, 0x2000
	s_add_u32 s76, s46, 0x80000
	s_addc_u32 s77, s47, 0
	s_add_i32 s18, s67, s58
	global_load_lds_dwordx4 v146, s[46:47]
	s_mov_b32 m0, s18
	s_nop 0
	global_load_lds_dwordx4 v150, s[76:77]
	s_add_i32 m0, s18, 0x2000
	s_nop 0
	global_load_lds_dwordx4 v146, s[76:77]
	s_add_u32 s80, s48, s16
	s_addc_u32 s81, s49, s17
	s_mov_b32 m0, s43
	s_nop 0
	global_load_lds_dwordx4 v152, s[48:49]
	s_mov_b32 m0, s59
	s_nop 0
	global_load_lds_dwordx4 v148, s[48:49]
	s_cmp_eq_u32 s101, 0
	s_cbranch_scc1 .Lfw_2_1
	s_waitcnt vmcnt(8)
; #define PG8_STAGE(bufoff, gbase, voff) do { _Pragma("unroll") for (int _i = 0; _i < 2; ++_i) \
;         __builtin_amdgcn_global_load_lds((const unsigned*)((const char*)(gbase) + (voff)[_i]), (PG8_LAS unsigned*)(lds + (bufoff) + ldsw + _i * 8192), 16, 0, 0); } while (0)
; #define PG8_LDA(dst, b, h) do { _Pragma("unroll") for (int m = 0; m < 4; ++m) _Pragma("unroll") for (int k = 0; k < 2; ++k) dst[m][k] = *(const PG8_LAS bf16x8*)(lds + PG8_SA(b, h) + aoff + m * 2048 + k * 1024); } while (0)
; #define PG8_LDB(dst, b, h) do { _Pragma("unroll") for (int n = 0; n < 2; ++n) _Pragma("unroll") for (int k = 0; k < 2; ++k) dst[n][k] = *(const PG8_LAS bf16x8*)(lds + PG8_SB(b, h) + boff + n * 2048 + k * 1024); } while (0)
; #define PG8_MMA(ai, bj, At, Bt) do { __builtin_amdgcn_s_setprio(1); _Pragma("unroll") for (int m = 0; m < 4; ++m) _Pragma("unroll") for (int n = 0; n < 2; ++n) _Pragma("unroll") for (int k = 0; k < 2; ++k) \
;         acc[ai][bj][m][n] = __builtin_amdgcn_mfma_f32_16x16x32_bf16(Bt[n][k], At[m][k], acc[ai][bj][m][n], 0, 0, 0); __builtin_amdgcn_s_setprio(0); } while (0)
; #define PG8_WAIT_V(n) asm volatile("s_waitcnt vmcnt(" #n ")" ::: "memory")
; #define PG8_WAIT_L(n) asm volatile("s_waitcnt lgkmcnt(" #n ")" ::: "memory")
; #define PG8_BAR __builtin_amdgcn_s_barrier()
; #define PG8_SCHED __builtin_amdgcn_sched_barrier(0)
; template <class Epi, class Sched, bool ALIGN_EPI = false, bool SP2 = false>
; __device__ __forceinline__ void gemm_phase(PG8_LAS unsigned char* lds, const Gemm g, const Sched& S, const Epi& E) {
;     ...
;             PG8_WAIT_V(8); PG8_WAIT_L(0); PG8_BAR; PG8_MMA(1, 0, At, B0); PG8_MMA(1, 1, At, B1); PG8_BAR; PG8_SCHED;
;             PG8_LDB(B0, 1, 0); PG8_LDB(B1, 1, 1); PG8_SCHED; PG8_LDA(At, 1, 0); PG8_STAGE(PG8_SA(0, 1), a2 + hA, voffA);
;             PG8_WAIT_V(8); PG8_WAIT_L(0); PG8_BAR; PG8_MMA(0, 0, At, B0); PG8_MMA(0, 1, At, B1); PG8_BAR; PG8_SCHED;
.Lfw_2_1:
	s_waitcnt lgkmcnt(0)
	s_barrier
	s_waitcnt lgkmcnt(0)
	v_mfma_f32_16x16x32_bf16 v[62:65], v[130:133], v[184:187], 0
	v_mfma_f32_16x16x32_bf16 v[58:61], v[138:141], v[184:187], 0
	v_mfma_f32_16x16x32_bf16 v[46:49], v[130:133], v[192:195], 0
	v_mfma_f32_16x16x32_bf16 v[42:45], v[138:141], v[192:195], 0
	v_mfma_f32_16x16x32_bf16 v[30:33], v[130:133], v[200:203], 0
	v_mfma_f32_16x16x32_bf16 v[26:29], v[138:141], v[200:203], 0
	v_mfma_f32_16x16x32_bf16 v[14:17], v[130:133], v[208:211], 0
	v_mfma_f32_16x16x32_bf16 v[10:13], v[138:141], v[208:211], 0
	v_mfma_f32_16x16x32_bf16 v[62:65], v[134:137], v[188:191], v[62:65]
	v_mfma_f32_16x16x32_bf16 v[58:61], v[142:145], v[188:191], v[58:61]
	v_mfma_f32_16x16x32_bf16 v[46:49], v[134:137], v[196:199], v[46:49]
	v_mfma_f32_16x16x32_bf16 v[42:45], v[142:145], v[196:199], v[42:45]
	v_mfma_f32_16x16x32_bf16 v[30:33], v[134:137], v[204:207], v[30:33]
	v_mfma_f32_16x16x32_bf16 v[26:29], v[142:145], v[204:207], v[26:29]
	v_mfma_f32_16x16x32_bf16 v[14:17], v[134:137], v[212:215], v[14:17]
	v_mfma_f32_16x16x32_bf16 v[10:13], v[142:145], v[212:215], v[10:13]
	v_mfma_f32_16x16x32_bf16 v[54:57], v[162:165], v[184:187], 0
	v_mfma_f32_16x16x32_bf16 v[50:53], v[176:179], v[184:187], 0
	v_mfma_f32_16x16x32_bf16 v[38:41], v[162:165], v[192:195], 0
	v_mfma_f32_16x16x32_bf16 v[34:37], v[176:179], v[192:195], 0
	v_mfma_f32_16x16x32_bf16 v[22:25], v[162:165], v[200:203], 0
	v_mfma_f32_16x16x32_bf16 v[18:21], v[176:179], v[200:203], 0
	v_mfma_f32_16x16x32_bf16 v[6:9], v[162:165], v[208:211], 0
	v_mfma_f32_16x16x32_bf16 v[2:5], v[176:179], v[208:211], 0
	v_mfma_f32_16x16x32_bf16 v[54:57], v[166:169], v[188:191], v[54:57]
	v_mfma_f32_16x16x32_bf16 v[50:53], v[180:183], v[188:191], v[50:53]
	v_mfma_f32_16x16x32_bf16 v[38:41], v[166:169], v[196:199], v[38:41]
	v_mfma_f32_16x16x32_bf16 v[34:37], v[180:183], v[196:199], v[34:37]
	v_mfma_f32_16x16x32_bf16 v[22:25], v[166:169], v[204:207], v[22:25]
	v_mfma_f32_16x16x32_bf16 v[18:21], v[180:183], v[204:207], v[18:21]
	v_mfma_f32_16x16x32_bf16 v[6:9], v[166:169], v[212:215], v[6:9]
	v_mfma_f32_16x16x32_bf16 v[2:5], v[180:183], v[212:215], v[2:5]
	s_barrier
	s_add_i32 s18, 0, 0x18000
	s_add_i32 s19, 0, 0x1c000
	v_add_u32_e32 v142, s18, v170
	v_add_u32_e32 v175, s19, v170
	ds_read_b128 v[130:133], v142
	ds_read_b128 v[134:137], v142 offset:1024
	ds_read_b128 v[138:141], v142 offset:2048
	ds_read_b128 v[142:145], v142 offset:3072
	ds_read_b128 v[162:165], v175
	ds_read_b128 v[166:169], v175 offset:1024
	ds_read_b128 v[176:179], v175 offset:2048
	ds_read_b128 v[180:183], v175 offset:3072
	s_add_u32 s48, s48, 0x80000
	s_addc_u32 s49, s49, 0
	s_mov_b32 m0, s60
	ds_read_b128 v[184:187], v174 offset:32768
	ds_read_b128 v[188:191], v174 offset:33792
	ds_read_b128 v[192:195], v174 offset:34816
	ds_read_b128 v[196:199], v174 offset:35840
	ds_read_b128 v[200:203], v174 offset:36864
	ds_read_b128 v[204:207], v174 offset:37888
	ds_read_b128 v[208:211], v174 offset:38912
	ds_read_b128 v[212:215], v174 offset:39936
	global_load_lds_dwordx4 v152, s[48:49]
	s_mov_b32 m0, s61
	s_nop 0
	global_load_lds_dwordx4 v148, s[48:49]
	s_waitcnt vmcnt(8)
	s_waitcnt lgkmcnt(0)
	s_barrier
	s_waitcnt lgkmcnt(0)
	v_mfma_f32_16x16x32_bf16 v[126:129], v[130:133], v[184:187], v[126:129]
	v_mfma_f32_16x16x32_bf16 v[122:125], v[138:141], v[184:187], v[122:125]
	v_mfma_f32_16x16x32_bf16 v[110:113], v[130:133], v[192:195], v[110:113]
	v_mfma_f32_16x16x32_bf16 v[106:109], v[138:141], v[192:195], v[106:109]
	v_mfma_f32_16x16x32_bf16 v[94:97], v[130:133], v[200:203], v[94:97]
	v_mfma_f32_16x16x32_bf16 v[90:93], v[138:141], v[200:203], v[90:93]
	v_mfma_f32_16x16x32_bf16 v[78:81], v[130:133], v[208:211], v[78:81]
	v_mfma_f32_16x16x32_bf16 v[74:77], v[138:141], v[208:211], v[74:77]
	v_mfma_f32_16x16x32_bf16 v[126:129], v[134:137], v[188:191], v[126:129]
	v_mfma_f32_16x16x32_bf16 v[122:125], v[142:145], v[188:191], v[122:125]
	v_mfma_f32_16x16x32_bf16 v[110:113], v[134:137], v[196:199], v[110:113]
	v_mfma_f32_16x16x32_bf16 v[106:109], v[142:145], v[196:199], v[106:109]
	v_mfma_f32_16x16x32_bf16 v[94:97], v[134:137], v[204:207], v[94:97]
	v_mfma_f32_16x16x32_bf16 v[90:93], v[142:145], v[204:207], v[90:93]
	v_mfma_f32_16x16x32_bf16 v[78:81], v[134:137], v[212:215], v[78:81]
	v_mfma_f32_16x16x32_bf16 v[74:77], v[142:145], v[212:215], v[74:77]
	v_mfma_f32_16x16x32_bf16 v[118:121], v[162:165], v[184:187], v[118:121]
	v_mfma_f32_16x16x32_bf16 v[114:117], v[176:179], v[184:187], v[114:117]
	v_mfma_f32_16x16x32_bf16 v[102:105], v[162:165], v[192:195], v[102:105]
	v_mfma_f32_16x16x32_bf16 v[98:101], v[176:179], v[192:195], v[98:101]
	v_mfma_f32_16x16x32_bf16 v[86:89], v[162:165], v[200:203], v[86:89]
	v_mfma_f32_16x16x32_bf16 v[82:85], v[176:179], v[200:203], v[82:85]
	v_mfma_f32_16x16x32_bf16 v[70:73], v[162:165], v[208:211], v[70:73]
	v_mfma_f32_16x16x32_bf16 v[66:69], v[176:179], v[208:211], v[66:69]
	v_mfma_f32_16x16x32_bf16 v[118:121], v[166:169], v[188:191], v[118:121]
	v_mfma_f32_16x16x32_bf16 v[114:117], v[180:183], v[188:191], v[114:117]
	v_mfma_f32_16x16x32_bf16 v[102:105], v[166:169], v[196:199], v[102:105]
	v_mfma_f32_16x16x32_bf16 v[98:101], v[180:183], v[196:199], v[98:101]
	v_mfma_f32_16x16x32_bf16 v[86:89], v[166:169], v[204:207], v[86:89]
	v_mfma_f32_16x16x32_bf16 v[82:85], v[180:183], v[204:207], v[82:85]
	v_mfma_f32_16x16x32_bf16 v[70:73], v[166:169], v[212:215], v[70:73]
	v_mfma_f32_16x16x32_bf16 v[66:69], v[180:183], v[212:215], v[66:69]
	s_barrier
; #define PG8_STAGE(bufoff, gbase, voff) do { _Pragma("unroll") for (int _i = 0; _i < 2; ++_i) \
;         __builtin_amdgcn_global_load_lds((const unsigned*)((const char*)(gbase) + (voff)[_i]), (PG8_LAS unsigned*)(lds + (bufoff) + ldsw + _i * 8192), 16, 0, 0); } while (0)
; #define PG8_LDA(dst, b, h) do { _Pragma("unroll") for (int m = 0; m < 4; ++m) _Pragma("unroll") for (int k = 0; k < 2; ++k) dst[m][k] = *(const PG8_LAS bf16x8*)(lds + PG8_SA(b, h) + aoff + m * 2048 + k * 1024); } while (0)
; #define PG8_MMA(ai, bj, At, Bt) do { __builtin_amdgcn_s_setprio(1); _Pragma("unroll") for (int m = 0; m < 4; ++m) _Pragma("unroll") for (int n = 0; n < 2; ++n) _Pragma("unroll") for (int k = 0; k < 2; ++k) \
;         acc[ai][bj][m][n] = __builtin_amdgcn_mfma_f32_16x16x32_bf16(Bt[n][k], At[m][k], acc[ai][bj][m][n], 0, 0, 0); __builtin_amdgcn_s_setprio(0); } while (0)
; #define PG8_WAIT_V(n) asm volatile("s_waitcnt vmcnt(" #n ")" ::: "memory")
; #define PG8_WAIT_L(n) asm volatile("s_waitcnt lgkmcnt(" #n ")" ::: "memory")
; #define PG8_BAR __builtin_amdgcn_s_barrier()
; #define PG8_SCHED __builtin_amdgcn_sched_barrier(0)
; template <class Epi, class Sched, bool ALIGN_EPI = false, bool SP2 = false>
; __device__ __forceinline__ void gemm_phase(PG8_LAS unsigned char* lds, const Gemm g, const Sched& S, const Epi& E) {
;     ...
;         for (int t = 0; t < nt; t += 2) {
;             const bool last = (t == nt - 2);
;             const char* a1 = cA + (size_t)(t + 1) * kstep;
;             const char* a2 = last ? nA : cA + (size_t)(t + 2) * kstep; const char* b2 = last ? nB : cB + (size_t)(t + 2) * kstep;
;     ...
;             PG8_LDA(At, 1, 1); PG8_STAGE(PG8_SB(1, 0), b3, voffB); PG8_STAGE(PG8_SB(1, 1), b3 + hB, voffB); PG8_STAGE(PG8_SA(1, 0), a3, voffA);
;             PG8_WAIT_V(8); PG8_WAIT_L(0); PG8_BAR; PG8_MMA(1, 0, At, B0); PG8_MMA(1, 1, At, B1); PG8_BAR; PG8_SCHED;
	s_add_i32 s18, s18, s58
	s_mov_b32 m0, s18
	ds_read_b128 v[184:187], v174 offset:49152
	ds_read_b128 v[188:191], v174 offset:50176
	ds_read_b128 v[192:195], v174 offset:51200
	ds_read_b128 v[196:199], v174 offset:52224
	ds_read_b128 v[200:203], v174 offset:53248
	ds_read_b128 v[204:207], v174 offset:54272
	ds_read_b128 v[208:211], v174 offset:55296
	ds_read_b128 v[212:215], v174 offset:56320
	global_load_lds_dwordx4 v150, s[78:79]
	s_add_i32 m0, s18, 0x2000
	s_add_u32 s46, s46, 0x80080
	s_addc_u32 s47, s47, 0
	s_add_i32 s18, s19, s58
	global_load_lds_dwordx4 v146, s[78:79]
	s_mov_b32 m0, s18
	s_nop 0
	global_load_lds_dwordx4 v150, s[46:47]
	s_add_i32 m0, s18, 0x2000
	s_nop 0
	global_load_lds_dwordx4 v146, s[46:47]
	s_mov_b32 m0, s63
	s_nop 0
	global_load_lds_dwordx4 v152, s[80:81]
	s_mov_b32 m0, s64
	s_nop 0
	global_load_lds_dwordx4 v148, s[80:81]
	s_waitcnt vmcnt(8)
	s_waitcnt lgkmcnt(0)
	s_barrier
	s_waitcnt lgkmcnt(0)
	v_mfma_f32_16x16x32_bf16 v[62:65], v[130:133], v[184:187], v[62:65]
	v_mfma_f32_16x16x32_bf16 v[58:61], v[138:141], v[184:187], v[58:61]
	v_mfma_f32_16x16x32_bf16 v[46:49], v[130:133], v[192:195], v[46:49]
	v_mfma_f32_16x16x32_bf16 v[42:45], v[138:141], v[192:195], v[42:45]
	v_mfma_f32_16x16x32_bf16 v[30:33], v[130:133], v[200:203], v[30:33]
	v_mfma_f32_16x16x32_bf16 v[26:29], v[138:141], v[200:203], v[26:29]
	v_mfma_f32_16x16x32_bf16 v[14:17], v[130:133], v[208:211], v[14:17]
	v_mfma_f32_16x16x32_bf16 v[10:13], v[138:141], v[208:211], v[10:13]
	v_mfma_f32_16x16x32_bf16 v[62:65], v[134:137], v[188:191], v[62:65]
	v_mfma_f32_16x16x32_bf16 v[58:61], v[142:145], v[188:191], v[58:61]
	v_mfma_f32_16x16x32_bf16 v[46:49], v[134:137], v[196:199], v[46:49]
	v_mfma_f32_16x16x32_bf16 v[42:45], v[142:145], v[196:199], v[42:45]
	v_mfma_f32_16x16x32_bf16 v[30:33], v[134:137], v[204:207], v[30:33]
	v_mfma_f32_16x16x32_bf16 v[26:29], v[142:145], v[204:207], v[26:29]
	v_mfma_f32_16x16x32_bf16 v[14:17], v[134:137], v[212:215], v[14:17]
	v_mfma_f32_16x16x32_bf16 v[10:13], v[142:145], v[212:215], v[10:13]
	v_mfma_f32_16x16x32_bf16 v[54:57], v[162:165], v[184:187], v[54:57]
	v_mfma_f32_16x16x32_bf16 v[50:53], v[176:179], v[184:187], v[50:53]
	v_mfma_f32_16x16x32_bf16 v[38:41], v[162:165], v[192:195], v[38:41]
	v_mfma_f32_16x16x32_bf16 v[34:37], v[176:179], v[192:195], v[34:37]
	v_mfma_f32_16x16x32_bf16 v[22:25], v[162:165], v[200:203], v[22:25]
	v_mfma_f32_16x16x32_bf16 v[18:21], v[176:179], v[200:203], v[18:21]
	v_mfma_f32_16x16x32_bf16 v[6:9], v[162:165], v[208:211], v[6:9]
	v_mfma_f32_16x16x32_bf16 v[2:5], v[176:179], v[208:211], v[2:5]
	v_mfma_f32_16x16x32_bf16 v[54:57], v[166:169], v[188:191], v[54:57]
	v_mfma_f32_16x16x32_bf16 v[50:53], v[180:183], v[188:191], v[50:53]
	v_mfma_f32_16x16x32_bf16 v[38:41], v[166:169], v[196:199], v[38:41]
	v_mfma_f32_16x16x32_bf16 v[34:37], v[180:183], v[196:199], v[34:37]
	v_mfma_f32_16x16x32_bf16 v[22:25], v[166:169], v[204:207], v[22:25]
	v_mfma_f32_16x16x32_bf16 v[18:21], v[180:183], v[204:207], v[18:21]
	v_mfma_f32_16x16x32_bf16 v[6:9], v[166:169], v[212:215], v[6:9]
	v_mfma_f32_16x16x32_bf16 v[2:5], v[180:183], v[212:215], v[2:5]
	s_barrier
	s_add_i32 s74, s74, 2
	s_add_u32 s44, s44, 0x100
	s_addc_u32 s45, s45, 0
	s_add_u32 s72, s72, 0x100
	s_addc_u32 s73, s73, 0
	s_cmp_gt_u32 s74, 29
	s_mov_b32 s101, 0

; #define PG8_STAGE(bufoff, gbase, voff) do { _Pragma("unroll") for (int _i = 0; _i < 2; ++_i) \
;         __builtin_amdgcn_global_load_lds((const unsigned*)((const char*)(gbase) + (voff)[_i]), (PG8_LAS unsigned*)(lds + (bufoff) + ldsw + _i * 8192), 16, 0, 0); } while (0)
; #define PG8_WAIT_V(n) asm volatile("s_waitcnt vmcnt(" #n ")" ::: "memory")
; #define PG8_BAR __builtin_amdgcn_s_barrier()
; template <class Epi, class Sched, bool ALIGN_EPI = false, bool SP2 = false>
; __device__ __forceinline__ void gemm_phase(PG8_LAS unsigned char* lds, const Gemm g, const Sched& S, const Epi& E) {
;     ...
;     const char* cA = (const char*)g.A + (size_t)cur.pm * tA + (size_t)cur.pn * pnA; const char* cB = (const char*)g.Bt + (size_t)cur.pn * tB;
;     S.a_ready(cur);
;     if constexpr (SP2) {
;         PG8_STAGE(PG8_SB(0, 0), cB, voffB); PG8_STAGE(PG8_SB(0, 1), cB + hB, voffB); PG8_STAGE(PG8_SA(0, 0), cA, voffA); PG8_STAGE(PG8_SA(0, 1), cA + hA, voffA);
;         if (wr == 1) PG8_BAR;
;         PG8_WAIT_V(2); PG8_BAR;
;         PG8_STAGE(PG8_SB(1, 0), cB + kstep, voffB); PG8_STAGE(PG8_SA(1, 0), cA + kstep, voffA); PG8_STAGE(PG8_SB(1, 1), cB + hB + kstep, voffB);
;         PG8_WAIT_V(6); PG8_BAR;
.LBB0_953:
	s_add_u32 s16, s6, 0x15800000
	s_addc_u32 s17, s7, 0
	s_add_u32 s20, s6, 0x1e00000
	s_mov_b64 s[22:23], 0x80
	s_addc_u32 s21, s7, 0
	s_and_b32 s67, s9, 3
	s_add_i32 m0, s62, 0x18000
	v_lshl_add_u64 v[8:9], v[8:9], 0, s[22:23]
	s_lshl_b32 s9, s24, 13
	s_lshl_b32 s18, s67, 12
	s_waitcnt vmcnt(2)
	s_barrier
	global_load_lds_dwordx4 v[8:9], off
	v_lshl_add_u64 v[6:7], v[6:7], 0, s[22:23]
	s_add_i32 m0, s62, 0x1a000
	s_add_i32 s69, s62, 0x8000
	s_add_i32 s70, s62, 0xa000
	global_load_lds_dwordx4 v[6:7], off
	v_lshl_add_u64 v[2:3], v[2:3], 0, s[22:23]
	s_mov_b32 m0, s69
	s_add_u32 s6, s50, 0x80080
	global_load_lds_dwordx4 v[2:3], off
	v_lshl_add_u64 v[2:3], v[4:5], 0, s[22:23]
	s_mov_b32 m0, s70
	s_addc_u32 s7, s51, 0
	global_load_lds_dwordx4 v[2:3], off
	s_add_i32 m0, s62, 0x1c000
	v_lshl_add_u64 v[2:3], s[6:7], 0, v[180:181]
	global_load_lds_dwordx4 v[2:3], off
	v_lshl_add_u64 v[2:3], s[6:7], 0, v[184:185]
	s_add_i32 m0, s62, 0x1e000
	s_cmpk_lt_u32 s8, 0x100
	global_load_lds_dwordx4 v[2:3], off
	v_bfe_u32 v3, v10, 4, 2
	v_and_b32_e32 v2, 15, v10
	v_lshlrev_b32_e32 v5, 4, v3
	v_lshl_or_b32 v1, s24, 6, v2
	v_lshl_or_b32 v2, v2, 6, v5
	v_lshlrev_b32_e32 v5, 2, v10
	v_and_b32_e32 v5, 32, v5
	v_bitop3_b32 v6, v2, s9, v5 bitop3:0xde
	v_bitop3_b32 v206, v2, s18, v5 bitop3:0xde
	v_lshlrev_b32_e32 v2, 15, v11
	v_and_b32_e32 v2, 0xffff0000, v2
	v_lshlrev_b32_e32 v4, 3, v3
	v_cmp_eq_u32_e64 s[6:7], 0, v3
	v_lshl_add_u32 v2, v12, 12, v2
	v_and_b32_e32 v3, 1, v11
	v_lshl_or_b32 v2, v3, 6, v2
	v_lshl_add_u32 v186, v13, 1, v2
	v_lshlrev_b32_e32 v2, 15, v14
	v_and_b32_e32 v2, 0xffff0000, v2
	s_waitcnt vmcnt(6)
	v_lshl_add_u32 v2, v15, 12, v2
	v_and_b32_e32 v3, 1, v14
	s_cselect_b64 s[24:25], -1, 0
	v_lshl_or_b32 v2, v3, 6, v2
	s_add_i32 s72, 0, 0x10000
	s_add_i32 s73, 0, 0x14000
	v_lshl_or_b32 v207, s67, 5, v4
	s_waitcnt lgkmcnt(0)
	s_ashr_i32 s71, s66, 31
	v_mov_b32_e32 v187, v181
	v_lshl_add_u32 v188, v16, 1, v2
	v_mov_b32_e32 v189, v181
	v_mov_b64_e32 v[190:191], 0x200
	v_mov_b64_e32 v[192:193], 0x1ff
	v_add_u32_e32 v208, s72, v206
	v_add_u32_e32 v209, s73, v206
	v_add_u32_e32 v210, 0, v6
	v_mbcnt_hi_u32_b32 v211, -1, v222
	s_mov_b32 s74, 0
	s_barrier
	s_mov_b32 s101, 1
	s_branch .LBB0_956

; #define PG8_STAGE(bufoff, gbase, voff) do { _Pragma("unroll") for (int _i = 0; _i < 2; ++_i) \
;         __builtin_amdgcn_global_load_lds((const unsigned*)((const char*)(gbase) + (voff)[_i]), (PG8_LAS unsigned*)(lds + (bufoff) + ldsw + _i * 8192), 16, 0, 0); } while (0)
; #define PG8_LDA(dst, b, h) do { _Pragma("unroll") for (int m = 0; m < 4; ++m) _Pragma("unroll") for (int k = 0; k < 2; ++k) dst[m][k] = *(const PG8_LAS bf16x8*)(lds + PG8_SA(b, h) + aoff + m * 2048 + k * 1024); } while (0)
; #define PG8_LDB(dst, b, h) do { _Pragma("unroll") for (int n = 0; n < 2; ++n) _Pragma("unroll") for (int k = 0; k < 2; ++k) dst[n][k] = *(const PG8_LAS bf16x8*)(lds + PG8_SB(b, h) + boff + n * 2048 + k * 1024); } while (0)
; #define PG8_MMA(ai, bj, At, Bt) do { __builtin_amdgcn_s_setprio(1); _Pragma("unroll") for (int m = 0; m < 4; ++m) _Pragma("unroll") for (int n = 0; n < 2; ++n) _Pragma("unroll") for (int k = 0; k < 2; ++k) \
;         acc[ai][bj][m][n] = __builtin_amdgcn_mfma_f32_16x16x32_bf16(Bt[n][k], At[m][k], acc[ai][bj][m][n], 0, 0, 0); __builtin_amdgcn_s_setprio(0); } while (0)
; template <class Epi, class Sched, bool ALIGN_EPI = false, bool SP2 = false>
; __device__ __forceinline__ void gemm_phase(PG8_LAS unsigned char* lds, const Gemm g, const Sched& S, const Epi& E) {
;     ...
;     for (;;) {
;         const bool has_next = S.next(ui + 1, nxt);
;         const char* nA = has_next ? (const char*)g.A + (size_t)nxt.pm * tA + (size_t)nxt.pn * pnA : cA; const char* nB = has_next ? (const char*)g.Bt + (size_t)nxt.pn * tB : cB;
; #pragma nounroll
;         for (int t = 0; t < nt; t += 2) {
;             const bool last = (t == nt - 2);
;             const char* a1 = cA + (size_t)(t + 1) * kstep;
;             const char* a2 = last ? nA : cA + (size_t)(t + 2) * kstep; const char* b2 = last ? nB : cB + (size_t)(t + 2) * kstep;
;             const char* a3 = a2 + kstep; const char* b3 = b2 + kstep;
;             if (last && has_next) S.a_ready(nxt);
;             if constexpr (SP2) {
;             PG8_LDB(B0, 0, 0); PG8_LDB(B1, 0, 1); PG8_SCHED; PG8_LDA(At, 0, 0); PG8_STAGE(PG8_SA(1, 1), a1 + hA, voffA);
;             PG8_WAIT_V(8); PG8_WAIT_L(0); PG8_BAR; PG8_MMA(0, 0, At, B0); PG8_MMA(0, 1, At, B1); PG8_BAR; PG8_SCHED;
;             PG8_LDA(At, 0, 1); PG8_STAGE(PG8_SB(0, 0), b2, voffB); PG8_STAGE(PG8_SB(0, 1), b2 + hB, voffB); PG8_STAGE(PG8_SA(0, 0), a2, voffA);
.LBB0_962:
	s_ashr_i32 s41, s40, 31
	s_lshl_b64 s[42:43], s[40:41], 20
	s_add_u32 s42, s33, s42
	s_addc_u32 s43, s58, s43
	s_and_b64 s[44:45], s[8:9], exec
	s_cselect_b32 s41, s43, s49
	s_cselect_b32 s47, s42, s48
	s_ashr_i32 s39, s38, 31
	s_lshl_b64 s[44:45], s[38:39], 20
	s_add_u32 s44, s59, s44
	s_addc_u32 s45, s60, s45
	s_and_b64 s[52:53], s[8:9], exec
	s_cselect_b32 s39, s45, s51
	s_cselect_b32 s75, s44, s50
	s_add_u32 s48, s48, 0x80080
	s_addc_u32 s49, s49, 0
	s_add_u32 s76, s50, 0x100
	v_mov_b32_e32 v2, 0
	s_addc_u32 s77, s51, 0
	s_mov_b32 s78, -2
	s_waitcnt lgkmcnt(0)
	v_mov_b32_e32 v3, v2
	ds_read_b128 v[130:133], v208
	ds_read_b128 v[134:137], v208 offset:1024
	ds_read_b128 v[138:141], v208 offset:2048
	ds_read_b128 v[142:145], v208 offset:3072
	ds_read_b128 v[146:149], v209
	ds_read_b128 v[150:153], v209 offset:1024
	ds_read_b128 v[154:157], v209 offset:2048
	ds_read_b128 v[158:161], v209 offset:3072
	s_add_u32 s18, s48, 0xfff80080
	s_addc_u32 s19, s49, -1
	s_cmp_eq_u32 s78, 28
	s_cselect_b32 s53, s41, s19
	s_cselect_b32 s52, s47, s18
	s_cselect_b32 s51, s39, s77
	s_cselect_b32 s50, s75, s76
	s_add_i32 m0, s62, 0xc000
	ds_read_b128 v[162:165], v210
	ds_read_b128 v[166:169], v210 offset:1024
	ds_read_b128 v[170:173], v210 offset:2048
	ds_read_b128 v[174:177], v210 offset:3072
	ds_read_b128 v[194:197], v210 offset:4096
	ds_read_b128 v[198:201], v210 offset:5120
	ds_read_b128 v[202:205], v210 offset:6144
	ds_read_b128 v[212:215], v210 offset:7168
	global_load_lds_dwordx4 v186, s[48:49]
	s_add_i32 m0, s62, 0xe000
	s_nop 0
	global_load_lds_dwordx4 v188, s[48:49]
	s_cmp_eq_u32 s101, 0
	s_cbranch_scc1 .Lfw_3_0
	s_waitcnt vmcnt(8)
.Lfw_3_0:
	s_waitcnt lgkmcnt(0)
	s_barrier
	s_waitcnt lgkmcnt(0)
	v_mfma_f32_16x16x32_bf16 v[126:129], v[130:133], v[162:165], 0
	v_mfma_f32_16x16x32_bf16 v[122:125], v[138:141], v[162:165], 0
	v_mfma_f32_16x16x32_bf16 v[110:113], v[130:133], v[170:173], 0
	v_mfma_f32_16x16x32_bf16 v[106:109], v[138:141], v[170:173], 0
	v_mfma_f32_16x16x32_bf16 v[94:97], v[130:133], v[194:197], 0
	v_mfma_f32_16x16x32_bf16 v[90:93], v[138:141], v[194:197], 0
	v_mfma_f32_16x16x32_bf16 v[78:81], v[130:133], v[202:205], 0
	v_mfma_f32_16x16x32_bf16 v[74:77], v[138:141], v[202:205], 0
	v_mfma_f32_16x16x32_bf16 v[126:129], v[134:137], v[166:169], v[126:129]
	v_mfma_f32_16x16x32_bf16 v[122:125], v[142:145], v[166:169], v[122:125]
	v_mfma_f32_16x16x32_bf16 v[110:113], v[134:137], v[174:177], v[110:113]
	v_mfma_f32_16x16x32_bf16 v[106:109], v[142:145], v[174:177], v[106:109]
	v_mfma_f32_16x16x32_bf16 v[94:97], v[134:137], v[198:201], v[94:97]
	v_mfma_f32_16x16x32_bf16 v[90:93], v[142:145], v[198:201], v[90:93]
	v_mfma_f32_16x16x32_bf16 v[78:81], v[134:137], v[212:215], v[78:81]
	v_mfma_f32_16x16x32_bf16 v[74:77], v[142:145], v[212:215], v[74:77]
	v_mfma_f32_16x16x32_bf16 v[118:121], v[146:149], v[162:165], 0
	v_mfma_f32_16x16x32_bf16 v[114:117], v[154:157], v[162:165], 0
	v_mfma_f32_16x16x32_bf16 v[102:105], v[146:149], v[170:173], 0
	v_mfma_f32_16x16x32_bf16 v[98:101], v[154:157], v[170:173], 0
	v_mfma_f32_16x16x32_bf16 v[86:89], v[146:149], v[194:197], 0
	v_mfma_f32_16x16x32_bf16 v[82:85], v[154:157], v[194:197], 0
	v_mfma_f32_16x16x32_bf16 v[70:73], v[146:149], v[202:205], 0
	v_mfma_f32_16x16x32_bf16 v[66:69], v[154:157], v[202:205], 0
	v_mfma_f32_16x16x32_bf16 v[118:121], v[150:153], v[166:169], v[118:121]
	v_mfma_f32_16x16x32_bf16 v[114:117], v[158:161], v[166:169], v[114:117]
	v_mfma_f32_16x16x32_bf16 v[102:105], v[150:153], v[174:177], v[102:105]
	v_mfma_f32_16x16x32_bf16 v[98:101], v[158:161], v[174:177], v[98:101]
	v_mfma_f32_16x16x32_bf16 v[86:89], v[150:153], v[198:201], v[86:89]
	v_mfma_f32_16x16x32_bf16 v[82:85], v[158:161], v[198:201], v[82:85]
	v_mfma_f32_16x16x32_bf16 v[70:73], v[150:153], v[212:215], v[70:73]
	v_mfma_f32_16x16x32_bf16 v[66:69], v[158:161], v[212:215], v[66:69]
	s_barrier
	s_add_i32 s18, s72, s61
	s_add_u32 s82, s50, s22
	s_addc_u32 s83, s51, s23
	s_mov_b32 m0, s18
	ds_read_b128 v[162:165], v210 offset:16384
	ds_read_b128 v[166:169], v210 offset:17408
	ds_read_b128 v[170:173], v210 offset:18432
	ds_read_b128 v[174:177], v210 offset:19456
	ds_read_b128 v[194:197], v210 offset:20480
	ds_read_b128 v[198:201], v210 offset:21504
	ds_read_b128 v[202:205], v210 offset:22528
	ds_read_b128 v[212:215], v210 offset:23552
	global_load_lds_dwordx4 v180, s[50:51]
	s_add_i32 m0, s18, 0x2000
	s_add_u32 s80, s50, 0x80000
	s_addc_u32 s81, s51, 0
	s_add_i32 s18, s73, s61
	global_load_lds_dwordx4 v184, s[50:51]
	s_mov_b32 m0, s18
	s_nop 0
	global_load_lds_dwordx4 v180, s[80:81]
	s_add_i32 m0, s18, 0x2000
	s_nop 0
	global_load_lds_dwordx4 v184, s[80:81]
	s_add_u32 s88, s52, s22
	s_addc_u32 s89, s53, s23
	s_mov_b32 m0, s62
	s_nop 0
	global_load_lds_dwordx4 v178, s[52:53]
	s_mov_b32 m0, s63
	s_nop 0
	global_load_lds_dwordx4 v182, s[52:53]
	s_cmp_eq_u32 s101, 0
	s_cbranch_scc1 .Lfw_3_1
	s_waitcnt vmcnt(8)
; #define PG8_STAGE(bufoff, gbase, voff) do { _Pragma("unroll") for (int _i = 0; _i < 2; ++_i) \
;         __builtin_amdgcn_global_load_lds((const unsigned*)((const char*)(gbase) + (voff)[_i]), (PG8_LAS unsigned*)(lds + (bufoff) + ldsw + _i * 8192), 16, 0, 0); } while (0)
; #define PG8_LDA(dst, b, h) do { _Pragma("unroll") for (int m = 0; m < 4; ++m) _Pragma("unroll") for (int k = 0; k < 2; ++k) dst[m][k] = *(const PG8_LAS bf16x8*)(lds + PG8_SA(b, h) + aoff + m * 2048 + k * 1024); } while (0)
; #define PG8_LDB(dst, b, h) do { _Pragma("unroll") for (int n = 0; n < 2; ++n) _Pragma("unroll") for (int k = 0; k < 2; ++k) dst[n][k] = *(const PG8_LAS bf16x8*)(lds + PG8_SB(b, h) + boff + n * 2048 + k * 1024); } while (0)
; #define PG8_MMA(ai, bj, At, Bt) do { __builtin_amdgcn_s_setprio(1); _Pragma("unroll") for (int m = 0; m < 4; ++m) _Pragma("unroll") for (int n = 0; n < 2; ++n) _Pragma("unroll") for (int k = 0; k < 2; ++k) \
;         acc[ai][bj][m][n] = __builtin_amdgcn_mfma_f32_16x16x32_bf16(Bt[n][k], At[m][k], acc[ai][bj][m][n], 0, 0, 0); __builtin_amdgcn_s_setprio(0); } while (0)
; #define PG8_WAIT_V(n) asm volatile("s_waitcnt vmcnt(" #n ")" ::: "memory")
; #define PG8_WAIT_L(n) asm volatile("s_waitcnt lgkmcnt(" #n ")" ::: "memory")
; #define PG8_BAR __builtin_amdgcn_s_barrier()
; #define PG8_SCHED __builtin_amdgcn_sched_barrier(0)
; template <class Epi, class Sched, bool ALIGN_EPI = false, bool SP2 = false>
; __device__ __forceinline__ void gemm_phase(PG8_LAS unsigned char* lds, const Gemm g, const Sched& S, const Epi& E) {
;     ...
;             PG8_WAIT_V(8); PG8_WAIT_L(0); PG8_BAR; PG8_MMA(1, 0, At, B0); PG8_MMA(1, 1, At, B1); PG8_BAR; PG8_SCHED;
;             PG8_LDB(B0, 1, 0); PG8_LDB(B1, 1, 1); PG8_SCHED; PG8_LDA(At, 1, 0); PG8_STAGE(PG8_SA(0, 1), a2 + hA, voffA);
;             PG8_WAIT_V(8); PG8_WAIT_L(0); PG8_BAR; PG8_MMA(0, 0, At, B0); PG8_MMA(0, 1, At, B1); PG8_BAR; PG8_SCHED;
.Lfw_3_1:
	s_waitcnt lgkmcnt(0)
	s_barrier
	s_waitcnt lgkmcnt(0)
	v_mfma_f32_16x16x32_bf16 v[62:65], v[130:133], v[162:165], 0
	v_mfma_f32_16x16x32_bf16 v[58:61], v[138:141], v[162:165], 0
	v_mfma_f32_16x16x32_bf16 v[46:49], v[130:133], v[170:173], 0
	v_mfma_f32_16x16x32_bf16 v[42:45], v[138:141], v[170:173], 0
	v_mfma_f32_16x16x32_bf16 v[30:33], v[130:133], v[194:197], 0
	v_mfma_f32_16x16x32_bf16 v[26:29], v[138:141], v[194:197], 0
	v_mfma_f32_16x16x32_bf16 v[14:17], v[130:133], v[202:205], 0
	v_mfma_f32_16x16x32_bf16 v[10:13], v[138:141], v[202:205], 0
	v_mfma_f32_16x16x32_bf16 v[62:65], v[134:137], v[166:169], v[62:65]
	v_mfma_f32_16x16x32_bf16 v[58:61], v[142:145], v[166:169], v[58:61]
	v_mfma_f32_16x16x32_bf16 v[46:49], v[134:137], v[174:177], v[46:49]
	v_mfma_f32_16x16x32_bf16 v[42:45], v[142:145], v[174:177], v[42:45]
	v_mfma_f32_16x16x32_bf16 v[30:33], v[134:137], v[198:201], v[30:33]
	v_mfma_f32_16x16x32_bf16 v[26:29], v[142:145], v[198:201], v[26:29]
	v_mfma_f32_16x16x32_bf16 v[14:17], v[134:137], v[212:215], v[14:17]
	v_mfma_f32_16x16x32_bf16 v[10:13], v[142:145], v[212:215], v[10:13]
	v_mfma_f32_16x16x32_bf16 v[54:57], v[146:149], v[162:165], 0
	v_mfma_f32_16x16x32_bf16 v[50:53], v[154:157], v[162:165], 0
	v_mfma_f32_16x16x32_bf16 v[38:41], v[146:149], v[170:173], 0
	v_mfma_f32_16x16x32_bf16 v[34:37], v[154:157], v[170:173], 0
	v_mfma_f32_16x16x32_bf16 v[22:25], v[146:149], v[194:197], 0
	v_mfma_f32_16x16x32_bf16 v[18:21], v[154:157], v[194:197], 0
	v_mfma_f32_16x16x32_bf16 v[6:9], v[146:149], v[202:205], 0
	v_mfma_f32_16x16x32_bf16 v[2:5], v[154:157], v[202:205], 0
	v_mfma_f32_16x16x32_bf16 v[54:57], v[150:153], v[166:169], v[54:57]
	v_mfma_f32_16x16x32_bf16 v[50:53], v[158:161], v[166:169], v[50:53]
	v_mfma_f32_16x16x32_bf16 v[38:41], v[150:153], v[174:177], v[38:41]
	v_mfma_f32_16x16x32_bf16 v[34:37], v[158:161], v[174:177], v[34:37]
	v_mfma_f32_16x16x32_bf16 v[22:25], v[150:153], v[198:201], v[22:25]
	v_mfma_f32_16x16x32_bf16 v[18:21], v[158:161], v[198:201], v[18:21]
	v_mfma_f32_16x16x32_bf16 v[6:9], v[150:153], v[212:215], v[6:9]
	v_mfma_f32_16x16x32_bf16 v[2:5], v[158:161], v[212:215], v[2:5]
	s_barrier
	s_add_i32 s18, 0, 0x18000
	s_add_i32 s19, 0, 0x1c000
	v_add_u32_e32 v142, s18, v206
	v_add_u32_e32 v158, s19, v206
	ds_read_b128 v[130:133], v142
	ds_read_b128 v[134:137], v142 offset:1024
	ds_read_b128 v[138:141], v142 offset:2048
	ds_read_b128 v[142:145], v142 offset:3072
	ds_read_b128 v[146:149], v158
	ds_read_b128 v[150:153], v158 offset:1024
	ds_read_b128 v[154:157], v158 offset:2048
	ds_read_b128 v[158:161], v158 offset:3072
	s_add_u32 s52, s52, 0x80000
	s_addc_u32 s53, s53, 0
	s_mov_b32 m0, s64
	ds_read_b128 v[162:165], v210 offset:32768
	ds_read_b128 v[166:169], v210 offset:33792
	ds_read_b128 v[170:173], v210 offset:34816
	ds_read_b128 v[174:177], v210 offset:35840
	ds_read_b128 v[194:197], v210 offset:36864
	ds_read_b128 v[198:201], v210 offset:37888
	ds_read_b128 v[202:205], v210 offset:38912
	ds_read_b128 v[212:215], v210 offset:39936
	global_load_lds_dwordx4 v178, s[52:53]
	s_mov_b32 m0, s65
	s_nop 0
	global_load_lds_dwordx4 v182, s[52:53]
	s_waitcnt vmcnt(8)
	s_waitcnt lgkmcnt(0)
	s_barrier
	s_waitcnt lgkmcnt(0)
	v_mfma_f32_16x16x32_bf16 v[126:129], v[130:133], v[162:165], v[126:129]
	v_mfma_f32_16x16x32_bf16 v[122:125], v[138:141], v[162:165], v[122:125]
	v_mfma_f32_16x16x32_bf16 v[110:113], v[130:133], v[170:173], v[110:113]
	v_mfma_f32_16x16x32_bf16 v[106:109], v[138:141], v[170:173], v[106:109]
	v_mfma_f32_16x16x32_bf16 v[94:97], v[130:133], v[194:197], v[94:97]
	v_mfma_f32_16x16x32_bf16 v[90:93], v[138:141], v[194:197], v[90:93]
	v_mfma_f32_16x16x32_bf16 v[78:81], v[130:133], v[202:205], v[78:81]
	v_mfma_f32_16x16x32_bf16 v[74:77], v[138:141], v[202:205], v[74:77]
	v_mfma_f32_16x16x32_bf16 v[126:129], v[134:137], v[166:169], v[126:129]
	v_mfma_f32_16x16x32_bf16 v[122:125], v[142:145], v[166:169], v[122:125]
	v_mfma_f32_16x16x32_bf16 v[110:113], v[134:137], v[174:177], v[110:113]
	v_mfma_f32_16x16x32_bf16 v[106:109], v[142:145], v[174:177], v[106:109]
	v_mfma_f32_16x16x32_bf16 v[94:97], v[134:137], v[198:201], v[94:97]
	v_mfma_f32_16x16x32_bf16 v[90:93], v[142:145], v[198:201], v[90:93]
	v_mfma_f32_16x16x32_bf16 v[78:81], v[134:137], v[212:215], v[78:81]
	v_mfma_f32_16x16x32_bf16 v[74:77], v[142:145], v[212:215], v[74:77]
	v_mfma_f32_16x16x32_bf16 v[118:121], v[146:149], v[162:165], v[118:121]
	v_mfma_f32_16x16x32_bf16 v[114:117], v[154:157], v[162:165], v[114:117]
	v_mfma_f32_16x16x32_bf16 v[102:105], v[146:149], v[170:173], v[102:105]
	v_mfma_f32_16x16x32_bf16 v[98:101], v[154:157], v[170:173], v[98:101]
	v_mfma_f32_16x16x32_bf16 v[86:89], v[146:149], v[194:197], v[86:89]
	v_mfma_f32_16x16x32_bf16 v[82:85], v[154:157], v[194:197], v[82:85]
	v_mfma_f32_16x16x32_bf16 v[70:73], v[146:149], v[202:205], v[70:73]
	v_mfma_f32_16x16x32_bf16 v[66:69], v[154:157], v[202:205], v[66:69]
	v_mfma_f32_16x16x32_bf16 v[118:121], v[150:153], v[166:169], v[118:121]
	v_mfma_f32_16x16x32_bf16 v[114:117], v[158:161], v[166:169], v[114:117]
	v_mfma_f32_16x16x32_bf16 v[102:105], v[150:153], v[174:177], v[102:105]
	v_mfma_f32_16x16x32_bf16 v[98:101], v[158:161], v[174:177], v[98:101]
	v_mfma_f32_16x16x32_bf16 v[86:89], v[150:153], v[198:201], v[86:89]
	v_mfma_f32_16x16x32_bf16 v[82:85], v[158:161], v[198:201], v[82:85]
	v_mfma_f32_16x16x32_bf16 v[70:73], v[150:153], v[212:215], v[70:73]
	v_mfma_f32_16x16x32_bf16 v[66:69], v[158:161], v[212:215], v[66:69]
	s_barrier
; #define PG8_STAGE(bufoff, gbase, voff) do { _Pragma("unroll") for (int _i = 0; _i < 2; ++_i) \
;         __builtin_amdgcn_global_load_lds((const unsigned*)((const char*)(gbase) + (voff)[_i]), (PG8_LAS unsigned*)(lds + (bufoff) + ldsw + _i * 8192), 16, 0, 0); } while (0)
; #define PG8_LDA(dst, b, h) do { _Pragma("unroll") for (int m = 0; m < 4; ++m) _Pragma("unroll") for (int k = 0; k < 2; ++k) dst[m][k] = *(const PG8_LAS bf16x8*)(lds + PG8_SA(b, h) + aoff + m * 2048 + k * 1024); } while (0)
; #define PG8_MMA(ai, bj, At, Bt) do { __builtin_amdgcn_s_setprio(1); _Pragma("unroll") for (int m = 0; m < 4; ++m) _Pragma("unroll") for (int n = 0; n < 2; ++n) _Pragma("unroll") for (int k = 0; k < 2; ++k) \
;         acc[ai][bj][m][n] = __builtin_amdgcn_mfma_f32_16x16x32_bf16(Bt[n][k], At[m][k], acc[ai][bj][m][n], 0, 0, 0); __builtin_amdgcn_s_setprio(0); } while (0)
; #define PG8_WAIT_V(n) asm volatile("s_waitcnt vmcnt(" #n ")" ::: "memory")
; #define PG8_WAIT_L(n) asm volatile("s_waitcnt lgkmcnt(" #n ")" ::: "memory")
; #define PG8_BAR __builtin_amdgcn_s_barrier()
; #define PG8_SCHED __builtin_amdgcn_sched_barrier(0)
; template <class Epi, class Sched, bool ALIGN_EPI = false, bool SP2 = false>
; __device__ __forceinline__ void gemm_phase(PG8_LAS unsigned char* lds, const Gemm g, const Sched& S, const Epi& E) {
;     ...
;         for (int t = 0; t < nt; t += 2) {
;             const bool last = (t == nt - 2);
;             const char* a1 = cA + (size_t)(t + 1) * kstep;
;             const char* a2 = last ? nA : cA + (size_t)(t + 2) * kstep; const char* b2 = last ? nB : cB + (size_t)(t + 2) * kstep;
;     ...
;             PG8_LDA(At, 1, 1); PG8_STAGE(PG8_SB(1, 0), b3, voffB); PG8_STAGE(PG8_SB(1, 1), b3 + hB, voffB); PG8_STAGE(PG8_SA(1, 0), a3, voffA);
;             PG8_WAIT_V(8); PG8_WAIT_L(0); PG8_BAR; PG8_MMA(1, 0, At, B0); PG8_MMA(1, 1, At, B1); PG8_BAR; PG8_SCHED;
	s_add_i32 s18, s18, s61
	s_mov_b32 m0, s18
	ds_read_b128 v[162:165], v210 offset:49152
	ds_read_b128 v[166:169], v210 offset:50176
	ds_read_b128 v[170:173], v210 offset:51200
	ds_read_b128 v[174:177], v210 offset:52224
	ds_read_b128 v[194:197], v210 offset:53248
	ds_read_b128 v[198:201], v210 offset:54272
	ds_read_b128 v[202:205], v210 offset:55296
	ds_read_b128 v[212:215], v210 offset:56320
	global_load_lds_dwordx4 v180, s[82:83]
	s_add_i32 m0, s18, 0x2000
	s_add_u32 s50, s50, 0x80080
	s_addc_u32 s51, s51, 0
	s_add_i32 s18, s19, s61
	global_load_lds_dwordx4 v184, s[82:83]
	s_mov_b32 m0, s18
	s_nop 0
	global_load_lds_dwordx4 v180, s[50:51]
	s_add_i32 m0, s18, 0x2000
	s_nop 0
	global_load_lds_dwordx4 v184, s[50:51]
	s_mov_b32 m0, s69
	s_nop 0
	global_load_lds_dwordx4 v178, s[88:89]
	s_mov_b32 m0, s70
	s_nop 0
	global_load_lds_dwordx4 v182, s[88:89]
	s_waitcnt vmcnt(8)
	s_waitcnt lgkmcnt(0)
	s_barrier
	s_waitcnt lgkmcnt(0)
	v_mfma_f32_16x16x32_bf16 v[62:65], v[130:133], v[162:165], v[62:65]
	v_mfma_f32_16x16x32_bf16 v[58:61], v[138:141], v[162:165], v[58:61]
	v_mfma_f32_16x16x32_bf16 v[46:49], v[130:133], v[170:173], v[46:49]
	v_mfma_f32_16x16x32_bf16 v[42:45], v[138:141], v[170:173], v[42:45]
	v_mfma_f32_16x16x32_bf16 v[30:33], v[130:133], v[194:197], v[30:33]
	v_mfma_f32_16x16x32_bf16 v[26:29], v[138:141], v[194:197], v[26:29]
	v_mfma_f32_16x16x32_bf16 v[14:17], v[130:133], v[202:205], v[14:17]
	v_mfma_f32_16x16x32_bf16 v[10:13], v[138:141], v[202:205], v[10:13]
	v_mfma_f32_16x16x32_bf16 v[62:65], v[134:137], v[166:169], v[62:65]
	v_mfma_f32_16x16x32_bf16 v[58:61], v[142:145], v[166:169], v[58:61]
	v_mfma_f32_16x16x32_bf16 v[46:49], v[134:137], v[174:177], v[46:49]
	v_mfma_f32_16x16x32_bf16 v[42:45], v[142:145], v[174:177], v[42:45]
	v_mfma_f32_16x16x32_bf16 v[30:33], v[134:137], v[198:201], v[30:33]
	v_mfma_f32_16x16x32_bf16 v[26:29], v[142:145], v[198:201], v[26:29]
	v_mfma_f32_16x16x32_bf16 v[14:17], v[134:137], v[212:215], v[14:17]
	v_mfma_f32_16x16x32_bf16 v[10:13], v[142:145], v[212:215], v[10:13]
	v_mfma_f32_16x16x32_bf16 v[54:57], v[146:149], v[162:165], v[54:57]
	v_mfma_f32_16x16x32_bf16 v[50:53], v[154:157], v[162:165], v[50:53]
	v_mfma_f32_16x16x32_bf16 v[38:41], v[146:149], v[170:173], v[38:41]
	v_mfma_f32_16x16x32_bf16 v[34:37], v[154:157], v[170:173], v[34:37]
	v_mfma_f32_16x16x32_bf16 v[22:25], v[146:149], v[194:197], v[22:25]
	v_mfma_f32_16x16x32_bf16 v[18:21], v[154:157], v[194:197], v[18:21]
	v_mfma_f32_16x16x32_bf16 v[6:9], v[146:149], v[202:205], v[6:9]
	v_mfma_f32_16x16x32_bf16 v[2:5], v[154:157], v[202:205], v[2:5]
	v_mfma_f32_16x16x32_bf16 v[54:57], v[150:153], v[166:169], v[54:57]
	v_mfma_f32_16x16x32_bf16 v[50:53], v[158:161], v[166:169], v[50:53]
	v_mfma_f32_16x16x32_bf16 v[38:41], v[150:153], v[174:177], v[38:41]
	v_mfma_f32_16x16x32_bf16 v[34:37], v[158:161], v[174:177], v[34:37]
	v_mfma_f32_16x16x32_bf16 v[22:25], v[150:153], v[198:201], v[22:25]
	v_mfma_f32_16x16x32_bf16 v[18:21], v[158:161], v[198:201], v[18:21]
	v_mfma_f32_16x16x32_bf16 v[6:9], v[150:153], v[212:215], v[6:9]
	v_mfma_f32_16x16x32_bf16 v[2:5], v[158:161], v[212:215], v[2:5]
	s_barrier
	s_add_i32 s78, s78, 2
	s_add_u32 s48, s48, 0x100
	s_addc_u32 s49, s49, 0
	s_add_u32 s76, s76, 0x100
	s_addc_u32 s77, s77, 0
	s_cmp_gt_u32 s78, 29
	s_mov_b32 s101, 0

; #define PG8_STAGE(bufoff, gbase, voff) do { _Pragma("unroll") for (int _i = 0; _i < 2; ++_i) \
;         __builtin_amdgcn_global_load_lds((const unsigned*)((const char*)(gbase) + (voff)[_i]), (PG8_LAS unsigned*)(lds + (bufoff) + ldsw + _i * 8192), 16, 0, 0); } while (0)
; #define PG8_WAIT_V(n) asm volatile("s_waitcnt vmcnt(" #n ")" ::: "memory")
; #define PG8_BAR __builtin_amdgcn_s_barrier()
; template <class Epi, class Sched, bool ALIGN_EPI = false, bool SP2 = false>
; __device__ __forceinline__ void gemm_phase(PG8_LAS unsigned char* lds, const Gemm g, const Sched& S, const Epi& E) {
;     ...
;     const char* cA = (const char*)g.A + (size_t)cur.pm * tA + (size_t)cur.pn * pnA; const char* cB = (const char*)g.Bt + (size_t)cur.pn * tB;
;     S.a_ready(cur);
;     if constexpr (SP2) {
;         PG8_STAGE(PG8_SB(0, 0), cB, voffB); PG8_STAGE(PG8_SB(0, 1), cB + hB, voffB); PG8_STAGE(PG8_SA(0, 0), cA, voffA); PG8_STAGE(PG8_SA(0, 1), cA + hA, voffA);
;         if (wr == 1) PG8_BAR;
;         PG8_WAIT_V(2); PG8_BAR;
;         PG8_STAGE(PG8_SB(1, 0), cB + kstep, voffB); PG8_STAGE(PG8_SA(1, 0), cA + kstep, voffA); PG8_STAGE(PG8_SB(1, 1), cB + hB + kstep, voffB);
;         PG8_WAIT_V(6); PG8_BAR;
.LBB0_1042:
	s_add_u32 s16, s6, 0x5800000
	s_addc_u32 s17, s7, 0
	s_lshl_b32 s18, s20, 5
	s_mov_b64 s[20:21], 0x80
	s_and_b32 s18, s18, 0x60
	s_add_i32 m0, s51, 0x18000
	v_lshl_add_u64 v[8:9], v[8:9], 0, s[20:21]
	s_lshl_b32 s1, s24, 13
	s_lshl_b32 s19, s18, 7
	s_waitcnt vmcnt(2)
	s_barrier
	global_load_lds_dwordx4 v[8:9], off
	v_lshl_add_u64 v[6:7], v[6:7], 0, s[20:21]
	s_add_i32 m0, s51, 0x1a000
	s_add_i32 s60, s51, 0x8000
	s_add_i32 s61, s51, 0xa000
	global_load_lds_dwordx4 v[6:7], off
	v_lshl_add_u64 v[2:3], v[2:3], 0, s[20:21]
	s_mov_b32 m0, s60
	s_add_u32 s36, s42, 0x80080
	global_load_lds_dwordx4 v[2:3], off
	v_lshl_add_u64 v[2:3], v[4:5], 0, s[20:21]
	s_mov_b32 m0, s61
	s_addc_u32 s37, s43, 0
	global_load_lds_dwordx4 v[2:3], off
	s_add_i32 m0, s51, 0x1c000
	v_lshl_add_u64 v[2:3], s[36:37], 0, v[134:135]
	global_load_lds_dwordx4 v[2:3], off
	v_lshl_add_u64 v[2:3], s[36:37], 0, v[130:131]
	s_add_i32 m0, s51, 0x1e000
	s_cmpk_lt_u32 s23, 0x100
	global_load_lds_dwordx4 v[2:3], off
	v_lshrrev_b32_e32 v3, 1, v12
	v_and_b32_e32 v4, 24, v3
	v_and_b32_e32 v2, 15, v12
	v_lshlrev_b32_e32 v3, 1, v4
	v_lshl_or_b32 v1, s24, 6, v2
	v_lshl_or_b32 v2, v2, 6, v3
	v_lshlrev_b32_e32 v3, 2, v12
	v_and_b32_e32 v3, 32, v3
	v_bitop3_b32 v5, v2, s1, v3 bitop3:0xde
	v_bitop3_b32 v165, v2, s19, v3 bitop3:0xde
	v_lshlrev_b32_e32 v2, 2, v4
	v_mov_b32_e32 v3, v135
	v_lshl_add_u64 v[2:3], s[6:7], 0, v[2:3]
	s_mov_b64 s[6:7], 0x1e00000
	v_lshl_add_u64 v[138:139], v[2:3], 0, s[6:7]
	v_lshlrev_b32_e32 v2, 15, v15
	v_and_b32_e32 v2, 0xffff0000, v2
	v_lshl_add_u32 v2, v14, 12, v2
	v_and_b32_e32 v3, 1, v15
	v_lshl_or_b32 v2, v3, 6, v2
	v_lshl_add_u32 v140, v16, 1, v2
	v_lshlrev_b32_e32 v2, 15, v10
	v_and_b32_e32 v2, 0xffff0000, v2
	s_waitcnt vmcnt(6)
	v_lshl_add_u32 v2, v11, 12, v2
	v_and_b32_e32 v3, 1, v10
	s_sext_i32_i16 s67, s22
	s_cselect_b64 s[22:23], -1, 0
	v_lshl_or_b32 v2, v3, 6, v2
	s_add_i32 s63, 0, 0x10000
	s_add_i32 s64, 0, 0x14000
	s_waitcnt lgkmcnt(0)
	s_ashr_i32 s62, s58, 31
	v_or_b32_e32 v167, s18, v4
	v_mov_b32_e32 v141, v135
	v_lshl_add_u32 v142, v13, 1, v2
	v_mov_b32_e32 v143, v135
	v_mov_b64_e32 v[144:145], 0xb00
	v_mov_b64_e32 v[146:147], 0xaff
	v_add_u32_e32 v169, s63, v165
	v_add_u32_e32 v171, s64, v165
	v_add_u32_e32 v173, 0, v5
	v_mbcnt_hi_u32_b32 v175, -1, v222
	v_mov_b32_e32 v177, 0x358637bd
	s_mov_b32 s65, 0xf800000
	v_mov_b32_e32 v179, 0x260
	s_movk_i32 s66, 0x2c00
	s_barrier
	s_mov_b32 s98, -1
	s_mov_b32 s101, 1
	s_branch .LBB0_1045

; #define PG8_STAGE(bufoff, gbase, voff) do { _Pragma("unroll") for (int _i = 0; _i < 2; ++_i) \
;         __builtin_amdgcn_global_load_lds((const unsigned*)((const char*)(gbase) + (voff)[_i]), (PG8_LAS unsigned*)(lds + (bufoff) + ldsw + _i * 8192), 16, 0, 0); } while (0)
; #define PG8_LDA(dst, b, h) do { _Pragma("unroll") for (int m = 0; m < 4; ++m) _Pragma("unroll") for (int k = 0; k < 2; ++k) dst[m][k] = *(const PG8_LAS bf16x8*)(lds + PG8_SA(b, h) + aoff + m * 2048 + k * 1024); } while (0)
; #define PG8_LDB(dst, b, h) do { _Pragma("unroll") for (int n = 0; n < 2; ++n) _Pragma("unroll") for (int k = 0; k < 2; ++k) dst[n][k] = *(const PG8_LAS bf16x8*)(lds + PG8_SB(b, h) + boff + n * 2048 + k * 1024); } while (0)
; #define PG8_MMA(ai, bj, At, Bt) do { __builtin_amdgcn_s_setprio(1); _Pragma("unroll") for (int m = 0; m < 4; ++m) _Pragma("unroll") for (int n = 0; n < 2; ++n) _Pragma("unroll") for (int k = 0; k < 2; ++k) \
;         acc[ai][bj][m][n] = __builtin_amdgcn_mfma_f32_16x16x32_bf16(Bt[n][k], At[m][k], acc[ai][bj][m][n], 0, 0, 0); __builtin_amdgcn_s_setprio(0); } while (0)
; template <class Epi, class Sched, bool ALIGN_EPI = false, bool SP2 = false>
; __device__ __forceinline__ void gemm_phase(PG8_LAS unsigned char* lds, const Gemm g, const Sched& S, const Epi& E) {
;     ...
;     for (;;) {
;         const bool has_next = S.next(ui + 1, nxt);
;         const char* nA = has_next ? (const char*)g.A + (size_t)nxt.pm * tA + (size_t)nxt.pn * pnA : cA; const char* nB = has_next ? (const char*)g.Bt + (size_t)nxt.pn * tB : cB;
; #pragma nounroll
;         for (int t = 0; t < nt; t += 2) {
;             const bool last = (t == nt - 2);
;             const char* a1 = cA + (size_t)(t + 1) * kstep;
;             const char* a2 = last ? nA : cA + (size_t)(t + 2) * kstep; const char* b2 = last ? nB : cB + (size_t)(t + 2) * kstep;
;             const char* a3 = a2 + kstep; const char* b3 = b2 + kstep;
;             if (last && has_next) S.a_ready(nxt);
;             if constexpr (SP2) {
;             PG8_LDB(B0, 0, 0); PG8_LDB(B1, 0, 1); PG8_SCHED; PG8_LDA(At, 0, 0); PG8_STAGE(PG8_SA(1, 1), a1 + hA, voffA);
;             PG8_WAIT_V(8); PG8_WAIT_L(0); PG8_BAR; PG8_MMA(0, 0, At, B0); PG8_MMA(0, 1, At, B1); PG8_BAR; PG8_SCHED;
;             PG8_LDA(At, 0, 1); PG8_STAGE(PG8_SB(0, 0), b2, voffB); PG8_STAGE(PG8_SB(0, 1), b2 + hB, voffB); PG8_STAGE(PG8_SA(0, 0), a2, voffA);
.LBB0_1047:
	s_ashr_i32 s37, s36, 31
	s_lshl_b64 s[38:39], s[36:37], 20
	s_add_u32 s38, s33, s38
	s_addc_u32 s39, s46, s39
	s_and_b64 s[40:41], s[6:7], exec
	s_cselect_b32 s1, s39, s9
	s_cselect_b32 s37, s38, s8
	s_ashr_i32 s25, s24, 31
	s_lshl_b64 s[40:41], s[24:25], 20
	s_add_u32 s40, s47, s40
	s_addc_u32 s41, s48, s41
	s_and_b64 s[44:45], s[6:7], exec
	s_cselect_b32 s25, s41, s43
	s_cselect_b32 s69, s40, s42
	s_add_u32 s8, s8, 0x80080
	s_addc_u32 s9, s9, 0
	s_add_u32 s70, s42, 0x100
	v_mov_b32_e32 v2, 0
	s_addc_u32 s71, s43, 0
	s_mov_b32 s72, -2
	v_mov_b32_e32 v3, v2
	ds_read_b128 v[148:151], v169
	ds_read_b128 v[152:155], v169 offset:1024
	ds_read_b128 v[156:159], v169 offset:2048
	ds_read_b128 v[160:163], v169 offset:3072
	ds_read_b128 v[180:183], v171
	ds_read_b128 v[184:187], v171 offset:1024
	ds_read_b128 v[188:191], v171 offset:2048
	ds_read_b128 v[192:195], v171 offset:3072
	s_add_u32 s18, s8, 0xfff80080
	s_addc_u32 s19, s9, -1
	s_cmp_eq_u32 s72, 28
	s_cselect_b32 s45, s1, s19
	s_cselect_b32 s44, s37, s18
	s_cselect_b32 s43, s25, s71
	s_cselect_b32 s42, s69, s70
	s_add_i32 m0, s51, 0xc000
	ds_read_b128 v[196:199], v173
	ds_read_b128 v[200:203], v173 offset:1024
	ds_read_b128 v[204:207], v173 offset:2048
	ds_read_b128 v[208:211], v173 offset:3072
	ds_read_b128 v[212:215], v173 offset:4096
	ds_read_b128 v[216:219], v173 offset:5120
	ds_read_b128 v[224:227], v173 offset:6144
	ds_read_b128 v[228:231], v173 offset:7168
	global_load_lds_dwordx4 v140, s[8:9]
	s_add_i32 m0, s51, 0xe000
	s_nop 0
	global_load_lds_dwordx4 v142, s[8:9]
	s_cmp_eq_u32 s101, 0
	s_cbranch_scc1 .Lfw_4_0
	s_waitcnt vmcnt(8)
.Lfw_4_0:
	s_waitcnt lgkmcnt(0)
	s_barrier
	s_waitcnt lgkmcnt(0)
	v_mfma_f32_16x16x32_bf16 v[126:129], v[148:151], v[196:199], 0
	v_mfma_f32_16x16x32_bf16 v[122:125], v[156:159], v[196:199], 0
	v_mfma_f32_16x16x32_bf16 v[110:113], v[148:151], v[204:207], 0
	v_mfma_f32_16x16x32_bf16 v[106:109], v[156:159], v[204:207], 0
	v_mfma_f32_16x16x32_bf16 v[94:97], v[148:151], v[212:215], 0
	v_mfma_f32_16x16x32_bf16 v[90:93], v[156:159], v[212:215], 0
	v_mfma_f32_16x16x32_bf16 v[78:81], v[148:151], v[224:227], 0
	v_mfma_f32_16x16x32_bf16 v[74:77], v[156:159], v[224:227], 0
	v_mfma_f32_16x16x32_bf16 v[126:129], v[152:155], v[200:203], v[126:129]
	v_mfma_f32_16x16x32_bf16 v[122:125], v[160:163], v[200:203], v[122:125]
	v_mfma_f32_16x16x32_bf16 v[110:113], v[152:155], v[208:211], v[110:113]
	v_mfma_f32_16x16x32_bf16 v[106:109], v[160:163], v[208:211], v[106:109]
	v_mfma_f32_16x16x32_bf16 v[94:97], v[152:155], v[216:219], v[94:97]
	v_mfma_f32_16x16x32_bf16 v[90:93], v[160:163], v[216:219], v[90:93]
	v_mfma_f32_16x16x32_bf16 v[78:81], v[152:155], v[228:231], v[78:81]
	v_mfma_f32_16x16x32_bf16 v[74:77], v[160:163], v[228:231], v[74:77]
	v_mfma_f32_16x16x32_bf16 v[118:121], v[180:183], v[196:199], 0
	v_mfma_f32_16x16x32_bf16 v[114:117], v[188:191], v[196:199], 0
	v_mfma_f32_16x16x32_bf16 v[102:105], v[180:183], v[204:207], 0
	v_mfma_f32_16x16x32_bf16 v[98:101], v[188:191], v[204:207], 0
	v_mfma_f32_16x16x32_bf16 v[86:89], v[180:183], v[212:215], 0
	v_mfma_f32_16x16x32_bf16 v[82:85], v[188:191], v[212:215], 0
	v_mfma_f32_16x16x32_bf16 v[70:73], v[180:183], v[224:227], 0
	v_mfma_f32_16x16x32_bf16 v[66:69], v[188:191], v[224:227], 0
	v_mfma_f32_16x16x32_bf16 v[118:121], v[184:187], v[200:203], v[118:121]
	v_mfma_f32_16x16x32_bf16 v[114:117], v[192:195], v[200:203], v[114:117]
	v_mfma_f32_16x16x32_bf16 v[102:105], v[184:187], v[208:211], v[102:105]
	v_mfma_f32_16x16x32_bf16 v[98:101], v[192:195], v[208:211], v[98:101]
	v_mfma_f32_16x16x32_bf16 v[86:89], v[184:187], v[216:219], v[86:89]
	v_mfma_f32_16x16x32_bf16 v[82:85], v[192:195], v[216:219], v[82:85]
	v_mfma_f32_16x16x32_bf16 v[70:73], v[184:187], v[228:231], v[70:73]
	v_mfma_f32_16x16x32_bf16 v[66:69], v[192:195], v[228:231], v[66:69]
	s_barrier
	s_add_i32 s18, s63, s49
	s_add_u32 s76, s42, s20
	s_addc_u32 s77, s43, s21
	s_mov_b32 m0, s18
	ds_read_b128 v[196:199], v173 offset:16384
	ds_read_b128 v[200:203], v173 offset:17408
	ds_read_b128 v[204:207], v173 offset:18432
	ds_read_b128 v[208:211], v173 offset:19456
	ds_read_b128 v[212:215], v173 offset:20480
	ds_read_b128 v[216:219], v173 offset:21504
	ds_read_b128 v[224:227], v173 offset:22528
	ds_read_b128 v[228:231], v173 offset:23552
	global_load_lds_dwordx4 v134, s[42:43]
	s_add_i32 m0, s18, 0x2000
	s_add_u32 s74, s42, 0x80000
	s_addc_u32 s75, s43, 0
	s_add_i32 s18, s64, s49
	global_load_lds_dwordx4 v130, s[42:43]
	s_mov_b32 m0, s18
	s_nop 0
	global_load_lds_dwordx4 v134, s[74:75]
	s_add_i32 m0, s18, 0x2000
	s_nop 0
	global_load_lds_dwordx4 v130, s[74:75]
	s_add_u32 s78, s44, s20
	s_addc_u32 s79, s45, s21
	s_mov_b32 m0, s51
	s_nop 0
	global_load_lds_dwordx4 v136, s[44:45]
	s_mov_b32 m0, s52
	s_nop 0
	global_load_lds_dwordx4 v132, s[44:45]
	s_cmp_eq_u32 s101, 0
	s_cbranch_scc1 .Lfw_4_1
	s_waitcnt vmcnt(8)
; #define PG8_STAGE(bufoff, gbase, voff) do { _Pragma("unroll") for (int _i = 0; _i < 2; ++_i) \
;         __builtin_amdgcn_global_load_lds((const unsigned*)((const char*)(gbase) + (voff)[_i]), (PG8_LAS unsigned*)(lds + (bufoff) + ldsw + _i * 8192), 16, 0, 0); } while (0)
; #define PG8_LDA(dst, b, h) do { _Pragma("unroll") for (int m = 0; m < 4; ++m) _Pragma("unroll") for (int k = 0; k < 2; ++k) dst[m][k] = *(const PG8_LAS bf16x8*)(lds + PG8_SA(b, h) + aoff + m * 2048 + k * 1024); } while (0)
; #define PG8_LDB(dst, b, h) do { _Pragma("unroll") for (int n = 0; n < 2; ++n) _Pragma("unroll") for (int k = 0; k < 2; ++k) dst[n][k] = *(const PG8_LAS bf16x8*)(lds + PG8_SB(b, h) + boff + n * 2048 + k * 1024); } while (0)
; #define PG8_MMA(ai, bj, At, Bt) do { __builtin_amdgcn_s_setprio(1); _Pragma("unroll") for (int m = 0; m < 4; ++m) _Pragma("unroll") for (int n = 0; n < 2; ++n) _Pragma("unroll") for (int k = 0; k < 2; ++k) \
;         acc[ai][bj][m][n] = __builtin_amdgcn_mfma_f32_16x16x32_bf16(Bt[n][k], At[m][k], acc[ai][bj][m][n], 0, 0, 0); __builtin_amdgcn_s_setprio(0); } while (0)
; #define PG8_WAIT_V(n) asm volatile("s_waitcnt vmcnt(" #n ")" ::: "memory")
; #define PG8_WAIT_L(n) asm volatile("s_waitcnt lgkmcnt(" #n ")" ::: "memory")
; #define PG8_BAR __builtin_amdgcn_s_barrier()
; #define PG8_SCHED __builtin_amdgcn_sched_barrier(0)
; template <class Epi, class Sched, bool ALIGN_EPI = false, bool SP2 = false>
; __device__ __forceinline__ void gemm_phase(PG8_LAS unsigned char* lds, const Gemm g, const Sched& S, const Epi& E) {
;     ...
;             PG8_WAIT_V(8); PG8_WAIT_L(0); PG8_BAR; PG8_MMA(1, 0, At, B0); PG8_MMA(1, 1, At, B1); PG8_BAR; PG8_SCHED;
;             PG8_LDB(B0, 1, 0); PG8_LDB(B1, 1, 1); PG8_SCHED; PG8_LDA(At, 1, 0); PG8_STAGE(PG8_SA(0, 1), a2 + hA, voffA);
;             PG8_WAIT_V(8); PG8_WAIT_L(0); PG8_BAR; PG8_MMA(0, 0, At, B0); PG8_MMA(0, 1, At, B1); PG8_BAR; PG8_SCHED;
.Lfw_4_1:
	s_waitcnt lgkmcnt(0)
	s_barrier
	s_waitcnt lgkmcnt(0)
	v_mfma_f32_16x16x32_bf16 v[62:65], v[148:151], v[196:199], 0
	v_mfma_f32_16x16x32_bf16 v[58:61], v[156:159], v[196:199], 0
	v_mfma_f32_16x16x32_bf16 v[46:49], v[148:151], v[204:207], 0
	v_mfma_f32_16x16x32_bf16 v[42:45], v[156:159], v[204:207], 0
	v_mfma_f32_16x16x32_bf16 v[30:33], v[148:151], v[212:215], 0
	v_mfma_f32_16x16x32_bf16 v[26:29], v[156:159], v[212:215], 0
	v_mfma_f32_16x16x32_bf16 v[14:17], v[148:151], v[224:227], 0
	v_mfma_f32_16x16x32_bf16 v[10:13], v[156:159], v[224:227], 0
	v_mfma_f32_16x16x32_bf16 v[62:65], v[152:155], v[200:203], v[62:65]
	v_mfma_f32_16x16x32_bf16 v[58:61], v[160:163], v[200:203], v[58:61]
	v_mfma_f32_16x16x32_bf16 v[46:49], v[152:155], v[208:211], v[46:49]
	v_mfma_f32_16x16x32_bf16 v[42:45], v[160:163], v[208:211], v[42:45]
	v_mfma_f32_16x16x32_bf16 v[30:33], v[152:155], v[216:219], v[30:33]
	v_mfma_f32_16x16x32_bf16 v[26:29], v[160:163], v[216:219], v[26:29]
	v_mfma_f32_16x16x32_bf16 v[14:17], v[152:155], v[228:231], v[14:17]
	v_mfma_f32_16x16x32_bf16 v[10:13], v[160:163], v[228:231], v[10:13]
	v_mfma_f32_16x16x32_bf16 v[54:57], v[180:183], v[196:199], 0
	v_mfma_f32_16x16x32_bf16 v[50:53], v[188:191], v[196:199], 0
	v_mfma_f32_16x16x32_bf16 v[38:41], v[180:183], v[204:207], 0
	v_mfma_f32_16x16x32_bf16 v[34:37], v[188:191], v[204:207], 0
	v_mfma_f32_16x16x32_bf16 v[22:25], v[180:183], v[212:215], 0
	v_mfma_f32_16x16x32_bf16 v[18:21], v[188:191], v[212:215], 0
	v_mfma_f32_16x16x32_bf16 v[6:9], v[180:183], v[224:227], 0
	v_mfma_f32_16x16x32_bf16 v[2:5], v[188:191], v[224:227], 0
	v_mfma_f32_16x16x32_bf16 v[54:57], v[184:187], v[200:203], v[54:57]
	v_mfma_f32_16x16x32_bf16 v[50:53], v[192:195], v[200:203], v[50:53]
	v_mfma_f32_16x16x32_bf16 v[38:41], v[184:187], v[208:211], v[38:41]
	v_mfma_f32_16x16x32_bf16 v[34:37], v[192:195], v[208:211], v[34:37]
	v_mfma_f32_16x16x32_bf16 v[22:25], v[184:187], v[216:219], v[22:25]
	v_mfma_f32_16x16x32_bf16 v[18:21], v[192:195], v[216:219], v[18:21]
	v_mfma_f32_16x16x32_bf16 v[6:9], v[184:187], v[228:231], v[6:9]
	v_mfma_f32_16x16x32_bf16 v[2:5], v[192:195], v[228:231], v[2:5]
	s_barrier
	s_add_i32 s18, 0, 0x18000
	s_add_i32 s19, 0, 0x1c000
	v_add_u32_e32 v160, s18, v165
	v_add_u32_e32 v164, s19, v165
	ds_read_b128 v[148:151], v160
	ds_read_b128 v[152:155], v160 offset:1024
	ds_read_b128 v[156:159], v160 offset:2048
	ds_read_b128 v[160:163], v160 offset:3072
	ds_read_b128 v[180:183], v164
	ds_read_b128 v[184:187], v164 offset:1024
	ds_read_b128 v[188:191], v164 offset:2048
	ds_read_b128 v[192:195], v164 offset:3072
	s_add_u32 s44, s44, 0x80000
	s_addc_u32 s45, s45, 0
	s_mov_b32 m0, s53
	ds_read_b128 v[196:199], v173 offset:32768
	ds_read_b128 v[200:203], v173 offset:33792
	ds_read_b128 v[204:207], v173 offset:34816
	ds_read_b128 v[208:211], v173 offset:35840
	ds_read_b128 v[212:215], v173 offset:36864
	ds_read_b128 v[216:219], v173 offset:37888
	ds_read_b128 v[224:227], v173 offset:38912
	ds_read_b128 v[228:231], v173 offset:39936
	global_load_lds_dwordx4 v136, s[44:45]
	s_mov_b32 m0, s57
	s_nop 0
	global_load_lds_dwordx4 v132, s[44:45]
	s_waitcnt vmcnt(8)
	s_waitcnt lgkmcnt(0)
	s_barrier
	s_waitcnt lgkmcnt(0)
	v_mfma_f32_16x16x32_bf16 v[126:129], v[148:151], v[196:199], v[126:129]
	v_mfma_f32_16x16x32_bf16 v[122:125], v[156:159], v[196:199], v[122:125]
	v_mfma_f32_16x16x32_bf16 v[110:113], v[148:151], v[204:207], v[110:113]
	v_mfma_f32_16x16x32_bf16 v[106:109], v[156:159], v[204:207], v[106:109]
	v_mfma_f32_16x16x32_bf16 v[94:97], v[148:151], v[212:215], v[94:97]
	v_mfma_f32_16x16x32_bf16 v[90:93], v[156:159], v[212:215], v[90:93]
	v_mfma_f32_16x16x32_bf16 v[78:81], v[148:151], v[224:227], v[78:81]
	v_mfma_f32_16x16x32_bf16 v[74:77], v[156:159], v[224:227], v[74:77]
	v_mfma_f32_16x16x32_bf16 v[126:129], v[152:155], v[200:203], v[126:129]
	v_mfma_f32_16x16x32_bf16 v[122:125], v[160:163], v[200:203], v[122:125]
	v_mfma_f32_16x16x32_bf16 v[110:113], v[152:155], v[208:211], v[110:113]
	v_mfma_f32_16x16x32_bf16 v[106:109], v[160:163], v[208:211], v[106:109]
	v_mfma_f32_16x16x32_bf16 v[94:97], v[152:155], v[216:219], v[94:97]
	v_mfma_f32_16x16x32_bf16 v[90:93], v[160:163], v[216:219], v[90:93]
	v_mfma_f32_16x16x32_bf16 v[78:81], v[152:155], v[228:231], v[78:81]
	v_mfma_f32_16x16x32_bf16 v[74:77], v[160:163], v[228:231], v[74:77]
	v_mfma_f32_16x16x32_bf16 v[118:121], v[180:183], v[196:199], v[118:121]
	v_mfma_f32_16x16x32_bf16 v[114:117], v[188:191], v[196:199], v[114:117]
	v_mfma_f32_16x16x32_bf16 v[102:105], v[180:183], v[204:207], v[102:105]
	v_mfma_f32_16x16x32_bf16 v[98:101], v[188:191], v[204:207], v[98:101]
	v_mfma_f32_16x16x32_bf16 v[86:89], v[180:183], v[212:215], v[86:89]
	v_mfma_f32_16x16x32_bf16 v[82:85], v[188:191], v[212:215], v[82:85]
	v_mfma_f32_16x16x32_bf16 v[70:73], v[180:183], v[224:227], v[70:73]
	v_mfma_f32_16x16x32_bf16 v[66:69], v[188:191], v[224:227], v[66:69]
	v_mfma_f32_16x16x32_bf16 v[118:121], v[184:187], v[200:203], v[118:121]
	v_mfma_f32_16x16x32_bf16 v[114:117], v[192:195], v[200:203], v[114:117]
	v_mfma_f32_16x16x32_bf16 v[102:105], v[184:187], v[208:211], v[102:105]
	v_mfma_f32_16x16x32_bf16 v[98:101], v[192:195], v[208:211], v[98:101]
	v_mfma_f32_16x16x32_bf16 v[86:89], v[184:187], v[216:219], v[86:89]
	v_mfma_f32_16x16x32_bf16 v[82:85], v[192:195], v[216:219], v[82:85]
	v_mfma_f32_16x16x32_bf16 v[70:73], v[184:187], v[228:231], v[70:73]
	v_mfma_f32_16x16x32_bf16 v[66:69], v[192:195], v[228:231], v[66:69]
	s_barrier
; #define PG8_STAGE(bufoff, gbase, voff) do { _Pragma("unroll") for (int _i = 0; _i < 2; ++_i) \
;         __builtin_amdgcn_global_load_lds((const unsigned*)((const char*)(gbase) + (voff)[_i]), (PG8_LAS unsigned*)(lds + (bufoff) + ldsw + _i * 8192), 16, 0, 0); } while (0)
; #define PG8_LDA(dst, b, h) do { _Pragma("unroll") for (int m = 0; m < 4; ++m) _Pragma("unroll") for (int k = 0; k < 2; ++k) dst[m][k] = *(const PG8_LAS bf16x8*)(lds + PG8_SA(b, h) + aoff + m * 2048 + k * 1024); } while (0)
; #define PG8_MMA(ai, bj, At, Bt) do { __builtin_amdgcn_s_setprio(1); _Pragma("unroll") for (int m = 0; m < 4; ++m) _Pragma("unroll") for (int n = 0; n < 2; ++n) _Pragma("unroll") for (int k = 0; k < 2; ++k) \
;         acc[ai][bj][m][n] = __builtin_amdgcn_mfma_f32_16x16x32_bf16(Bt[n][k], At[m][k], acc[ai][bj][m][n], 0, 0, 0); __builtin_amdgcn_s_setprio(0); } while (0)
; #define PG8_WAIT_V(n) asm volatile("s_waitcnt vmcnt(" #n ")" ::: "memory")
; #define PG8_WAIT_L(n) asm volatile("s_waitcnt lgkmcnt(" #n ")" ::: "memory")
; #define PG8_BAR __builtin_amdgcn_s_barrier()
; #define PG8_SCHED __builtin_amdgcn_sched_barrier(0)
; template <class Epi, class Sched, bool ALIGN_EPI = false, bool SP2 = false>
; __device__ __forceinline__ void gemm_phase(PG8_LAS unsigned char* lds, const Gemm g, const Sched& S, const Epi& E) {
;     ...
;         for (int t = 0; t < nt; t += 2) {
;             const bool last = (t == nt - 2);
;             const char* a1 = cA + (size_t)(t + 1) * kstep;
;             const char* a2 = last ? nA : cA + (size_t)(t + 2) * kstep; const char* b2 = last ? nB : cB + (size_t)(t + 2) * kstep;
;     ...
;             PG8_LDA(At, 1, 1); PG8_STAGE(PG8_SB(1, 0), b3, voffB); PG8_STAGE(PG8_SB(1, 1), b3 + hB, voffB); PG8_STAGE(PG8_SA(1, 0), a3, voffA);
;             PG8_WAIT_V(8); PG8_WAIT_L(0); PG8_BAR; PG8_MMA(1, 0, At, B0); PG8_MMA(1, 1, At, B1); PG8_BAR; PG8_SCHED;
	s_add_i32 s18, s18, s49
	s_mov_b32 m0, s18
	ds_read_b128 v[196:199], v173 offset:49152
	ds_read_b128 v[200:203], v173 offset:50176
	ds_read_b128 v[204:207], v173 offset:51200
	ds_read_b128 v[208:211], v173 offset:52224
	ds_read_b128 v[212:215], v173 offset:53248
	ds_read_b128 v[216:219], v173 offset:54272
	ds_read_b128 v[224:227], v173 offset:55296
	ds_read_b128 v[228:231], v173 offset:56320
	global_load_lds_dwordx4 v134, s[76:77]
	s_add_i32 m0, s18, 0x2000
	s_add_u32 s42, s42, 0x80080
	s_addc_u32 s43, s43, 0
	s_add_i32 s18, s19, s49
	global_load_lds_dwordx4 v130, s[76:77]
	s_mov_b32 m0, s18
	s_nop 0
	global_load_lds_dwordx4 v134, s[42:43]
	s_add_i32 m0, s18, 0x2000
	s_nop 0
	global_load_lds_dwordx4 v130, s[42:43]
	s_mov_b32 m0, s60
	s_nop 0
	global_load_lds_dwordx4 v136, s[78:79]
	s_mov_b32 m0, s61
	s_nop 0
	global_load_lds_dwordx4 v132, s[78:79]
	s_waitcnt vmcnt(8)
	s_waitcnt lgkmcnt(0)
	s_barrier
	s_waitcnt lgkmcnt(0)
	v_mfma_f32_16x16x32_bf16 v[62:65], v[148:151], v[196:199], v[62:65]
	v_mfma_f32_16x16x32_bf16 v[58:61], v[156:159], v[196:199], v[58:61]
	v_mfma_f32_16x16x32_bf16 v[46:49], v[148:151], v[204:207], v[46:49]
	v_mfma_f32_16x16x32_bf16 v[42:45], v[156:159], v[204:207], v[42:45]
	v_mfma_f32_16x16x32_bf16 v[30:33], v[148:151], v[212:215], v[30:33]
	v_mfma_f32_16x16x32_bf16 v[26:29], v[156:159], v[212:215], v[26:29]
	v_mfma_f32_16x16x32_bf16 v[14:17], v[148:151], v[224:227], v[14:17]
	v_mfma_f32_16x16x32_bf16 v[10:13], v[156:159], v[224:227], v[10:13]
	v_mfma_f32_16x16x32_bf16 v[62:65], v[152:155], v[200:203], v[62:65]
	v_mfma_f32_16x16x32_bf16 v[58:61], v[160:163], v[200:203], v[58:61]
	v_mfma_f32_16x16x32_bf16 v[46:49], v[152:155], v[208:211], v[46:49]
	v_mfma_f32_16x16x32_bf16 v[42:45], v[160:163], v[208:211], v[42:45]
	v_mfma_f32_16x16x32_bf16 v[30:33], v[152:155], v[216:219], v[30:33]
	v_mfma_f32_16x16x32_bf16 v[26:29], v[160:163], v[216:219], v[26:29]
	v_mfma_f32_16x16x32_bf16 v[14:17], v[152:155], v[228:231], v[14:17]
	v_mfma_f32_16x16x32_bf16 v[10:13], v[160:163], v[228:231], v[10:13]
	v_mfma_f32_16x16x32_bf16 v[54:57], v[180:183], v[196:199], v[54:57]
	v_mfma_f32_16x16x32_bf16 v[50:53], v[188:191], v[196:199], v[50:53]
	v_mfma_f32_16x16x32_bf16 v[38:41], v[180:183], v[204:207], v[38:41]
	v_mfma_f32_16x16x32_bf16 v[34:37], v[188:191], v[204:207], v[34:37]
	v_mfma_f32_16x16x32_bf16 v[22:25], v[180:183], v[212:215], v[22:25]
	v_mfma_f32_16x16x32_bf16 v[18:21], v[188:191], v[212:215], v[18:21]
	v_mfma_f32_16x16x32_bf16 v[6:9], v[180:183], v[224:227], v[6:9]
	v_mfma_f32_16x16x32_bf16 v[2:5], v[188:191], v[224:227], v[2:5]
	v_mfma_f32_16x16x32_bf16 v[54:57], v[184:187], v[200:203], v[54:57]
	v_mfma_f32_16x16x32_bf16 v[50:53], v[192:195], v[200:203], v[50:53]
	v_mfma_f32_16x16x32_bf16 v[38:41], v[184:187], v[208:211], v[38:41]
	v_mfma_f32_16x16x32_bf16 v[34:37], v[192:195], v[208:211], v[34:37]
	v_mfma_f32_16x16x32_bf16 v[22:25], v[184:187], v[216:219], v[22:25]
	v_mfma_f32_16x16x32_bf16 v[18:21], v[192:195], v[216:219], v[18:21]
	v_mfma_f32_16x16x32_bf16 v[6:9], v[184:187], v[228:231], v[6:9]
	v_mfma_f32_16x16x32_bf16 v[2:5], v[192:195], v[228:231], v[2:5]
	s_barrier
	s_add_i32 s72, s72, 2
	s_add_u32 s8, s8, 0x100
	s_addc_u32 s9, s9, 0
	s_add_u32 s70, s70, 0x100
	s_addc_u32 s71, s71, 0
	s_cmp_gt_u32 s72, 29
	s_mov_b32 s101, 0

; __device__ __forceinline__ u32x4 pack8(f32x4 a, f32x4 b) { u32x4 w; w.x = cvt_pk_bf16(a[0], a[1]); w.y = cvt_pk_bf16(a[2], a[3]); w.z = cvt_pk_bf16(b[0], b[1]); w.w = cvt_pk_bf16(b[2], b[3]); return w; }
; __device__ __forceinline__ f32x4 sig4(f32x4 v) { f32x4 r; r[0] = sigmoidf_(v[0]); r[1] = sigmoidf_(v[1]); r[2] = sigmoidf_(v[2]); r[3] = sigmoidf_(v[3]); return r; }
; __device__ __forceinline__ float sum4(f32x4 a) { return (a[0] + a[1]) + (a[2] + a[3]); }
;     __device__ __forceinline__ void operator()(AccRef acc, const pg8::Unit& u, int wr, int wc, int fr, int fq) const {
;         const int row0 = u.pm * 256 + wr * 64 + fr, c0 = u.pn * 128 + wc * 32 + 8 * fq;
;         float r2[2][4];
; #pragma unroll
;         for (int ai = 0; ai < 2; ++ai)
; #pragma unroll
;             for (int m = 0; m < 4; ++m) { const int r = row0 + ai * 128 + m * 16;
;                 const float* pp = part + (size_t)r * 32 + 8 * fq;
;                 float s = sum4(*(const f32x4*)pp) + sum4(*(const f32x4*)(pp + 4));
;                 s += __shfl_xor(s, 16); s += __shfl_xor(s, 32);
;                 r2[ai][m] = 1.0f / sqrtf(s * (1.0f / 2048.0f) + EPS); }
; #pragma unroll
;         for (int ai = 0; ai < 2; ++ai)
; #pragma unroll
;             for (int m = 0; m < 4; ++m) { const int r = row0 + ai * 128 + m * 16; const float rr = r2[ai][m];
;                 const f32x4 a0 = acc[ai][0][m][0] * rr, a1 = acc[ai][0][m][1] * rr, b0 = acc[ai][1][m][0] * rr, b1 = acc[ai][1][m][1] * rr;
;                 *(u32x4*)(act + (size_t)r * DFF + c0) = pack8(a0 * sig4(a0) * b0, a1 * sig4(a1) * b1); }
.Lp5_have_r2:
	v_mov_b32_e32 v168, v248
	v_mov_b32_e32 v172, v249
	v_mov_b32_e32 v174, v250
	v_mov_b32_e32 v178, v251
	v_mov_b32_e32 v176, v252
	v_mov_b32_e32 v170, v253
	v_mov_b32_e32 v166, v254
	v_mov_b32_e32 v164, v255
	v_or_b32_e32 v152, 16, v158
	v_or_b32_e32 v150, 32, v158
	v_or_b32_e32 v148, 48, v158
	v_add_u32_e32 v154, 0x80, v158
	v_add_u32_e32 v156, 0x90, v158
	v_add_u32_e32 v160, 0xa0, v158
	v_add_u32_e32 v162, 0xb0, v158
	v_lshl_or_b32 v180, s67, 7, v167
	v_ashrrev_i32_e32 v181, 31, v180
	v_pk_mul_f32 v[126:127], v[126:127], v[168:169] op_sel_hi:[1,0]
	v_pk_mul_f32 v[128:129], v[128:129], v[168:169] op_sel_hi:[1,0]
	v_pk_mul_f32 v[122:123], v[122:123], v[168:169] op_sel_hi:[1,0]
	v_pk_mul_f32 v[124:125], v[124:125], v[168:169] op_sel_hi:[1,0]
	v_pk_mul_f32 v[118:119], v[118:119], v[168:169] op_sel_hi:[1,0]
	v_pk_mul_f32 v[120:121], v[120:121], v[168:169] op_sel_hi:[1,0]
	v_pk_mul_f32 v[114:115], v[114:115], v[168:169] op_sel_hi:[1,0]
	v_pk_mul_f32 v[116:117], v[116:117], v[168:169] op_sel_hi:[1,0]
	v_pk_mul_f32 v[112:113], v[112:113], v[172:173] op_sel_hi:[1,0]
	v_pk_mul_f32 v[110:111], v[110:111], v[172:173] op_sel_hi:[1,0]
	v_pk_mul_f32 v[108:109], v[108:109], v[172:173] op_sel_hi:[1,0]
	v_pk_mul_f32 v[106:107], v[106:107], v[172:173] op_sel_hi:[1,0]
	v_pk_mul_f32 v[102:103], v[102:103], v[172:173] op_sel_hi:[1,0]
	v_pk_mul_f32 v[104:105], v[104:105], v[172:173] op_sel_hi:[1,0]
	v_pk_mul_f32 v[98:99], v[98:99], v[172:173] op_sel_hi:[1,0]
	v_pk_mul_f32 v[100:101], v[100:101], v[172:173] op_sel_hi:[1,0]
	v_pk_mul_f32 v[96:97], v[96:97], v[174:175] op_sel_hi:[1,0]
	v_pk_mul_f32 v[94:95], v[94:95], v[174:175] op_sel_hi:[1,0]
	v_pk_mul_f32 v[92:93], v[92:93], v[174:175] op_sel_hi:[1,0]
	v_pk_mul_f32 v[90:91], v[90:91], v[174:175] op_sel_hi:[1,0]
	v_pk_mul_f32 v[86:87], v[86:87], v[174:175] op_sel_hi:[1,0]
	v_mul_f32_e32 v149, 0xbfb8aa3b, v126
	v_exp_f32_e32 v149, v149
	v_mul_f32_e32 v151, 0xbfb8aa3b, v127
	v_exp_f32_e32 v151, v151
	v_mul_f32_e32 v153, 0xbfb8aa3b, v129
	v_add_f32_e32 v149, 1.0, v149
	v_rcp_f32_e32 v182, v149
	v_add_f32_e32 v149, 1.0, v151
	v_mul_f32_e32 v151, 0xbfb8aa3b, v128
	v_exp_f32_e32 v151, v151
	v_exp_f32_e32 v153, v153
	v_rcp_f32_e32 v183, v149
	v_pk_mul_f32 v[88:89], v[88:89], v[174:175] op_sel_hi:[1,0]
	v_add_f32_e32 v149, 1.0, v151
	v_rcp_f32_e32 v184, v149
	v_add_f32_e32 v149, 1.0, v153
	v_rcp_f32_e32 v185, v149
	v_mul_f32_e32 v149, 0xbfb8aa3b, v122
	v_exp_f32_e32 v149, v149
	v_mul_f32_e32 v151, 0xbfb8aa3b, v123
	v_exp_f32_e32 v151, v151
	v_pk_mul_f32 v[126:127], v[126:127], v[182:183]
	v_add_f32_e32 v149, 1.0, v149
	v_rcp_f32_e32 v182, v149
	v_add_f32_e32 v149, 1.0, v151
	v_mul_f32_e32 v151, 0xbfb8aa3b, v124
	v_exp_f32_e32 v151, v151
	v_mul_f32_e32 v153, 0xbfb8aa3b, v125
	v_exp_f32_e32 v153, v153
	v_rcp_f32_e32 v183, v149
	v_add_f32_e32 v149, 1.0, v151
	v_pk_mul_f32 v[128:129], v[128:129], v[184:185]
	v_rcp_f32_e32 v184, v149
	v_add_f32_e32 v149, 1.0, v153
	v_rcp_f32_e32 v185, v149
	v_pk_mul_f32 v[122:123], v[122:123], v[182:183]
	v_pk_mul_f32 v[120:121], v[120:121], v[128:129]
	v_pk_mul_f32 v[118:119], v[118:119], v[126:127]
	v_pk_mul_f32 v[124:125], v[124:125], v[184:185]
	v_pk_mul_f32 v[114:115], v[114:115], v[122:123]
	v_pk_mul_f32 v[116:117], v[116:117], v[124:125]
	v_cvt_pk_bf16_f32 v118, v118, v119
	v_cvt_pk_bf16_f32 v119, v120, v121
	v_cvt_pk_bf16_f32 v120, v114, v115
	v_mov_b64_e32 v[114:115], s[16:17]
	v_cvt_pk_bf16_f32 v121, v116, v117
	v_mad_i64_i32 v[122:123], s[0:1], v158, s66, v[114:115]
	v_lshlrev_b64 v[116:117], 1, v[180:181]
	v_lshl_add_u64 v[122:123], v[122:123], 0, v[116:117]
	s_waitcnt vmcnt(0)
	global_store_dwordx4 v[122:123], v[118:121], off
	v_pk_mul_f32 v[82:83], v[82:83], v[174:175] op_sel_hi:[1,0]
	v_pk_mul_f32 v[84:85], v[84:85], v[174:175] op_sel_hi:[1,0]
	v_mul_f32_e32 v118, 0xbfb8aa3b, v110
	v_mul_f32_e32 v119, 0xbfb8aa3b, v111
	v_mul_f32_e32 v120, 0xbfb8aa3b, v112
	v_mul_f32_e32 v121, 0xbfb8aa3b, v113
	v_exp_f32_e32 v118, v118
	v_exp_f32_e32 v119, v119
	v_exp_f32_e32 v120, v120
	v_exp_f32_e32 v121, v121
	v_add_f32_e32 v118, 1.0, v118
	v_add_f32_e32 v119, 1.0, v119
	v_add_f32_e32 v120, 1.0, v120
	v_add_f32_e32 v121, 1.0, v121
	v_rcp_f32_e32 v118, v118
	v_rcp_f32_e32 v119, v119
	v_rcp_f32_e32 v120, v120
	v_rcp_f32_e32 v121, v121
	v_pk_mul_f32 v[80:81], v[80:81], v[178:179] op_sel_hi:[1,0]
	v_pk_mul_f32 v[110:111], v[110:111], v[118:119]
	v_mul_f32_e32 v118, 0xbfb8aa3b, v106
	v_mul_f32_e32 v119, 0xbfb8aa3b, v107
	v_pk_mul_f32 v[112:113], v[112:113], v[120:121]
	v_mul_f32_e32 v120, 0xbfb8aa3b, v108
	v_mul_f32_e32 v121, 0xbfb8aa3b, v109
	v_exp_f32_e32 v118, v118
	v_exp_f32_e32 v119, v119
	v_exp_f32_e32 v120, v120
	v_exp_f32_e32 v121, v121
	v_add_f32_e32 v118, 1.0, v118
	v_add_f32_e32 v119, 1.0, v119
	v_add_f32_e32 v120, 1.0, v120
	v_add_f32_e32 v121, 1.0, v121
	v_rcp_f32_e32 v118, v118
	v_rcp_f32_e32 v119, v119
	v_rcp_f32_e32 v120, v120
	v_rcp_f32_e32 v121, v121
	v_pk_mul_f32 v[102:103], v[102:103], v[110:111]
	v_pk_mul_f32 v[106:107], v[106:107], v[118:119]
	v_pk_mul_f32 v[104:105], v[104:105], v[112:113]
	v_pk_mul_f32 v[108:109], v[108:109], v[120:121]
	v_pk_mul_f32 v[78:79], v[78:79], v[178:179] op_sel_hi:[1,0]
	v_pk_mul_f32 v[108:109], v[100:101], v[108:109]
	v_pk_mul_f32 v[100:101], v[98:99], v[106:107]
	v_cvt_pk_bf16_f32 v98, v102, v103
	v_mad_i64_i32 v[102:103], s[0:1], v152, s66, v[114:115]
	v_cvt_pk_bf16_f32 v99, v104, v105
	v_cvt_pk_bf16_f32 v100, v100, v101
	v_cvt_pk_bf16_f32 v101, v108, v109
	v_lshl_add_u64 v[102:103], v[102:103], 0, v[116:117]
	global_store_dwordx4 v[102:103], v[98:101], off
	v_pk_mul_f32 v[76:77], v[76:77], v[178:179] op_sel_hi:[1,0]
; __device__ __forceinline__ u32x4 pack8(f32x4 a, f32x4 b) { u32x4 w; w.x = cvt_pk_bf16(a[0], a[1]); w.y = cvt_pk_bf16(a[2], a[3]); w.z = cvt_pk_bf16(b[0], b[1]); w.w = cvt_pk_bf16(b[2], b[3]); return w; }
; __device__ __forceinline__ f32x4 sig4(f32x4 v) { f32x4 r; r[0] = sigmoidf_(v[0]); r[1] = sigmoidf_(v[1]); r[2] = sigmoidf_(v[2]); r[3] = sigmoidf_(v[3]); return r; }
;     __device__ __forceinline__ void operator()(AccRef acc, const pg8::Unit& u, int wr, int wc, int fr, int fq) const {
;     ...
;             for (int m = 0; m < 4; ++m) { const int r = row0 + ai * 128 + m * 16; const float rr = r2[ai][m];
;                 const f32x4 a0 = acc[ai][0][m][0] * rr, a1 = acc[ai][0][m][1] * rr, b0 = acc[ai][1][m][0] * rr, b1 = acc[ai][1][m][1] * rr;
;                 *(u32x4*)(act + (size_t)r * DFF + c0) = pack8(a0 * sig4(a0) * b0, a1 * sig4(a1) * b1); }
	v_pk_mul_f32 v[74:75], v[74:75], v[178:179] op_sel_hi:[1,0]
	v_mul_f32_e32 v98, 0xbfb8aa3b, v94
	v_mul_f32_e32 v99, 0xbfb8aa3b, v95
	v_mul_f32_e32 v100, 0xbfb8aa3b, v96
	v_mul_f32_e32 v101, 0xbfb8aa3b, v97
	v_exp_f32_e32 v98, v98
	v_exp_f32_e32 v99, v99
	v_exp_f32_e32 v100, v100
	v_exp_f32_e32 v101, v101
	v_add_f32_e32 v98, 1.0, v98
	v_add_f32_e32 v99, 1.0, v99
	v_add_f32_e32 v100, 1.0, v100
	v_add_f32_e32 v101, 1.0, v101
	v_rcp_f32_e32 v98, v98
	v_rcp_f32_e32 v99, v99
	v_rcp_f32_e32 v100, v100
	v_rcp_f32_e32 v101, v101
	v_pk_mul_f32 v[70:71], v[70:71], v[178:179] op_sel_hi:[1,0]
	v_pk_mul_f32 v[94:95], v[94:95], v[98:99]
	v_mul_f32_e32 v98, 0xbfb8aa3b, v90
	v_mul_f32_e32 v99, 0xbfb8aa3b, v91
	v_pk_mul_f32 v[96:97], v[96:97], v[100:101]
	v_mul_f32_e32 v100, 0xbfb8aa3b, v92
	v_mul_f32_e32 v101, 0xbfb8aa3b, v93
	v_exp_f32_e32 v98, v98
	v_exp_f32_e32 v99, v99
	v_exp_f32_e32 v100, v100
	v_exp_f32_e32 v101, v101
	v_add_f32_e32 v98, 1.0, v98
	v_add_f32_e32 v99, 1.0, v99
	v_add_f32_e32 v100, 1.0, v100
	v_add_f32_e32 v101, 1.0, v101
	v_rcp_f32_e32 v98, v98
	v_rcp_f32_e32 v99, v99
	v_rcp_f32_e32 v100, v100
	v_rcp_f32_e32 v101, v101
	v_pk_mul_f32 v[86:87], v[86:87], v[94:95]
	v_pk_mul_f32 v[90:91], v[90:91], v[98:99]
	v_pk_mul_f32 v[88:89], v[88:89], v[96:97]
	v_pk_mul_f32 v[92:93], v[92:93], v[100:101]
	v_pk_mul_f32 v[72:73], v[72:73], v[178:179] op_sel_hi:[1,0]
	v_pk_mul_f32 v[92:93], v[84:85], v[92:93]
	v_pk_mul_f32 v[84:85], v[82:83], v[90:91]
	v_cvt_pk_bf16_f32 v82, v86, v87
	v_mad_i64_i32 v[86:87], s[0:1], v150, s66, v[114:115]
	v_cvt_pk_bf16_f32 v83, v88, v89
	v_cvt_pk_bf16_f32 v84, v84, v85
	v_cvt_pk_bf16_f32 v85, v92, v93
	v_lshl_add_u64 v[86:87], v[86:87], 0, v[116:117]
	global_store_dwordx4 v[86:87], v[82:85], off
	v_pk_mul_f32 v[66:67], v[66:67], v[178:179] op_sel_hi:[1,0]
	v_pk_mul_f32 v[68:69], v[68:69], v[178:179] op_sel_hi:[1,0]
	v_mul_f32_e32 v82, 0xbfb8aa3b, v78
	v_mul_f32_e32 v83, 0xbfb8aa3b, v79
	v_mul_f32_e32 v84, 0xbfb8aa3b, v80
	v_mul_f32_e32 v85, 0xbfb8aa3b, v81
	v_exp_f32_e32 v82, v82
	v_exp_f32_e32 v83, v83
	v_exp_f32_e32 v84, v84
	v_exp_f32_e32 v85, v85
	v_add_f32_e32 v82, 1.0, v82
	v_add_f32_e32 v83, 1.0, v83
	v_add_f32_e32 v84, 1.0, v84
	v_add_f32_e32 v85, 1.0, v85
	v_rcp_f32_e32 v82, v82
	v_rcp_f32_e32 v83, v83
	v_rcp_f32_e32 v84, v84
	v_rcp_f32_e32 v85, v85
	v_pk_mul_f32 v[64:65], v[64:65], v[176:177] op_sel_hi:[1,0]
	v_pk_mul_f32 v[78:79], v[78:79], v[82:83]
	v_mul_f32_e32 v82, 0xbfb8aa3b, v74
	v_mul_f32_e32 v83, 0xbfb8aa3b, v75
	v_pk_mul_f32 v[80:81], v[80:81], v[84:85]
	v_mul_f32_e32 v84, 0xbfb8aa3b, v76
	v_mul_f32_e32 v85, 0xbfb8aa3b, v77
	v_exp_f32_e32 v82, v82
	v_exp_f32_e32 v83, v83
	v_exp_f32_e32 v84, v84
	v_exp_f32_e32 v85, v85
	v_add_f32_e32 v82, 1.0, v82
	v_add_f32_e32 v83, 1.0, v83
	v_add_f32_e32 v84, 1.0, v84
	v_add_f32_e32 v85, 1.0, v85
	v_rcp_f32_e32 v82, v82
	v_rcp_f32_e32 v83, v83
	v_rcp_f32_e32 v84, v84
	v_rcp_f32_e32 v85, v85
	v_pk_mul_f32 v[70:71], v[70:71], v[78:79]
	v_pk_mul_f32 v[74:75], v[74:75], v[82:83]
	v_pk_mul_f32 v[72:73], v[72:73], v[80:81]
	v_pk_mul_f32 v[76:77], v[76:77], v[84:85]
	v_pk_mul_f32 v[62:63], v[62:63], v[176:177] op_sel_hi:[1,0]
	v_pk_mul_f32 v[76:77], v[68:69], v[76:77]
	v_pk_mul_f32 v[68:69], v[66:67], v[74:75]
	v_cvt_pk_bf16_f32 v66, v70, v71
	v_mad_i64_i32 v[70:71], s[0:1], v148, s66, v[114:115]
	v_cvt_pk_bf16_f32 v67, v72, v73
	v_cvt_pk_bf16_f32 v68, v68, v69
	v_cvt_pk_bf16_f32 v69, v76, v77
	v_lshl_add_u64 v[70:71], v[70:71], 0, v[116:117]
	global_store_dwordx4 v[70:71], v[66:69], off
	v_pk_mul_f32 v[60:61], v[60:61], v[176:177] op_sel_hi:[1,0]
	v_pk_mul_f32 v[58:59], v[58:59], v[176:177] op_sel_hi:[1,0]
	v_mul_f32_e32 v66, 0xbfb8aa3b, v62
	v_mul_f32_e32 v67, 0xbfb8aa3b, v63
	v_mul_f32_e32 v68, 0xbfb8aa3b, v64
	v_mul_f32_e32 v69, 0xbfb8aa3b, v65
	v_exp_f32_e32 v66, v66
	v_exp_f32_e32 v67, v67
	v_exp_f32_e32 v68, v68
	v_exp_f32_e32 v69, v69
	v_add_f32_e32 v66, 1.0, v66
	v_add_f32_e32 v67, 1.0, v67
	v_add_f32_e32 v68, 1.0, v68
	v_add_f32_e32 v69, 1.0, v69
	v_rcp_f32_e32 v66, v66
	v_rcp_f32_e32 v67, v67
	v_rcp_f32_e32 v68, v68
	v_rcp_f32_e32 v69, v69
	v_pk_mul_f32 v[54:55], v[54:55], v[176:177] op_sel_hi:[1,0]
	v_pk_mul_f32 v[62:63], v[62:63], v[66:67]
	v_mul_f32_e32 v66, 0xbfb8aa3b, v58
	v_mul_f32_e32 v67, 0xbfb8aa3b, v59
	v_pk_mul_f32 v[64:65], v[64:65], v[68:69]
	v_mul_f32_e32 v68, 0xbfb8aa3b, v60
	v_mul_f32_e32 v69, 0xbfb8aa3b, v61
	v_exp_f32_e32 v66, v66
	v_exp_f32_e32 v67, v67
	v_exp_f32_e32 v68, v68
	v_exp_f32_e32 v69, v69
	v_add_f32_e32 v66, 1.0, v66
	v_add_f32_e32 v67, 1.0, v67
	v_add_f32_e32 v68, 1.0, v68
	v_add_f32_e32 v69, 1.0, v69
	v_rcp_f32_e32 v66, v66
	v_rcp_f32_e32 v67, v67
	v_rcp_f32_e32 v68, v68
	v_rcp_f32_e32 v69, v69
	v_pk_mul_f32 v[56:57], v[56:57], v[176:177] op_sel_hi:[1,0]
	v_pk_mul_f32 v[50:51], v[50:51], v[176:177] op_sel_hi:[1,0]
	v_pk_mul_f32 v[52:53], v[52:53], v[176:177] op_sel_hi:[1,0]
	v_pk_mul_f32 v[54:55], v[54:55], v[62:63]
	v_pk_mul_f32 v[58:59], v[58:59], v[66:67]
	v_pk_mul_f32 v[60:61], v[60:61], v[68:69]
	v_pk_mul_f32 v[56:57], v[56:57], v[64:65]
	v_pk_mul_f32 v[60:61], v[52:53], v[60:61]
	v_pk_mul_f32 v[52:53], v[50:51], v[58:59]
	v_cvt_pk_bf16_f32 v50, v54, v55
	v_mad_i64_i32 v[54:55], s[0:1], v154, s66, v[114:115]
	v_cvt_pk_bf16_f32 v51, v56, v57
	v_cvt_pk_bf16_f32 v52, v52, v53
	v_cvt_pk_bf16_f32 v53, v60, v61
	v_lshl_add_u64 v[54:55], v[54:55], 0, v[116:117]
	v_pk_mul_f32 v[48:49], v[48:49], v[170:171] op_sel_hi:[1,0]
	v_pk_mul_f32 v[46:47], v[46:47], v[170:171] op_sel_hi:[1,0]
	global_store_dwordx4 v[54:55], v[50:53], off
	v_pk_mul_f32 v[44:45], v[44:45], v[170:171] op_sel_hi:[1,0]
	v_pk_mul_f32 v[42:43], v[42:43], v[170:171] op_sel_hi:[1,0]
; #define PG8_BAR __builtin_amdgcn_s_barrier()
; __device__ __forceinline__ u32x4 pack8(f32x4 a, f32x4 b) { u32x4 w; w.x = cvt_pk_bf16(a[0], a[1]); w.y = cvt_pk_bf16(a[2], a[3]); w.z = cvt_pk_bf16(b[0], b[1]); w.w = cvt_pk_bf16(b[2], b[3]); return w; }
; __device__ __forceinline__ f32x4 sig4(f32x4 v) { f32x4 r; r[0] = sigmoidf_(v[0]); r[1] = sigmoidf_(v[1]); r[2] = sigmoidf_(v[2]); r[3] = sigmoidf_(v[3]); return r; }
; template <class Epi, class Sched, bool ALIGN_EPI = false, bool SP2 = false>
; __device__ __forceinline__ void gemm_phase(PG8_LAS unsigned char* lds, const Gemm g, const Sched& S, const Epi& E) {
;     ...
;         if constexpr (ALIGN_EPI) { if (wr == 0) PG8_BAR; }
;         if constexpr (!Epi::AFTER_DRAIN) { E(acc, cur, wr, wc, fr, fq); S.done(cur); }
;         if (!has_next) break;
; #pragma unroll
;         for (int a = 0; a < 2; ++a)
; #pragma unroll
;             for (int b = 0; b < 2; ++b)
; #pragma unroll
;                 for (int m = 0; m < 4; ++m)
; #pragma unroll
;                     for (int n = 0; n < 2; ++n) acc[a][b][m][n] = (f32x4){0.f, 0.f, 0.f, 0.f};
;         cur = nxt; cA = nA; cB = nB; ++ui;
;         if constexpr (ALIGN_EPI) { if (wr == 1) PG8_BAR; }
;     }
;     __device__ __forceinline__ void operator()(AccRef acc, const pg8::Unit& u, int wr, int wc, int fr, int fq) const {
;     ...
;             for (int m = 0; m < 4; ++m) { const int r = row0 + ai * 128 + m * 16; const float rr = r2[ai][m];
;                 const f32x4 a0 = acc[ai][0][m][0] * rr, a1 = acc[ai][0][m][1] * rr, b0 = acc[ai][1][m][0] * rr, b1 = acc[ai][1][m][1] * rr;
;                 *(u32x4*)(act + (size_t)r * DFF + c0) = pack8(a0 * sig4(a0) * b0, a1 * sig4(a1) * b1); }
	v_mul_f32_e32 v50, 0xbfb8aa3b, v46
	v_mul_f32_e32 v51, 0xbfb8aa3b, v47
	v_mul_f32_e32 v52, 0xbfb8aa3b, v48
	v_mul_f32_e32 v53, 0xbfb8aa3b, v49
	v_exp_f32_e32 v50, v50
	v_exp_f32_e32 v51, v51
	v_exp_f32_e32 v52, v52
	v_exp_f32_e32 v53, v53
	v_add_f32_e32 v50, 1.0, v50
	v_add_f32_e32 v51, 1.0, v51
	v_add_f32_e32 v52, 1.0, v52
	v_add_f32_e32 v53, 1.0, v53
	v_rcp_f32_e32 v50, v50
	v_rcp_f32_e32 v51, v51
	v_rcp_f32_e32 v52, v52
	v_rcp_f32_e32 v53, v53
	v_pk_mul_f32 v[38:39], v[38:39], v[170:171] op_sel_hi:[1,0]
	v_pk_mul_f32 v[46:47], v[46:47], v[50:51]
	v_mul_f32_e32 v50, 0xbfb8aa3b, v42
	v_mul_f32_e32 v51, 0xbfb8aa3b, v43
	v_pk_mul_f32 v[48:49], v[48:49], v[52:53]
	v_mul_f32_e32 v52, 0xbfb8aa3b, v44
	v_mul_f32_e32 v53, 0xbfb8aa3b, v45
	v_exp_f32_e32 v50, v50
	v_exp_f32_e32 v51, v51
	v_exp_f32_e32 v52, v52
	v_exp_f32_e32 v53, v53
	v_add_f32_e32 v50, 1.0, v50
	v_add_f32_e32 v51, 1.0, v51
	v_add_f32_e32 v52, 1.0, v52
	v_add_f32_e32 v53, 1.0, v53
	v_rcp_f32_e32 v50, v50
	v_rcp_f32_e32 v51, v51
	v_rcp_f32_e32 v52, v52
	v_rcp_f32_e32 v53, v53
	v_pk_mul_f32 v[40:41], v[40:41], v[170:171] op_sel_hi:[1,0]
	v_pk_mul_f32 v[34:35], v[34:35], v[170:171] op_sel_hi:[1,0]
	v_pk_mul_f32 v[36:37], v[36:37], v[170:171] op_sel_hi:[1,0]
	v_pk_mul_f32 v[38:39], v[38:39], v[46:47]
	v_pk_mul_f32 v[42:43], v[42:43], v[50:51]
	v_pk_mul_f32 v[44:45], v[44:45], v[52:53]
	v_pk_mul_f32 v[40:41], v[40:41], v[48:49]
	v_pk_mul_f32 v[44:45], v[36:37], v[44:45]
	v_pk_mul_f32 v[36:37], v[34:35], v[42:43]
	v_cvt_pk_bf16_f32 v34, v38, v39
	v_mad_i64_i32 v[38:39], s[0:1], v156, s66, v[114:115]
	v_cvt_pk_bf16_f32 v35, v40, v41
	v_cvt_pk_bf16_f32 v36, v36, v37
	v_cvt_pk_bf16_f32 v37, v44, v45
	v_lshl_add_u64 v[38:39], v[38:39], 0, v[116:117]
	v_pk_mul_f32 v[32:33], v[32:33], v[166:167] op_sel_hi:[1,0]
	v_pk_mul_f32 v[30:31], v[30:31], v[166:167] op_sel_hi:[1,0]
	global_store_dwordx4 v[38:39], v[34:37], off
	v_pk_mul_f32 v[28:29], v[28:29], v[166:167] op_sel_hi:[1,0]
	v_pk_mul_f32 v[26:27], v[26:27], v[166:167] op_sel_hi:[1,0]
	v_mul_f32_e32 v34, 0xbfb8aa3b, v30
	v_mul_f32_e32 v35, 0xbfb8aa3b, v31
	v_mul_f32_e32 v36, 0xbfb8aa3b, v32
	v_mul_f32_e32 v37, 0xbfb8aa3b, v33
	v_exp_f32_e32 v34, v34
	v_exp_f32_e32 v35, v35
	v_exp_f32_e32 v36, v36
	v_exp_f32_e32 v37, v37
	v_add_f32_e32 v34, 1.0, v34
	v_add_f32_e32 v35, 1.0, v35
	v_add_f32_e32 v36, 1.0, v36
	v_add_f32_e32 v37, 1.0, v37
	v_rcp_f32_e32 v34, v34
	v_rcp_f32_e32 v35, v35
	v_rcp_f32_e32 v36, v36
	v_rcp_f32_e32 v37, v37
	v_pk_mul_f32 v[22:23], v[22:23], v[166:167] op_sel_hi:[1,0]
	v_pk_mul_f32 v[30:31], v[30:31], v[34:35]
	v_mul_f32_e32 v34, 0xbfb8aa3b, v26
	v_mul_f32_e32 v35, 0xbfb8aa3b, v27
	v_pk_mul_f32 v[32:33], v[32:33], v[36:37]
	v_mul_f32_e32 v36, 0xbfb8aa3b, v28
	v_mul_f32_e32 v37, 0xbfb8aa3b, v29
	v_exp_f32_e32 v34, v34
	v_exp_f32_e32 v35, v35
	v_exp_f32_e32 v36, v36
	v_exp_f32_e32 v37, v37
	v_add_f32_e32 v34, 1.0, v34
	v_add_f32_e32 v35, 1.0, v35
	v_add_f32_e32 v36, 1.0, v36
	v_add_f32_e32 v37, 1.0, v37
	v_rcp_f32_e32 v34, v34
	v_rcp_f32_e32 v35, v35
	v_rcp_f32_e32 v36, v36
	v_rcp_f32_e32 v37, v37
	v_pk_mul_f32 v[24:25], v[24:25], v[166:167] op_sel_hi:[1,0]
	v_pk_mul_f32 v[18:19], v[18:19], v[166:167] op_sel_hi:[1,0]
	v_pk_mul_f32 v[20:21], v[20:21], v[166:167] op_sel_hi:[1,0]
	v_pk_mul_f32 v[22:23], v[22:23], v[30:31]
	v_pk_mul_f32 v[26:27], v[26:27], v[34:35]
	v_pk_mul_f32 v[28:29], v[28:29], v[36:37]
	v_pk_mul_f32 v[24:25], v[24:25], v[32:33]
	v_pk_mul_f32 v[28:29], v[20:21], v[28:29]
	v_pk_mul_f32 v[20:21], v[18:19], v[26:27]
	v_cvt_pk_bf16_f32 v18, v22, v23
	v_mad_i64_i32 v[22:23], s[0:1], v160, s66, v[114:115]
	v_cvt_pk_bf16_f32 v19, v24, v25
	v_cvt_pk_bf16_f32 v20, v20, v21
	v_cvt_pk_bf16_f32 v21, v28, v29
	v_lshl_add_u64 v[22:23], v[22:23], 0, v[116:117]
	v_pk_mul_f32 v[16:17], v[16:17], v[164:165] op_sel_hi:[1,0]
	v_pk_mul_f32 v[14:15], v[14:15], v[164:165] op_sel_hi:[1,0]
	global_store_dwordx4 v[22:23], v[18:21], off
	v_pk_mul_f32 v[12:13], v[12:13], v[164:165] op_sel_hi:[1,0]
	v_pk_mul_f32 v[10:11], v[10:11], v[164:165] op_sel_hi:[1,0]
	v_mul_f32_e32 v18, 0xbfb8aa3b, v14
	v_mul_f32_e32 v19, 0xbfb8aa3b, v15
	v_mul_f32_e32 v20, 0xbfb8aa3b, v16
	v_mul_f32_e32 v21, 0xbfb8aa3b, v17
	v_exp_f32_e32 v18, v18
	v_exp_f32_e32 v19, v19
	v_exp_f32_e32 v20, v20
	v_exp_f32_e32 v21, v21
	v_add_f32_e32 v18, 1.0, v18
	v_add_f32_e32 v19, 1.0, v19
	v_add_f32_e32 v20, 1.0, v20
	v_add_f32_e32 v21, 1.0, v21
	v_rcp_f32_e32 v18, v18
	v_rcp_f32_e32 v19, v19
	v_rcp_f32_e32 v20, v20
	v_rcp_f32_e32 v21, v21
	v_pk_mul_f32 v[6:7], v[6:7], v[164:165] op_sel_hi:[1,0]
	v_pk_mul_f32 v[14:15], v[14:15], v[18:19]
	v_mul_f32_e32 v18, 0xbfb8aa3b, v10
	v_mul_f32_e32 v19, 0xbfb8aa3b, v11
	v_pk_mul_f32 v[16:17], v[16:17], v[20:21]
	v_mul_f32_e32 v20, 0xbfb8aa3b, v12
	v_mul_f32_e32 v21, 0xbfb8aa3b, v13
	v_exp_f32_e32 v18, v18
	v_exp_f32_e32 v19, v19
	v_exp_f32_e32 v20, v20
	v_exp_f32_e32 v21, v21
	v_add_f32_e32 v18, 1.0, v18
	v_add_f32_e32 v19, 1.0, v19
	v_add_f32_e32 v20, 1.0, v20
	v_add_f32_e32 v21, 1.0, v21
	v_rcp_f32_e32 v18, v18
	v_rcp_f32_e32 v19, v19
	v_rcp_f32_e32 v20, v20
	v_rcp_f32_e32 v21, v21
	v_pk_mul_f32 v[8:9], v[8:9], v[164:165] op_sel_hi:[1,0]
	v_pk_mul_f32 v[2:3], v[2:3], v[164:165] op_sel_hi:[1,0]
	v_pk_mul_f32 v[4:5], v[4:5], v[164:165] op_sel_hi:[1,0]
	v_pk_mul_f32 v[6:7], v[6:7], v[14:15]
	v_pk_mul_f32 v[10:11], v[10:11], v[18:19]
	v_pk_mul_f32 v[12:13], v[12:13], v[20:21]
	v_pk_mul_f32 v[8:9], v[8:9], v[16:17]
	v_pk_mul_f32 v[12:13], v[4:5], v[12:13]
	v_pk_mul_f32 v[4:5], v[2:3], v[10:11]
	v_cvt_pk_bf16_f32 v2, v6, v7
	v_mad_i64_i32 v[6:7], s[0:1], v162, s66, v[114:115]
	v_cvt_pk_bf16_f32 v3, v8, v9
	v_cvt_pk_bf16_f32 v4, v4, v5
	v_cvt_pk_bf16_f32 v5, v12, v13
	v_lshl_add_u64 v[6:7], v[6:7], 0, v[116:117]
	s_andn2_b64 vcc, exec, s[6:7]
	s_mov_b64 s[0:1], -1
	global_store_dwordx4 v[6:7], v[2:5], off
	s_cbranch_vccnz .LBB0_1044
	s_andn2_b64 vcc, exec, s[14:15]
	s_cbranch_vccnz .LBB0_1043
	s_barrier
	s_branch .LBB0_1043

; #define PG8_STAGE(bufoff, gbase, voff) do { _Pragma("unroll") for (int _i = 0; _i < 2; ++_i) \
;         __builtin_amdgcn_global_load_lds((const unsigned*)((const char*)(gbase) + (voff)[_i]), (PG8_LAS unsigned*)(lds + (bufoff) + ldsw + _i * 8192), 16, 0, 0); } while (0)
; #define PG8_WAIT_V(n) asm volatile("s_waitcnt vmcnt(" #n ")" ::: "memory")
; #define PG8_BAR __builtin_amdgcn_s_barrier()
; template <class Epi, class Sched, bool ALIGN_EPI = false, bool SP2 = false>
; __device__ __forceinline__ void gemm_phase(PG8_LAS unsigned char* lds, const Gemm g, const Sched& S, const Epi& E) {
;     ...
;     const char* cA = (const char*)g.A + (size_t)cur.pm * tA + (size_t)cur.pn * pnA; const char* cB = (const char*)g.Bt + (size_t)cur.pn * tB;
;     S.a_ready(cur);
;     if constexpr (SP2) {
;         PG8_STAGE(PG8_SB(0, 0), cB, voffB); PG8_STAGE(PG8_SB(0, 1), cB + hB, voffB); PG8_STAGE(PG8_SA(0, 0), cA, voffA); PG8_STAGE(PG8_SA(0, 1), cA + hA, voffA);
;         if (wr == 1) PG8_BAR;
;         PG8_WAIT_V(2); PG8_BAR;
;         PG8_STAGE(PG8_SB(1, 0), cB + kstep, voffB); PG8_STAGE(PG8_SA(1, 0), cA + kstep, voffA); PG8_STAGE(PG8_SB(1, 1), cB + hB + kstep, voffB);
;         PG8_WAIT_V(6); PG8_BAR;
.LBB0_1113:
	s_add_u32 s12, s6, 0x15800000
	s_addc_u32 s13, s7, 0
	s_add_u32 s14, s6, 0x2000000
	s_mov_b64 s[16:17], 0x80
	s_addc_u32 s15, s7, 0
	s_and_b32 s51, s4, 3
	s_add_i32 m0, s46, 0x18000
	v_lshl_add_u64 v[8:9], v[8:9], 0, s[16:17]
	s_lshl_b32 s4, s5, 13
	s_lshl_b32 s18, s51, 12
	s_waitcnt vmcnt(2)
	s_barrier
	global_load_lds_dwordx4 v[8:9], off
	v_lshl_add_u64 v[4:5], v[4:5], 0, s[16:17]
	s_add_i32 m0, s46, 0x1a000
	s_add_i32 s52, s46, 0x8000
	s_add_i32 s53, s46, 0xa000
	global_load_lds_dwordx4 v[4:5], off
	v_lshl_add_u64 v[2:3], v[2:3], 0, s[16:17]
	s_mov_b32 m0, s52
	s_add_u32 s6, s36, 0x160080
	global_load_lds_dwordx4 v[2:3], off
	v_lshl_add_u64 v[2:3], v[6:7], 0, s[16:17]
	s_mov_b32 m0, s53
	s_addc_u32 s7, s37, 0
	global_load_lds_dwordx4 v[2:3], off
	s_add_i32 m0, s46, 0x1c000
	v_lshl_add_u64 v[2:3], s[6:7], 0, v[156:157]
	global_load_lds_dwordx4 v[2:3], off
	v_lshl_add_u64 v[2:3], s[6:7], 0, v[160:161]
	s_add_i32 m0, s46, 0x1e000
	s_mov_b64 s[6:7], 0x160080
	global_load_lds_dwordx4 v[2:3], off
	v_bfe_u32 v3, v10, 4, 2
	v_and_b32_e32 v2, 15, v10
	v_lshlrev_b32_e32 v5, 4, v3
	v_lshl_or_b32 v1, s5, 6, v2
	v_lshl_or_b32 v2, v2, 6, v5
	v_lshlrev_b32_e32 v5, 2, v10
	v_and_b32_e32 v5, 32, v5
	v_lshlrev_b32_e32 v4, 3, v3
	v_bitop3_b32 v6, v2, s4, v5 bitop3:0xde
	v_bitop3_b32 v188, v2, s18, v5 bitop3:0xde
	v_cmp_eq_u32_e64 s[4:5], 0, v3
	v_lshrrev_b32_e32 v3, 1, v11
	v_mul_lo_u32 v2, v12, s9
	v_mad_u64_u32 v[2:3], s[38:39], v3, s22, v[2:3]
	v_or_b32_e32 v2, v2, v13
	v_add_lshl_u32 v2, v2, v14, 1
	v_mov_b32_e32 v3, v157
	v_lshl_add_u64 v[162:163], v[2:3], 0, s[6:7]
	v_lshrrev_b32_e32 v3, 1, v15
	v_mul_lo_u32 v2, v16, s9
	s_cmpk_lt_u32 s8, 0x100
	v_mad_u64_u32 v[2:3], s[8:9], v3, s22, v[2:3]
	s_waitcnt vmcnt(6)
	v_or_b32_e32 v2, v2, v17
	s_cselect_b64 s[20:21], -1, 0
	v_add_lshl_u32 v2, v2, v18, 1
	v_mov_b32_e32 v3, v157
	s_add_i32 s55, 0, 0x10000
	s_add_i32 s56, 0, 0x14000
	v_lshl_or_b32 v189, s51, 5, v4
	s_waitcnt lgkmcnt(0)
	s_ashr_i32 s54, s50, 31
	v_lshl_add_u64 v[164:165], v[2:3], 0, s[6:7]
	v_mov_b64_e32 v[166:167], 0x200
	v_mov_b64_e32 v[168:169], 0x1ff
	v_add_u32_e32 v190, s55, v188
	v_add_u32_e32 v191, s56, v188
	v_add_u32_e32 v192, 0, v6
	v_mbcnt_hi_u32_b32 v193, -1, v222
	s_mov_b32 s57, 0
	s_barrier
	s_mov_b32 s101, 1
	s_branch .LBB0_1116

; #define PG8_STAGE(bufoff, gbase, voff) do { _Pragma("unroll") for (int _i = 0; _i < 2; ++_i) \
;         __builtin_amdgcn_global_load_lds((const unsigned*)((const char*)(gbase) + (voff)[_i]), (PG8_LAS unsigned*)(lds + (bufoff) + ldsw + _i * 8192), 16, 0, 0); } while (0)
; #define PG8_LDA(dst, b, h) do { _Pragma("unroll") for (int m = 0; m < 4; ++m) _Pragma("unroll") for (int k = 0; k < 2; ++k) dst[m][k] = *(const PG8_LAS bf16x8*)(lds + PG8_SA(b, h) + aoff + m * 2048 + k * 1024); } while (0)
; #define PG8_LDB(dst, b, h) do { _Pragma("unroll") for (int n = 0; n < 2; ++n) _Pragma("unroll") for (int k = 0; k < 2; ++k) dst[n][k] = *(const PG8_LAS bf16x8*)(lds + PG8_SB(b, h) + boff + n * 2048 + k * 1024); } while (0)
; #define PG8_MMA(ai, bj, At, Bt) do { __builtin_amdgcn_s_setprio(1); _Pragma("unroll") for (int m = 0; m < 4; ++m) _Pragma("unroll") for (int n = 0; n < 2; ++n) _Pragma("unroll") for (int k = 0; k < 2; ++k) \
;         acc[ai][bj][m][n] = __builtin_amdgcn_mfma_f32_16x16x32_bf16(Bt[n][k], At[m][k], acc[ai][bj][m][n], 0, 0, 0); __builtin_amdgcn_s_setprio(0); } while (0)
; #define PG8_WAIT_V(n) asm volatile("s_waitcnt vmcnt(" #n ")" ::: "memory")
; template <class Epi, class Sched, bool ALIGN_EPI = false, bool SP2 = false>
; __device__ __forceinline__ void gemm_phase(PG8_LAS unsigned char* lds, const Gemm g, const Sched& S, const Epi& E) {
;     ...
;         const char* nA = has_next ? (const char*)g.A + (size_t)nxt.pm * tA + (size_t)nxt.pn * pnA : cA; const char* nB = has_next ? (const char*)g.Bt + (size_t)nxt.pn * tB : cB;
; #pragma nounroll
;         for (int t = 0; t < nt; t += 2) {
;             const bool last = (t == nt - 2);
;             const char* a1 = cA + (size_t)(t + 1) * kstep;
;             const char* a2 = last ? nA : cA + (size_t)(t + 2) * kstep; const char* b2 = last ? nB : cB + (size_t)(t + 2) * kstep;
;             const char* a3 = a2 + kstep; const char* b3 = b2 + kstep;
;             if (last && has_next) S.a_ready(nxt);
;             if constexpr (SP2) {
;             PG8_LDB(B0, 0, 0); PG8_LDB(B1, 0, 1); PG8_SCHED; PG8_LDA(At, 0, 0); PG8_STAGE(PG8_SA(1, 1), a1 + hA, voffA);
;             PG8_WAIT_V(8); PG8_WAIT_L(0); PG8_BAR; PG8_MMA(0, 0, At, B0); PG8_MMA(0, 1, At, B1); PG8_BAR; PG8_SCHED;
;             PG8_LDA(At, 0, 1); PG8_STAGE(PG8_SB(0, 0), b2, voffB); PG8_STAGE(PG8_SB(0, 1), b2 + hB, voffB); PG8_STAGE(PG8_SA(0, 0), a2, voffA);
.LBB0_1126:
	s_add_u32 s61, s36, 0x100
	v_mov_b32_e32 v2, 0
	s_addc_u32 s62, s37, 0
	s_mov_b32 s63, -2
	s_waitcnt lgkmcnt(0)
	v_mov_b32_e32 v3, v2
	ds_read_b128 v[130:133], v190
	ds_read_b128 v[134:137], v190 offset:1024
	ds_read_b128 v[138:141], v190 offset:2048
	ds_read_b128 v[142:145], v190 offset:3072
	ds_read_b128 v[146:149], v191
	ds_read_b128 v[150:153], v191 offset:1024
	ds_read_b128 v[170:173], v191 offset:2048
	ds_read_b128 v[174:177], v191 offset:3072
	s_add_u32 s36, s24, 0x100
	s_addc_u32 s37, s25, 0
	s_cmpk_eq_i32 s63, 0x54
	s_cselect_b32 s41, s9, s37
	s_cselect_b32 s40, s8, s36
	s_cselect_b32 s39, s23, s62
	s_cselect_b32 s38, s22, s61
	s_add_i32 m0, s46, 0xc000
	ds_read_b128 v[178:181], v192
	ds_read_b128 v[182:185], v192 offset:1024
	ds_read_b128 v[194:197], v192 offset:2048
	ds_read_b128 v[198:201], v192 offset:3072
	ds_read_b128 v[202:205], v192 offset:4096
	ds_read_b128 v[206:209], v192 offset:5120
	ds_read_b128 v[210:213], v192 offset:6144
	ds_read_b128 v[214:217], v192 offset:7168
	global_load_lds_dwordx4 v162, s[24:25]
	s_add_i32 m0, s46, 0xe000
	s_nop 0
	global_load_lds_dwordx4 v164, s[24:25]
	s_cmp_eq_u32 s101, 0
	s_cbranch_scc1 .Lfw_5_0
	s_waitcnt vmcnt(8)
.Lfw_5_0:
	s_waitcnt lgkmcnt(0)
	s_barrier
	s_waitcnt lgkmcnt(0)
	v_mfma_f32_16x16x32_bf16 v[126:129], v[130:133], v[178:181], 0
	v_mfma_f32_16x16x32_bf16 v[122:125], v[138:141], v[178:181], 0
	v_mfma_f32_16x16x32_bf16 v[110:113], v[130:133], v[194:197], 0
	v_mfma_f32_16x16x32_bf16 v[106:109], v[138:141], v[194:197], 0
	v_mfma_f32_16x16x32_bf16 v[94:97], v[130:133], v[202:205], 0
	v_mfma_f32_16x16x32_bf16 v[90:93], v[138:141], v[202:205], 0
	v_mfma_f32_16x16x32_bf16 v[78:81], v[130:133], v[210:213], 0
	v_mfma_f32_16x16x32_bf16 v[74:77], v[138:141], v[210:213], 0
	v_mfma_f32_16x16x32_bf16 v[126:129], v[134:137], v[182:185], v[126:129]
	v_mfma_f32_16x16x32_bf16 v[122:125], v[142:145], v[182:185], v[122:125]
	v_mfma_f32_16x16x32_bf16 v[110:113], v[134:137], v[198:201], v[110:113]
	v_mfma_f32_16x16x32_bf16 v[106:109], v[142:145], v[198:201], v[106:109]
	v_mfma_f32_16x16x32_bf16 v[94:97], v[134:137], v[206:209], v[94:97]
	v_mfma_f32_16x16x32_bf16 v[90:93], v[142:145], v[206:209], v[90:93]
	v_mfma_f32_16x16x32_bf16 v[78:81], v[134:137], v[214:217], v[78:81]
	v_mfma_f32_16x16x32_bf16 v[74:77], v[142:145], v[214:217], v[74:77]
	v_mfma_f32_16x16x32_bf16 v[118:121], v[146:149], v[178:181], 0
	v_mfma_f32_16x16x32_bf16 v[114:117], v[170:173], v[178:181], 0
	v_mfma_f32_16x16x32_bf16 v[102:105], v[146:149], v[194:197], 0
	v_mfma_f32_16x16x32_bf16 v[98:101], v[170:173], v[194:197], 0
	v_mfma_f32_16x16x32_bf16 v[86:89], v[146:149], v[202:205], 0
	v_mfma_f32_16x16x32_bf16 v[82:85], v[170:173], v[202:205], 0
	v_mfma_f32_16x16x32_bf16 v[70:73], v[146:149], v[210:213], 0
	v_mfma_f32_16x16x32_bf16 v[66:69], v[170:173], v[210:213], 0
	v_mfma_f32_16x16x32_bf16 v[118:121], v[150:153], v[182:185], v[118:121]
	v_mfma_f32_16x16x32_bf16 v[114:117], v[174:177], v[182:185], v[114:117]
	v_mfma_f32_16x16x32_bf16 v[102:105], v[150:153], v[198:201], v[102:105]
	v_mfma_f32_16x16x32_bf16 v[98:101], v[174:177], v[198:201], v[98:101]
	v_mfma_f32_16x16x32_bf16 v[86:89], v[150:153], v[206:209], v[86:89]
	v_mfma_f32_16x16x32_bf16 v[82:85], v[174:177], v[206:209], v[82:85]
	v_mfma_f32_16x16x32_bf16 v[70:73], v[150:153], v[214:217], v[70:73]
	v_mfma_f32_16x16x32_bf16 v[66:69], v[174:177], v[214:217], v[66:69]
	s_barrier
	s_add_i32 s18, s55, s45
	s_add_u32 s76, s38, s16
	s_addc_u32 s77, s39, s17
	s_mov_b32 m0, s18
	ds_read_b128 v[178:181], v192 offset:16384
	ds_read_b128 v[182:185], v192 offset:17408
	ds_read_b128 v[194:197], v192 offset:18432
	ds_read_b128 v[198:201], v192 offset:19456
	ds_read_b128 v[202:205], v192 offset:20480
	ds_read_b128 v[206:209], v192 offset:21504
	ds_read_b128 v[210:213], v192 offset:22528
	ds_read_b128 v[214:217], v192 offset:23552
	global_load_lds_dwordx4 v156, s[38:39]
	s_add_i32 m0, s18, 0x2000
	s_add_u32 s24, s38, 0x160000
	s_addc_u32 s25, s39, 0
	s_add_i32 s18, s56, s45
	global_load_lds_dwordx4 v160, s[38:39]
	s_mov_b32 m0, s18
	s_nop 0
	global_load_lds_dwordx4 v156, s[24:25]
	s_add_i32 m0, s18, 0x2000
	s_nop 0
	global_load_lds_dwordx4 v160, s[24:25]
	s_add_u32 s78, s40, s16
	s_addc_u32 s79, s41, s17
	s_mov_b32 m0, s46
	s_nop 0
	global_load_lds_dwordx4 v154, s[40:41]
	s_mov_b32 m0, s47
	s_nop 0
	global_load_lds_dwordx4 v158, s[40:41]
	s_cmp_eq_u32 s101, 0
	s_cbranch_scc1 .Lfw_5_1
	s_waitcnt vmcnt(8)
; #define PG8_STAGE(bufoff, gbase, voff) do { _Pragma("unroll") for (int _i = 0; _i < 2; ++_i) \
;         __builtin_amdgcn_global_load_lds((const unsigned*)((const char*)(gbase) + (voff)[_i]), (PG8_LAS unsigned*)(lds + (bufoff) + ldsw + _i * 8192), 16, 0, 0); } while (0)
; #define PG8_LDA(dst, b, h) do { _Pragma("unroll") for (int m = 0; m < 4; ++m) _Pragma("unroll") for (int k = 0; k < 2; ++k) dst[m][k] = *(const PG8_LAS bf16x8*)(lds + PG8_SA(b, h) + aoff + m * 2048 + k * 1024); } while (0)
; #define PG8_LDB(dst, b, h) do { _Pragma("unroll") for (int n = 0; n < 2; ++n) _Pragma("unroll") for (int k = 0; k < 2; ++k) dst[n][k] = *(const PG8_LAS bf16x8*)(lds + PG8_SB(b, h) + boff + n * 2048 + k * 1024); } while (0)
; #define PG8_MMA(ai, bj, At, Bt) do { __builtin_amdgcn_s_setprio(1); _Pragma("unroll") for (int m = 0; m < 4; ++m) _Pragma("unroll") for (int n = 0; n < 2; ++n) _Pragma("unroll") for (int k = 0; k < 2; ++k) \
;         acc[ai][bj][m][n] = __builtin_amdgcn_mfma_f32_16x16x32_bf16(Bt[n][k], At[m][k], acc[ai][bj][m][n], 0, 0, 0); __builtin_amdgcn_s_setprio(0); } while (0)
; #define PG8_WAIT_V(n) asm volatile("s_waitcnt vmcnt(" #n ")" ::: "memory")
; #define PG8_WAIT_L(n) asm volatile("s_waitcnt lgkmcnt(" #n ")" ::: "memory")
; #define PG8_BAR __builtin_amdgcn_s_barrier()
; #define PG8_SCHED __builtin_amdgcn_sched_barrier(0)
; template <class Epi, class Sched, bool ALIGN_EPI = false, bool SP2 = false>
; __device__ __forceinline__ void gemm_phase(PG8_LAS unsigned char* lds, const Gemm g, const Sched& S, const Epi& E) {
;     ...
;             PG8_WAIT_V(8); PG8_WAIT_L(0); PG8_BAR; PG8_MMA(1, 0, At, B0); PG8_MMA(1, 1, At, B1); PG8_BAR; PG8_SCHED;
;             PG8_LDB(B0, 1, 0); PG8_LDB(B1, 1, 1); PG8_SCHED; PG8_LDA(At, 1, 0); PG8_STAGE(PG8_SA(0, 1), a2 + hA, voffA);
;             PG8_WAIT_V(8); PG8_WAIT_L(0); PG8_BAR; PG8_MMA(0, 0, At, B0); PG8_MMA(0, 1, At, B1); PG8_BAR; PG8_SCHED;
.Lfw_5_1:
	s_waitcnt lgkmcnt(0)
	s_barrier
	s_waitcnt lgkmcnt(0)
	v_mfma_f32_16x16x32_bf16 v[62:65], v[130:133], v[178:181], 0
	v_mfma_f32_16x16x32_bf16 v[58:61], v[138:141], v[178:181], 0
	v_mfma_f32_16x16x32_bf16 v[46:49], v[130:133], v[194:197], 0
	v_mfma_f32_16x16x32_bf16 v[42:45], v[138:141], v[194:197], 0
	v_mfma_f32_16x16x32_bf16 v[30:33], v[130:133], v[202:205], 0
	v_mfma_f32_16x16x32_bf16 v[26:29], v[138:141], v[202:205], 0
	v_mfma_f32_16x16x32_bf16 v[14:17], v[130:133], v[210:213], 0
	v_mfma_f32_16x16x32_bf16 v[10:13], v[138:141], v[210:213], 0
	v_mfma_f32_16x16x32_bf16 v[62:65], v[134:137], v[182:185], v[62:65]
	v_mfma_f32_16x16x32_bf16 v[58:61], v[142:145], v[182:185], v[58:61]
	v_mfma_f32_16x16x32_bf16 v[46:49], v[134:137], v[198:201], v[46:49]
	v_mfma_f32_16x16x32_bf16 v[42:45], v[142:145], v[198:201], v[42:45]
	v_mfma_f32_16x16x32_bf16 v[30:33], v[134:137], v[206:209], v[30:33]
	v_mfma_f32_16x16x32_bf16 v[26:29], v[142:145], v[206:209], v[26:29]
	v_mfma_f32_16x16x32_bf16 v[14:17], v[134:137], v[214:217], v[14:17]
	v_mfma_f32_16x16x32_bf16 v[10:13], v[142:145], v[214:217], v[10:13]
	v_mfma_f32_16x16x32_bf16 v[54:57], v[146:149], v[178:181], 0
	v_mfma_f32_16x16x32_bf16 v[50:53], v[170:173], v[178:181], 0
	v_mfma_f32_16x16x32_bf16 v[38:41], v[146:149], v[194:197], 0
	v_mfma_f32_16x16x32_bf16 v[34:37], v[170:173], v[194:197], 0
	v_mfma_f32_16x16x32_bf16 v[22:25], v[146:149], v[202:205], 0
	v_mfma_f32_16x16x32_bf16 v[18:21], v[170:173], v[202:205], 0
	v_mfma_f32_16x16x32_bf16 v[6:9], v[146:149], v[210:213], 0
	v_mfma_f32_16x16x32_bf16 v[2:5], v[170:173], v[210:213], 0
	v_mfma_f32_16x16x32_bf16 v[54:57], v[150:153], v[182:185], v[54:57]
	v_mfma_f32_16x16x32_bf16 v[50:53], v[174:177], v[182:185], v[50:53]
	v_mfma_f32_16x16x32_bf16 v[38:41], v[150:153], v[198:201], v[38:41]
	v_mfma_f32_16x16x32_bf16 v[34:37], v[174:177], v[198:201], v[34:37]
	v_mfma_f32_16x16x32_bf16 v[22:25], v[150:153], v[206:209], v[22:25]
	v_mfma_f32_16x16x32_bf16 v[18:21], v[174:177], v[206:209], v[18:21]
	v_mfma_f32_16x16x32_bf16 v[6:9], v[150:153], v[214:217], v[6:9]
	v_mfma_f32_16x16x32_bf16 v[2:5], v[174:177], v[214:217], v[2:5]
	s_barrier
	s_add_i32 s18, 0, 0x18000
	s_add_i32 s19, 0, 0x1c000
	v_add_u32_e32 v142, s18, v188
	v_add_u32_e32 v174, s19, v188
	ds_read_b128 v[130:133], v142
	ds_read_b128 v[134:137], v142 offset:1024
	ds_read_b128 v[138:141], v142 offset:2048
	ds_read_b128 v[142:145], v142 offset:3072
	ds_read_b128 v[146:149], v174
	ds_read_b128 v[150:153], v174 offset:1024
	ds_read_b128 v[170:173], v174 offset:2048
	ds_read_b128 v[174:177], v174 offset:3072
	s_add_u32 s24, s40, 0x160000
	s_addc_u32 s25, s41, 0
	s_mov_b32 m0, s48
	ds_read_b128 v[178:181], v192 offset:32768
	ds_read_b128 v[182:185], v192 offset:33792
	ds_read_b128 v[194:197], v192 offset:34816
	ds_read_b128 v[198:201], v192 offset:35840
	ds_read_b128 v[202:205], v192 offset:36864
	ds_read_b128 v[206:209], v192 offset:37888
	ds_read_b128 v[210:213], v192 offset:38912
	ds_read_b128 v[214:217], v192 offset:39936
	global_load_lds_dwordx4 v154, s[24:25]
	s_mov_b32 m0, s49
	s_nop 0
	global_load_lds_dwordx4 v158, s[24:25]
	s_waitcnt vmcnt(8)
	s_waitcnt lgkmcnt(0)
	s_barrier
	s_waitcnt lgkmcnt(0)
	v_mfma_f32_16x16x32_bf16 v[126:129], v[130:133], v[178:181], v[126:129]
	v_mfma_f32_16x16x32_bf16 v[122:125], v[138:141], v[178:181], v[122:125]
	v_mfma_f32_16x16x32_bf16 v[110:113], v[130:133], v[194:197], v[110:113]
	v_mfma_f32_16x16x32_bf16 v[106:109], v[138:141], v[194:197], v[106:109]
	v_mfma_f32_16x16x32_bf16 v[94:97], v[130:133], v[202:205], v[94:97]
	v_mfma_f32_16x16x32_bf16 v[90:93], v[138:141], v[202:205], v[90:93]
	v_mfma_f32_16x16x32_bf16 v[78:81], v[130:133], v[210:213], v[78:81]
	v_mfma_f32_16x16x32_bf16 v[74:77], v[138:141], v[210:213], v[74:77]
	v_mfma_f32_16x16x32_bf16 v[126:129], v[134:137], v[182:185], v[126:129]
	v_mfma_f32_16x16x32_bf16 v[122:125], v[142:145], v[182:185], v[122:125]
	v_mfma_f32_16x16x32_bf16 v[110:113], v[134:137], v[198:201], v[110:113]
	v_mfma_f32_16x16x32_bf16 v[106:109], v[142:145], v[198:201], v[106:109]
	v_mfma_f32_16x16x32_bf16 v[94:97], v[134:137], v[206:209], v[94:97]
	v_mfma_f32_16x16x32_bf16 v[90:93], v[142:145], v[206:209], v[90:93]
	v_mfma_f32_16x16x32_bf16 v[78:81], v[134:137], v[214:217], v[78:81]
	v_mfma_f32_16x16x32_bf16 v[74:77], v[142:145], v[214:217], v[74:77]
	v_mfma_f32_16x16x32_bf16 v[118:121], v[146:149], v[178:181], v[118:121]
	v_mfma_f32_16x16x32_bf16 v[114:117], v[170:173], v[178:181], v[114:117]
	v_mfma_f32_16x16x32_bf16 v[102:105], v[146:149], v[194:197], v[102:105]
	v_mfma_f32_16x16x32_bf16 v[98:101], v[170:173], v[194:197], v[98:101]
	v_mfma_f32_16x16x32_bf16 v[86:89], v[146:149], v[202:205], v[86:89]
	v_mfma_f32_16x16x32_bf16 v[82:85], v[170:173], v[202:205], v[82:85]
	v_mfma_f32_16x16x32_bf16 v[70:73], v[146:149], v[210:213], v[70:73]
	v_mfma_f32_16x16x32_bf16 v[66:69], v[170:173], v[210:213], v[66:69]
	v_mfma_f32_16x16x32_bf16 v[118:121], v[150:153], v[182:185], v[118:121]
	v_mfma_f32_16x16x32_bf16 v[114:117], v[174:177], v[182:185], v[114:117]
	v_mfma_f32_16x16x32_bf16 v[102:105], v[150:153], v[198:201], v[102:105]
	v_mfma_f32_16x16x32_bf16 v[98:101], v[174:177], v[198:201], v[98:101]
	v_mfma_f32_16x16x32_bf16 v[86:89], v[150:153], v[206:209], v[86:89]
	v_mfma_f32_16x16x32_bf16 v[82:85], v[174:177], v[206:209], v[82:85]
	v_mfma_f32_16x16x32_bf16 v[70:73], v[150:153], v[214:217], v[70:73]
	v_mfma_f32_16x16x32_bf16 v[66:69], v[174:177], v[214:217], v[66:69]
	s_barrier
; #define PG8_STAGE(bufoff, gbase, voff) do { _Pragma("unroll") for (int _i = 0; _i < 2; ++_i) \
;         __builtin_amdgcn_global_load_lds((const unsigned*)((const char*)(gbase) + (voff)[_i]), (PG8_LAS unsigned*)(lds + (bufoff) + ldsw + _i * 8192), 16, 0, 0); } while (0)
; #define PG8_LDA(dst, b, h) do { _Pragma("unroll") for (int m = 0; m < 4; ++m) _Pragma("unroll") for (int k = 0; k < 2; ++k) dst[m][k] = *(const PG8_LAS bf16x8*)(lds + PG8_SA(b, h) + aoff + m * 2048 + k * 1024); } while (0)
; #define PG8_MMA(ai, bj, At, Bt) do { __builtin_amdgcn_s_setprio(1); _Pragma("unroll") for (int m = 0; m < 4; ++m) _Pragma("unroll") for (int n = 0; n < 2; ++n) _Pragma("unroll") for (int k = 0; k < 2; ++k) \
;         acc[ai][bj][m][n] = __builtin_amdgcn_mfma_f32_16x16x32_bf16(Bt[n][k], At[m][k], acc[ai][bj][m][n], 0, 0, 0); __builtin_amdgcn_s_setprio(0); } while (0)
; #define PG8_WAIT_V(n) asm volatile("s_waitcnt vmcnt(" #n ")" ::: "memory")
; #define PG8_WAIT_L(n) asm volatile("s_waitcnt lgkmcnt(" #n ")" ::: "memory")
; #define PG8_BAR __builtin_amdgcn_s_barrier()
; #define PG8_SCHED __builtin_amdgcn_sched_barrier(0)
; template <class Epi, class Sched, bool ALIGN_EPI = false, bool SP2 = false>
; __device__ __forceinline__ void gemm_phase(PG8_LAS unsigned char* lds, const Gemm g, const Sched& S, const Epi& E) {
;     ...
;         for (int t = 0; t < nt; t += 2) {
;             const bool last = (t == nt - 2);
;             const char* a1 = cA + (size_t)(t + 1) * kstep;
;             const char* a2 = last ? nA : cA + (size_t)(t + 2) * kstep; const char* b2 = last ? nB : cB + (size_t)(t + 2) * kstep;
;     ...
;             PG8_LDA(At, 1, 1); PG8_STAGE(PG8_SB(1, 0), b3, voffB); PG8_STAGE(PG8_SB(1, 1), b3 + hB, voffB); PG8_STAGE(PG8_SA(1, 0), a3, voffA);
;             PG8_WAIT_V(8); PG8_WAIT_L(0); PG8_BAR; PG8_MMA(1, 0, At, B0); PG8_MMA(1, 1, At, B1); PG8_BAR; PG8_SCHED;
	s_add_i32 s18, s18, s45
	s_mov_b32 m0, s18
	ds_read_b128 v[178:181], v192 offset:49152
	ds_read_b128 v[182:185], v192 offset:50176
	ds_read_b128 v[194:197], v192 offset:51200
	ds_read_b128 v[198:201], v192 offset:52224
	ds_read_b128 v[202:205], v192 offset:53248
	ds_read_b128 v[206:209], v192 offset:54272
	ds_read_b128 v[210:213], v192 offset:55296
	ds_read_b128 v[214:217], v192 offset:56320
	global_load_lds_dwordx4 v156, s[76:77]
	s_add_i32 m0, s18, 0x2000
	s_add_u32 s24, s38, 0x160080
	s_addc_u32 s25, s39, 0
	s_add_i32 s18, s19, s45
	global_load_lds_dwordx4 v160, s[76:77]
	s_mov_b32 m0, s18
	s_nop 0
	global_load_lds_dwordx4 v156, s[24:25]
	s_add_i32 m0, s18, 0x2000
	s_nop 0
	global_load_lds_dwordx4 v160, s[24:25]
	s_mov_b32 m0, s52
	s_nop 0
	global_load_lds_dwordx4 v154, s[78:79]
	s_mov_b32 m0, s53
	s_nop 0
	global_load_lds_dwordx4 v158, s[78:79]
	s_waitcnt vmcnt(8)
	s_waitcnt lgkmcnt(0)
	s_barrier
	s_waitcnt lgkmcnt(0)
	v_mfma_f32_16x16x32_bf16 v[62:65], v[130:133], v[178:181], v[62:65]
	v_mfma_f32_16x16x32_bf16 v[58:61], v[138:141], v[178:181], v[58:61]
	v_mfma_f32_16x16x32_bf16 v[46:49], v[130:133], v[194:197], v[46:49]
	v_mfma_f32_16x16x32_bf16 v[42:45], v[138:141], v[194:197], v[42:45]
	v_mfma_f32_16x16x32_bf16 v[30:33], v[130:133], v[202:205], v[30:33]
	v_mfma_f32_16x16x32_bf16 v[26:29], v[138:141], v[202:205], v[26:29]
	v_mfma_f32_16x16x32_bf16 v[14:17], v[130:133], v[210:213], v[14:17]
	v_mfma_f32_16x16x32_bf16 v[10:13], v[138:141], v[210:213], v[10:13]
	v_mfma_f32_16x16x32_bf16 v[62:65], v[134:137], v[182:185], v[62:65]
	v_mfma_f32_16x16x32_bf16 v[58:61], v[142:145], v[182:185], v[58:61]
	v_mfma_f32_16x16x32_bf16 v[46:49], v[134:137], v[198:201], v[46:49]
	v_mfma_f32_16x16x32_bf16 v[42:45], v[142:145], v[198:201], v[42:45]
	v_mfma_f32_16x16x32_bf16 v[30:33], v[134:137], v[206:209], v[30:33]
	v_mfma_f32_16x16x32_bf16 v[26:29], v[142:145], v[206:209], v[26:29]
	v_mfma_f32_16x16x32_bf16 v[14:17], v[134:137], v[214:217], v[14:17]
	v_mfma_f32_16x16x32_bf16 v[10:13], v[142:145], v[214:217], v[10:13]
	v_mfma_f32_16x16x32_bf16 v[54:57], v[146:149], v[178:181], v[54:57]
	v_mfma_f32_16x16x32_bf16 v[50:53], v[170:173], v[178:181], v[50:53]
	v_mfma_f32_16x16x32_bf16 v[38:41], v[146:149], v[194:197], v[38:41]
	v_mfma_f32_16x16x32_bf16 v[34:37], v[170:173], v[194:197], v[34:37]
	v_mfma_f32_16x16x32_bf16 v[22:25], v[146:149], v[202:205], v[22:25]
	v_mfma_f32_16x16x32_bf16 v[18:21], v[170:173], v[202:205], v[18:21]
	v_mfma_f32_16x16x32_bf16 v[6:9], v[146:149], v[210:213], v[6:9]
	v_mfma_f32_16x16x32_bf16 v[2:5], v[170:173], v[210:213], v[2:5]
	v_mfma_f32_16x16x32_bf16 v[54:57], v[150:153], v[182:185], v[54:57]
	v_mfma_f32_16x16x32_bf16 v[50:53], v[174:177], v[182:185], v[50:53]
	v_mfma_f32_16x16x32_bf16 v[38:41], v[150:153], v[198:201], v[38:41]
	v_mfma_f32_16x16x32_bf16 v[34:37], v[174:177], v[198:201], v[34:37]
	v_mfma_f32_16x16x32_bf16 v[22:25], v[150:153], v[206:209], v[22:25]
	v_mfma_f32_16x16x32_bf16 v[18:21], v[174:177], v[206:209], v[18:21]
	v_mfma_f32_16x16x32_bf16 v[6:9], v[150:153], v[214:217], v[6:9]
	v_mfma_f32_16x16x32_bf16 v[2:5], v[174:177], v[214:217], v[2:5]
	s_barrier
	s_add_i32 s63, s63, 2
	s_add_u32 s61, s61, 0x100
	s_addc_u32 s62, s62, 0
	s_cmpk_gt_u32 s63, 0x55
	s_mov_b64 s[24:25], s[36:37]
	s_mov_b32 s101, 0
